# GEMM K-loop LDS-DMA pieces use SGPR-base + 32-bit VGPR offset addressing (drops per-piece 64-bit VALU adds); plus nosync+cvt4
# speedup vs baseline: 1.0046x; 1.0046x over previous
; #define PG8_STAGE(bufoff, gbase, voff) do { _Pragma("unroll") for (int _i = 0; _i < 2; ++_i) \
;         __builtin_amdgcn_global_load_lds((const unsigned*)((const char*)(gbase) + (voff)[_i]), (PG8_LAS unsigned*)(lds + (bufoff) + ldsw + _i * 8192), 16, 0, 0); } while (0)
; #define PG8_LDA(dst, b, h) do { _Pragma("unroll") for (int m = 0; m < 4; ++m) _Pragma("unroll") for (int k = 0; k < 2; ++k) dst[m][k] = *(const PG8_LAS bf16x8*)(lds + PG8_SA(b, h) + aoff + m * 2048 + k * 1024); } while (0)
; #define PG8_LDB(dst, b, h) do { _Pragma("unroll") for (int n = 0; n < 2; ++n) _Pragma("unroll") for (int k = 0; k < 2; ++k) dst[n][k] = *(const PG8_LAS bf16x8*)(lds + PG8_SB(b, h) + boff + n * 2048 + k * 1024); } while (0)
; #define PG8_MMA(ai, bj, At, Bt) do { __builtin_amdgcn_s_setprio(1); _Pragma("unroll") for (int m = 0; m < 4; ++m) _Pragma("unroll") for (int n = 0; n < 2; ++n) _Pragma("unroll") for (int k = 0; k < 2; ++k) \
;         acc[ai][bj][m][n] = __builtin_amdgcn_mfma_f32_16x16x32_bf16(Bt[n][k], At[m][k], acc[ai][bj][m][n], 0, 0, 0); __builtin_amdgcn_s_setprio(0); } while (0)
; #define PG8_WAIT_V(n) asm volatile("s_waitcnt vmcnt(" #n ")" ::: "memory")
; #define PG8_WAIT_L(n) asm volatile("s_waitcnt lgkmcnt(" #n ")" ::: "memory")
; template <class Epi, class Sched, bool ALIGN_EPI = false, bool SP2 = false>
; __device__ __forceinline__ void gemm_phase(PG8_LAS unsigned char* lds, const Gemm g, const Sched& S, const Epi& E) {
;     ...
;             const bool last = (t == nt - 2);
;             const char* a1 = cA + PG8_AK(t + 1);
;             const char* a2 = last ? nA : cA + PG8_AK(t + 2); const char* b2 = last ? nB : cB + (size_t)(t + 2) * kstep;
;             const char* a3 = last ? nA + PG8_AK(1) : cA + PG8_AK(t + 3); const char* b3 = b2 + kstep;
;             if (last && has_next) S.a_ready(nxt);
;             if constexpr (SP2) {
;             PG8_LDB(B0, 0, 0); PG8_LDB(B1, 0, 1); PG8_SCHED; PG8_LDA(At, 0, 0); PG8_STAGE(PG8_SA(1, 1), a1 + hstepA, voffA);
;             PG8_WAIT_V(8); PG8_WAIT_L(0); PG8_BAR; PG8_MMA(0, 0, At, B0); PG8_MMA(0, 1, At, B1); PG8_BAR; PG8_SCHED;
;             PG8_LDA(At, 0, 1); PG8_STAGE(PG8_SB(0, 0), b2, voffB); PG8_STAGE(PG8_SB(0, 1), b2 + hstepB, voffB); PG8_STAGE(PG8_SA(0, 0), a2, voffA);
;             PG8_WAIT_V(8); PG8_WAIT_L(0); PG8_BAR; PG8_MMA(1, 0, At, B0); PG8_MMA(1, 1, At, B1); PG8_BAR; PG8_SCHED;
.LBB0_129:
	ds_read_b128 v[132:135], v172
	ds_read_b128 v[158:161], v172 offset:1024
	ds_read_b128 v[176:179], v172 offset:2048
	ds_read_b128 v[180:183], v172 offset:3072
	ds_read_b128 v[184:187], v173
	ds_read_b128 v[188:191], v173 offset:1024
	ds_read_b128 v[192:195], v173 offset:2048
	ds_read_b128 v[196:199], v173 offset:3072
	s_add_u32 s38, s28, s34
	s_addc_u32 s39, s29, s35
	s_add_u32 s42, s38, 0x100
	s_addc_u32 s43, s39, 0
	s_add_u32 s40, s62, s34
	s_addc_u32 s41, s63, s35
	s_add_u32 s38, s38, 0x180
	s_addc_u32 s39, s39, 0
	s_cmpk_eq_i32 s34, 0x700
	s_cselect_b32 s39, s37, s39
	s_cselect_b32 s38, s31, s38
	s_cselect_b32 s41, s21, s41
	s_cselect_b32 s40, s23, s40
	s_cselect_b32 s43, s3, s43
	s_cselect_b32 s42, s10, s42
	v_lshl_add_u64 v[204:205], v[130:131], 0, s[34:35]
	s_add_i32 m0, s49, 0xc000
	ds_read_b128 v[200:203], v174
	ds_read_b128 v[208:211], v174 offset:1024
	ds_read_b128 v[212:215], v174 offset:2048
	ds_read_b128 v[216:219], v174 offset:3072
	ds_read_b128 v[220:223], v174 offset:4096
	ds_read_b128 v[224:227], v174 offset:5120
	ds_read_b128 v[228:231], v174 offset:6144
	ds_read_b128 v[232:235], v174 offset:7168
	global_load_lds_dwordx4 v[204:205], off
	v_lshl_add_u64 v[204:205], v[128:129], 0, s[34:35]
	s_add_i32 m0, s49, 0xe000
	s_nop 0
	global_load_lds_dwordx4 v[204:205], off
	s_waitcnt vmcnt(8)
	s_waitcnt lgkmcnt(0)
	s_barrier
	s_setprio 1
	s_waitcnt lgkmcnt(0)
	v_mfma_f32_16x16x32_bf16 v[124:127], v[132:135], v[200:203], v[124:127]
	v_mfma_f32_16x16x32_bf16 v[120:123], v[176:179], v[200:203], v[120:123]
	v_mfma_f32_16x16x32_bf16 v[108:111], v[132:135], v[212:215], v[108:111]
	v_mfma_f32_16x16x32_bf16 v[104:107], v[176:179], v[212:215], v[104:107]
	v_mfma_f32_16x16x32_bf16 v[92:95], v[132:135], v[220:223], v[92:95]
	v_mfma_f32_16x16x32_bf16 v[88:91], v[176:179], v[220:223], v[88:91]
	v_mfma_f32_16x16x32_bf16 v[76:79], v[132:135], v[228:231], v[76:79]
	v_mfma_f32_16x16x32_bf16 v[72:75], v[176:179], v[228:231], v[72:75]
	v_mfma_f32_16x16x32_bf16 v[124:127], v[158:161], v[208:211], v[124:127]
	v_mfma_f32_16x16x32_bf16 v[120:123], v[180:183], v[208:211], v[120:123]
	v_mfma_f32_16x16x32_bf16 v[108:111], v[158:161], v[216:219], v[108:111]
	v_mfma_f32_16x16x32_bf16 v[104:107], v[180:183], v[216:219], v[104:107]
	v_mfma_f32_16x16x32_bf16 v[92:95], v[158:161], v[224:227], v[92:95]
	v_mfma_f32_16x16x32_bf16 v[88:91], v[180:183], v[224:227], v[88:91]
	v_mfma_f32_16x16x32_bf16 v[76:79], v[158:161], v[232:235], v[76:79]
	v_mfma_f32_16x16x32_bf16 v[72:75], v[180:183], v[232:235], v[72:75]
	s_setprio 0
	s_setprio 1
	v_mfma_f32_16x16x32_bf16 v[116:119], v[184:187], v[200:203], v[116:119]
	v_mfma_f32_16x16x32_bf16 v[112:115], v[192:195], v[200:203], v[112:115]
	v_mfma_f32_16x16x32_bf16 v[100:103], v[184:187], v[212:215], v[100:103]
	v_mfma_f32_16x16x32_bf16 v[96:99], v[192:195], v[212:215], v[96:99]
	v_mfma_f32_16x16x32_bf16 v[84:87], v[184:187], v[220:223], v[84:87]
	v_mfma_f32_16x16x32_bf16 v[80:83], v[192:195], v[220:223], v[80:83]
	v_mfma_f32_16x16x32_bf16 v[68:71], v[184:187], v[228:231], v[68:71]
	v_mfma_f32_16x16x32_bf16 v[64:67], v[192:195], v[228:231], v[64:67]
	v_mfma_f32_16x16x32_bf16 v[116:119], v[188:191], v[208:211], v[116:119]
	v_mfma_f32_16x16x32_bf16 v[112:115], v[196:199], v[208:211], v[112:115]
	v_mfma_f32_16x16x32_bf16 v[100:103], v[188:191], v[216:219], v[100:103]
	v_mfma_f32_16x16x32_bf16 v[96:99], v[196:199], v[216:219], v[96:99]
	v_mfma_f32_16x16x32_bf16 v[84:87], v[188:191], v[224:227], v[84:87]
	v_mfma_f32_16x16x32_bf16 v[80:83], v[196:199], v[224:227], v[80:83]
	v_mfma_f32_16x16x32_bf16 v[68:71], v[188:191], v[232:235], v[68:71]
	v_mfma_f32_16x16x32_bf16 v[64:67], v[196:199], v[232:235], v[64:67]
	s_setprio 0
	s_barrier
	s_add_i32 s65, s58, s48
	v_lshl_add_u64 v[204:205], s[40:41], 0, v[138:139]
	s_mov_b32 m0, s65
	ds_read_b128 v[200:203], v174 offset:16384
	ds_read_b128 v[208:211], v174 offset:17408
	ds_read_b128 v[212:215], v174 offset:18432
	ds_read_b128 v[216:219], v174 offset:19456
	ds_read_b128 v[220:223], v174 offset:20480
	ds_read_b128 v[224:227], v174 offset:21504
	ds_read_b128 v[228:231], v174 offset:22528
	ds_read_b128 v[232:235], v174 offset:23552
	global_load_lds_dwordx4 v138, s[40:41]
	s_add_i32 m0, s65, 0x2000
	s_add_u32 s66, s40, 0x40000
	v_lshl_add_u64 v[206:207], s[40:41], 0, v[142:143]
	s_addc_u32 s67, s41, 0
	s_add_i32 s65, s59, s48
	global_load_lds_dwordx4 v142, s[40:41]
	s_mov_b32 m0, s65
	s_nop 0
	global_load_lds_dwordx4 v138, s[66:67]
	s_add_i32 m0, s65, 0x2000
	s_nop 0
	global_load_lds_dwordx4 v142, s[66:67]
	s_mov_b32 m0, s49
	s_nop 0
	global_load_lds_dwordx4 v136, s[42:43]
	v_lshl_add_u64 v[236:237], s[42:43], 0, v[140:141]
	s_mov_b32 m0, s50
	s_nop 0
	global_load_lds_dwordx4 v140, s[42:43]
	s_waitcnt vmcnt(8)
	s_waitcnt lgkmcnt(0)
	s_barrier
; #define PG8_STAGE(bufoff, gbase, voff) do { _Pragma("unroll") for (int _i = 0; _i < 2; ++_i) \
;         __builtin_amdgcn_global_load_lds((const unsigned*)((const char*)(gbase) + (voff)[_i]), (PG8_LAS unsigned*)(lds + (bufoff) + ldsw + _i * 8192), 16, 0, 0); } while (0)
; #define PG8_LDA(dst, b, h) do { _Pragma("unroll") for (int m = 0; m < 4; ++m) _Pragma("unroll") for (int k = 0; k < 2; ++k) dst[m][k] = *(const PG8_LAS bf16x8*)(lds + PG8_SA(b, h) + aoff + m * 2048 + k * 1024); } while (0)
; #define PG8_LDB(dst, b, h) do { _Pragma("unroll") for (int n = 0; n < 2; ++n) _Pragma("unroll") for (int k = 0; k < 2; ++k) dst[n][k] = *(const PG8_LAS bf16x8*)(lds + PG8_SB(b, h) + boff + n * 2048 + k * 1024); } while (0)
; #define PG8_MMA(ai, bj, At, Bt) do { __builtin_amdgcn_s_setprio(1); _Pragma("unroll") for (int m = 0; m < 4; ++m) _Pragma("unroll") for (int n = 0; n < 2; ++n) _Pragma("unroll") for (int k = 0; k < 2; ++k) \
;         acc[ai][bj][m][n] = __builtin_amdgcn_mfma_f32_16x16x32_bf16(Bt[n][k], At[m][k], acc[ai][bj][m][n], 0, 0, 0); __builtin_amdgcn_s_setprio(0); } while (0)
; #define PG8_WAIT_V(n) asm volatile("s_waitcnt vmcnt(" #n ")" ::: "memory")
; #define PG8_WAIT_L(n) asm volatile("s_waitcnt lgkmcnt(" #n ")" ::: "memory")
; #define PG8_BAR __builtin_amdgcn_s_barrier()
; #define PG8_SCHED __builtin_amdgcn_sched_barrier(0)
; template <class Epi, class Sched, bool ALIGN_EPI = false, bool SP2 = false>
; __device__ __forceinline__ void gemm_phase(PG8_LAS unsigned char* lds, const Gemm g, const Sched& S, const Epi& E) {
;     ...
;             PG8_WAIT_V(8); PG8_WAIT_L(0); PG8_BAR; PG8_MMA(1, 0, At, B0); PG8_MMA(1, 1, At, B1); PG8_BAR; PG8_SCHED;
;             PG8_LDB(B0, 1, 0); PG8_LDB(B1, 1, 1); PG8_SCHED; PG8_LDA(At, 1, 0); PG8_STAGE(PG8_SA(0, 1), a2 + hstepA, voffA);
;             PG8_WAIT_V(8); PG8_WAIT_L(0); PG8_BAR; PG8_MMA(0, 0, At, B0); PG8_MMA(0, 1, At, B1); PG8_BAR; PG8_SCHED;
	s_setprio 1
	s_waitcnt lgkmcnt(0)
	v_mfma_f32_16x16x32_bf16 v[60:63], v[132:135], v[200:203], v[60:63]
	v_mfma_f32_16x16x32_bf16 v[56:59], v[176:179], v[200:203], v[56:59]
	v_mfma_f32_16x16x32_bf16 v[44:47], v[132:135], v[212:215], v[44:47]
	v_mfma_f32_16x16x32_bf16 v[40:43], v[176:179], v[212:215], v[40:43]
	v_mfma_f32_16x16x32_bf16 v[28:31], v[132:135], v[220:223], v[28:31]
	v_mfma_f32_16x16x32_bf16 v[24:27], v[176:179], v[220:223], v[24:27]
	v_mfma_f32_16x16x32_bf16 v[12:15], v[132:135], v[228:231], v[12:15]
	v_mfma_f32_16x16x32_bf16 v[8:11], v[176:179], v[228:231], v[8:11]
	v_mfma_f32_16x16x32_bf16 v[60:63], v[158:161], v[208:211], v[60:63]
	v_mfma_f32_16x16x32_bf16 v[56:59], v[180:183], v[208:211], v[56:59]
	v_mfma_f32_16x16x32_bf16 v[44:47], v[158:161], v[216:219], v[44:47]
	v_mfma_f32_16x16x32_bf16 v[40:43], v[180:183], v[216:219], v[40:43]
	v_mfma_f32_16x16x32_bf16 v[28:31], v[158:161], v[224:227], v[28:31]
	v_mfma_f32_16x16x32_bf16 v[24:27], v[180:183], v[224:227], v[24:27]
	v_mfma_f32_16x16x32_bf16 v[12:15], v[158:161], v[232:235], v[12:15]
	v_mfma_f32_16x16x32_bf16 v[8:11], v[180:183], v[232:235], v[8:11]
	s_setprio 0
	s_setprio 1
	v_mfma_f32_16x16x32_bf16 v[52:55], v[184:187], v[200:203], v[52:55]
	v_mfma_f32_16x16x32_bf16 v[48:51], v[192:195], v[200:203], v[48:51]
	v_mfma_f32_16x16x32_bf16 v[36:39], v[184:187], v[212:215], v[36:39]
	v_mfma_f32_16x16x32_bf16 v[32:35], v[192:195], v[212:215], v[32:35]
	v_mfma_f32_16x16x32_bf16 v[20:23], v[184:187], v[220:223], v[20:23]
	v_mfma_f32_16x16x32_bf16 v[16:19], v[192:195], v[220:223], v[16:19]
	v_mfma_f32_16x16x32_bf16 v[4:7], v[184:187], v[228:231], v[4:7]
	v_mfma_f32_16x16x32_bf16 v[0:3], v[192:195], v[228:231], v[0:3]
	v_mfma_f32_16x16x32_bf16 v[52:55], v[188:191], v[208:211], v[52:55]
	v_mfma_f32_16x16x32_bf16 v[48:51], v[196:199], v[208:211], v[48:51]
	v_mfma_f32_16x16x32_bf16 v[36:39], v[188:191], v[216:219], v[36:39]
	v_mfma_f32_16x16x32_bf16 v[32:35], v[196:199], v[216:219], v[32:35]
	v_mfma_f32_16x16x32_bf16 v[20:23], v[188:191], v[224:227], v[20:23]
	v_mfma_f32_16x16x32_bf16 v[16:19], v[196:199], v[224:227], v[16:19]
	v_mfma_f32_16x16x32_bf16 v[4:7], v[188:191], v[232:235], v[4:7]
	v_mfma_f32_16x16x32_bf16 v[0:3], v[196:199], v[232:235], v[0:3]
	s_setprio 0
	s_barrier
	s_add_i32 s65, 0, 0x18000
	v_add_u32_e32 v144, s65, v163
	s_add_i32 s66, 0, 0x1c000
	ds_read_b128 v[132:135], v144
	ds_read_b128 v[158:161], v144 offset:1024
	ds_read_b128 v[176:179], v144 offset:2048
	ds_read_b128 v[180:183], v144 offset:3072
	v_add_u32_e32 v144, s66, v163
	ds_read_b128 v[184:187], v144
	ds_read_b128 v[188:191], v144 offset:1024
	ds_read_b128 v[192:195], v144 offset:2048
	ds_read_b128 v[196:199], v144 offset:3072
	s_add_u32 s42, s42, 0x40000
	s_addc_u32 s43, s43, 0
	s_mov_b32 m0, s51
	ds_read_b128 v[200:203], v174 offset:32768
	ds_read_b128 v[208:211], v174 offset:33792
	ds_read_b128 v[212:215], v174 offset:34816
	ds_read_b128 v[216:219], v174 offset:35840
	ds_read_b128 v[220:223], v174 offset:36864
	ds_read_b128 v[224:227], v174 offset:37888
	ds_read_b128 v[228:231], v174 offset:38912
	ds_read_b128 v[232:235], v174 offset:39936
	global_load_lds_dwordx4 v136, s[42:43]
	v_lshl_add_u64 v[236:237], s[42:43], 0, v[140:141]
	s_mov_b32 m0, s52
	s_nop 0
	global_load_lds_dwordx4 v140, s[42:43]
	s_waitcnt vmcnt(8)
	s_waitcnt lgkmcnt(0)
	s_barrier
	s_setprio 1
	s_waitcnt lgkmcnt(0)
	v_mfma_f32_16x16x32_bf16 v[124:127], v[132:135], v[200:203], v[124:127]
	v_mfma_f32_16x16x32_bf16 v[120:123], v[176:179], v[200:203], v[120:123]
	v_mfma_f32_16x16x32_bf16 v[108:111], v[132:135], v[212:215], v[108:111]
	v_mfma_f32_16x16x32_bf16 v[104:107], v[176:179], v[212:215], v[104:107]
	v_mfma_f32_16x16x32_bf16 v[92:95], v[132:135], v[220:223], v[92:95]
	v_mfma_f32_16x16x32_bf16 v[88:91], v[176:179], v[220:223], v[88:91]
	v_mfma_f32_16x16x32_bf16 v[76:79], v[132:135], v[228:231], v[76:79]
	v_mfma_f32_16x16x32_bf16 v[72:75], v[176:179], v[228:231], v[72:75]
	v_mfma_f32_16x16x32_bf16 v[124:127], v[158:161], v[208:211], v[124:127]
	v_mfma_f32_16x16x32_bf16 v[120:123], v[180:183], v[208:211], v[120:123]
	v_mfma_f32_16x16x32_bf16 v[108:111], v[158:161], v[216:219], v[108:111]
	v_mfma_f32_16x16x32_bf16 v[104:107], v[180:183], v[216:219], v[104:107]
	v_mfma_f32_16x16x32_bf16 v[92:95], v[158:161], v[224:227], v[92:95]
	v_mfma_f32_16x16x32_bf16 v[88:91], v[180:183], v[224:227], v[88:91]
	v_mfma_f32_16x16x32_bf16 v[76:79], v[158:161], v[232:235], v[76:79]
	v_mfma_f32_16x16x32_bf16 v[72:75], v[180:183], v[232:235], v[72:75]
	s_setprio 0
	s_setprio 1
	v_mfma_f32_16x16x32_bf16 v[116:119], v[184:187], v[200:203], v[116:119]
	v_mfma_f32_16x16x32_bf16 v[112:115], v[192:195], v[200:203], v[112:115]
	v_mfma_f32_16x16x32_bf16 v[100:103], v[184:187], v[212:215], v[100:103]
	v_mfma_f32_16x16x32_bf16 v[96:99], v[192:195], v[212:215], v[96:99]
	v_mfma_f32_16x16x32_bf16 v[84:87], v[184:187], v[220:223], v[84:87]
	v_mfma_f32_16x16x32_bf16 v[80:83], v[192:195], v[220:223], v[80:83]
	v_mfma_f32_16x16x32_bf16 v[68:71], v[184:187], v[228:231], v[68:71]
	v_mfma_f32_16x16x32_bf16 v[64:67], v[192:195], v[228:231], v[64:67]
	v_mfma_f32_16x16x32_bf16 v[116:119], v[188:191], v[208:211], v[116:119]
	v_mfma_f32_16x16x32_bf16 v[112:115], v[196:199], v[208:211], v[112:115]
	v_mfma_f32_16x16x32_bf16 v[100:103], v[188:191], v[216:219], v[100:103]
	v_mfma_f32_16x16x32_bf16 v[96:99], v[196:199], v[216:219], v[96:99]
	v_mfma_f32_16x16x32_bf16 v[84:87], v[188:191], v[224:227], v[84:87]
	v_mfma_f32_16x16x32_bf16 v[80:83], v[196:199], v[224:227], v[80:83]
	v_mfma_f32_16x16x32_bf16 v[68:71], v[188:191], v[232:235], v[68:71]
	v_mfma_f32_16x16x32_bf16 v[64:67], v[196:199], v[232:235], v[64:67]
	s_setprio 0
	s_barrier
; #define PG8_STAGE(bufoff, gbase, voff) do { _Pragma("unroll") for (int _i = 0; _i < 2; ++_i) \
;         __builtin_amdgcn_global_load_lds((const unsigned*)((const char*)(gbase) + (voff)[_i]), (PG8_LAS unsigned*)(lds + (bufoff) + ldsw + _i * 8192), 16, 0, 0); } while (0)
; #define PG8_LDA(dst, b, h) do { _Pragma("unroll") for (int m = 0; m < 4; ++m) _Pragma("unroll") for (int k = 0; k < 2; ++k) dst[m][k] = *(const PG8_LAS bf16x8*)(lds + PG8_SA(b, h) + aoff + m * 2048 + k * 1024); } while (0)
; #define PG8_MMA(ai, bj, At, Bt) do { __builtin_amdgcn_s_setprio(1); _Pragma("unroll") for (int m = 0; m < 4; ++m) _Pragma("unroll") for (int n = 0; n < 2; ++n) _Pragma("unroll") for (int k = 0; k < 2; ++k) \
;         acc[ai][bj][m][n] = __builtin_amdgcn_mfma_f32_16x16x32_bf16(Bt[n][k], At[m][k], acc[ai][bj][m][n], 0, 0, 0); __builtin_amdgcn_s_setprio(0); } while (0)
; #define PG8_WAIT_V(n) asm volatile("s_waitcnt vmcnt(" #n ")" ::: "memory")
; #define PG8_WAIT_L(n) asm volatile("s_waitcnt lgkmcnt(" #n ")" ::: "memory")
; #define PG8_BAR __builtin_amdgcn_s_barrier()
; #define PG8_SCHED __builtin_amdgcn_sched_barrier(0)
; template <class Epi, class Sched, bool ALIGN_EPI = false, bool SP2 = false>
; __device__ __forceinline__ void gemm_phase(PG8_LAS unsigned char* lds, const Gemm g, const Sched& S, const Epi& E) {
;     ...
;             PG8_LDA(At, 1, 1); PG8_STAGE(PG8_SB(1, 0), b3, voffB); PG8_STAGE(PG8_SB(1, 1), b3 + hstepB, voffB); PG8_STAGE(PG8_SA(1, 0), a3, voffA);
;             PG8_WAIT_V(8); PG8_WAIT_L(0); PG8_BAR; PG8_MMA(1, 0, At, B0); PG8_MMA(1, 1, At, B1); PG8_BAR; PG8_SCHED;
;     ...
;         if constexpr (ALIGN_EPI) { if (wr == 0) PG8_BAR; }
	s_add_i32 s42, s65, s48
	v_lshl_add_u64 v[204:205], v[204:205], 0, s[14:15]
	s_mov_b32 m0, s42
	ds_read_b128 v[200:203], v174 offset:49152
	ds_read_b128 v[208:211], v174 offset:50176
	ds_read_b128 v[212:215], v174 offset:51200
	ds_read_b128 v[216:219], v174 offset:52224
	ds_read_b128 v[220:223], v174 offset:53248
	ds_read_b128 v[224:227], v174 offset:54272
	ds_read_b128 v[228:231], v174 offset:55296
	ds_read_b128 v[232:235], v174 offset:56320
	global_load_lds_dwordx4 v[204:205], off
	s_add_i32 m0, s42, 0x2000
	s_add_u32 s40, s40, 0x40080
	v_lshl_add_u64 v[204:205], v[206:207], 0, s[14:15]
	s_addc_u32 s41, s41, 0
	s_add_i32 s42, s66, s48
	global_load_lds_dwordx4 v[204:205], off
	s_mov_b32 m0, s42
	s_nop 0
	global_load_lds_dwordx4 v138, s[40:41]
	s_add_i32 m0, s42, 0x2000
	s_nop 0
	global_load_lds_dwordx4 v142, s[40:41]
	s_mov_b32 m0, s53
	s_nop 0
	global_load_lds_dwordx4 v136, s[38:39]
	v_lshl_add_u64 v[204:205], s[38:39], 0, v[140:141]
	s_mov_b32 m0, s54
	s_nop 0
	global_load_lds_dwordx4 v140, s[38:39]
	s_waitcnt vmcnt(8)
	s_waitcnt lgkmcnt(0)
	s_barrier
	s_setprio 1
	s_waitcnt lgkmcnt(0)
	v_mfma_f32_16x16x32_bf16 v[60:63], v[132:135], v[200:203], v[60:63]
	v_mfma_f32_16x16x32_bf16 v[56:59], v[176:179], v[200:203], v[56:59]
	v_mfma_f32_16x16x32_bf16 v[44:47], v[132:135], v[212:215], v[44:47]
	v_mfma_f32_16x16x32_bf16 v[40:43], v[176:179], v[212:215], v[40:43]
	v_mfma_f32_16x16x32_bf16 v[28:31], v[132:135], v[220:223], v[28:31]
	v_mfma_f32_16x16x32_bf16 v[24:27], v[176:179], v[220:223], v[24:27]
	v_mfma_f32_16x16x32_bf16 v[12:15], v[132:135], v[228:231], v[12:15]
	v_mfma_f32_16x16x32_bf16 v[8:11], v[176:179], v[228:231], v[8:11]
	v_mfma_f32_16x16x32_bf16 v[60:63], v[158:161], v[208:211], v[60:63]
	v_mfma_f32_16x16x32_bf16 v[56:59], v[180:183], v[208:211], v[56:59]
	v_mfma_f32_16x16x32_bf16 v[44:47], v[158:161], v[216:219], v[44:47]
	v_mfma_f32_16x16x32_bf16 v[40:43], v[180:183], v[216:219], v[40:43]
	v_mfma_f32_16x16x32_bf16 v[28:31], v[158:161], v[224:227], v[28:31]
	v_mfma_f32_16x16x32_bf16 v[24:27], v[180:183], v[224:227], v[24:27]
	v_mfma_f32_16x16x32_bf16 v[12:15], v[158:161], v[232:235], v[12:15]
	v_mfma_f32_16x16x32_bf16 v[8:11], v[180:183], v[232:235], v[8:11]
	s_setprio 0
	s_setprio 1
	v_mfma_f32_16x16x32_bf16 v[52:55], v[184:187], v[200:203], v[52:55]
	v_mfma_f32_16x16x32_bf16 v[48:51], v[192:195], v[200:203], v[48:51]
	v_mfma_f32_16x16x32_bf16 v[36:39], v[184:187], v[212:215], v[36:39]
	v_mfma_f32_16x16x32_bf16 v[32:35], v[192:195], v[212:215], v[32:35]
	v_mfma_f32_16x16x32_bf16 v[20:23], v[184:187], v[220:223], v[20:23]
	v_mfma_f32_16x16x32_bf16 v[16:19], v[192:195], v[220:223], v[16:19]
	v_mfma_f32_16x16x32_bf16 v[4:7], v[184:187], v[228:231], v[4:7]
	v_mfma_f32_16x16x32_bf16 v[0:3], v[192:195], v[228:231], v[0:3]
	v_mfma_f32_16x16x32_bf16 v[52:55], v[188:191], v[208:211], v[52:55]
	v_mfma_f32_16x16x32_bf16 v[48:51], v[196:199], v[208:211], v[48:51]
	v_mfma_f32_16x16x32_bf16 v[36:39], v[188:191], v[216:219], v[36:39]
	v_mfma_f32_16x16x32_bf16 v[32:35], v[196:199], v[216:219], v[32:35]
	v_mfma_f32_16x16x32_bf16 v[20:23], v[188:191], v[224:227], v[20:23]
	v_mfma_f32_16x16x32_bf16 v[16:19], v[196:199], v[224:227], v[16:19]
	v_mfma_f32_16x16x32_bf16 v[4:7], v[188:191], v[232:235], v[4:7]
	v_mfma_f32_16x16x32_bf16 v[0:3], v[196:199], v[232:235], v[0:3]
	s_setprio 0
	s_barrier
	s_add_i32 s64, s64, 2
	s_add_u32 s34, s34, 0x100
	s_addc_u32 s35, s35, 0
	s_cmp_gt_u32 s64, 13
	s_cbranch_scc0 .LBB0_129
	s_and_b64 vcc, exec, s[16:17]
	s_cbranch_vccz .LBB0_134
	s_barrier
	s_cmp_gt_i32 s30, 3
	s_mov_b64 s[28:29], -1
	s_cbranch_scc1 .LBB0_135

; #define PG8_STAGE(bufoff, gbase, voff) do { _Pragma("unroll") for (int _i = 0; _i < 2; ++_i) \
;         __builtin_amdgcn_global_load_lds((const unsigned*)((const char*)(gbase) + (voff)[_i]), (PG8_LAS unsigned*)(lds + (bufoff) + ldsw + _i * 8192), 16, 0, 0); } while (0)
; #define PG8_LDA(dst, b, h) do { _Pragma("unroll") for (int m = 0; m < 4; ++m) _Pragma("unroll") for (int k = 0; k < 2; ++k) dst[m][k] = *(const PG8_LAS bf16x8*)(lds + PG8_SA(b, h) + aoff + m * 2048 + k * 1024); } while (0)
; #define PG8_LDB(dst, b, h) do { _Pragma("unroll") for (int n = 0; n < 2; ++n) _Pragma("unroll") for (int k = 0; k < 2; ++k) dst[n][k] = *(const PG8_LAS bf16x8*)(lds + PG8_SB(b, h) + boff + n * 2048 + k * 1024); } while (0)
; #define PG8_MMA(ai, bj, At, Bt) do { __builtin_amdgcn_s_setprio(1); _Pragma("unroll") for (int m = 0; m < 4; ++m) _Pragma("unroll") for (int n = 0; n < 2; ++n) _Pragma("unroll") for (int k = 0; k < 2; ++k) \
;         acc[ai][bj][m][n] = __builtin_amdgcn_mfma_f32_16x16x32_bf16(Bt[n][k], At[m][k], acc[ai][bj][m][n], 0, 0, 0); __builtin_amdgcn_s_setprio(0); } while (0)
; #define PG8_WAIT_V(n) asm volatile("s_waitcnt vmcnt(" #n ")" ::: "memory")
; #define PG8_WAIT_L(n) asm volatile("s_waitcnt lgkmcnt(" #n ")" ::: "memory")
; template <class Epi, class Sched, bool ALIGN_EPI = false, bool SP2 = false>
; __device__ __forceinline__ void gemm_phase(PG8_LAS unsigned char* lds, const Gemm g, const Sched& S, const Epi& E) {
;     ...
;             const bool last = (t == nt - 2);
;             const char* a1 = cA + PG8_AK(t + 1);
;             const char* a2 = last ? nA : cA + PG8_AK(t + 2); const char* b2 = last ? nB : cB + (size_t)(t + 2) * kstep;
;             const char* a3 = last ? nA + PG8_AK(1) : cA + PG8_AK(t + 3); const char* b3 = b2 + kstep;
;             if (last && has_next) S.a_ready(nxt);
;             if constexpr (SP2) {
;             PG8_LDB(B0, 0, 0); PG8_LDB(B1, 0, 1); PG8_SCHED; PG8_LDA(At, 0, 0); PG8_STAGE(PG8_SA(1, 1), a1 + hstepA, voffA);
;             PG8_WAIT_V(8); PG8_WAIT_L(0); PG8_BAR; PG8_MMA(0, 0, At, B0); PG8_MMA(0, 1, At, B1); PG8_BAR; PG8_SCHED;
;             PG8_LDA(At, 0, 1); PG8_STAGE(PG8_SB(0, 0), b2, voffB); PG8_STAGE(PG8_SB(0, 1), b2 + hstepB, voffB); PG8_STAGE(PG8_SA(0, 0), a2, voffA);
;             PG8_WAIT_V(8); PG8_WAIT_L(0); PG8_BAR; PG8_MMA(1, 0, At, B0); PG8_MMA(1, 1, At, B1); PG8_BAR; PG8_SCHED;
.LBB0_332:
	ds_read_b128 v[180:183], v147
	ds_read_b128 v[184:187], v147 offset:1024
	ds_read_b128 v[188:191], v147 offset:2048
	ds_read_b128 v[192:195], v147 offset:3072
	ds_read_b128 v[196:199], v149
	ds_read_b128 v[200:203], v149 offset:1024
	ds_read_b128 v[208:211], v149 offset:2048
	ds_read_b128 v[212:215], v149 offset:3072
	s_add_u32 s42, s38, s40
	s_addc_u32 s43, s39, s41
	s_add_u32 s46, s42, 0x100
	s_addc_u32 s47, s43, 0
	s_add_u32 s44, s79, s40
	s_addc_u32 s45, s80, s41
	s_add_u32 s42, s42, 0x180
	s_addc_u32 s43, s43, 0
	s_cmpk_eq_i32 s40, 0x700
	s_cselect_b32 s43, s78, s43
	s_cselect_b32 s42, s69, s42
	s_cselect_b32 s45, s27, s45
	s_cselect_b32 s44, s37, s44
	s_cselect_b32 s47, s3, s47
	s_cselect_b32 s46, s29, s46
	v_lshl_add_u64 v[204:205], v[178:179], 0, s[40:41]
	s_add_i32 m0, s54, 0xc000
	ds_read_b128 v[216:219], v143
	ds_read_b128 v[220:223], v143 offset:1024
	ds_read_b128 v[224:227], v143 offset:2048
	ds_read_b128 v[228:231], v143 offset:3072
	ds_read_b128 v[232:235], v143 offset:4096
	ds_read_b128 v[236:239], v143 offset:5120
	ds_read_b128 v[240:243], v143 offset:6144
	ds_read_b128 v[244:247], v143 offset:7168
	global_load_lds_dwordx4 v[204:205], off
	v_lshl_add_u64 v[204:205], v[176:177], 0, s[40:41]
	s_add_i32 m0, s54, 0xe000
	s_nop 0
	global_load_lds_dwordx4 v[204:205], off
	s_waitcnt vmcnt(8)
	s_waitcnt lgkmcnt(0)
	s_barrier
	s_setprio 1
	s_waitcnt lgkmcnt(0)
	v_mfma_f32_16x16x32_bf16 v[124:127], v[180:183], v[216:219], v[124:127]
	v_mfma_f32_16x16x32_bf16 v[120:123], v[188:191], v[216:219], v[120:123]
	v_mfma_f32_16x16x32_bf16 v[116:119], v[180:183], v[224:227], v[116:119]
	v_mfma_f32_16x16x32_bf16 v[112:115], v[188:191], v[224:227], v[112:115]
	v_mfma_f32_16x16x32_bf16 v[108:111], v[180:183], v[232:235], v[108:111]
	v_mfma_f32_16x16x32_bf16 v[104:107], v[188:191], v[232:235], v[104:107]
	v_mfma_f32_16x16x32_bf16 v[100:103], v[180:183], v[240:243], v[100:103]
	v_mfma_f32_16x16x32_bf16 v[96:99], v[188:191], v[240:243], v[96:99]
	v_mfma_f32_16x16x32_bf16 v[124:127], v[184:187], v[220:223], v[124:127]
	v_mfma_f32_16x16x32_bf16 v[120:123], v[192:195], v[220:223], v[120:123]
	v_mfma_f32_16x16x32_bf16 v[116:119], v[184:187], v[228:231], v[116:119]
	v_mfma_f32_16x16x32_bf16 v[112:115], v[192:195], v[228:231], v[112:115]
	v_mfma_f32_16x16x32_bf16 v[108:111], v[184:187], v[236:239], v[108:111]
	v_mfma_f32_16x16x32_bf16 v[104:107], v[192:195], v[236:239], v[104:107]
	v_mfma_f32_16x16x32_bf16 v[100:103], v[184:187], v[244:247], v[100:103]
	v_mfma_f32_16x16x32_bf16 v[96:99], v[192:195], v[244:247], v[96:99]
	s_setprio 0
	s_setprio 1
	v_mfma_f32_16x16x32_bf16 v[64:67], v[196:199], v[216:219], v[64:67]
	v_mfma_f32_16x16x32_bf16 v[56:59], v[208:211], v[216:219], v[56:59]
	v_mfma_f32_16x16x32_bf16 v[52:55], v[196:199], v[224:227], v[52:55]
	v_mfma_f32_16x16x32_bf16 v[48:51], v[208:211], v[224:227], v[48:51]
	v_mfma_f32_16x16x32_bf16 v[44:47], v[196:199], v[232:235], v[44:47]
	v_mfma_f32_16x16x32_bf16 v[40:43], v[208:211], v[232:235], v[40:43]
	v_mfma_f32_16x16x32_bf16 v[36:39], v[196:199], v[240:243], v[36:39]
	v_mfma_f32_16x16x32_bf16 v[32:35], v[208:211], v[240:243], v[32:35]
	v_mfma_f32_16x16x32_bf16 v[64:67], v[200:203], v[220:223], v[64:67]
	v_mfma_f32_16x16x32_bf16 v[56:59], v[212:215], v[220:223], v[56:59]
	v_mfma_f32_16x16x32_bf16 v[52:55], v[200:203], v[228:231], v[52:55]
	v_mfma_f32_16x16x32_bf16 v[48:51], v[212:215], v[228:231], v[48:51]
	v_mfma_f32_16x16x32_bf16 v[44:47], v[200:203], v[236:239], v[44:47]
	v_mfma_f32_16x16x32_bf16 v[40:43], v[212:215], v[236:239], v[40:43]
	v_mfma_f32_16x16x32_bf16 v[36:39], v[200:203], v[244:247], v[36:39]
	v_mfma_f32_16x16x32_bf16 v[32:35], v[212:215], v[244:247], v[32:35]
	s_setprio 0
	s_barrier
	s_add_i32 s70, s66, s53
	v_lshl_add_u64 v[204:205], s[44:45], 0, v[130:131]
	s_mov_b32 m0, s70
	ds_read_b128 v[216:219], v143 offset:16384
	ds_read_b128 v[220:223], v143 offset:17408
	ds_read_b128 v[224:227], v143 offset:18432
	ds_read_b128 v[228:231], v143 offset:19456
	ds_read_b128 v[232:235], v143 offset:20480
	ds_read_b128 v[236:239], v143 offset:21504
	ds_read_b128 v[240:243], v143 offset:22528
	ds_read_b128 v[244:247], v143 offset:23552
	global_load_lds_dwordx4 v130, s[44:45]
	s_add_i32 m0, s70, 0x2000
	s_add_u32 s70, s44, 0x40000
	v_lshl_add_u64 v[206:207], s[44:45], 0, v[134:135]
	s_addc_u32 s71, s45, 0
	s_add_i32 s82, s67, s53
	global_load_lds_dwordx4 v134, s[44:45]
	s_mov_b32 m0, s82
	s_nop 0
	global_load_lds_dwordx4 v130, s[70:71]
	s_add_i32 m0, s82, 0x2000
	s_nop 0
	global_load_lds_dwordx4 v134, s[70:71]
	s_mov_b32 m0, s54
	s_nop 0
	global_load_lds_dwordx4 v128, s[46:47]
	v_lshl_add_u64 v[248:249], s[46:47], 0, v[132:133]
	s_mov_b32 m0, s55
	s_nop 0
	global_load_lds_dwordx4 v132, s[46:47]
	s_waitcnt vmcnt(8)
	s_waitcnt lgkmcnt(0)
	s_barrier
; #define PG8_STAGE(bufoff, gbase, voff) do { _Pragma("unroll") for (int _i = 0; _i < 2; ++_i) \
;         __builtin_amdgcn_global_load_lds((const unsigned*)((const char*)(gbase) + (voff)[_i]), (PG8_LAS unsigned*)(lds + (bufoff) + ldsw + _i * 8192), 16, 0, 0); } while (0)
; #define PG8_LDA(dst, b, h) do { _Pragma("unroll") for (int m = 0; m < 4; ++m) _Pragma("unroll") for (int k = 0; k < 2; ++k) dst[m][k] = *(const PG8_LAS bf16x8*)(lds + PG8_SA(b, h) + aoff + m * 2048 + k * 1024); } while (0)
; #define PG8_LDB(dst, b, h) do { _Pragma("unroll") for (int n = 0; n < 2; ++n) _Pragma("unroll") for (int k = 0; k < 2; ++k) dst[n][k] = *(const PG8_LAS bf16x8*)(lds + PG8_SB(b, h) + boff + n * 2048 + k * 1024); } while (0)
; #define PG8_MMA(ai, bj, At, Bt) do { __builtin_amdgcn_s_setprio(1); _Pragma("unroll") for (int m = 0; m < 4; ++m) _Pragma("unroll") for (int n = 0; n < 2; ++n) _Pragma("unroll") for (int k = 0; k < 2; ++k) \
;         acc[ai][bj][m][n] = __builtin_amdgcn_mfma_f32_16x16x32_bf16(Bt[n][k], At[m][k], acc[ai][bj][m][n], 0, 0, 0); __builtin_amdgcn_s_setprio(0); } while (0)
; #define PG8_WAIT_V(n) asm volatile("s_waitcnt vmcnt(" #n ")" ::: "memory")
; #define PG8_WAIT_L(n) asm volatile("s_waitcnt lgkmcnt(" #n ")" ::: "memory")
; #define PG8_BAR __builtin_amdgcn_s_barrier()
; #define PG8_SCHED __builtin_amdgcn_sched_barrier(0)
; template <class Epi, class Sched, bool ALIGN_EPI = false, bool SP2 = false>
; __device__ __forceinline__ void gemm_phase(PG8_LAS unsigned char* lds, const Gemm g, const Sched& S, const Epi& E) {
;     ...
;             PG8_WAIT_V(8); PG8_WAIT_L(0); PG8_BAR; PG8_MMA(1, 0, At, B0); PG8_MMA(1, 1, At, B1); PG8_BAR; PG8_SCHED;
;             PG8_LDB(B0, 1, 0); PG8_LDB(B1, 1, 1); PG8_SCHED; PG8_LDA(At, 1, 0); PG8_STAGE(PG8_SA(0, 1), a2 + hstepA, voffA);
;             PG8_WAIT_V(8); PG8_WAIT_L(0); PG8_BAR; PG8_MMA(0, 0, At, B0); PG8_MMA(0, 1, At, B1); PG8_BAR; PG8_SCHED;
	s_setprio 1
	s_waitcnt lgkmcnt(0)
	v_mfma_f32_16x16x32_bf16 v[92:95], v[180:183], v[216:219], v[92:95]
	v_mfma_f32_16x16x32_bf16 v[88:91], v[188:191], v[216:219], v[88:91]
	v_mfma_f32_16x16x32_bf16 v[84:87], v[180:183], v[224:227], v[84:87]
	v_mfma_f32_16x16x32_bf16 v[80:83], v[188:191], v[224:227], v[80:83]
	v_mfma_f32_16x16x32_bf16 v[76:79], v[180:183], v[232:235], v[76:79]
	v_mfma_f32_16x16x32_bf16 v[72:75], v[188:191], v[232:235], v[72:75]
	v_mfma_f32_16x16x32_bf16 v[68:71], v[180:183], v[240:243], v[68:71]
	v_mfma_f32_16x16x32_bf16 v[60:63], v[188:191], v[240:243], v[60:63]
	v_mfma_f32_16x16x32_bf16 v[92:95], v[184:187], v[220:223], v[92:95]
	v_mfma_f32_16x16x32_bf16 v[88:91], v[192:195], v[220:223], v[88:91]
	v_mfma_f32_16x16x32_bf16 v[84:87], v[184:187], v[228:231], v[84:87]
	v_mfma_f32_16x16x32_bf16 v[80:83], v[192:195], v[228:231], v[80:83]
	v_mfma_f32_16x16x32_bf16 v[76:79], v[184:187], v[236:239], v[76:79]
	v_mfma_f32_16x16x32_bf16 v[72:75], v[192:195], v[236:239], v[72:75]
	v_mfma_f32_16x16x32_bf16 v[68:71], v[184:187], v[244:247], v[68:71]
	v_mfma_f32_16x16x32_bf16 v[60:63], v[192:195], v[244:247], v[60:63]
	s_setprio 0
	s_setprio 1
	v_mfma_f32_16x16x32_bf16 v[28:31], v[196:199], v[216:219], v[28:31]
	v_mfma_f32_16x16x32_bf16 v[24:27], v[208:211], v[216:219], v[24:27]
	v_mfma_f32_16x16x32_bf16 v[20:23], v[196:199], v[224:227], v[20:23]
	v_mfma_f32_16x16x32_bf16 v[16:19], v[208:211], v[224:227], v[16:19]
	v_mfma_f32_16x16x32_bf16 v[12:15], v[196:199], v[232:235], v[12:15]
	v_mfma_f32_16x16x32_bf16 v[8:11], v[208:211], v[232:235], v[8:11]
	v_mfma_f32_16x16x32_bf16 v[4:7], v[196:199], v[240:243], v[4:7]
	v_mfma_f32_16x16x32_bf16 v[0:3], v[208:211], v[240:243], v[0:3]
	v_mfma_f32_16x16x32_bf16 v[28:31], v[200:203], v[220:223], v[28:31]
	v_mfma_f32_16x16x32_bf16 v[24:27], v[212:215], v[220:223], v[24:27]
	v_mfma_f32_16x16x32_bf16 v[20:23], v[200:203], v[228:231], v[20:23]
	v_mfma_f32_16x16x32_bf16 v[16:19], v[212:215], v[228:231], v[16:19]
	v_mfma_f32_16x16x32_bf16 v[12:15], v[200:203], v[236:239], v[12:15]
	v_mfma_f32_16x16x32_bf16 v[8:11], v[212:215], v[236:239], v[8:11]
	v_mfma_f32_16x16x32_bf16 v[4:7], v[200:203], v[244:247], v[4:7]
	v_mfma_f32_16x16x32_bf16 v[0:3], v[212:215], v[244:247], v[0:3]
	s_setprio 0
	s_barrier
	s_add_i32 s70, 0, 0x18000
	v_add_u32_e32 v137, s70, v141
	s_add_i32 s71, 0, 0x1c000
	ds_read_b128 v[180:183], v137
	ds_read_b128 v[184:187], v137 offset:1024
	ds_read_b128 v[188:191], v137 offset:2048
	ds_read_b128 v[192:195], v137 offset:3072
	v_add_u32_e32 v137, s71, v141
	ds_read_b128 v[196:199], v137
	ds_read_b128 v[200:203], v137 offset:1024
	ds_read_b128 v[208:211], v137 offset:2048
	ds_read_b128 v[212:215], v137 offset:3072
	s_add_u32 s46, s46, 0x40000
	s_addc_u32 s47, s47, 0
	s_mov_b32 m0, s56
	ds_read_b128 v[216:219], v143 offset:32768
	ds_read_b128 v[220:223], v143 offset:33792
	ds_read_b128 v[224:227], v143 offset:34816
	ds_read_b128 v[228:231], v143 offset:35840
	ds_read_b128 v[232:235], v143 offset:36864
	ds_read_b128 v[236:239], v143 offset:37888
	ds_read_b128 v[240:243], v143 offset:38912
	ds_read_b128 v[244:247], v143 offset:39936
	global_load_lds_dwordx4 v128, s[46:47]
	v_lshl_add_u64 v[248:249], s[46:47], 0, v[132:133]
	s_mov_b32 m0, s57
	s_nop 0
	global_load_lds_dwordx4 v132, s[46:47]
	s_waitcnt vmcnt(8)
	s_waitcnt lgkmcnt(0)
	s_barrier
	s_setprio 1
	s_waitcnt lgkmcnt(0)
	v_mfma_f32_16x16x32_bf16 v[124:127], v[180:183], v[216:219], v[124:127]
	v_mfma_f32_16x16x32_bf16 v[120:123], v[188:191], v[216:219], v[120:123]
	v_mfma_f32_16x16x32_bf16 v[116:119], v[180:183], v[224:227], v[116:119]
	v_mfma_f32_16x16x32_bf16 v[112:115], v[188:191], v[224:227], v[112:115]
	v_mfma_f32_16x16x32_bf16 v[108:111], v[180:183], v[232:235], v[108:111]
	v_mfma_f32_16x16x32_bf16 v[104:107], v[188:191], v[232:235], v[104:107]
	v_mfma_f32_16x16x32_bf16 v[100:103], v[180:183], v[240:243], v[100:103]
	v_mfma_f32_16x16x32_bf16 v[96:99], v[188:191], v[240:243], v[96:99]
	v_mfma_f32_16x16x32_bf16 v[124:127], v[184:187], v[220:223], v[124:127]
	v_mfma_f32_16x16x32_bf16 v[120:123], v[192:195], v[220:223], v[120:123]
	v_mfma_f32_16x16x32_bf16 v[116:119], v[184:187], v[228:231], v[116:119]
	v_mfma_f32_16x16x32_bf16 v[112:115], v[192:195], v[228:231], v[112:115]
	v_mfma_f32_16x16x32_bf16 v[108:111], v[184:187], v[236:239], v[108:111]
	v_mfma_f32_16x16x32_bf16 v[104:107], v[192:195], v[236:239], v[104:107]
	v_mfma_f32_16x16x32_bf16 v[100:103], v[184:187], v[244:247], v[100:103]
	v_mfma_f32_16x16x32_bf16 v[96:99], v[192:195], v[244:247], v[96:99]
	s_setprio 0
	s_setprio 1
	v_mfma_f32_16x16x32_bf16 v[64:67], v[196:199], v[216:219], v[64:67]
	v_mfma_f32_16x16x32_bf16 v[56:59], v[208:211], v[216:219], v[56:59]
	v_mfma_f32_16x16x32_bf16 v[52:55], v[196:199], v[224:227], v[52:55]
	v_mfma_f32_16x16x32_bf16 v[48:51], v[208:211], v[224:227], v[48:51]
	v_mfma_f32_16x16x32_bf16 v[44:47], v[196:199], v[232:235], v[44:47]
	v_mfma_f32_16x16x32_bf16 v[40:43], v[208:211], v[232:235], v[40:43]
	v_mfma_f32_16x16x32_bf16 v[36:39], v[196:199], v[240:243], v[36:39]
	v_mfma_f32_16x16x32_bf16 v[32:35], v[208:211], v[240:243], v[32:35]
	v_mfma_f32_16x16x32_bf16 v[64:67], v[200:203], v[220:223], v[64:67]
	v_mfma_f32_16x16x32_bf16 v[56:59], v[212:215], v[220:223], v[56:59]
	v_mfma_f32_16x16x32_bf16 v[52:55], v[200:203], v[228:231], v[52:55]
	v_mfma_f32_16x16x32_bf16 v[48:51], v[212:215], v[228:231], v[48:51]
	v_mfma_f32_16x16x32_bf16 v[44:47], v[200:203], v[236:239], v[44:47]
	v_mfma_f32_16x16x32_bf16 v[40:43], v[212:215], v[236:239], v[40:43]
	v_mfma_f32_16x16x32_bf16 v[36:39], v[200:203], v[244:247], v[36:39]
	v_mfma_f32_16x16x32_bf16 v[32:35], v[212:215], v[244:247], v[32:35]
	s_setprio 0
	s_barrier
; #define PG8_STAGE(bufoff, gbase, voff) do { _Pragma("unroll") for (int _i = 0; _i < 2; ++_i) \
;         __builtin_amdgcn_global_load_lds((const unsigned*)((const char*)(gbase) + (voff)[_i]), (PG8_LAS unsigned*)(lds + (bufoff) + ldsw + _i * 8192), 16, 0, 0); } while (0)
; #define PG8_LDA(dst, b, h) do { _Pragma("unroll") for (int m = 0; m < 4; ++m) _Pragma("unroll") for (int k = 0; k < 2; ++k) dst[m][k] = *(const PG8_LAS bf16x8*)(lds + PG8_SA(b, h) + aoff + m * 2048 + k * 1024); } while (0)
; #define PG8_MMA(ai, bj, At, Bt) do { __builtin_amdgcn_s_setprio(1); _Pragma("unroll") for (int m = 0; m < 4; ++m) _Pragma("unroll") for (int n = 0; n < 2; ++n) _Pragma("unroll") for (int k = 0; k < 2; ++k) \
;         acc[ai][bj][m][n] = __builtin_amdgcn_mfma_f32_16x16x32_bf16(Bt[n][k], At[m][k], acc[ai][bj][m][n], 0, 0, 0); __builtin_amdgcn_s_setprio(0); } while (0)
; #define PG8_WAIT_V(n) asm volatile("s_waitcnt vmcnt(" #n ")" ::: "memory")
; #define PG8_WAIT_L(n) asm volatile("s_waitcnt lgkmcnt(" #n ")" ::: "memory")
; #define PG8_BAR __builtin_amdgcn_s_barrier()
; #define PG8_SCHED __builtin_amdgcn_sched_barrier(0)
; template <class Epi, class Sched, bool ALIGN_EPI = false, bool SP2 = false>
; __device__ __forceinline__ void gemm_phase(PG8_LAS unsigned char* lds, const Gemm g, const Sched& S, const Epi& E) {
;     ...
;             PG8_LDA(At, 1, 1); PG8_STAGE(PG8_SB(1, 0), b3, voffB); PG8_STAGE(PG8_SB(1, 1), b3 + hstepB, voffB); PG8_STAGE(PG8_SA(1, 0), a3, voffA);
;             PG8_WAIT_V(8); PG8_WAIT_L(0); PG8_BAR; PG8_MMA(1, 0, At, B0); PG8_MMA(1, 1, At, B1); PG8_BAR; PG8_SCHED;
;     ...
;         if constexpr (ALIGN_EPI) { if (wr == 0) PG8_BAR; }
	s_add_i32 s46, s70, s53
	v_lshl_add_u64 v[204:205], v[204:205], 0, s[20:21]
	s_mov_b32 m0, s46
	ds_read_b128 v[216:219], v143 offset:49152
	ds_read_b128 v[220:223], v143 offset:50176
	ds_read_b128 v[224:227], v143 offset:51200
	ds_read_b128 v[228:231], v143 offset:52224
	ds_read_b128 v[232:235], v143 offset:53248
	ds_read_b128 v[236:239], v143 offset:54272
	ds_read_b128 v[240:243], v143 offset:55296
	ds_read_b128 v[244:247], v143 offset:56320
	global_load_lds_dwordx4 v[204:205], off
	s_add_i32 m0, s46, 0x2000
	s_add_u32 s44, s44, 0x40080
	v_lshl_add_u64 v[204:205], v[206:207], 0, s[20:21]
	s_addc_u32 s45, s45, 0
	s_add_i32 s46, s71, s53
	global_load_lds_dwordx4 v[204:205], off
	s_mov_b32 m0, s46
	s_nop 0
	global_load_lds_dwordx4 v130, s[44:45]
	s_add_i32 m0, s46, 0x2000
	s_nop 0
	global_load_lds_dwordx4 v134, s[44:45]
	s_mov_b32 m0, s62
	s_nop 0
	global_load_lds_dwordx4 v128, s[42:43]
	v_lshl_add_u64 v[204:205], s[42:43], 0, v[132:133]
	s_mov_b32 m0, s63
	s_nop 0
	global_load_lds_dwordx4 v132, s[42:43]
	s_waitcnt vmcnt(8)
	s_waitcnt lgkmcnt(0)
	s_barrier
	s_setprio 1
	s_waitcnt lgkmcnt(0)
	v_mfma_f32_16x16x32_bf16 v[92:95], v[180:183], v[216:219], v[92:95]
	v_mfma_f32_16x16x32_bf16 v[88:91], v[188:191], v[216:219], v[88:91]
	v_mfma_f32_16x16x32_bf16 v[84:87], v[180:183], v[224:227], v[84:87]
	v_mfma_f32_16x16x32_bf16 v[80:83], v[188:191], v[224:227], v[80:83]
	v_mfma_f32_16x16x32_bf16 v[76:79], v[180:183], v[232:235], v[76:79]
	v_mfma_f32_16x16x32_bf16 v[72:75], v[188:191], v[232:235], v[72:75]
	v_mfma_f32_16x16x32_bf16 v[68:71], v[180:183], v[240:243], v[68:71]
	v_mfma_f32_16x16x32_bf16 v[60:63], v[188:191], v[240:243], v[60:63]
	v_mfma_f32_16x16x32_bf16 v[92:95], v[184:187], v[220:223], v[92:95]
	v_mfma_f32_16x16x32_bf16 v[88:91], v[192:195], v[220:223], v[88:91]
	v_mfma_f32_16x16x32_bf16 v[84:87], v[184:187], v[228:231], v[84:87]
	v_mfma_f32_16x16x32_bf16 v[80:83], v[192:195], v[228:231], v[80:83]
	v_mfma_f32_16x16x32_bf16 v[76:79], v[184:187], v[236:239], v[76:79]
	v_mfma_f32_16x16x32_bf16 v[72:75], v[192:195], v[236:239], v[72:75]
	v_mfma_f32_16x16x32_bf16 v[68:71], v[184:187], v[244:247], v[68:71]
	v_mfma_f32_16x16x32_bf16 v[60:63], v[192:195], v[244:247], v[60:63]
	s_setprio 0
	s_setprio 1
	v_mfma_f32_16x16x32_bf16 v[28:31], v[196:199], v[216:219], v[28:31]
	v_mfma_f32_16x16x32_bf16 v[24:27], v[208:211], v[216:219], v[24:27]
	v_mfma_f32_16x16x32_bf16 v[20:23], v[196:199], v[224:227], v[20:23]
	v_mfma_f32_16x16x32_bf16 v[16:19], v[208:211], v[224:227], v[16:19]
	v_mfma_f32_16x16x32_bf16 v[12:15], v[196:199], v[232:235], v[12:15]
	v_mfma_f32_16x16x32_bf16 v[8:11], v[208:211], v[232:235], v[8:11]
	v_mfma_f32_16x16x32_bf16 v[4:7], v[196:199], v[240:243], v[4:7]
	v_mfma_f32_16x16x32_bf16 v[0:3], v[208:211], v[240:243], v[0:3]
	v_mfma_f32_16x16x32_bf16 v[28:31], v[200:203], v[220:223], v[28:31]
	v_mfma_f32_16x16x32_bf16 v[24:27], v[212:215], v[220:223], v[24:27]
	v_mfma_f32_16x16x32_bf16 v[20:23], v[200:203], v[228:231], v[20:23]
	v_mfma_f32_16x16x32_bf16 v[16:19], v[212:215], v[228:231], v[16:19]
	v_mfma_f32_16x16x32_bf16 v[12:15], v[200:203], v[236:239], v[12:15]
	v_mfma_f32_16x16x32_bf16 v[8:11], v[212:215], v[236:239], v[8:11]
	v_mfma_f32_16x16x32_bf16 v[4:7], v[200:203], v[244:247], v[4:7]
	v_mfma_f32_16x16x32_bf16 v[0:3], v[212:215], v[244:247], v[0:3]
	s_setprio 0
	s_barrier
	s_add_i32 s81, s81, 2
	s_add_u32 s40, s40, 0x100
	s_addc_u32 s41, s41, 0
	s_cmp_gt_u32 s81, 13
	s_cbranch_scc0 .LBB0_332
	s_and_b64 vcc, exec, s[22:23]
	s_cbranch_vccz .LBB0_335
	s_barrier

; #define PG8_STAGE(bufoff, gbase, voff) do { _Pragma("unroll") for (int _i = 0; _i < 2; ++_i) \
;         __builtin_amdgcn_global_load_lds((const unsigned*)((const char*)(gbase) + (voff)[_i]), (PG8_LAS unsigned*)(lds + (bufoff) + ldsw + _i * 8192), 16, 0, 0); } while (0)
; #define PG8_LDA(dst, b, h) do { _Pragma("unroll") for (int m = 0; m < 4; ++m) _Pragma("unroll") for (int k = 0; k < 2; ++k) dst[m][k] = *(const PG8_LAS bf16x8*)(lds + PG8_SA(b, h) + aoff + m * 2048 + k * 1024); } while (0)
; #define PG8_LDB(dst, b, h) do { _Pragma("unroll") for (int n = 0; n < 2; ++n) _Pragma("unroll") for (int k = 0; k < 2; ++k) dst[n][k] = *(const PG8_LAS bf16x8*)(lds + PG8_SB(b, h) + boff + n * 2048 + k * 1024); } while (0)
; #define PG8_MMA(ai, bj, At, Bt) do { __builtin_amdgcn_s_setprio(1); _Pragma("unroll") for (int m = 0; m < 4; ++m) _Pragma("unroll") for (int n = 0; n < 2; ++n) _Pragma("unroll") for (int k = 0; k < 2; ++k) \
;         acc[ai][bj][m][n] = __builtin_amdgcn_mfma_f32_16x16x32_bf16(Bt[n][k], At[m][k], acc[ai][bj][m][n], 0, 0, 0); __builtin_amdgcn_s_setprio(0); } while (0)
; #define PG8_WAIT_V(n) asm volatile("s_waitcnt vmcnt(" #n ")" ::: "memory")
; #define PG8_WAIT_L(n) asm volatile("s_waitcnt lgkmcnt(" #n ")" ::: "memory")
; template <class Epi, class Sched, bool ALIGN_EPI = false, bool SP2 = false>
; __device__ __forceinline__ void gemm_phase(PG8_LAS unsigned char* lds, const Gemm g, const Sched& S, const Epi& E) {
;     ...
;             const bool last = (t == nt - 2);
;             const char* a1 = cA + PG8_AK(t + 1);
;             const char* a2 = last ? nA : cA + PG8_AK(t + 2); const char* b2 = last ? nB : cB + (size_t)(t + 2) * kstep;
;             const char* a3 = last ? nA + PG8_AK(1) : cA + PG8_AK(t + 3); const char* b3 = b2 + kstep;
;             if (last && has_next) S.a_ready(nxt);
;             if constexpr (SP2) {
;             PG8_LDB(B0, 0, 0); PG8_LDB(B1, 0, 1); PG8_SCHED; PG8_LDA(At, 0, 0); PG8_STAGE(PG8_SA(1, 1), a1 + hstepA, voffA);
;             PG8_WAIT_V(8); PG8_WAIT_L(0); PG8_BAR; PG8_MMA(0, 0, At, B0); PG8_MMA(0, 1, At, B1); PG8_BAR; PG8_SCHED;
;             PG8_LDA(At, 0, 1); PG8_STAGE(PG8_SB(0, 0), b2, voffB); PG8_STAGE(PG8_SB(0, 1), b2 + hstepB, voffB); PG8_STAGE(PG8_SA(0, 0), a2, voffA);
;             PG8_WAIT_V(8); PG8_WAIT_L(0); PG8_BAR; PG8_MMA(1, 0, At, B0); PG8_MMA(1, 1, At, B1); PG8_BAR; PG8_SCHED;
.LBB0_416:
	ds_read_b128 v[132:135], v171
	ds_read_b128 v[136:139], v171 offset:1024
	ds_read_b128 v[140:143], v171 offset:2048
	ds_read_b128 v[178:181], v171 offset:3072
	ds_read_b128 v[182:185], v173
	ds_read_b128 v[186:189], v173 offset:1024
	ds_read_b128 v[190:193], v173 offset:2048
	ds_read_b128 v[194:197], v173 offset:3072
	s_add_u32 s38, s34, s36
	s_addc_u32 s39, s35, s37
	s_add_u32 s42, s38, 0x100
	s_addc_u32 s43, s39, 0
	s_add_u32 s40, s66, s36
	s_addc_u32 s41, s67, s37
	s_add_u32 s38, s38, 0x180
	s_addc_u32 s39, s39, 0
	s_cmpk_eq_i32 s36, 0x700
	s_cselect_b32 s39, s65, s39
	s_cselect_b32 s38, s64, s38
	s_cselect_b32 s41, s23, s41
	s_cselect_b32 s40, s63, s40
	s_cselect_b32 s43, s3, s43
	s_cselect_b32 s42, s25, s42
	v_lshl_add_u64 v[206:207], v[130:131], 0, s[36:37]
	s_add_i32 m0, s31, 0xc000
	ds_read_b128 v[198:201], v175
	ds_read_b128 v[202:205], v175 offset:1024
	ds_read_b128 v[208:211], v175 offset:2048
	ds_read_b128 v[212:215], v175 offset:3072
	ds_read_b128 v[216:219], v175 offset:4096
	ds_read_b128 v[220:223], v175 offset:5120
	ds_read_b128 v[224:227], v175 offset:6144
	ds_read_b128 v[228:231], v175 offset:7168
	global_load_lds_dwordx4 v[206:207], off
	v_lshl_add_u64 v[206:207], v[128:129], 0, s[36:37]
	s_add_i32 m0, s31, 0xe000
	s_nop 0
	global_load_lds_dwordx4 v[206:207], off
	s_waitcnt vmcnt(8)
	s_waitcnt lgkmcnt(0)
	s_barrier
	s_setprio 1
	s_waitcnt lgkmcnt(0)
	v_mfma_f32_16x16x32_bf16 v[124:127], v[132:135], v[198:201], v[124:127]
	v_mfma_f32_16x16x32_bf16 v[120:123], v[140:143], v[198:201], v[120:123]
	v_mfma_f32_16x16x32_bf16 v[116:119], v[132:135], v[208:211], v[116:119]
	v_mfma_f32_16x16x32_bf16 v[112:115], v[140:143], v[208:211], v[112:115]
	v_mfma_f32_16x16x32_bf16 v[108:111], v[132:135], v[216:219], v[108:111]
	v_mfma_f32_16x16x32_bf16 v[104:107], v[140:143], v[216:219], v[104:107]
	v_mfma_f32_16x16x32_bf16 v[100:103], v[132:135], v[224:227], v[100:103]
	v_mfma_f32_16x16x32_bf16 v[96:99], v[140:143], v[224:227], v[96:99]
	v_mfma_f32_16x16x32_bf16 v[124:127], v[136:139], v[202:205], v[124:127]
	v_mfma_f32_16x16x32_bf16 v[120:123], v[178:181], v[202:205], v[120:123]
	v_mfma_f32_16x16x32_bf16 v[116:119], v[136:139], v[212:215], v[116:119]
	v_mfma_f32_16x16x32_bf16 v[112:115], v[178:181], v[212:215], v[112:115]
	v_mfma_f32_16x16x32_bf16 v[108:111], v[136:139], v[220:223], v[108:111]
	v_mfma_f32_16x16x32_bf16 v[104:107], v[178:181], v[220:223], v[104:107]
	v_mfma_f32_16x16x32_bf16 v[100:103], v[136:139], v[228:231], v[100:103]
	v_mfma_f32_16x16x32_bf16 v[96:99], v[178:181], v[228:231], v[96:99]
	s_setprio 0
	s_setprio 1
	v_mfma_f32_16x16x32_bf16 v[64:67], v[182:185], v[198:201], v[64:67]
	v_mfma_f32_16x16x32_bf16 v[56:59], v[190:193], v[198:201], v[56:59]
	v_mfma_f32_16x16x32_bf16 v[52:55], v[182:185], v[208:211], v[52:55]
	v_mfma_f32_16x16x32_bf16 v[48:51], v[190:193], v[208:211], v[48:51]
	v_mfma_f32_16x16x32_bf16 v[44:47], v[182:185], v[216:219], v[44:47]
	v_mfma_f32_16x16x32_bf16 v[40:43], v[190:193], v[216:219], v[40:43]
	v_mfma_f32_16x16x32_bf16 v[36:39], v[182:185], v[224:227], v[36:39]
	v_mfma_f32_16x16x32_bf16 v[32:35], v[190:193], v[224:227], v[32:35]
	v_mfma_f32_16x16x32_bf16 v[64:67], v[186:189], v[202:205], v[64:67]
	v_mfma_f32_16x16x32_bf16 v[56:59], v[194:197], v[202:205], v[56:59]
	v_mfma_f32_16x16x32_bf16 v[52:55], v[186:189], v[212:215], v[52:55]
	v_mfma_f32_16x16x32_bf16 v[48:51], v[194:197], v[212:215], v[48:51]
	v_mfma_f32_16x16x32_bf16 v[44:47], v[186:189], v[220:223], v[44:47]
	v_mfma_f32_16x16x32_bf16 v[40:43], v[194:197], v[220:223], v[40:43]
	v_mfma_f32_16x16x32_bf16 v[36:39], v[186:189], v[228:231], v[36:39]
	v_mfma_f32_16x16x32_bf16 v[32:35], v[194:197], v[228:231], v[32:35]
	s_setprio 0
	s_barrier
	s_add_i32 s69, s59, s49
	v_lshl_add_u64 v[206:207], s[40:41], 0, v[148:149]
	s_mov_b32 m0, s69
	ds_read_b128 v[198:201], v175 offset:16384
	ds_read_b128 v[202:205], v175 offset:17408
	ds_read_b128 v[208:211], v175 offset:18432
	ds_read_b128 v[212:215], v175 offset:19456
	ds_read_b128 v[216:219], v175 offset:20480
	ds_read_b128 v[220:223], v175 offset:21504
	ds_read_b128 v[224:227], v175 offset:22528
	ds_read_b128 v[228:231], v175 offset:23552
	global_load_lds_dwordx4 v148, s[40:41]
	s_add_i32 m0, s69, 0x2000
	s_add_u32 s70, s40, 0x40000
	v_lshl_add_u64 v[232:233], s[40:41], 0, v[144:145]
	s_addc_u32 s71, s41, 0
	s_add_i32 s69, s60, s49
	global_load_lds_dwordx4 v144, s[40:41]
	s_mov_b32 m0, s69
	s_nop 0
	global_load_lds_dwordx4 v148, s[70:71]
	s_add_i32 m0, s69, 0x2000
	s_nop 0
	global_load_lds_dwordx4 v144, s[70:71]
	s_mov_b32 m0, s31
	s_nop 0
	global_load_lds_dwordx4 v150, s[42:43]
	v_lshl_add_u64 v[234:235], s[42:43], 0, v[146:147]
	s_mov_b32 m0, s52
	s_nop 0
	global_load_lds_dwordx4 v146, s[42:43]
	s_waitcnt vmcnt(8)
	s_waitcnt lgkmcnt(0)
	s_barrier
; #define PG8_STAGE(bufoff, gbase, voff) do { _Pragma("unroll") for (int _i = 0; _i < 2; ++_i) \
;         __builtin_amdgcn_global_load_lds((const unsigned*)((const char*)(gbase) + (voff)[_i]), (PG8_LAS unsigned*)(lds + (bufoff) + ldsw + _i * 8192), 16, 0, 0); } while (0)
; #define PG8_LDA(dst, b, h) do { _Pragma("unroll") for (int m = 0; m < 4; ++m) _Pragma("unroll") for (int k = 0; k < 2; ++k) dst[m][k] = *(const PG8_LAS bf16x8*)(lds + PG8_SA(b, h) + aoff + m * 2048 + k * 1024); } while (0)
; #define PG8_LDB(dst, b, h) do { _Pragma("unroll") for (int n = 0; n < 2; ++n) _Pragma("unroll") for (int k = 0; k < 2; ++k) dst[n][k] = *(const PG8_LAS bf16x8*)(lds + PG8_SB(b, h) + boff + n * 2048 + k * 1024); } while (0)
; #define PG8_MMA(ai, bj, At, Bt) do { __builtin_amdgcn_s_setprio(1); _Pragma("unroll") for (int m = 0; m < 4; ++m) _Pragma("unroll") for (int n = 0; n < 2; ++n) _Pragma("unroll") for (int k = 0; k < 2; ++k) \
;         acc[ai][bj][m][n] = __builtin_amdgcn_mfma_f32_16x16x32_bf16(Bt[n][k], At[m][k], acc[ai][bj][m][n], 0, 0, 0); __builtin_amdgcn_s_setprio(0); } while (0)
; #define PG8_WAIT_V(n) asm volatile("s_waitcnt vmcnt(" #n ")" ::: "memory")
; #define PG8_WAIT_L(n) asm volatile("s_waitcnt lgkmcnt(" #n ")" ::: "memory")
; #define PG8_BAR __builtin_amdgcn_s_barrier()
; #define PG8_SCHED __builtin_amdgcn_sched_barrier(0)
; template <class Epi, class Sched, bool ALIGN_EPI = false, bool SP2 = false>
; __device__ __forceinline__ void gemm_phase(PG8_LAS unsigned char* lds, const Gemm g, const Sched& S, const Epi& E) {
;     ...
;             PG8_WAIT_V(8); PG8_WAIT_L(0); PG8_BAR; PG8_MMA(1, 0, At, B0); PG8_MMA(1, 1, At, B1); PG8_BAR; PG8_SCHED;
;             PG8_LDB(B0, 1, 0); PG8_LDB(B1, 1, 1); PG8_SCHED; PG8_LDA(At, 1, 0); PG8_STAGE(PG8_SA(0, 1), a2 + hstepA, voffA);
;             PG8_WAIT_V(8); PG8_WAIT_L(0); PG8_BAR; PG8_MMA(0, 0, At, B0); PG8_MMA(0, 1, At, B1); PG8_BAR; PG8_SCHED;
	s_setprio 1
	s_waitcnt lgkmcnt(0)
	v_mfma_f32_16x16x32_bf16 v[92:95], v[132:135], v[198:201], v[92:95]
	v_mfma_f32_16x16x32_bf16 v[88:91], v[140:143], v[198:201], v[88:91]
	v_mfma_f32_16x16x32_bf16 v[84:87], v[132:135], v[208:211], v[84:87]
	v_mfma_f32_16x16x32_bf16 v[80:83], v[140:143], v[208:211], v[80:83]
	v_mfma_f32_16x16x32_bf16 v[76:79], v[132:135], v[216:219], v[76:79]
	v_mfma_f32_16x16x32_bf16 v[72:75], v[140:143], v[216:219], v[72:75]
	v_mfma_f32_16x16x32_bf16 v[68:71], v[132:135], v[224:227], v[68:71]
	v_mfma_f32_16x16x32_bf16 v[60:63], v[140:143], v[224:227], v[60:63]
	v_mfma_f32_16x16x32_bf16 v[92:95], v[136:139], v[202:205], v[92:95]
	v_mfma_f32_16x16x32_bf16 v[88:91], v[178:181], v[202:205], v[88:91]
	v_mfma_f32_16x16x32_bf16 v[84:87], v[136:139], v[212:215], v[84:87]
	v_mfma_f32_16x16x32_bf16 v[80:83], v[178:181], v[212:215], v[80:83]
	v_mfma_f32_16x16x32_bf16 v[76:79], v[136:139], v[220:223], v[76:79]
	v_mfma_f32_16x16x32_bf16 v[72:75], v[178:181], v[220:223], v[72:75]
	v_mfma_f32_16x16x32_bf16 v[68:71], v[136:139], v[228:231], v[68:71]
	v_mfma_f32_16x16x32_bf16 v[60:63], v[178:181], v[228:231], v[60:63]
	s_setprio 0
	s_setprio 1
	v_mfma_f32_16x16x32_bf16 v[28:31], v[182:185], v[198:201], v[28:31]
	v_mfma_f32_16x16x32_bf16 v[24:27], v[190:193], v[198:201], v[24:27]
	v_mfma_f32_16x16x32_bf16 v[20:23], v[182:185], v[208:211], v[20:23]
	v_mfma_f32_16x16x32_bf16 v[16:19], v[190:193], v[208:211], v[16:19]
	v_mfma_f32_16x16x32_bf16 v[12:15], v[182:185], v[216:219], v[12:15]
	v_mfma_f32_16x16x32_bf16 v[8:11], v[190:193], v[216:219], v[8:11]
	v_mfma_f32_16x16x32_bf16 v[4:7], v[182:185], v[224:227], v[4:7]
	v_mfma_f32_16x16x32_bf16 v[0:3], v[190:193], v[224:227], v[0:3]
	v_mfma_f32_16x16x32_bf16 v[28:31], v[186:189], v[202:205], v[28:31]
	v_mfma_f32_16x16x32_bf16 v[24:27], v[194:197], v[202:205], v[24:27]
	v_mfma_f32_16x16x32_bf16 v[20:23], v[186:189], v[212:215], v[20:23]
	v_mfma_f32_16x16x32_bf16 v[16:19], v[194:197], v[212:215], v[16:19]
	v_mfma_f32_16x16x32_bf16 v[12:15], v[186:189], v[220:223], v[12:15]
	v_mfma_f32_16x16x32_bf16 v[8:11], v[194:197], v[220:223], v[8:11]
	v_mfma_f32_16x16x32_bf16 v[4:7], v[186:189], v[228:231], v[4:7]
	v_mfma_f32_16x16x32_bf16 v[0:3], v[194:197], v[228:231], v[0:3]
	s_setprio 0
	s_barrier
	s_add_i32 s69, 0, 0x18000
	v_add_u32_e32 v160, s69, v163
	s_add_i32 s70, 0, 0x1c000
	ds_read_b128 v[132:135], v160
	ds_read_b128 v[136:139], v160 offset:1024
	ds_read_b128 v[140:143], v160 offset:2048
	ds_read_b128 v[178:181], v160 offset:3072
	v_add_u32_e32 v160, s70, v163
	ds_read_b128 v[182:185], v160
	ds_read_b128 v[186:189], v160 offset:1024
	ds_read_b128 v[190:193], v160 offset:2048
	ds_read_b128 v[194:197], v160 offset:3072
	s_add_u32 s42, s42, 0x40000
	s_addc_u32 s43, s43, 0
	s_mov_b32 m0, s53
	ds_read_b128 v[198:201], v175 offset:32768
	ds_read_b128 v[202:205], v175 offset:33792
	ds_read_b128 v[208:211], v175 offset:34816
	ds_read_b128 v[212:215], v175 offset:35840
	ds_read_b128 v[216:219], v175 offset:36864
	ds_read_b128 v[220:223], v175 offset:37888
	ds_read_b128 v[224:227], v175 offset:38912
	ds_read_b128 v[228:231], v175 offset:39936
	global_load_lds_dwordx4 v150, s[42:43]
	v_lshl_add_u64 v[234:235], s[42:43], 0, v[146:147]
	s_mov_b32 m0, s54
	s_nop 0
	global_load_lds_dwordx4 v146, s[42:43]
	s_waitcnt vmcnt(8)
	s_waitcnt lgkmcnt(0)
	s_barrier
	s_setprio 1
	s_waitcnt lgkmcnt(0)
	v_mfma_f32_16x16x32_bf16 v[124:127], v[132:135], v[198:201], v[124:127]
	v_mfma_f32_16x16x32_bf16 v[120:123], v[140:143], v[198:201], v[120:123]
	v_mfma_f32_16x16x32_bf16 v[116:119], v[132:135], v[208:211], v[116:119]
	v_mfma_f32_16x16x32_bf16 v[112:115], v[140:143], v[208:211], v[112:115]
	v_mfma_f32_16x16x32_bf16 v[108:111], v[132:135], v[216:219], v[108:111]
	v_mfma_f32_16x16x32_bf16 v[104:107], v[140:143], v[216:219], v[104:107]
	v_mfma_f32_16x16x32_bf16 v[100:103], v[132:135], v[224:227], v[100:103]
	v_mfma_f32_16x16x32_bf16 v[96:99], v[140:143], v[224:227], v[96:99]
	v_mfma_f32_16x16x32_bf16 v[124:127], v[136:139], v[202:205], v[124:127]
	v_mfma_f32_16x16x32_bf16 v[120:123], v[178:181], v[202:205], v[120:123]
	v_mfma_f32_16x16x32_bf16 v[116:119], v[136:139], v[212:215], v[116:119]
	v_mfma_f32_16x16x32_bf16 v[112:115], v[178:181], v[212:215], v[112:115]
	v_mfma_f32_16x16x32_bf16 v[108:111], v[136:139], v[220:223], v[108:111]
	v_mfma_f32_16x16x32_bf16 v[104:107], v[178:181], v[220:223], v[104:107]
	v_mfma_f32_16x16x32_bf16 v[100:103], v[136:139], v[228:231], v[100:103]
	v_mfma_f32_16x16x32_bf16 v[96:99], v[178:181], v[228:231], v[96:99]
	s_setprio 0
	s_setprio 1
	v_mfma_f32_16x16x32_bf16 v[64:67], v[182:185], v[198:201], v[64:67]
	v_mfma_f32_16x16x32_bf16 v[56:59], v[190:193], v[198:201], v[56:59]
	v_mfma_f32_16x16x32_bf16 v[52:55], v[182:185], v[208:211], v[52:55]
	v_mfma_f32_16x16x32_bf16 v[48:51], v[190:193], v[208:211], v[48:51]
	v_mfma_f32_16x16x32_bf16 v[44:47], v[182:185], v[216:219], v[44:47]
	v_mfma_f32_16x16x32_bf16 v[40:43], v[190:193], v[216:219], v[40:43]
	v_mfma_f32_16x16x32_bf16 v[36:39], v[182:185], v[224:227], v[36:39]
	v_mfma_f32_16x16x32_bf16 v[32:35], v[190:193], v[224:227], v[32:35]
	v_mfma_f32_16x16x32_bf16 v[64:67], v[186:189], v[202:205], v[64:67]
	v_mfma_f32_16x16x32_bf16 v[56:59], v[194:197], v[202:205], v[56:59]
	v_mfma_f32_16x16x32_bf16 v[52:55], v[186:189], v[212:215], v[52:55]
	v_mfma_f32_16x16x32_bf16 v[48:51], v[194:197], v[212:215], v[48:51]
	v_mfma_f32_16x16x32_bf16 v[44:47], v[186:189], v[220:223], v[44:47]
	v_mfma_f32_16x16x32_bf16 v[40:43], v[194:197], v[220:223], v[40:43]
	v_mfma_f32_16x16x32_bf16 v[36:39], v[186:189], v[228:231], v[36:39]
	v_mfma_f32_16x16x32_bf16 v[32:35], v[194:197], v[228:231], v[32:35]
	s_setprio 0
	s_barrier
; #define PG8_STAGE(bufoff, gbase, voff) do { _Pragma("unroll") for (int _i = 0; _i < 2; ++_i) \
;         __builtin_amdgcn_global_load_lds((const unsigned*)((const char*)(gbase) + (voff)[_i]), (PG8_LAS unsigned*)(lds + (bufoff) + ldsw + _i * 8192), 16, 0, 0); } while (0)
; #define PG8_LDA(dst, b, h) do { _Pragma("unroll") for (int m = 0; m < 4; ++m) _Pragma("unroll") for (int k = 0; k < 2; ++k) dst[m][k] = *(const PG8_LAS bf16x8*)(lds + PG8_SA(b, h) + aoff + m * 2048 + k * 1024); } while (0)
; #define PG8_MMA(ai, bj, At, Bt) do { __builtin_amdgcn_s_setprio(1); _Pragma("unroll") for (int m = 0; m < 4; ++m) _Pragma("unroll") for (int n = 0; n < 2; ++n) _Pragma("unroll") for (int k = 0; k < 2; ++k) \
;         acc[ai][bj][m][n] = __builtin_amdgcn_mfma_f32_16x16x32_bf16(Bt[n][k], At[m][k], acc[ai][bj][m][n], 0, 0, 0); __builtin_amdgcn_s_setprio(0); } while (0)
; #define PG8_WAIT_V(n) asm volatile("s_waitcnt vmcnt(" #n ")" ::: "memory")
; #define PG8_WAIT_L(n) asm volatile("s_waitcnt lgkmcnt(" #n ")" ::: "memory")
; #define PG8_BAR __builtin_amdgcn_s_barrier()
; #define PG8_SCHED __builtin_amdgcn_sched_barrier(0)
; template <class Epi, class Sched, bool ALIGN_EPI = false, bool SP2 = false>
; __device__ __forceinline__ void gemm_phase(PG8_LAS unsigned char* lds, const Gemm g, const Sched& S, const Epi& E) {
;     ...
;             PG8_LDA(At, 1, 1); PG8_STAGE(PG8_SB(1, 0), b3, voffB); PG8_STAGE(PG8_SB(1, 1), b3 + hstepB, voffB); PG8_STAGE(PG8_SA(1, 0), a3, voffA);
;             PG8_WAIT_V(8); PG8_WAIT_L(0); PG8_BAR; PG8_MMA(1, 0, At, B0); PG8_MMA(1, 1, At, B1); PG8_BAR; PG8_SCHED;
;     ...
;         if constexpr (ALIGN_EPI) { if (wr == 0) PG8_BAR; }
	s_add_i32 s42, s69, s49
	v_lshl_add_u64 v[206:207], v[206:207], 0, s[16:17]
	s_mov_b32 m0, s42
	ds_read_b128 v[198:201], v175 offset:49152
	ds_read_b128 v[202:205], v175 offset:50176
	ds_read_b128 v[208:211], v175 offset:51200
	ds_read_b128 v[212:215], v175 offset:52224
	ds_read_b128 v[216:219], v175 offset:53248
	ds_read_b128 v[220:223], v175 offset:54272
	ds_read_b128 v[224:227], v175 offset:55296
	ds_read_b128 v[228:231], v175 offset:56320
	global_load_lds_dwordx4 v[206:207], off
	s_add_i32 m0, s42, 0x2000
	s_add_u32 s40, s40, 0x40080
	v_lshl_add_u64 v[206:207], v[232:233], 0, s[16:17]
	s_addc_u32 s41, s41, 0
	s_add_i32 s42, s70, s49
	global_load_lds_dwordx4 v[206:207], off
	s_mov_b32 m0, s42
	s_nop 0
	global_load_lds_dwordx4 v148, s[40:41]
	s_add_i32 m0, s42, 0x2000
	s_nop 0
	global_load_lds_dwordx4 v144, s[40:41]
	s_mov_b32 m0, s56
	s_nop 0
	global_load_lds_dwordx4 v150, s[38:39]
	v_lshl_add_u64 v[206:207], s[38:39], 0, v[146:147]
	s_mov_b32 m0, s57
	s_nop 0
	global_load_lds_dwordx4 v146, s[38:39]
	s_waitcnt vmcnt(8)
	s_waitcnt lgkmcnt(0)
	s_barrier
	s_setprio 1
	s_waitcnt lgkmcnt(0)
	v_mfma_f32_16x16x32_bf16 v[92:95], v[132:135], v[198:201], v[92:95]
	v_mfma_f32_16x16x32_bf16 v[88:91], v[140:143], v[198:201], v[88:91]
	v_mfma_f32_16x16x32_bf16 v[84:87], v[132:135], v[208:211], v[84:87]
	v_mfma_f32_16x16x32_bf16 v[80:83], v[140:143], v[208:211], v[80:83]
	v_mfma_f32_16x16x32_bf16 v[76:79], v[132:135], v[216:219], v[76:79]
	v_mfma_f32_16x16x32_bf16 v[72:75], v[140:143], v[216:219], v[72:75]
	v_mfma_f32_16x16x32_bf16 v[68:71], v[132:135], v[224:227], v[68:71]
	v_mfma_f32_16x16x32_bf16 v[60:63], v[140:143], v[224:227], v[60:63]
	v_mfma_f32_16x16x32_bf16 v[92:95], v[136:139], v[202:205], v[92:95]
	v_mfma_f32_16x16x32_bf16 v[88:91], v[178:181], v[202:205], v[88:91]
	v_mfma_f32_16x16x32_bf16 v[84:87], v[136:139], v[212:215], v[84:87]
	v_mfma_f32_16x16x32_bf16 v[80:83], v[178:181], v[212:215], v[80:83]
	v_mfma_f32_16x16x32_bf16 v[76:79], v[136:139], v[220:223], v[76:79]
	v_mfma_f32_16x16x32_bf16 v[72:75], v[178:181], v[220:223], v[72:75]
	v_mfma_f32_16x16x32_bf16 v[68:71], v[136:139], v[228:231], v[68:71]
	v_mfma_f32_16x16x32_bf16 v[60:63], v[178:181], v[228:231], v[60:63]
	s_setprio 0
	s_setprio 1
	v_mfma_f32_16x16x32_bf16 v[28:31], v[182:185], v[198:201], v[28:31]
	v_mfma_f32_16x16x32_bf16 v[24:27], v[190:193], v[198:201], v[24:27]
	v_mfma_f32_16x16x32_bf16 v[20:23], v[182:185], v[208:211], v[20:23]
	v_mfma_f32_16x16x32_bf16 v[16:19], v[190:193], v[208:211], v[16:19]
	v_mfma_f32_16x16x32_bf16 v[12:15], v[182:185], v[216:219], v[12:15]
	v_mfma_f32_16x16x32_bf16 v[8:11], v[190:193], v[216:219], v[8:11]
	v_mfma_f32_16x16x32_bf16 v[4:7], v[182:185], v[224:227], v[4:7]
	v_mfma_f32_16x16x32_bf16 v[0:3], v[190:193], v[224:227], v[0:3]
	v_mfma_f32_16x16x32_bf16 v[28:31], v[186:189], v[202:205], v[28:31]
	v_mfma_f32_16x16x32_bf16 v[24:27], v[194:197], v[202:205], v[24:27]
	v_mfma_f32_16x16x32_bf16 v[20:23], v[186:189], v[212:215], v[20:23]
	v_mfma_f32_16x16x32_bf16 v[16:19], v[194:197], v[212:215], v[16:19]
	v_mfma_f32_16x16x32_bf16 v[12:15], v[186:189], v[220:223], v[12:15]
	v_mfma_f32_16x16x32_bf16 v[8:11], v[194:197], v[220:223], v[8:11]
	v_mfma_f32_16x16x32_bf16 v[4:7], v[186:189], v[228:231], v[4:7]
	v_mfma_f32_16x16x32_bf16 v[0:3], v[194:197], v[228:231], v[0:3]
	s_setprio 0
	s_barrier
	s_add_i32 s68, s68, 2
	s_add_u32 s36, s36, 0x100
	s_addc_u32 s37, s37, 0
	s_cmp_gt_u32 s68, 13
	s_cbranch_scc0 .LBB0_416
	s_and_b64 vcc, exec, s[18:19]
	s_cbranch_vccz .LBB0_419
	s_barrier

; #define PG8_STAGE(bufoff, gbase, voff) do { _Pragma("unroll") for (int _i = 0; _i < 2; ++_i) \
;         __builtin_amdgcn_global_load_lds((const unsigned*)((const char*)(gbase) + (voff)[_i]), (PG8_LAS unsigned*)(lds + (bufoff) + ldsw + _i * 8192), 16, 0, 0); } while (0)
; #define PG8_LDA(dst, b, h) do { _Pragma("unroll") for (int m = 0; m < 4; ++m) _Pragma("unroll") for (int k = 0; k < 2; ++k) dst[m][k] = *(const PG8_LAS bf16x8*)(lds + PG8_SA(b, h) + aoff + m * 2048 + k * 1024); } while (0)
; #define PG8_LDB(dst, b, h) do { _Pragma("unroll") for (int n = 0; n < 2; ++n) _Pragma("unroll") for (int k = 0; k < 2; ++k) dst[n][k] = *(const PG8_LAS bf16x8*)(lds + PG8_SB(b, h) + boff + n * 2048 + k * 1024); } while (0)
; #define PG8_MMA(ai, bj, At, Bt) do { __builtin_amdgcn_s_setprio(1); _Pragma("unroll") for (int m = 0; m < 4; ++m) _Pragma("unroll") for (int n = 0; n < 2; ++n) _Pragma("unroll") for (int k = 0; k < 2; ++k) \
;         acc[ai][bj][m][n] = __builtin_amdgcn_mfma_f32_16x16x32_bf16(Bt[n][k], At[m][k], acc[ai][bj][m][n], 0, 0, 0); __builtin_amdgcn_s_setprio(0); } while (0)
; template <class Epi, class Sched, bool ALIGN_EPI = false, bool SP2 = false>
; __device__ __forceinline__ void gemm_phase(PG8_LAS unsigned char* lds, const Gemm g, const Sched& S, const Epi& E) {
;     ...
;         const bool has_next = S.next(ui + 1, nxt);
;         const char* nA = has_next ? (const char*)g.A + (size_t)nxt.pm * tstepA : cA; const char* nB = has_next ? (const char*)g.Bt + (size_t)nxt.pn * tstepB : cB;
;         for (int t = 0; t < nt; t += 2) {
;             const bool last = (t == nt - 2);
;             const char* a1 = cA + PG8_AK(t + 1);
;             const char* a2 = last ? nA : cA + PG8_AK(t + 2); const char* b2 = last ? nB : cB + (size_t)(t + 2) * kstep;
;             const char* a3 = last ? nA + PG8_AK(1) : cA + PG8_AK(t + 3); const char* b3 = b2 + kstep;
;             if (last && has_next) S.a_ready(nxt);
;             if constexpr (SP2) {
;             PG8_LDB(B0, 0, 0); PG8_LDB(B1, 0, 1); PG8_SCHED; PG8_LDA(At, 0, 0); PG8_STAGE(PG8_SA(1, 1), a1 + hstepA, voffA);
;             PG8_WAIT_V(8); PG8_WAIT_L(0); PG8_BAR; PG8_MMA(0, 0, At, B0); PG8_MMA(0, 1, At, B1); PG8_BAR; PG8_SCHED;
;             PG8_LDA(At, 0, 1); PG8_STAGE(PG8_SB(0, 0), b2, voffB); PG8_STAGE(PG8_SB(0, 1), b2 + hstepB, voffB); PG8_STAGE(PG8_SA(0, 0), a2, voffA);
.LBB0_439:
	ds_read_b128 v[0:3], v145
	ds_read_b128 v[4:7], v145 offset:1024
	ds_read_b128 v[8:11], v145 offset:2048
	ds_read_b128 v[12:15], v145 offset:3072
	ds_read_b128 v[16:19], v146
	ds_read_b128 v[20:23], v146 offset:1024
	ds_read_b128 v[24:27], v146 offset:2048
	ds_read_b128 v[28:31], v146 offset:3072
	s_ashr_i32 s31, s30, 31
	s_lshl_b64 s[34:35], s[30:31], 17
	s_add_u32 s34, s49, s34
	s_addc_u32 s35, s50, s35
	s_and_b64 s[36:37], s[4:5], exec
	s_cselect_b32 s47, s35, s41
	s_cselect_b32 s46, s34, s40
	s_ashr_i32 s29, s28, 31
	s_lshl_b64 s[36:37], s[28:29], 17
	s_add_u32 s36, s51, s36
	s_addc_u32 s37, s52, s37
	s_and_b64 s[44:45], s[4:5], exec
	s_cselect_b32 s45, s37, s43
	s_cselect_b32 s44, s36, s42
	s_add_u32 s66, s40, 0x10080
	s_addc_u32 s67, s41, 0
	s_add_i32 s78, s3, 0xc000
	s_mov_b32 m0, s78
	s_add_i32 s29, s3, 0xe000
	ds_read_b128 v[32:35], v147
	ds_read_b128 v[36:39], v147 offset:1024
	ds_read_b128 v[40:43], v147 offset:2048
	ds_read_b128 v[44:47], v147 offset:3072
	ds_read_b128 v[48:51], v147 offset:4096
	ds_read_b128 v[52:55], v147 offset:5120
	ds_read_b128 v[56:59], v147 offset:6144
	ds_read_b128 v[60:63], v147 offset:7168
	global_load_lds_dwordx4 v128, s[66:67]
	v_lshl_add_u64 v[64:65], s[66:67], 0, v[132:133]
	s_mov_b32 m0, s29
	s_nop 0
	global_load_lds_dwordx4 v132, s[66:67]
	s_waitcnt vmcnt(8)
	s_waitcnt lgkmcnt(0)
	s_barrier
	s_setprio 1
	s_waitcnt lgkmcnt(0)
	v_mfma_f32_16x16x32_bf16 v[64:67], v[0:3], v[32:35], 0
	v_mfma_f32_16x16x32_bf16 v[68:71], v[8:11], v[32:35], 0
	v_mfma_f32_16x16x32_bf16 v[72:75], v[0:3], v[40:43], 0
	v_mfma_f32_16x16x32_bf16 v[76:79], v[8:11], v[40:43], 0
	v_mfma_f32_16x16x32_bf16 v[80:83], v[0:3], v[48:51], 0
	v_mfma_f32_16x16x32_bf16 v[84:87], v[8:11], v[48:51], 0
	v_mfma_f32_16x16x32_bf16 v[88:91], v[0:3], v[56:59], 0
	v_mfma_f32_16x16x32_bf16 v[92:95], v[8:11], v[56:59], 0
	v_mfma_f32_16x16x32_bf16 v[64:67], v[4:7], v[36:39], v[64:67]
	v_mfma_f32_16x16x32_bf16 v[68:71], v[12:15], v[36:39], v[68:71]
	v_mfma_f32_16x16x32_bf16 v[72:75], v[4:7], v[44:47], v[72:75]
	v_mfma_f32_16x16x32_bf16 v[76:79], v[12:15], v[44:47], v[76:79]
	v_mfma_f32_16x16x32_bf16 v[80:83], v[4:7], v[52:55], v[80:83]
	v_mfma_f32_16x16x32_bf16 v[84:87], v[12:15], v[52:55], v[84:87]
	v_mfma_f32_16x16x32_bf16 v[88:91], v[4:7], v[60:63], v[88:91]
	v_mfma_f32_16x16x32_bf16 v[92:95], v[12:15], v[60:63], v[92:95]
	s_setprio 0
	s_setprio 1
	v_mfma_f32_16x16x32_bf16 v[96:99], v[16:19], v[32:35], 0
	v_mfma_f32_16x16x32_bf16 v[32:35], v[24:27], v[32:35], 0
	v_mfma_f32_16x16x32_bf16 v[96:99], v[20:23], v[36:39], v[96:99]
	v_mfma_f32_16x16x32_bf16 v[32:35], v[28:31], v[36:39], v[32:35]
	v_mfma_f32_16x16x32_bf16 v[36:39], v[16:19], v[40:43], 0
	v_mfma_f32_16x16x32_bf16 v[40:43], v[24:27], v[40:43], 0
	v_mfma_f32_16x16x32_bf16 v[36:39], v[20:23], v[44:47], v[36:39]
	v_mfma_f32_16x16x32_bf16 v[40:43], v[28:31], v[44:47], v[40:43]
	v_mfma_f32_16x16x32_bf16 v[44:47], v[16:19], v[48:51], 0
	v_mfma_f32_16x16x32_bf16 v[48:51], v[24:27], v[48:51], 0
	v_mfma_f32_16x16x32_bf16 v[44:47], v[20:23], v[52:55], v[44:47]
	v_mfma_f32_16x16x32_bf16 v[48:51], v[28:31], v[52:55], v[48:51]
	v_mfma_f32_16x16x32_bf16 v[52:55], v[16:19], v[56:59], 0
	v_mfma_f32_16x16x32_bf16 v[56:59], v[24:27], v[56:59], 0
	v_mfma_f32_16x16x32_bf16 v[52:55], v[20:23], v[60:63], v[52:55]
	v_mfma_f32_16x16x32_bf16 v[56:59], v[28:31], v[60:63], v[56:59]
	s_setprio 0
	s_barrier
	s_add_i32 s68, s59, s53
	v_lshl_add_u64 v[140:141], s[42:43], 0, v[130:131]
	s_add_i32 s31, s68, 0x2000
	v_lshl_add_u64 v[148:149], v[140:141], 0, s[16:17]
	s_mov_b32 m0, s68
	v_lshl_add_u64 v[204:205], s[42:43], 0, v[134:135]
	s_add_u32 s70, s42, 0x10100
	ds_read_b128 v[60:63], v147 offset:16384
	ds_read_b128 v[100:103], v147 offset:17408
	ds_read_b128 v[104:107], v147 offset:18432
	ds_read_b128 v[108:111], v147 offset:19456
	ds_read_b128 v[112:115], v147 offset:20480
	ds_read_b128 v[116:119], v147 offset:21504
	ds_read_b128 v[120:123], v147 offset:22528
	ds_read_b128 v[124:127], v147 offset:23552
	global_load_lds_dwordx4 v[148:149], off
	v_lshl_add_u64 v[148:149], v[204:205], 0, s[16:17]
	s_mov_b32 m0, s31
	s_addc_u32 s71, s43, 0
	s_add_i32 s66, s60, s53
	global_load_lds_dwordx4 v[148:149], off
	s_mov_b32 m0, s66
	s_add_i32 s67, s66, 0x2000
	global_load_lds_dwordx4 v130, s[70:71]
	s_mov_b32 m0, s67
	v_lshl_add_u64 v[206:207], s[40:41], 0, v[128:129]
	global_load_lds_dwordx4 v134, s[70:71]
	v_lshl_add_u64 v[148:149], v[206:207], 0, s[16:17]
	s_mov_b32 m0, s3
	v_lshl_add_u64 v[216:217], s[40:41], 0, v[132:133]
	global_load_lds_dwordx4 v[148:149], off
	v_lshl_add_u64 v[148:149], v[216:217], 0, s[16:17]
	s_mov_b32 m0, s39
	s_nop 0
	global_load_lds_dwordx4 v[148:149], off
	s_waitcnt vmcnt(8)
	s_waitcnt lgkmcnt(0)
	s_barrier
; #define PG8_STAGE(bufoff, gbase, voff) do { _Pragma("unroll") for (int _i = 0; _i < 2; ++_i) \
;         __builtin_amdgcn_global_load_lds((const unsigned*)((const char*)(gbase) + (voff)[_i]), (PG8_LAS unsigned*)(lds + (bufoff) + ldsw + _i * 8192), 16, 0, 0); } while (0)
; #define PG8_LDA(dst, b, h) do { _Pragma("unroll") for (int m = 0; m < 4; ++m) _Pragma("unroll") for (int k = 0; k < 2; ++k) dst[m][k] = *(const PG8_LAS bf16x8*)(lds + PG8_SA(b, h) + aoff + m * 2048 + k * 1024); } while (0)
; #define PG8_LDB(dst, b, h) do { _Pragma("unroll") for (int n = 0; n < 2; ++n) _Pragma("unroll") for (int k = 0; k < 2; ++k) dst[n][k] = *(const PG8_LAS bf16x8*)(lds + PG8_SB(b, h) + boff + n * 2048 + k * 1024); } while (0)
; #define PG8_MMA(ai, bj, At, Bt) do { __builtin_amdgcn_s_setprio(1); _Pragma("unroll") for (int m = 0; m < 4; ++m) _Pragma("unroll") for (int n = 0; n < 2; ++n) _Pragma("unroll") for (int k = 0; k < 2; ++k) \
;         acc[ai][bj][m][n] = __builtin_amdgcn_mfma_f32_16x16x32_bf16(Bt[n][k], At[m][k], acc[ai][bj][m][n], 0, 0, 0); __builtin_amdgcn_s_setprio(0); } while (0)
; #define PG8_WAIT_V(n) asm volatile("s_waitcnt vmcnt(" #n ")" ::: "memory")
; #define PG8_WAIT_L(n) asm volatile("s_waitcnt lgkmcnt(" #n ")" ::: "memory")
; #define PG8_BAR __builtin_amdgcn_s_barrier()
; #define PG8_SCHED __builtin_amdgcn_sched_barrier(0)
; template <class Epi, class Sched, bool ALIGN_EPI = false, bool SP2 = false>
; __device__ __forceinline__ void gemm_phase(PG8_LAS unsigned char* lds, const Gemm g, const Sched& S, const Epi& E) {
;     ...
;             PG8_LDA(At, 0, 1); PG8_STAGE(PG8_SB(0, 0), b2, voffB); PG8_STAGE(PG8_SB(0, 1), b2 + hstepB, voffB); PG8_STAGE(PG8_SA(0, 0), a2, voffA);
;             PG8_WAIT_V(8); PG8_WAIT_L(0); PG8_BAR; PG8_MMA(1, 0, At, B0); PG8_MMA(1, 1, At, B1); PG8_BAR; PG8_SCHED;
;             PG8_LDB(B0, 1, 0); PG8_LDB(B1, 1, 1); PG8_SCHED; PG8_LDA(At, 1, 0); PG8_STAGE(PG8_SA(0, 1), a2 + hstepA, voffA);
;             PG8_WAIT_V(8); PG8_WAIT_L(0); PG8_BAR; PG8_MMA(0, 0, At, B0); PG8_MMA(0, 1, At, B1); PG8_BAR; PG8_SCHED;
	s_setprio 1
	s_waitcnt lgkmcnt(0)
	v_mfma_f32_16x16x32_bf16 v[148:151], v[0:3], v[60:63], 0
	v_mfma_f32_16x16x32_bf16 v[156:159], v[0:3], v[104:107], 0
	v_mfma_f32_16x16x32_bf16 v[164:167], v[0:3], v[112:115], 0
	v_mfma_f32_16x16x32_bf16 v[0:3], v[0:3], v[120:123], 0
	v_mfma_f32_16x16x32_bf16 v[148:151], v[4:7], v[100:103], v[148:151]
	v_mfma_f32_16x16x32_bf16 v[156:159], v[4:7], v[108:111], v[156:159]
	v_mfma_f32_16x16x32_bf16 v[164:167], v[4:7], v[116:119], v[164:167]
	v_mfma_f32_16x16x32_bf16 v[0:3], v[4:7], v[124:127], v[0:3]
	v_mfma_f32_16x16x32_bf16 v[4:7], v[8:11], v[120:123], 0
	v_mfma_f32_16x16x32_bf16 v[152:155], v[8:11], v[60:63], 0
	v_mfma_f32_16x16x32_bf16 v[160:163], v[8:11], v[104:107], 0
	v_mfma_f32_16x16x32_bf16 v[168:171], v[8:11], v[112:115], 0
	v_mfma_f32_16x16x32_bf16 v[4:7], v[12:15], v[124:127], v[4:7]
	v_mfma_f32_16x16x32_bf16 v[152:155], v[12:15], v[100:103], v[152:155]
	v_mfma_f32_16x16x32_bf16 v[160:163], v[12:15], v[108:111], v[160:163]
	v_mfma_f32_16x16x32_bf16 v[168:171], v[12:15], v[116:119], v[168:171]
	s_setprio 0
	s_setprio 1
	v_mfma_f32_16x16x32_bf16 v[8:11], v[16:19], v[60:63], 0
	v_mfma_f32_16x16x32_bf16 v[12:15], v[24:27], v[60:63], 0
	v_mfma_f32_16x16x32_bf16 v[8:11], v[20:23], v[100:103], v[8:11]
	v_mfma_f32_16x16x32_bf16 v[12:15], v[28:31], v[100:103], v[12:15]
	v_mfma_f32_16x16x32_bf16 v[60:63], v[16:19], v[104:107], 0
	v_mfma_f32_16x16x32_bf16 v[100:103], v[24:27], v[104:107], 0
	v_mfma_f32_16x16x32_bf16 v[104:107], v[16:19], v[112:115], 0
	v_mfma_f32_16x16x32_bf16 v[16:19], v[16:19], v[120:123], 0
	v_mfma_f32_16x16x32_bf16 v[60:63], v[20:23], v[108:111], v[60:63]
	v_mfma_f32_16x16x32_bf16 v[100:103], v[28:31], v[108:111], v[100:103]
	v_mfma_f32_16x16x32_bf16 v[104:107], v[20:23], v[116:119], v[104:107]
	v_mfma_f32_16x16x32_bf16 v[108:111], v[24:27], v[112:115], 0
	v_mfma_f32_16x16x32_bf16 v[16:19], v[20:23], v[124:127], v[16:19]
	v_mfma_f32_16x16x32_bf16 v[20:23], v[24:27], v[120:123], 0
	v_mfma_f32_16x16x32_bf16 v[108:111], v[28:31], v[116:119], v[108:111]
	v_mfma_f32_16x16x32_bf16 v[20:23], v[28:31], v[124:127], v[20:23]
	s_setprio 0
	s_barrier
	s_add_i32 s79, 0, 0x18000
	s_add_i32 s80, 0, 0x1c000
	v_add_u32_e32 v228, s79, v143
	v_add_u32_e32 v236, s80, v143
	ds_read_b128 v[24:27], v228
	ds_read_b128 v[28:31], v228 offset:1024
	ds_read_b128 v[112:115], v228 offset:2048
	ds_read_b128 v[116:119], v228 offset:3072
	ds_read_b128 v[120:123], v236
	ds_read_b128 v[124:127], v236 offset:1024
	ds_read_b128 v[172:175], v236 offset:2048
	ds_read_b128 v[176:179], v236 offset:3072
	s_add_u32 s70, s40, 0x10100
	s_addc_u32 s71, s41, 0
	s_mov_b32 m0, s54
	ds_read_b128 v[180:183], v147 offset:32768
	ds_read_b128 v[184:187], v147 offset:33792
	ds_read_b128 v[188:191], v147 offset:34816
	ds_read_b128 v[192:195], v147 offset:35840
	ds_read_b128 v[196:199], v147 offset:36864
	ds_read_b128 v[200:203], v147 offset:37888
	ds_read_b128 v[208:211], v147 offset:38912
	ds_read_b128 v[212:215], v147 offset:39936
	global_load_lds_dwordx4 v128, s[70:71]
	v_lshl_add_u64 v[218:219], s[70:71], 0, v[132:133]
	s_mov_b32 m0, s55
	s_nop 0
	global_load_lds_dwordx4 v132, s[70:71]
	s_waitcnt vmcnt(8)
	s_waitcnt lgkmcnt(0)
	s_barrier
	s_setprio 1
	s_waitcnt lgkmcnt(0)
	v_mfma_f32_16x16x32_bf16 v[64:67], v[24:27], v[180:183], v[64:67]
	v_mfma_f32_16x16x32_bf16 v[68:71], v[112:115], v[180:183], v[68:71]
	v_mfma_f32_16x16x32_bf16 v[72:75], v[24:27], v[188:191], v[72:75]
	v_mfma_f32_16x16x32_bf16 v[76:79], v[112:115], v[188:191], v[76:79]
	v_mfma_f32_16x16x32_bf16 v[80:83], v[24:27], v[196:199], v[80:83]
	v_mfma_f32_16x16x32_bf16 v[84:87], v[112:115], v[196:199], v[84:87]
	v_mfma_f32_16x16x32_bf16 v[88:91], v[24:27], v[208:211], v[88:91]
	v_mfma_f32_16x16x32_bf16 v[92:95], v[112:115], v[208:211], v[92:95]
	v_mfma_f32_16x16x32_bf16 v[64:67], v[28:31], v[184:187], v[64:67]
	v_mfma_f32_16x16x32_bf16 v[68:71], v[116:119], v[184:187], v[68:71]
	v_mfma_f32_16x16x32_bf16 v[72:75], v[28:31], v[192:195], v[72:75]
	v_mfma_f32_16x16x32_bf16 v[76:79], v[116:119], v[192:195], v[76:79]
	v_mfma_f32_16x16x32_bf16 v[80:83], v[28:31], v[200:203], v[80:83]
	v_mfma_f32_16x16x32_bf16 v[84:87], v[116:119], v[200:203], v[84:87]
	v_mfma_f32_16x16x32_bf16 v[88:91], v[28:31], v[212:215], v[88:91]
	v_mfma_f32_16x16x32_bf16 v[92:95], v[116:119], v[212:215], v[92:95]
	s_setprio 0
	s_setprio 1
	v_mfma_f32_16x16x32_bf16 v[96:99], v[120:123], v[180:183], v[96:99]
	v_mfma_f32_16x16x32_bf16 v[32:35], v[172:175], v[180:183], v[32:35]
	v_mfma_f32_16x16x32_bf16 v[36:39], v[120:123], v[188:191], v[36:39]
	v_mfma_f32_16x16x32_bf16 v[40:43], v[172:175], v[188:191], v[40:43]
	v_mfma_f32_16x16x32_bf16 v[44:47], v[120:123], v[196:199], v[44:47]
	v_mfma_f32_16x16x32_bf16 v[48:51], v[172:175], v[196:199], v[48:51]
	v_mfma_f32_16x16x32_bf16 v[52:55], v[120:123], v[208:211], v[52:55]
	v_mfma_f32_16x16x32_bf16 v[56:59], v[172:175], v[208:211], v[56:59]
	v_mfma_f32_16x16x32_bf16 v[96:99], v[124:127], v[184:187], v[96:99]
	v_mfma_f32_16x16x32_bf16 v[32:35], v[176:179], v[184:187], v[32:35]
	v_mfma_f32_16x16x32_bf16 v[36:39], v[124:127], v[192:195], v[36:39]
	v_mfma_f32_16x16x32_bf16 v[40:43], v[176:179], v[192:195], v[40:43]
	v_mfma_f32_16x16x32_bf16 v[44:47], v[124:127], v[200:203], v[44:47]
	v_mfma_f32_16x16x32_bf16 v[48:51], v[176:179], v[200:203], v[48:51]
	v_mfma_f32_16x16x32_bf16 v[52:55], v[124:127], v[212:215], v[52:55]
	v_mfma_f32_16x16x32_bf16 v[56:59], v[176:179], v[212:215], v[56:59]
	s_setprio 0
	s_barrier
; #define PG8_STAGE(bufoff, gbase, voff) do { _Pragma("unroll") for (int _i = 0; _i < 2; ++_i) \
;         __builtin_amdgcn_global_load_lds((const unsigned*)((const char*)(gbase) + (voff)[_i]), (PG8_LAS unsigned*)(lds + (bufoff) + ldsw + _i * 8192), 16, 0, 0); } while (0)
; #define PG8_LDA(dst, b, h) do { _Pragma("unroll") for (int m = 0; m < 4; ++m) _Pragma("unroll") for (int k = 0; k < 2; ++k) dst[m][k] = *(const PG8_LAS bf16x8*)(lds + PG8_SA(b, h) + aoff + m * 2048 + k * 1024); } while (0)
; #define PG8_LDB(dst, b, h) do { _Pragma("unroll") for (int n = 0; n < 2; ++n) _Pragma("unroll") for (int k = 0; k < 2; ++k) dst[n][k] = *(const PG8_LAS bf16x8*)(lds + PG8_SB(b, h) + boff + n * 2048 + k * 1024); } while (0)
; #define PG8_MMA(ai, bj, At, Bt) do { __builtin_amdgcn_s_setprio(1); _Pragma("unroll") for (int m = 0; m < 4; ++m) _Pragma("unroll") for (int n = 0; n < 2; ++n) _Pragma("unroll") for (int k = 0; k < 2; ++k) \
;         acc[ai][bj][m][n] = __builtin_amdgcn_mfma_f32_16x16x32_bf16(Bt[n][k], At[m][k], acc[ai][bj][m][n], 0, 0, 0); __builtin_amdgcn_s_setprio(0); } while (0)
; #define PG8_WAIT_V(n) asm volatile("s_waitcnt vmcnt(" #n ")" ::: "memory")
; #define PG8_WAIT_L(n) asm volatile("s_waitcnt lgkmcnt(" #n ")" ::: "memory")
; #define PG8_BAR __builtin_amdgcn_s_barrier()
; #define PG8_SCHED __builtin_amdgcn_sched_barrier(0)
; template <class Epi, class Sched, bool ALIGN_EPI = false, bool SP2 = false>
; __device__ __forceinline__ void gemm_phase(PG8_LAS unsigned char* lds, const Gemm g, const Sched& S, const Epi& E) {
;     ...
;             PG8_LDB(B0, 0, 0); PG8_LDB(B1, 0, 1); PG8_SCHED; PG8_LDA(At, 0, 0); PG8_STAGE(PG8_SA(1, 1), a1 + hstepA, voffA);
;             PG8_WAIT_V(8); PG8_WAIT_L(0); PG8_BAR; PG8_MMA(0, 0, At, B0); PG8_MMA(0, 1, At, B1); PG8_BAR; PG8_SCHED;
;     ...
;             PG8_LDA(At, 1, 1); PG8_STAGE(PG8_SB(1, 0), b3, voffB); PG8_STAGE(PG8_SB(1, 1), b3 + hstepB, voffB); PG8_STAGE(PG8_SA(1, 0), a3, voffA);
;             PG8_WAIT_V(8); PG8_WAIT_L(0); PG8_BAR; PG8_MMA(1, 0, At, B0); PG8_MMA(1, 1, At, B1); PG8_BAR; PG8_SCHED;
	s_add_i32 s79, s79, s53
	s_add_i32 s69, s79, 0x2000
	v_lshl_add_u64 v[140:141], v[140:141], 0, s[18:19]
	s_mov_b32 m0, s79
	s_add_u32 s70, s42, 0x10180
	ds_read_b128 v[180:183], v147 offset:49152
	ds_read_b128 v[184:187], v147 offset:50176
	ds_read_b128 v[188:191], v147 offset:51200
	ds_read_b128 v[192:195], v147 offset:52224
	ds_read_b128 v[196:199], v147 offset:53248
	ds_read_b128 v[200:203], v147 offset:54272
	ds_read_b128 v[208:211], v147 offset:55296
	ds_read_b128 v[212:215], v147 offset:56320
	global_load_lds_dwordx4 v[140:141], off
	v_lshl_add_u64 v[140:141], v[204:205], 0, s[18:19]
	s_mov_b32 m0, s69
	s_addc_u32 s71, s43, 0
	s_add_i32 s42, s80, s53
	global_load_lds_dwordx4 v[140:141], off
	s_mov_b32 m0, s42
	s_add_i32 s43, s42, 0x2000
	global_load_lds_dwordx4 v130, s[70:71]
	s_mov_b32 m0, s43
	s_nop 0
	global_load_lds_dwordx4 v134, s[70:71]
	v_lshl_add_u64 v[140:141], v[206:207], 0, s[18:19]
	s_mov_b32 m0, s56
	s_nop 0
	global_load_lds_dwordx4 v[140:141], off
	v_lshl_add_u64 v[140:141], v[216:217], 0, s[18:19]
	s_mov_b32 m0, s57
	s_nop 0
	global_load_lds_dwordx4 v[140:141], off
	s_waitcnt vmcnt(8)
	s_waitcnt lgkmcnt(0)
	s_barrier
	s_setprio 1
	s_waitcnt lgkmcnt(0)
	v_mfma_f32_16x16x32_bf16 v[0:3], v[24:27], v[208:211], v[0:3]
	v_mfma_f32_16x16x32_bf16 v[4:7], v[112:115], v[208:211], v[4:7]
	v_mfma_f32_16x16x32_bf16 v[148:151], v[24:27], v[180:183], v[148:151]
	v_mfma_f32_16x16x32_bf16 v[152:155], v[112:115], v[180:183], v[152:155]
	v_mfma_f32_16x16x32_bf16 v[156:159], v[24:27], v[188:191], v[156:159]
	v_mfma_f32_16x16x32_bf16 v[160:163], v[112:115], v[188:191], v[160:163]
	v_mfma_f32_16x16x32_bf16 v[164:167], v[24:27], v[196:199], v[164:167]
	v_mfma_f32_16x16x32_bf16 v[168:171], v[112:115], v[196:199], v[168:171]
	v_mfma_f32_16x16x32_bf16 v[0:3], v[28:31], v[212:215], v[0:3]
	v_mfma_f32_16x16x32_bf16 v[4:7], v[116:119], v[212:215], v[4:7]
	v_mfma_f32_16x16x32_bf16 v[148:151], v[28:31], v[184:187], v[148:151]
	v_mfma_f32_16x16x32_bf16 v[152:155], v[116:119], v[184:187], v[152:155]
	v_mfma_f32_16x16x32_bf16 v[156:159], v[28:31], v[192:195], v[156:159]
	v_mfma_f32_16x16x32_bf16 v[160:163], v[116:119], v[192:195], v[160:163]
	v_mfma_f32_16x16x32_bf16 v[164:167], v[28:31], v[200:203], v[164:167]
	v_mfma_f32_16x16x32_bf16 v[168:171], v[116:119], v[200:203], v[168:171]
	s_setprio 0
	s_setprio 1
	v_mfma_f32_16x16x32_bf16 v[8:11], v[120:123], v[180:183], v[8:11]
	v_mfma_f32_16x16x32_bf16 v[12:15], v[172:175], v[180:183], v[12:15]
	v_mfma_f32_16x16x32_bf16 v[24:27], v[120:123], v[188:191], v[60:63]
	v_mfma_f32_16x16x32_bf16 v[28:31], v[172:175], v[188:191], v[100:103]
	v_mfma_f32_16x16x32_bf16 v[60:63], v[120:123], v[196:199], v[104:107]
	v_mfma_f32_16x16x32_bf16 v[100:103], v[172:175], v[196:199], v[108:111]
	v_mfma_f32_16x16x32_bf16 v[16:19], v[120:123], v[208:211], v[16:19]
	v_mfma_f32_16x16x32_bf16 v[20:23], v[172:175], v[208:211], v[20:23]
	v_mfma_f32_16x16x32_bf16 v[8:11], v[124:127], v[184:187], v[8:11]
	v_mfma_f32_16x16x32_bf16 v[12:15], v[176:179], v[184:187], v[12:15]
	v_mfma_f32_16x16x32_bf16 v[24:27], v[124:127], v[192:195], v[24:27]
	v_mfma_f32_16x16x32_bf16 v[28:31], v[176:179], v[192:195], v[28:31]
	v_mfma_f32_16x16x32_bf16 v[60:63], v[124:127], v[200:203], v[60:63]
	v_mfma_f32_16x16x32_bf16 v[100:103], v[176:179], v[200:203], v[100:103]
	v_mfma_f32_16x16x32_bf16 v[16:19], v[124:127], v[212:215], v[16:19]
	v_mfma_f32_16x16x32_bf16 v[20:23], v[176:179], v[212:215], v[20:23]
	s_setprio 0
	s_barrier
	ds_read_b128 v[104:107], v145
	ds_read_b128 v[108:111], v145 offset:1024
	ds_read_b128 v[112:115], v145 offset:2048
	ds_read_b128 v[116:119], v145 offset:3072
	ds_read_b128 v[120:123], v146
	ds_read_b128 v[124:127], v146 offset:1024
	ds_read_b128 v[172:175], v146 offset:2048
	ds_read_b128 v[176:179], v146 offset:3072
	s_add_u32 s40, s40, 0x10180
	s_addc_u32 s41, s41, 0
	s_mov_b32 m0, s78
	ds_read_b128 v[180:183], v147
	ds_read_b128 v[184:187], v147 offset:1024
	ds_read_b128 v[188:191], v147 offset:2048
	ds_read_b128 v[192:195], v147 offset:3072
	ds_read_b128 v[196:199], v147 offset:4096
	ds_read_b128 v[200:203], v147 offset:5120
	ds_read_b128 v[208:211], v147 offset:6144
	ds_read_b128 v[212:215], v147 offset:7168
	global_load_lds_dwordx4 v128, s[40:41]
	v_lshl_add_u64 v[140:141], s[40:41], 0, v[132:133]
	s_mov_b32 m0, s29
	s_nop 0
	global_load_lds_dwordx4 v132, s[40:41]
	s_waitcnt vmcnt(8)
	s_waitcnt lgkmcnt(0)
	s_barrier
	s_setprio 1
	s_waitcnt lgkmcnt(0)
	v_mfma_f32_16x16x32_bf16 v[88:91], v[104:107], v[208:211], v[88:91]
	v_mfma_f32_16x16x32_bf16 v[64:67], v[104:107], v[180:183], v[64:67]
	v_mfma_f32_16x16x32_bf16 v[68:71], v[112:115], v[180:183], v[68:71]
	v_mfma_f32_16x16x32_bf16 v[72:75], v[104:107], v[188:191], v[72:75]
	v_mfma_f32_16x16x32_bf16 v[76:79], v[112:115], v[188:191], v[76:79]
	v_mfma_f32_16x16x32_bf16 v[80:83], v[104:107], v[196:199], v[80:83]
	v_mfma_f32_16x16x32_bf16 v[84:87], v[112:115], v[196:199], v[84:87]
	v_mfma_f32_16x16x32_bf16 v[216:219], v[108:111], v[212:215], v[88:91]
	v_mfma_f32_16x16x32_bf16 v[88:91], v[112:115], v[208:211], v[92:95]
	v_mfma_f32_16x16x32_bf16 v[64:67], v[108:111], v[184:187], v[64:67]
	v_mfma_f32_16x16x32_bf16 v[68:71], v[116:119], v[184:187], v[68:71]
	v_mfma_f32_16x16x32_bf16 v[72:75], v[108:111], v[192:195], v[72:75]
	v_mfma_f32_16x16x32_bf16 v[76:79], v[116:119], v[192:195], v[76:79]
	v_mfma_f32_16x16x32_bf16 v[80:83], v[108:111], v[200:203], v[80:83]
	v_mfma_f32_16x16x32_bf16 v[84:87], v[116:119], v[200:203], v[84:87]
	v_mfma_f32_16x16x32_bf16 v[92:95], v[116:119], v[212:215], v[88:91]
	s_setprio 0
	s_setprio 1
	v_mfma_f32_16x16x32_bf16 v[48:51], v[172:175], v[196:199], v[48:51]
	v_mfma_f32_16x16x32_bf16 v[88:91], v[120:123], v[180:183], v[96:99]
	v_mfma_f32_16x16x32_bf16 v[32:35], v[172:175], v[180:183], v[32:35]
	v_mfma_f32_16x16x32_bf16 v[36:39], v[120:123], v[188:191], v[36:39]
	v_mfma_f32_16x16x32_bf16 v[40:43], v[172:175], v[188:191], v[40:43]
	v_mfma_f32_16x16x32_bf16 v[44:47], v[120:123], v[196:199], v[44:47]
	v_mfma_f32_16x16x32_bf16 v[180:183], v[176:179], v[200:203], v[48:51]
	v_mfma_f32_16x16x32_bf16 v[48:51], v[120:123], v[208:211], v[52:55]
	v_mfma_f32_16x16x32_bf16 v[32:35], v[176:179], v[184:187], v[32:35]
	v_mfma_f32_16x16x32_bf16 v[36:39], v[124:127], v[192:195], v[36:39]
	v_mfma_f32_16x16x32_bf16 v[40:43], v[176:179], v[192:195], v[40:43]
	v_mfma_f32_16x16x32_bf16 v[44:47], v[124:127], v[200:203], v[44:47]
	v_mfma_f32_16x16x32_bf16 v[52:55], v[124:127], v[212:215], v[48:51]
	v_mfma_f32_16x16x32_bf16 v[48:51], v[172:175], v[208:211], v[56:59]
	v_mfma_f32_16x16x32_bf16 v[220:223], v[124:127], v[184:187], v[88:91]
	v_mfma_f32_16x16x32_bf16 v[184:187], v[176:179], v[212:215], v[48:51]
	s_setprio 0
	s_barrier
; #define PG8_STAGE(bufoff, gbase, voff) do { _Pragma("unroll") for (int _i = 0; _i < 2; ++_i) \
;         __builtin_amdgcn_global_load_lds((const unsigned*)((const char*)(gbase) + (voff)[_i]), (PG8_LAS unsigned*)(lds + (bufoff) + ldsw + _i * 8192), 16, 0, 0); } while (0)
; #define PG8_LDA(dst, b, h) do { _Pragma("unroll") for (int m = 0; m < 4; ++m) _Pragma("unroll") for (int k = 0; k < 2; ++k) dst[m][k] = *(const PG8_LAS bf16x8*)(lds + PG8_SA(b, h) + aoff + m * 2048 + k * 1024); } while (0)
; #define PG8_LDB(dst, b, h) do { _Pragma("unroll") for (int n = 0; n < 2; ++n) _Pragma("unroll") for (int k = 0; k < 2; ++k) dst[n][k] = *(const PG8_LAS bf16x8*)(lds + PG8_SB(b, h) + boff + n * 2048 + k * 1024); } while (0)
; #define PG8_MMA(ai, bj, At, Bt) do { __builtin_amdgcn_s_setprio(1); _Pragma("unroll") for (int m = 0; m < 4; ++m) _Pragma("unroll") for (int n = 0; n < 2; ++n) _Pragma("unroll") for (int k = 0; k < 2; ++k) \
;         acc[ai][bj][m][n] = __builtin_amdgcn_mfma_f32_16x16x32_bf16(Bt[n][k], At[m][k], acc[ai][bj][m][n], 0, 0, 0); __builtin_amdgcn_s_setprio(0); } while (0)
; #define PG8_WAIT_V(n) asm volatile("s_waitcnt vmcnt(" #n ")" ::: "memory")
; #define PG8_WAIT_L(n) asm volatile("s_waitcnt lgkmcnt(" #n ")" ::: "memory")
; #define PG8_BAR __builtin_amdgcn_s_barrier()
; #define PG8_SCHED __builtin_amdgcn_sched_barrier(0)
; template <class Epi, class Sched, bool ALIGN_EPI = false, bool SP2 = false>
; __device__ __forceinline__ void gemm_phase(PG8_LAS unsigned char* lds, const Gemm g, const Sched& S, const Epi& E) {
;     ...
;             PG8_LDA(At, 0, 1); PG8_STAGE(PG8_SB(0, 0), b2, voffB); PG8_STAGE(PG8_SB(0, 1), b2 + hstepB, voffB); PG8_STAGE(PG8_SA(0, 0), a2, voffA);
;             PG8_WAIT_V(8); PG8_WAIT_L(0); PG8_BAR; PG8_MMA(1, 0, At, B0); PG8_MMA(1, 1, At, B1); PG8_BAR; PG8_SCHED;
;             PG8_LDB(B0, 1, 0); PG8_LDB(B1, 1, 1); PG8_SCHED; PG8_LDA(At, 1, 0); PG8_STAGE(PG8_SA(0, 1), a2 + hstepA, voffA);
;             PG8_WAIT_V(8); PG8_WAIT_L(0); PG8_BAR; PG8_MMA(0, 0, At, B0); PG8_MMA(0, 1, At, B1); PG8_BAR; PG8_SCHED;
	s_mov_b32 m0, s68
	v_lshl_add_u64 v[140:141], s[44:45], 0, v[130:131]
	s_add_u32 s40, s44, 0x10000
	s_nop 0
	ds_read_b128 v[48:51], v147 offset:16384
	ds_read_b128 v[56:59], v147 offset:17408
	ds_read_b128 v[88:91], v147 offset:18432
	ds_read_b128 v[96:99], v147 offset:19456
	ds_read_b128 v[188:191], v147 offset:20480
	ds_read_b128 v[192:195], v147 offset:21504
	ds_read_b128 v[196:199], v147 offset:22528
	ds_read_b128 v[200:203], v147 offset:23552
	global_load_lds_dwordx4 v130, s[44:45]
	v_lshl_add_u64 v[252:253], s[44:45], 0, v[134:135]
	s_mov_b32 m0, s31
	s_addc_u32 s41, s45, 0
	global_load_lds_dwordx4 v134, s[44:45]
	s_mov_b32 m0, s66
	v_lshl_add_u64 v[136:137], s[46:47], 0, v[128:129]
	global_load_lds_dwordx4 v130, s[40:41]
	v_lshl_add_u64 v[204:205], s[40:41], 0, v[134:135]
	s_mov_b32 m0, s67
	v_lshl_add_u64 v[138:139], s[46:47], 0, v[132:133]
	global_load_lds_dwordx4 v134, s[40:41]
	s_mov_b32 m0, s3
	s_nop 0
	global_load_lds_dwordx4 v128, s[46:47]
	s_mov_b32 m0, s39
	s_nop 0
	global_load_lds_dwordx4 v132, s[46:47]
	s_waitcnt vmcnt(8)
	s_waitcnt lgkmcnt(0)
	s_barrier
	s_setprio 1
	s_waitcnt lgkmcnt(0)
	v_mfma_f32_16x16x32_bf16 v[0:3], v[104:107], v[196:199], v[0:3]
	v_mfma_f32_16x16x32_bf16 v[4:7], v[112:115], v[196:199], v[4:7]
	v_mfma_f32_16x16x32_bf16 v[148:151], v[104:107], v[48:51], v[148:151]
	v_mfma_f32_16x16x32_bf16 v[152:155], v[112:115], v[48:51], v[152:155]
	v_mfma_f32_16x16x32_bf16 v[156:159], v[104:107], v[88:91], v[156:159]
	v_mfma_f32_16x16x32_bf16 v[160:163], v[112:115], v[88:91], v[160:163]
	v_mfma_f32_16x16x32_bf16 v[164:167], v[104:107], v[188:191], v[164:167]
	v_mfma_f32_16x16x32_bf16 v[168:171], v[112:115], v[188:191], v[168:171]
	v_mfma_f32_16x16x32_bf16 v[0:3], v[108:111], v[200:203], v[0:3]
	v_mfma_f32_16x16x32_bf16 v[4:7], v[116:119], v[200:203], v[4:7]
	v_mfma_f32_16x16x32_bf16 v[148:151], v[108:111], v[56:59], v[148:151]
	v_mfma_f32_16x16x32_bf16 v[152:155], v[116:119], v[56:59], v[152:155]
	v_mfma_f32_16x16x32_bf16 v[156:159], v[108:111], v[96:99], v[156:159]
	v_mfma_f32_16x16x32_bf16 v[160:163], v[116:119], v[96:99], v[160:163]
	v_mfma_f32_16x16x32_bf16 v[164:167], v[108:111], v[192:195], v[164:167]
	v_mfma_f32_16x16x32_bf16 v[168:171], v[116:119], v[192:195], v[168:171]
	s_setprio 0
	s_setprio 1
	v_mfma_f32_16x16x32_bf16 v[12:15], v[172:175], v[48:51], v[12:15]
	v_mfma_f32_16x16x32_bf16 v[208:211], v[176:179], v[56:59], v[12:15]
	v_mfma_f32_16x16x32_bf16 v[12:15], v[120:123], v[88:91], v[24:27]
	v_mfma_f32_16x16x32_bf16 v[24:27], v[124:127], v[96:99], v[12:15]
	v_mfma_f32_16x16x32_bf16 v[12:15], v[172:175], v[88:91], v[28:31]
	v_mfma_f32_16x16x32_bf16 v[212:215], v[176:179], v[96:99], v[12:15]
	v_mfma_f32_16x16x32_bf16 v[12:15], v[120:123], v[188:191], v[60:63]
	v_mfma_f32_16x16x32_bf16 v[224:227], v[124:127], v[192:195], v[12:15]
	v_mfma_f32_16x16x32_bf16 v[12:15], v[172:175], v[188:191], v[100:103]
	v_mfma_f32_16x16x32_bf16 v[8:11], v[120:123], v[48:51], v[8:11]
	v_mfma_f32_16x16x32_bf16 v[188:191], v[176:179], v[192:195], v[12:15]
	v_mfma_f32_16x16x32_bf16 v[12:15], v[120:123], v[196:199], v[16:19]
	v_mfma_f32_16x16x32_bf16 v[8:11], v[124:127], v[56:59], v[8:11]
	v_mfma_f32_16x16x32_bf16 v[192:195], v[124:127], v[200:203], v[12:15]
	v_mfma_f32_16x16x32_bf16 v[12:15], v[172:175], v[196:199], v[20:23]
	v_mfma_f32_16x16x32_bf16 v[172:175], v[176:179], v[200:203], v[12:15]
	s_setprio 0
	s_barrier
	s_nop 4
	ds_read_b128 v[12:15], v228
	ds_read_b128 v[16:19], v228 offset:1024
	ds_read_b128 v[176:179], v228 offset:2048
	ds_read_b128 v[196:199], v228 offset:3072
	ds_read_b128 v[200:203], v236
	ds_read_b128 v[228:231], v236 offset:1024
	ds_read_b128 v[232:235], v236 offset:2048
	ds_read_b128 v[236:239], v236 offset:3072
	s_add_u32 s40, s46, 0x10000
	s_addc_u32 s41, s47, 0
	s_mov_b32 m0, s54
	ds_read_b128 v[20:23], v147 offset:32768
	ds_read_b128 v[28:31], v147 offset:33792
	ds_read_b128 v[60:63], v147 offset:34816
	ds_read_b128 v[100:103], v147 offset:35840
	ds_read_b128 v[240:243], v147 offset:36864
	ds_read_b128 v[244:247], v147 offset:37888
	ds_read_b128 v[248:251], v147 offset:38912
	ds_read_b128 v[204:207], v147 offset:39936
	global_load_lds_dwordx4 v128, s[40:41]
	v_lshl_add_u64 v[48:49], s[40:41], 0, v[132:133]
	s_mov_b32 m0, s55
	s_nop 0
	global_load_lds_dwordx4 v132, s[40:41]
	s_waitcnt vmcnt(8)
	s_waitcnt lgkmcnt(0)
	s_barrier
; #define PG8_STAGE(bufoff, gbase, voff) do { _Pragma("unroll") for (int _i = 0; _i < 2; ++_i) \
;         __builtin_amdgcn_global_load_lds((const unsigned*)((const char*)(gbase) + (voff)[_i]), (PG8_LAS unsigned*)(lds + (bufoff) + ldsw + _i * 8192), 16, 0, 0); } while (0)
; #define PG8_LDA(dst, b, h) do { _Pragma("unroll") for (int m = 0; m < 4; ++m) _Pragma("unroll") for (int k = 0; k < 2; ++k) dst[m][k] = *(const PG8_LAS bf16x8*)(lds + PG8_SA(b, h) + aoff + m * 2048 + k * 1024); } while (0)
; #define PG8_MMA(ai, bj, At, Bt) do { __builtin_amdgcn_s_setprio(1); _Pragma("unroll") for (int m = 0; m < 4; ++m) _Pragma("unroll") for (int n = 0; n < 2; ++n) _Pragma("unroll") for (int k = 0; k < 2; ++k) \
;         acc[ai][bj][m][n] = __builtin_amdgcn_mfma_f32_16x16x32_bf16(Bt[n][k], At[m][k], acc[ai][bj][m][n], 0, 0, 0); __builtin_amdgcn_s_setprio(0); } while (0)
; #define PG8_WAIT_V(n) asm volatile("s_waitcnt vmcnt(" #n ")" ::: "memory")
; #define PG8_WAIT_L(n) asm volatile("s_waitcnt lgkmcnt(" #n ")" ::: "memory")
; #define PG8_BAR __builtin_amdgcn_s_barrier()
; #define PG8_SCHED __builtin_amdgcn_sched_barrier(0)
; template <class Epi, class Sched, bool ALIGN_EPI = false, bool SP2 = false>
; __device__ __forceinline__ void gemm_phase(PG8_LAS unsigned char* lds, const Gemm g, const Sched& S, const Epi& E) {
;     ...
;             PG8_WAIT_V(8); PG8_WAIT_L(0); PG8_BAR; PG8_MMA(0, 0, At, B0); PG8_MMA(0, 1, At, B1); PG8_BAR; PG8_SCHED;
;             PG8_LDA(At, 1, 1); PG8_STAGE(PG8_SB(1, 0), b3, voffB); PG8_STAGE(PG8_SB(1, 1), b3 + hstepB, voffB); PG8_STAGE(PG8_SA(1, 0), a3, voffA);
;             PG8_WAIT_V(8); PG8_WAIT_L(0); PG8_BAR; PG8_MMA(1, 0, At, B0); PG8_MMA(1, 1, At, B1); PG8_BAR; PG8_SCHED;
;     ...
;         if constexpr (ALIGN_EPI) { if (wr == 0) PG8_BAR; }
	s_setprio 1
	s_waitcnt lgkmcnt(0)
	v_mfma_f32_16x16x32_bf16 v[48:51], v[12:15], v[20:23], v[64:67]
	v_mfma_f32_16x16x32_bf16 v[120:123], v[16:19], v[28:31], v[48:51]
	v_mfma_f32_16x16x32_bf16 v[48:51], v[176:179], v[20:23], v[68:71]
	v_mfma_f32_16x16x32_bf16 v[112:115], v[196:199], v[28:31], v[48:51]
	v_mfma_f32_16x16x32_bf16 v[48:51], v[12:15], v[60:63], v[72:75]
	v_mfma_f32_16x16x32_bf16 v[104:107], v[16:19], v[100:103], v[48:51]
	v_mfma_f32_16x16x32_bf16 v[48:51], v[176:179], v[60:63], v[76:79]
	v_mfma_f32_16x16x32_bf16 v[96:99], v[196:199], v[100:103], v[48:51]
	v_mfma_f32_16x16x32_bf16 v[48:51], v[12:15], v[240:243], v[80:83]
	v_mfma_f32_16x16x32_bf16 v[88:91], v[16:19], v[244:247], v[48:51]
	v_mfma_f32_16x16x32_bf16 v[48:51], v[176:179], v[240:243], v[84:87]
	v_mfma_f32_16x16x32_bf16 v[80:83], v[196:199], v[244:247], v[48:51]
	v_mfma_f32_16x16x32_bf16 v[48:51], v[12:15], v[248:251], v[216:219]
	v_mfma_f32_16x16x32_bf16 v[56:59], v[16:19], v[204:207], v[48:51]
	v_mfma_f32_16x16x32_bf16 v[48:51], v[176:179], v[248:251], v[92:95]
	v_mfma_f32_16x16x32_bf16 v[48:51], v[196:199], v[204:207], v[48:51]
	s_setprio 0
	s_setprio 1
	v_mfma_f32_16x16x32_bf16 v[64:67], v[200:203], v[20:23], v[220:223]
	v_mfma_f32_16x16x32_bf16 v[20:23], v[232:235], v[20:23], v[32:35]
	v_mfma_f32_16x16x32_bf16 v[116:119], v[236:239], v[28:31], v[20:23]
	v_mfma_f32_16x16x32_bf16 v[20:23], v[200:203], v[60:63], v[36:39]
	v_mfma_f32_16x16x32_bf16 v[108:111], v[228:231], v[100:103], v[20:23]
	v_mfma_f32_16x16x32_bf16 v[20:23], v[232:235], v[60:63], v[40:43]
	v_mfma_f32_16x16x32_bf16 v[100:103], v[236:239], v[100:103], v[20:23]
	v_mfma_f32_16x16x32_bf16 v[20:23], v[200:203], v[240:243], v[44:47]
	v_mfma_f32_16x16x32_bf16 v[92:95], v[228:231], v[244:247], v[20:23]
	v_mfma_f32_16x16x32_bf16 v[20:23], v[232:235], v[240:243], v[180:183]
	v_mfma_f32_16x16x32_bf16 v[84:87], v[236:239], v[244:247], v[20:23]
	v_mfma_f32_16x16x32_bf16 v[20:23], v[200:203], v[248:251], v[52:55]
	v_mfma_f32_16x16x32_bf16 v[60:63], v[228:231], v[204:207], v[20:23]
	v_mfma_f32_16x16x32_bf16 v[20:23], v[232:235], v[248:251], v[184:187]
	v_mfma_f32_16x16x32_bf16 v[124:127], v[228:231], v[28:31], v[64:67]
	v_mfma_f32_16x16x32_bf16 v[52:55], v[236:239], v[204:207], v[20:23]
	s_setprio 0
	s_barrier
	s_mov_b32 m0, s79
	s_nop 2
	v_lshl_add_u64 v[20:21], v[140:141], 0, s[10:11]
	s_add_u32 s40, s44, 0x10080
	ds_read_b128 v[32:35], v147 offset:49152
	ds_read_b128 v[40:43], v147 offset:50176
	ds_read_b128 v[180:183], v147 offset:51200
	ds_read_b128 v[184:187], v147 offset:52224
	ds_read_b128 v[204:207], v147 offset:53248
	ds_read_b128 v[216:219], v147 offset:54272
	ds_read_b128 v[220:223], v147 offset:55296
	ds_read_b128 v[240:243], v147 offset:56320
	global_load_lds_dwordx4 v[20:21], off
	v_lshl_add_u64 v[20:21], v[252:253], 0, s[10:11]
	s_mov_b32 m0, s69
	s_addc_u32 s41, s45, 0
	global_load_lds_dwordx4 v[20:21], off
	s_mov_b32 m0, s42
	s_nop 0
	global_load_lds_dwordx4 v130, s[40:41]
	s_mov_b32 m0, s43
	s_nop 0
	global_load_lds_dwordx4 v134, s[40:41]
	v_lshl_add_u64 v[20:21], v[136:137], 0, s[10:11]
	s_mov_b32 m0, s56
	s_nop 0
	global_load_lds_dwordx4 v[20:21], off
	v_lshl_add_u64 v[20:21], v[138:139], 0, s[10:11]
	s_mov_b32 m0, s57
	s_nop 0
	global_load_lds_dwordx4 v[20:21], off
	s_waitcnt vmcnt(8)
	s_waitcnt lgkmcnt(0)
	s_barrier
	s_setprio 1
	s_waitcnt lgkmcnt(0)
	v_mfma_f32_16x16x32_bf16 v[20:23], v[12:15], v[32:35], v[148:151]
	v_mfma_f32_16x16x32_bf16 v[76:79], v[16:19], v[40:43], v[20:23]
	v_mfma_f32_16x16x32_bf16 v[20:23], v[176:179], v[32:35], v[152:155]
	v_mfma_f32_16x16x32_bf16 v[68:71], v[196:199], v[40:43], v[20:23]
	v_mfma_f32_16x16x32_bf16 v[20:23], v[12:15], v[180:183], v[156:159]
	v_mfma_f32_16x16x32_bf16 v[44:47], v[16:19], v[184:187], v[20:23]
	v_mfma_f32_16x16x32_bf16 v[20:23], v[176:179], v[180:183], v[160:163]
	v_mfma_f32_16x16x32_bf16 v[36:39], v[196:199], v[184:187], v[20:23]
	v_mfma_f32_16x16x32_bf16 v[20:23], v[12:15], v[204:207], v[164:167]
	v_mfma_f32_16x16x32_bf16 v[0:3], v[12:15], v[220:223], v[0:3]
	v_mfma_f32_16x16x32_bf16 v[28:31], v[16:19], v[216:219], v[20:23]
	v_mfma_f32_16x16x32_bf16 v[20:23], v[176:179], v[204:207], v[168:171]
	v_mfma_f32_16x16x32_bf16 v[12:15], v[16:19], v[240:243], v[0:3]
	v_mfma_f32_16x16x32_bf16 v[0:3], v[176:179], v[220:223], v[4:7]
	v_mfma_f32_16x16x32_bf16 v[20:23], v[196:199], v[216:219], v[20:23]
	v_mfma_f32_16x16x32_bf16 v[4:7], v[196:199], v[240:243], v[0:3]
	s_setprio 0
	s_setprio 1
	v_mfma_f32_16x16x32_bf16 v[0:3], v[200:203], v[32:35], v[8:11]
	v_mfma_f32_16x16x32_bf16 v[72:75], v[228:231], v[40:43], v[0:3]
	v_mfma_f32_16x16x32_bf16 v[0:3], v[232:235], v[32:35], v[208:211]
	v_mfma_f32_16x16x32_bf16 v[64:67], v[236:239], v[40:43], v[0:3]
	v_mfma_f32_16x16x32_bf16 v[0:3], v[200:203], v[180:183], v[24:27]
	v_mfma_f32_16x16x32_bf16 v[40:43], v[228:231], v[184:187], v[0:3]
	v_mfma_f32_16x16x32_bf16 v[0:3], v[232:235], v[180:183], v[212:215]
	v_mfma_f32_16x16x32_bf16 v[32:35], v[236:239], v[184:187], v[0:3]
	v_mfma_f32_16x16x32_bf16 v[0:3], v[200:203], v[204:207], v[224:227]
	v_mfma_f32_16x16x32_bf16 v[24:27], v[228:231], v[216:219], v[0:3]
	v_mfma_f32_16x16x32_bf16 v[0:3], v[232:235], v[204:207], v[188:191]
	v_mfma_f32_16x16x32_bf16 v[16:19], v[236:239], v[216:219], v[0:3]
	v_mfma_f32_16x16x32_bf16 v[0:3], v[200:203], v[220:223], v[192:195]
	v_mfma_f32_16x16x32_bf16 v[8:11], v[228:231], v[240:243], v[0:3]
	v_mfma_f32_16x16x32_bf16 v[0:3], v[232:235], v[220:223], v[172:175]
	v_mfma_f32_16x16x32_bf16 v[0:3], v[236:239], v[240:243], v[0:3]
	s_setprio 0
	s_barrier
	s_andn2_b64 vcc, exec, s[12:13]
	s_cbranch_vccnz .LBB0_441
	s_barrier

; #define PG8_STAGE(bufoff, gbase, voff) do { _Pragma("unroll") for (int _i = 0; _i < 2; ++_i) \
;         __builtin_amdgcn_global_load_lds((const unsigned*)((const char*)(gbase) + (voff)[_i]), (PG8_LAS unsigned*)(lds + (bufoff) + ldsw + _i * 8192), 16, 0, 0); } while (0)
; #define PG8_LDA(dst, b, h) do { _Pragma("unroll") for (int m = 0; m < 4; ++m) _Pragma("unroll") for (int k = 0; k < 2; ++k) dst[m][k] = *(const PG8_LAS bf16x8*)(lds + PG8_SA(b, h) + aoff + m * 2048 + k * 1024); } while (0)
; #define PG8_LDB(dst, b, h) do { _Pragma("unroll") for (int n = 0; n < 2; ++n) _Pragma("unroll") for (int k = 0; k < 2; ++k) dst[n][k] = *(const PG8_LAS bf16x8*)(lds + PG8_SB(b, h) + boff + n * 2048 + k * 1024); } while (0)
; #define PG8_MMA(ai, bj, At, Bt) do { __builtin_amdgcn_s_setprio(1); _Pragma("unroll") for (int m = 0; m < 4; ++m) _Pragma("unroll") for (int n = 0; n < 2; ++n) _Pragma("unroll") for (int k = 0; k < 2; ++k) \
;         acc[ai][bj][m][n] = __builtin_amdgcn_mfma_f32_16x16x32_bf16(Bt[n][k], At[m][k], acc[ai][bj][m][n], 0, 0, 0); __builtin_amdgcn_s_setprio(0); } while (0)
; #define PG8_WAIT_V(n) asm volatile("s_waitcnt vmcnt(" #n ")" ::: "memory")
; #define PG8_WAIT_L(n) asm volatile("s_waitcnt lgkmcnt(" #n ")" ::: "memory")
; #define PG8_BAR __builtin_amdgcn_s_barrier()
; #define PG8_SCHED __builtin_amdgcn_sched_barrier(0)
; template <class Epi, class Sched, bool ALIGN_EPI = false, bool SP2 = false>
; __device__ __forceinline__ void gemm_phase(PG8_LAS unsigned char* lds, const Gemm g, const Sched& S, const Epi& E) {
;     ...
;             const bool last = (t == nt - 2);
;             const char* a1 = cA + PG8_AK(t + 1);
;             const char* a2 = last ? nA : cA + PG8_AK(t + 2); const char* b2 = last ? nB : cB + (size_t)(t + 2) * kstep;
;             const char* a3 = last ? nA + PG8_AK(1) : cA + PG8_AK(t + 3); const char* b3 = b2 + kstep;
;             if (last && has_next) S.a_ready(nxt);
;             if constexpr (SP2) {
;             PG8_LDB(B0, 0, 0); PG8_LDB(B1, 0, 1); PG8_SCHED; PG8_LDA(At, 0, 0); PG8_STAGE(PG8_SA(1, 1), a1 + hstepA, voffA);
;             PG8_WAIT_V(8); PG8_WAIT_L(0); PG8_BAR; PG8_MMA(0, 0, At, B0); PG8_MMA(0, 1, At, B1); PG8_BAR; PG8_SCHED;
;             PG8_LDA(At, 0, 1); PG8_STAGE(PG8_SB(0, 0), b2, voffB); PG8_STAGE(PG8_SB(0, 1), b2 + hstepB, voffB); PG8_STAGE(PG8_SA(0, 0), a2, voffA);
.LBB0_520:
	ds_read_b128 v[124:127], v210
	ds_read_b128 v[128:131], v210 offset:1024
	ds_read_b128 v[132:135], v210 offset:2048
	ds_read_b128 v[144:147], v210 offset:3072
	ds_read_b128 v[148:151], v211
	ds_read_b128 v[170:173], v211 offset:1024
	ds_read_b128 v[174:177], v211 offset:2048
	ds_read_b128 v[178:181], v211 offset:3072
	s_add_u32 s42, s38, s40
	s_addc_u32 s43, s39, s41
	s_add_u32 s46, s42, 0x100
	s_addc_u32 s47, s43, 0
	s_add_u32 s44, s79, s40
	s_addc_u32 s45, s83, s41
	s_add_u32 s42, s42, 0x180
	s_addc_u32 s43, s43, 0
	s_cmpk_eq_i32 s40, 0x1500
	s_cselect_b32 s43, s78, s43
	s_cselect_b32 s42, s3, s42
	s_cselect_b32 s45, s37, s45
	s_cselect_b32 s44, s36, s44
	s_cselect_b32 s47, s9, s47
	s_cselect_b32 s46, s8, s46
	v_lshl_add_u64 v[206:207], v[122:123], 0, s[40:41]
	s_add_i32 m0, s53, 0xc000
	ds_read_b128 v[212:215], v191
	ds_read_b128 v[216:219], v191 offset:1024
	ds_read_b128 v[220:223], v191 offset:2048
	ds_read_b128 v[224:227], v191 offset:3072
	ds_read_b128 v[228:231], v191 offset:4096
	ds_read_b128 v[232:235], v191 offset:5120
	ds_read_b128 v[236:239], v191 offset:6144
	ds_read_b128 v[240:243], v191 offset:7168
	global_load_lds_dwordx4 v[206:207], off
	v_lshl_add_u64 v[206:207], v[120:121], 0, s[40:41]
	s_add_i32 m0, s53, 0xe000
	s_nop 0
	global_load_lds_dwordx4 v[206:207], off
	s_waitcnt vmcnt(8)
	s_waitcnt lgkmcnt(0)
	s_barrier
	s_setprio 1
	s_waitcnt lgkmcnt(0)
	v_mfma_f32_16x16x32_bf16 v[140:143], v[124:127], v[212:215], v[140:143]
	v_mfma_f32_16x16x32_bf16 v[136:139], v[132:135], v[212:215], v[136:139]
	v_mfma_f32_16x16x32_bf16 v[116:119], v[124:127], v[220:223], v[116:119]
	v_mfma_f32_16x16x32_bf16 v[112:115], v[132:135], v[220:223], v[112:115]
	v_mfma_f32_16x16x32_bf16 v[108:111], v[124:127], v[228:231], v[108:111]
	v_mfma_f32_16x16x32_bf16 v[104:107], v[132:135], v[228:231], v[104:107]
	v_mfma_f32_16x16x32_bf16 v[100:103], v[124:127], v[236:239], v[100:103]
	v_mfma_f32_16x16x32_bf16 v[96:99], v[132:135], v[236:239], v[96:99]
	v_mfma_f32_16x16x32_bf16 v[140:143], v[128:131], v[216:219], v[140:143]
	v_mfma_f32_16x16x32_bf16 v[136:139], v[144:147], v[216:219], v[136:139]
	v_mfma_f32_16x16x32_bf16 v[116:119], v[128:131], v[224:227], v[116:119]
	v_mfma_f32_16x16x32_bf16 v[112:115], v[144:147], v[224:227], v[112:115]
	v_mfma_f32_16x16x32_bf16 v[108:111], v[128:131], v[232:235], v[108:111]
	v_mfma_f32_16x16x32_bf16 v[104:107], v[144:147], v[232:235], v[104:107]
	v_mfma_f32_16x16x32_bf16 v[100:103], v[128:131], v[240:243], v[100:103]
	v_mfma_f32_16x16x32_bf16 v[96:99], v[144:147], v[240:243], v[96:99]
	s_setprio 0
	s_setprio 1
	v_mfma_f32_16x16x32_bf16 v[60:63], v[148:151], v[212:215], v[60:63]
	v_mfma_f32_16x16x32_bf16 v[56:59], v[174:177], v[212:215], v[56:59]
	v_mfma_f32_16x16x32_bf16 v[52:55], v[148:151], v[220:223], v[52:55]
	v_mfma_f32_16x16x32_bf16 v[48:51], v[174:177], v[220:223], v[48:51]
	v_mfma_f32_16x16x32_bf16 v[44:47], v[148:151], v[228:231], v[44:47]
	v_mfma_f32_16x16x32_bf16 v[40:43], v[174:177], v[228:231], v[40:43]
	v_mfma_f32_16x16x32_bf16 v[36:39], v[148:151], v[236:239], v[36:39]
	v_mfma_f32_16x16x32_bf16 v[32:35], v[174:177], v[236:239], v[32:35]
	v_mfma_f32_16x16x32_bf16 v[60:63], v[170:173], v[216:219], v[60:63]
	v_mfma_f32_16x16x32_bf16 v[56:59], v[178:181], v[216:219], v[56:59]
	v_mfma_f32_16x16x32_bf16 v[52:55], v[170:173], v[224:227], v[52:55]
	v_mfma_f32_16x16x32_bf16 v[48:51], v[178:181], v[224:227], v[48:51]
	v_mfma_f32_16x16x32_bf16 v[44:47], v[170:173], v[232:235], v[44:47]
	v_mfma_f32_16x16x32_bf16 v[40:43], v[178:181], v[232:235], v[40:43]
	v_mfma_f32_16x16x32_bf16 v[36:39], v[170:173], v[240:243], v[36:39]
	v_mfma_f32_16x16x32_bf16 v[32:35], v[178:181], v[240:243], v[32:35]
	s_setprio 0
	s_barrier
	s_add_i32 s70, s67, s52
	v_lshl_add_u64 v[206:207], s[44:45], 0, v[154:155]
	s_mov_b32 m0, s70
	ds_read_b128 v[212:215], v191 offset:16384
	ds_read_b128 v[216:219], v191 offset:17408
	ds_read_b128 v[220:223], v191 offset:18432
	ds_read_b128 v[224:227], v191 offset:19456
	ds_read_b128 v[228:231], v191 offset:20480
	ds_read_b128 v[232:235], v191 offset:21504
	ds_read_b128 v[236:239], v191 offset:22528
	ds_read_b128 v[240:243], v191 offset:23552
	global_load_lds_dwordx4 v154, s[44:45]
	s_add_i32 m0, s70, 0x2000
	s_add_u32 s70, s44, 0xb0000
	v_lshl_add_u64 v[244:245], s[44:45], 0, v[158:159]
	s_addc_u32 s71, s45, 0
	s_add_i32 s85, s68, s52
	global_load_lds_dwordx4 v158, s[44:45]
	s_mov_b32 m0, s85
	s_nop 0
	global_load_lds_dwordx4 v154, s[70:71]
	s_add_i32 m0, s85, 0x2000
	s_nop 0
	global_load_lds_dwordx4 v158, s[70:71]
	s_mov_b32 m0, s53
	s_nop 0
	global_load_lds_dwordx4 v152, s[46:47]
	v_lshl_add_u64 v[246:247], s[46:47], 0, v[156:157]
	s_mov_b32 m0, s54
	s_nop 0
	global_load_lds_dwordx4 v156, s[46:47]
	s_waitcnt vmcnt(8)
	s_waitcnt lgkmcnt(0)
	s_barrier
; #define PG8_STAGE(bufoff, gbase, voff) do { _Pragma("unroll") for (int _i = 0; _i < 2; ++_i) \
;         __builtin_amdgcn_global_load_lds((const unsigned*)((const char*)(gbase) + (voff)[_i]), (PG8_LAS unsigned*)(lds + (bufoff) + ldsw + _i * 8192), 16, 0, 0); } while (0)
; #define PG8_LDA(dst, b, h) do { _Pragma("unroll") for (int m = 0; m < 4; ++m) _Pragma("unroll") for (int k = 0; k < 2; ++k) dst[m][k] = *(const PG8_LAS bf16x8*)(lds + PG8_SA(b, h) + aoff + m * 2048 + k * 1024); } while (0)
; #define PG8_LDB(dst, b, h) do { _Pragma("unroll") for (int n = 0; n < 2; ++n) _Pragma("unroll") for (int k = 0; k < 2; ++k) dst[n][k] = *(const PG8_LAS bf16x8*)(lds + PG8_SB(b, h) + boff + n * 2048 + k * 1024); } while (0)
; #define PG8_MMA(ai, bj, At, Bt) do { __builtin_amdgcn_s_setprio(1); _Pragma("unroll") for (int m = 0; m < 4; ++m) _Pragma("unroll") for (int n = 0; n < 2; ++n) _Pragma("unroll") for (int k = 0; k < 2; ++k) \
;         acc[ai][bj][m][n] = __builtin_amdgcn_mfma_f32_16x16x32_bf16(Bt[n][k], At[m][k], acc[ai][bj][m][n], 0, 0, 0); __builtin_amdgcn_s_setprio(0); } while (0)
; #define PG8_WAIT_V(n) asm volatile("s_waitcnt vmcnt(" #n ")" ::: "memory")
; #define PG8_WAIT_L(n) asm volatile("s_waitcnt lgkmcnt(" #n ")" ::: "memory")
; #define PG8_BAR __builtin_amdgcn_s_barrier()
; #define PG8_SCHED __builtin_amdgcn_sched_barrier(0)
; template <class Epi, class Sched, bool ALIGN_EPI = false, bool SP2 = false>
; __device__ __forceinline__ void gemm_phase(PG8_LAS unsigned char* lds, const Gemm g, const Sched& S, const Epi& E) {
;     ...
;             PG8_WAIT_V(8); PG8_WAIT_L(0); PG8_BAR; PG8_MMA(0, 0, At, B0); PG8_MMA(0, 1, At, B1); PG8_BAR; PG8_SCHED;
;             PG8_LDA(At, 0, 1); PG8_STAGE(PG8_SB(0, 0), b2, voffB); PG8_STAGE(PG8_SB(0, 1), b2 + hstepB, voffB); PG8_STAGE(PG8_SA(0, 0), a2, voffA);
;             PG8_WAIT_V(8); PG8_WAIT_L(0); PG8_BAR; PG8_MMA(1, 0, At, B0); PG8_MMA(1, 1, At, B1); PG8_BAR; PG8_SCHED;
;             PG8_LDB(B0, 1, 0); PG8_LDB(B1, 1, 1); PG8_SCHED; PG8_LDA(At, 1, 0); PG8_STAGE(PG8_SA(0, 1), a2 + hstepA, voffA);
;             PG8_WAIT_V(8); PG8_WAIT_L(0); PG8_BAR; PG8_MMA(0, 0, At, B0); PG8_MMA(0, 1, At, B1); PG8_BAR; PG8_SCHED;
	s_setprio 1
	s_waitcnt lgkmcnt(0)
	v_mfma_f32_16x16x32_bf16 v[92:95], v[124:127], v[212:215], v[92:95]
	v_mfma_f32_16x16x32_bf16 v[88:91], v[132:135], v[212:215], v[88:91]
	v_mfma_f32_16x16x32_bf16 v[84:87], v[124:127], v[220:223], v[84:87]
	v_mfma_f32_16x16x32_bf16 v[80:83], v[132:135], v[220:223], v[80:83]
	v_mfma_f32_16x16x32_bf16 v[76:79], v[124:127], v[228:231], v[76:79]
	v_mfma_f32_16x16x32_bf16 v[72:75], v[132:135], v[228:231], v[72:75]
	v_mfma_f32_16x16x32_bf16 v[68:71], v[124:127], v[236:239], v[68:71]
	v_mfma_f32_16x16x32_bf16 v[64:67], v[132:135], v[236:239], v[64:67]
	v_mfma_f32_16x16x32_bf16 v[92:95], v[128:131], v[216:219], v[92:95]
	v_mfma_f32_16x16x32_bf16 v[88:91], v[144:147], v[216:219], v[88:91]
	v_mfma_f32_16x16x32_bf16 v[84:87], v[128:131], v[224:227], v[84:87]
	v_mfma_f32_16x16x32_bf16 v[80:83], v[144:147], v[224:227], v[80:83]
	v_mfma_f32_16x16x32_bf16 v[76:79], v[128:131], v[232:235], v[76:79]
	v_mfma_f32_16x16x32_bf16 v[72:75], v[144:147], v[232:235], v[72:75]
	v_mfma_f32_16x16x32_bf16 v[68:71], v[128:131], v[240:243], v[68:71]
	v_mfma_f32_16x16x32_bf16 v[64:67], v[144:147], v[240:243], v[64:67]
	s_setprio 0
	s_setprio 1
	v_mfma_f32_16x16x32_bf16 v[28:31], v[148:151], v[212:215], v[28:31]
	v_mfma_f32_16x16x32_bf16 v[24:27], v[174:177], v[212:215], v[24:27]
	v_mfma_f32_16x16x32_bf16 v[20:23], v[148:151], v[220:223], v[20:23]
	v_mfma_f32_16x16x32_bf16 v[16:19], v[174:177], v[220:223], v[16:19]
	v_mfma_f32_16x16x32_bf16 v[12:15], v[148:151], v[228:231], v[12:15]
	v_mfma_f32_16x16x32_bf16 v[8:11], v[174:177], v[228:231], v[8:11]
	v_mfma_f32_16x16x32_bf16 v[4:7], v[148:151], v[236:239], v[4:7]
	v_mfma_f32_16x16x32_bf16 v[0:3], v[174:177], v[236:239], v[0:3]
	v_mfma_f32_16x16x32_bf16 v[28:31], v[170:173], v[216:219], v[28:31]
	v_mfma_f32_16x16x32_bf16 v[24:27], v[178:181], v[216:219], v[24:27]
	v_mfma_f32_16x16x32_bf16 v[20:23], v[170:173], v[224:227], v[20:23]
	v_mfma_f32_16x16x32_bf16 v[16:19], v[178:181], v[224:227], v[16:19]
	v_mfma_f32_16x16x32_bf16 v[12:15], v[170:173], v[232:235], v[12:15]
	v_mfma_f32_16x16x32_bf16 v[8:11], v[178:181], v[232:235], v[8:11]
	v_mfma_f32_16x16x32_bf16 v[4:7], v[170:173], v[240:243], v[4:7]
	v_mfma_f32_16x16x32_bf16 v[0:3], v[178:181], v[240:243], v[0:3]
	s_setprio 0
	s_barrier
	s_add_i32 s70, 0, 0x18000
	s_add_i32 s71, 0, 0x1c000
	v_add_u32_e32 v144, s70, v185
	v_add_u32_e32 v161, s71, v185
	ds_read_b128 v[124:127], v144
	ds_read_b128 v[128:131], v144 offset:1024
	ds_read_b128 v[132:135], v144 offset:2048
	ds_read_b128 v[144:147], v144 offset:3072
	ds_read_b128 v[148:151], v161
	ds_read_b128 v[170:173], v161 offset:1024
	ds_read_b128 v[174:177], v161 offset:2048
	ds_read_b128 v[178:181], v161 offset:3072
	s_add_u32 s46, s46, 0xb0000
	s_addc_u32 s47, s47, 0
	s_mov_b32 m0, s55
	ds_read_b128 v[212:215], v191 offset:32768
	ds_read_b128 v[216:219], v191 offset:33792
	ds_read_b128 v[220:223], v191 offset:34816
	ds_read_b128 v[224:227], v191 offset:35840
	ds_read_b128 v[228:231], v191 offset:36864
	ds_read_b128 v[232:235], v191 offset:37888
	ds_read_b128 v[236:239], v191 offset:38912
	ds_read_b128 v[240:243], v191 offset:39936
	global_load_lds_dwordx4 v152, s[46:47]
	v_lshl_add_u64 v[246:247], s[46:47], 0, v[156:157]
	s_mov_b32 m0, s56
	s_nop 0
	global_load_lds_dwordx4 v156, s[46:47]
	s_waitcnt vmcnt(8)
	s_waitcnt lgkmcnt(0)
	s_barrier
	s_setprio 1
	s_waitcnt lgkmcnt(0)
	v_mfma_f32_16x16x32_bf16 v[140:143], v[124:127], v[212:215], v[140:143]
	v_mfma_f32_16x16x32_bf16 v[136:139], v[132:135], v[212:215], v[136:139]
	v_mfma_f32_16x16x32_bf16 v[116:119], v[124:127], v[220:223], v[116:119]
	v_mfma_f32_16x16x32_bf16 v[112:115], v[132:135], v[220:223], v[112:115]
	v_mfma_f32_16x16x32_bf16 v[108:111], v[124:127], v[228:231], v[108:111]
	v_mfma_f32_16x16x32_bf16 v[104:107], v[132:135], v[228:231], v[104:107]
	v_mfma_f32_16x16x32_bf16 v[100:103], v[124:127], v[236:239], v[100:103]
	v_mfma_f32_16x16x32_bf16 v[96:99], v[132:135], v[236:239], v[96:99]
	v_mfma_f32_16x16x32_bf16 v[140:143], v[128:131], v[216:219], v[140:143]
	v_mfma_f32_16x16x32_bf16 v[136:139], v[144:147], v[216:219], v[136:139]
	v_mfma_f32_16x16x32_bf16 v[116:119], v[128:131], v[224:227], v[116:119]
	v_mfma_f32_16x16x32_bf16 v[112:115], v[144:147], v[224:227], v[112:115]
	v_mfma_f32_16x16x32_bf16 v[108:111], v[128:131], v[232:235], v[108:111]
	v_mfma_f32_16x16x32_bf16 v[104:107], v[144:147], v[232:235], v[104:107]
	v_mfma_f32_16x16x32_bf16 v[100:103], v[128:131], v[240:243], v[100:103]
	v_mfma_f32_16x16x32_bf16 v[96:99], v[144:147], v[240:243], v[96:99]
	s_setprio 0
	s_setprio 1
	v_mfma_f32_16x16x32_bf16 v[60:63], v[148:151], v[212:215], v[60:63]
	v_mfma_f32_16x16x32_bf16 v[56:59], v[174:177], v[212:215], v[56:59]
	v_mfma_f32_16x16x32_bf16 v[52:55], v[148:151], v[220:223], v[52:55]
	v_mfma_f32_16x16x32_bf16 v[48:51], v[174:177], v[220:223], v[48:51]
	v_mfma_f32_16x16x32_bf16 v[44:47], v[148:151], v[228:231], v[44:47]
	v_mfma_f32_16x16x32_bf16 v[40:43], v[174:177], v[228:231], v[40:43]
	v_mfma_f32_16x16x32_bf16 v[36:39], v[148:151], v[236:239], v[36:39]
	v_mfma_f32_16x16x32_bf16 v[32:35], v[174:177], v[236:239], v[32:35]
	v_mfma_f32_16x16x32_bf16 v[60:63], v[170:173], v[216:219], v[60:63]
	v_mfma_f32_16x16x32_bf16 v[56:59], v[178:181], v[216:219], v[56:59]
	v_mfma_f32_16x16x32_bf16 v[52:55], v[170:173], v[224:227], v[52:55]
	v_mfma_f32_16x16x32_bf16 v[48:51], v[178:181], v[224:227], v[48:51]
	v_mfma_f32_16x16x32_bf16 v[44:47], v[170:173], v[232:235], v[44:47]
	v_mfma_f32_16x16x32_bf16 v[40:43], v[178:181], v[232:235], v[40:43]
	v_mfma_f32_16x16x32_bf16 v[36:39], v[170:173], v[240:243], v[36:39]
	v_mfma_f32_16x16x32_bf16 v[32:35], v[178:181], v[240:243], v[32:35]
	s_setprio 0
	s_barrier
; #define PG8_STAGE(bufoff, gbase, voff) do { _Pragma("unroll") for (int _i = 0; _i < 2; ++_i) \
;         __builtin_amdgcn_global_load_lds((const unsigned*)((const char*)(gbase) + (voff)[_i]), (PG8_LAS unsigned*)(lds + (bufoff) + ldsw + _i * 8192), 16, 0, 0); } while (0)
; #define PG8_LDA(dst, b, h) do { _Pragma("unroll") for (int m = 0; m < 4; ++m) _Pragma("unroll") for (int k = 0; k < 2; ++k) dst[m][k] = *(const PG8_LAS bf16x8*)(lds + PG8_SA(b, h) + aoff + m * 2048 + k * 1024); } while (0)
; #define PG8_MMA(ai, bj, At, Bt) do { __builtin_amdgcn_s_setprio(1); _Pragma("unroll") for (int m = 0; m < 4; ++m) _Pragma("unroll") for (int n = 0; n < 2; ++n) _Pragma("unroll") for (int k = 0; k < 2; ++k) \
;         acc[ai][bj][m][n] = __builtin_amdgcn_mfma_f32_16x16x32_bf16(Bt[n][k], At[m][k], acc[ai][bj][m][n], 0, 0, 0); __builtin_amdgcn_s_setprio(0); } while (0)
; #define PG8_WAIT_V(n) asm volatile("s_waitcnt vmcnt(" #n ")" ::: "memory")
; #define PG8_WAIT_L(n) asm volatile("s_waitcnt lgkmcnt(" #n ")" ::: "memory")
; #define PG8_BAR __builtin_amdgcn_s_barrier()
; #define PG8_SCHED __builtin_amdgcn_sched_barrier(0)
; template <class Epi, class Sched, bool ALIGN_EPI = false, bool SP2 = false>
; __device__ __forceinline__ void gemm_phase(PG8_LAS unsigned char* lds, const Gemm g, const Sched& S, const Epi& E) {
;     ...
;         for (int t = 0; t < nt; t += 2) {
;     ...
;             PG8_LDA(At, 1, 1); PG8_STAGE(PG8_SB(1, 0), b3, voffB); PG8_STAGE(PG8_SB(1, 1), b3 + hstepB, voffB); PG8_STAGE(PG8_SA(1, 0), a3, voffA);
;             PG8_WAIT_V(8); PG8_WAIT_L(0); PG8_BAR; PG8_MMA(1, 0, At, B0); PG8_MMA(1, 1, At, B1); PG8_BAR; PG8_SCHED;
	s_add_i32 s46, s70, s52
	v_lshl_add_u64 v[206:207], v[206:207], 0, s[26:27]
	s_mov_b32 m0, s46
	ds_read_b128 v[212:215], v191 offset:49152
	ds_read_b128 v[216:219], v191 offset:50176
	ds_read_b128 v[220:223], v191 offset:51200
	ds_read_b128 v[224:227], v191 offset:52224
	ds_read_b128 v[228:231], v191 offset:53248
	ds_read_b128 v[232:235], v191 offset:54272
	ds_read_b128 v[236:239], v191 offset:55296
	ds_read_b128 v[240:243], v191 offset:56320
	global_load_lds_dwordx4 v[206:207], off
	s_add_i32 m0, s46, 0x2000
	s_add_u32 s44, s44, 0xb0080
	v_lshl_add_u64 v[206:207], v[244:245], 0, s[26:27]
	s_addc_u32 s45, s45, 0
	s_add_i32 s46, s71, s52
	global_load_lds_dwordx4 v[206:207], off
	s_mov_b32 m0, s46
	s_nop 0
	global_load_lds_dwordx4 v154, s[44:45]
	s_add_i32 m0, s46, 0x2000
	s_nop 0
	global_load_lds_dwordx4 v158, s[44:45]
	s_mov_b32 m0, s63
	s_nop 0
	global_load_lds_dwordx4 v152, s[42:43]
	v_lshl_add_u64 v[206:207], s[42:43], 0, v[156:157]
	s_mov_b32 m0, s64
	s_nop 0
	global_load_lds_dwordx4 v156, s[42:43]
	s_waitcnt vmcnt(8)
	s_waitcnt lgkmcnt(0)
	s_barrier
	s_setprio 1
	s_waitcnt lgkmcnt(0)
	v_mfma_f32_16x16x32_bf16 v[92:95], v[124:127], v[212:215], v[92:95]
	v_mfma_f32_16x16x32_bf16 v[88:91], v[132:135], v[212:215], v[88:91]
	v_mfma_f32_16x16x32_bf16 v[84:87], v[124:127], v[220:223], v[84:87]
	v_mfma_f32_16x16x32_bf16 v[80:83], v[132:135], v[220:223], v[80:83]
	v_mfma_f32_16x16x32_bf16 v[76:79], v[124:127], v[228:231], v[76:79]
	v_mfma_f32_16x16x32_bf16 v[72:75], v[132:135], v[228:231], v[72:75]
	v_mfma_f32_16x16x32_bf16 v[68:71], v[124:127], v[236:239], v[68:71]
	v_mfma_f32_16x16x32_bf16 v[64:67], v[132:135], v[236:239], v[64:67]
	v_mfma_f32_16x16x32_bf16 v[92:95], v[128:131], v[216:219], v[92:95]
	v_mfma_f32_16x16x32_bf16 v[88:91], v[144:147], v[216:219], v[88:91]
	v_mfma_f32_16x16x32_bf16 v[84:87], v[128:131], v[224:227], v[84:87]
	v_mfma_f32_16x16x32_bf16 v[80:83], v[144:147], v[224:227], v[80:83]
	v_mfma_f32_16x16x32_bf16 v[76:79], v[128:131], v[232:235], v[76:79]
	v_mfma_f32_16x16x32_bf16 v[72:75], v[144:147], v[232:235], v[72:75]
	v_mfma_f32_16x16x32_bf16 v[68:71], v[128:131], v[240:243], v[68:71]
	v_mfma_f32_16x16x32_bf16 v[64:67], v[144:147], v[240:243], v[64:67]
	s_setprio 0
	s_setprio 1
	v_mfma_f32_16x16x32_bf16 v[28:31], v[148:151], v[212:215], v[28:31]
	v_mfma_f32_16x16x32_bf16 v[24:27], v[174:177], v[212:215], v[24:27]
	v_mfma_f32_16x16x32_bf16 v[20:23], v[148:151], v[220:223], v[20:23]
	v_mfma_f32_16x16x32_bf16 v[16:19], v[174:177], v[220:223], v[16:19]
	v_mfma_f32_16x16x32_bf16 v[12:15], v[148:151], v[228:231], v[12:15]
	v_mfma_f32_16x16x32_bf16 v[8:11], v[174:177], v[228:231], v[8:11]
	v_mfma_f32_16x16x32_bf16 v[4:7], v[148:151], v[236:239], v[4:7]
	v_mfma_f32_16x16x32_bf16 v[0:3], v[174:177], v[236:239], v[0:3]
	v_mfma_f32_16x16x32_bf16 v[28:31], v[170:173], v[216:219], v[28:31]
	v_mfma_f32_16x16x32_bf16 v[24:27], v[178:181], v[216:219], v[24:27]
	v_mfma_f32_16x16x32_bf16 v[20:23], v[170:173], v[224:227], v[20:23]
	v_mfma_f32_16x16x32_bf16 v[16:19], v[178:181], v[224:227], v[16:19]
	v_mfma_f32_16x16x32_bf16 v[12:15], v[170:173], v[232:235], v[12:15]
	v_mfma_f32_16x16x32_bf16 v[8:11], v[178:181], v[232:235], v[8:11]
	v_mfma_f32_16x16x32_bf16 v[4:7], v[170:173], v[240:243], v[4:7]
	v_mfma_f32_16x16x32_bf16 v[0:3], v[178:181], v[240:243], v[0:3]
	s_setprio 0
	s_barrier
	s_add_i32 s84, s84, 2
	s_add_u32 s40, s40, 0x100
	s_addc_u32 s41, s41, 0
	s_cmp_gt_u32 s84, 41
	s_cbranch_scc0 .LBB0_520
	s_and_b64 vcc, exec, s[28:29]
	s_cbranch_vccz .LBB0_523
	s_barrier

; #define PG8_STAGE(bufoff, gbase, voff) do { _Pragma("unroll") for (int _i = 0; _i < 2; ++_i) \
;         __builtin_amdgcn_global_load_lds((const unsigned*)((const char*)(gbase) + (voff)[_i]), (PG8_LAS unsigned*)(lds + (bufoff) + ldsw + _i * 8192), 16, 0, 0); } while (0)
; #define PG8_LDA(dst, b, h) do { _Pragma("unroll") for (int m = 0; m < 4; ++m) _Pragma("unroll") for (int k = 0; k < 2; ++k) dst[m][k] = *(const PG8_LAS bf16x8*)(lds + PG8_SA(b, h) + aoff + m * 2048 + k * 1024); } while (0)
; #define PG8_LDB(dst, b, h) do { _Pragma("unroll") for (int n = 0; n < 2; ++n) _Pragma("unroll") for (int k = 0; k < 2; ++k) dst[n][k] = *(const PG8_LAS bf16x8*)(lds + PG8_SB(b, h) + boff + n * 2048 + k * 1024); } while (0)
; #define PG8_MMA(ai, bj, At, Bt) do { __builtin_amdgcn_s_setprio(1); _Pragma("unroll") for (int m = 0; m < 4; ++m) _Pragma("unroll") for (int n = 0; n < 2; ++n) _Pragma("unroll") for (int k = 0; k < 2; ++k) \
;         acc[ai][bj][m][n] = __builtin_amdgcn_mfma_f32_16x16x32_bf16(Bt[n][k], At[m][k], acc[ai][bj][m][n], 0, 0, 0); __builtin_amdgcn_s_setprio(0); } while (0)
; #define PG8_WAIT_V(n) asm volatile("s_waitcnt vmcnt(" #n ")" ::: "memory")
; #define PG8_WAIT_L(n) asm volatile("s_waitcnt lgkmcnt(" #n ")" ::: "memory")
; #define PG8_BAR __builtin_amdgcn_s_barrier()
; #define PG8_SCHED __builtin_amdgcn_sched_barrier(0)
; template <class Epi, class Sched, bool ALIGN_EPI = false, bool SP2 = false>
; __device__ __forceinline__ void gemm_phase(PG8_LAS unsigned char* lds, const Gemm g, const Sched& S, const Epi& E) {
;     ...
;             const bool last = (t == nt - 2);
;             const char* a1 = cA + PG8_AK(t + 1);
;             const char* a2 = last ? nA : cA + PG8_AK(t + 2); const char* b2 = last ? nB : cB + (size_t)(t + 2) * kstep;
;             const char* a3 = last ? nA + PG8_AK(1) : cA + PG8_AK(t + 3); const char* b3 = b2 + kstep;
;             if (last && has_next) S.a_ready(nxt);
;             if constexpr (SP2) {
;             PG8_LDB(B0, 0, 0); PG8_LDB(B1, 0, 1); PG8_SCHED; PG8_LDA(At, 0, 0); PG8_STAGE(PG8_SA(1, 1), a1 + hstepA, voffA);
;             PG8_WAIT_V(8); PG8_WAIT_L(0); PG8_BAR; PG8_MMA(0, 0, At, B0); PG8_MMA(0, 1, At, B1); PG8_BAR; PG8_SCHED;
;             PG8_LDA(At, 0, 1); PG8_STAGE(PG8_SB(0, 0), b2, voffB); PG8_STAGE(PG8_SB(0, 1), b2 + hstepB, voffB); PG8_STAGE(PG8_SA(0, 0), a2, voffA);
.LBB0_612:
	ds_read_b128 v[100:103], v226
	ds_read_b128 v[104:107], v226 offset:1024
	ds_read_b128 v[108:111], v226 offset:2048
	ds_read_b128 v[120:123], v226 offset:3072
	ds_read_b128 v[124:127], v227
	ds_read_b128 v[128:131], v227 offset:1024
	ds_read_b128 v[132:135], v227 offset:2048
	ds_read_b128 v[160:163], v227 offset:3072
	s_add_u32 s44, s40, s42
	s_addc_u32 s45, s41, s43
	s_add_u32 s48, s44, 0x100
	s_addc_u32 s49, s45, 0
	s_add_u32 s46, s83, s42
	s_addc_u32 s47, s84, s43
	s_add_u32 s44, s44, 0x180
	s_addc_u32 s45, s45, 0
	s_cmpk_eq_i32 s42, 0x700
	s_cselect_b32 s45, s82, s45
	s_cselect_b32 s44, s79, s44
	s_cselect_b32 s47, s29, s47
	s_cselect_b32 s46, s78, s46
	s_cselect_b32 s49, s3, s49
	s_cselect_b32 s48, s31, s48
	v_lshl_add_u64 v[236:237], v[98:99], 0, s[42:43]
	s_add_i32 m0, s57, 0xc000
	ds_read_b128 v[164:167], v209
	ds_read_b128 v[168:171], v209 offset:1024
	ds_read_b128 v[192:195], v209 offset:2048
	ds_read_b128 v[196:199], v209 offset:3072
	ds_read_b128 v[200:203], v209 offset:4096
	ds_read_b128 v[204:207], v209 offset:5120
	ds_read_b128 v[228:231], v209 offset:6144
	ds_read_b128 v[232:235], v209 offset:7168
	global_load_lds_dwordx4 v[236:237], off
	v_lshl_add_u64 v[236:237], v[96:97], 0, s[42:43]
	s_add_i32 m0, s57, 0xe000
	s_nop 0
	global_load_lds_dwordx4 v[236:237], off
	s_waitcnt vmcnt(8)
	s_waitcnt lgkmcnt(0)
	s_barrier
	s_setprio 1
	s_waitcnt lgkmcnt(0)
	v_mfma_f32_16x16x32_bf16 v[156:159], v[100:103], v[164:167], v[156:159]
	v_mfma_f32_16x16x32_bf16 v[152:155], v[108:111], v[164:167], v[152:155]
	v_mfma_f32_16x16x32_bf16 v[148:151], v[100:103], v[192:195], v[148:151]
	v_mfma_f32_16x16x32_bf16 v[144:147], v[108:111], v[192:195], v[144:147]
	v_mfma_f32_16x16x32_bf16 v[140:143], v[100:103], v[200:203], v[140:143]
	v_mfma_f32_16x16x32_bf16 v[136:139], v[108:111], v[200:203], v[136:139]
	v_mfma_f32_16x16x32_bf16 v[116:119], v[100:103], v[228:231], v[116:119]
	v_mfma_f32_16x16x32_bf16 v[112:115], v[108:111], v[228:231], v[112:115]
	v_mfma_f32_16x16x32_bf16 v[156:159], v[104:107], v[168:171], v[156:159]
	v_mfma_f32_16x16x32_bf16 v[152:155], v[120:123], v[168:171], v[152:155]
	v_mfma_f32_16x16x32_bf16 v[148:151], v[104:107], v[196:199], v[148:151]
	v_mfma_f32_16x16x32_bf16 v[144:147], v[120:123], v[196:199], v[144:147]
	v_mfma_f32_16x16x32_bf16 v[140:143], v[104:107], v[204:207], v[140:143]
	v_mfma_f32_16x16x32_bf16 v[136:139], v[120:123], v[204:207], v[136:139]
	v_mfma_f32_16x16x32_bf16 v[116:119], v[104:107], v[232:235], v[116:119]
	v_mfma_f32_16x16x32_bf16 v[112:115], v[120:123], v[232:235], v[112:115]
	s_setprio 0
	s_setprio 1
	v_mfma_f32_16x16x32_bf16 v[60:63], v[124:127], v[164:167], v[60:63]
	v_mfma_f32_16x16x32_bf16 v[56:59], v[132:135], v[164:167], v[56:59]
	v_mfma_f32_16x16x32_bf16 v[52:55], v[124:127], v[192:195], v[52:55]
	v_mfma_f32_16x16x32_bf16 v[48:51], v[132:135], v[192:195], v[48:51]
	v_mfma_f32_16x16x32_bf16 v[44:47], v[124:127], v[200:203], v[44:47]
	v_mfma_f32_16x16x32_bf16 v[40:43], v[132:135], v[200:203], v[40:43]
	v_mfma_f32_16x16x32_bf16 v[36:39], v[124:127], v[228:231], v[36:39]
	v_mfma_f32_16x16x32_bf16 v[32:35], v[132:135], v[228:231], v[32:35]
	v_mfma_f32_16x16x32_bf16 v[60:63], v[128:131], v[168:171], v[60:63]
	v_mfma_f32_16x16x32_bf16 v[56:59], v[160:163], v[168:171], v[56:59]
	v_mfma_f32_16x16x32_bf16 v[52:55], v[128:131], v[196:199], v[52:55]
	v_mfma_f32_16x16x32_bf16 v[48:51], v[160:163], v[196:199], v[48:51]
	v_mfma_f32_16x16x32_bf16 v[44:47], v[128:131], v[204:207], v[44:47]
	v_mfma_f32_16x16x32_bf16 v[40:43], v[160:163], v[204:207], v[40:43]
	v_mfma_f32_16x16x32_bf16 v[36:39], v[128:131], v[232:235], v[36:39]
	v_mfma_f32_16x16x32_bf16 v[32:35], v[160:163], v[232:235], v[32:35]
	s_setprio 0
	s_barrier
	s_add_i32 s70, s69, s56
	v_lshl_add_u64 v[236:237], s[46:47], 0, v[174:175]
	s_mov_b32 m0, s70
	ds_read_b128 v[164:167], v209 offset:16384
	ds_read_b128 v[168:171], v209 offset:17408
	ds_read_b128 v[192:195], v209 offset:18432
	ds_read_b128 v[196:199], v209 offset:19456
	ds_read_b128 v[200:203], v209 offset:20480
	ds_read_b128 v[204:207], v209 offset:21504
	ds_read_b128 v[228:231], v209 offset:22528
	ds_read_b128 v[232:235], v209 offset:23552
	global_load_lds_dwordx4 v174, s[46:47]
	s_add_i32 m0, s70, 0x2000
	s_add_u32 s70, s46, 0x40000
	v_lshl_add_u64 v[238:239], s[46:47], 0, v[178:179]
	s_addc_u32 s71, s47, 0
	s_add_i32 s86, s80, s56
	global_load_lds_dwordx4 v178, s[46:47]
	s_mov_b32 m0, s86
	s_nop 0
	global_load_lds_dwordx4 v174, s[70:71]
	s_add_i32 m0, s86, 0x2000
	s_nop 0
	global_load_lds_dwordx4 v178, s[70:71]
	s_mov_b32 m0, s57
	s_nop 0
	global_load_lds_dwordx4 v172, s[48:49]
	v_lshl_add_u64 v[240:241], s[48:49], 0, v[176:177]
	s_mov_b32 m0, s58
	s_nop 0
	global_load_lds_dwordx4 v176, s[48:49]
	s_waitcnt vmcnt(8)
	s_waitcnt lgkmcnt(0)
	s_barrier
; #define PG8_STAGE(bufoff, gbase, voff) do { _Pragma("unroll") for (int _i = 0; _i < 2; ++_i) \
;         __builtin_amdgcn_global_load_lds((const unsigned*)((const char*)(gbase) + (voff)[_i]), (PG8_LAS unsigned*)(lds + (bufoff) + ldsw + _i * 8192), 16, 0, 0); } while (0)
; #define PG8_LDA(dst, b, h) do { _Pragma("unroll") for (int m = 0; m < 4; ++m) _Pragma("unroll") for (int k = 0; k < 2; ++k) dst[m][k] = *(const PG8_LAS bf16x8*)(lds + PG8_SA(b, h) + aoff + m * 2048 + k * 1024); } while (0)
; #define PG8_LDB(dst, b, h) do { _Pragma("unroll") for (int n = 0; n < 2; ++n) _Pragma("unroll") for (int k = 0; k < 2; ++k) dst[n][k] = *(const PG8_LAS bf16x8*)(lds + PG8_SB(b, h) + boff + n * 2048 + k * 1024); } while (0)
; #define PG8_MMA(ai, bj, At, Bt) do { __builtin_amdgcn_s_setprio(1); _Pragma("unroll") for (int m = 0; m < 4; ++m) _Pragma("unroll") for (int n = 0; n < 2; ++n) _Pragma("unroll") for (int k = 0; k < 2; ++k) \
;         acc[ai][bj][m][n] = __builtin_amdgcn_mfma_f32_16x16x32_bf16(Bt[n][k], At[m][k], acc[ai][bj][m][n], 0, 0, 0); __builtin_amdgcn_s_setprio(0); } while (0)
; #define PG8_WAIT_V(n) asm volatile("s_waitcnt vmcnt(" #n ")" ::: "memory")
; #define PG8_WAIT_L(n) asm volatile("s_waitcnt lgkmcnt(" #n ")" ::: "memory")
; #define PG8_BAR __builtin_amdgcn_s_barrier()
; #define PG8_SCHED __builtin_amdgcn_sched_barrier(0)
; template <class Epi, class Sched, bool ALIGN_EPI = false, bool SP2 = false>
; __device__ __forceinline__ void gemm_phase(PG8_LAS unsigned char* lds, const Gemm g, const Sched& S, const Epi& E) {
;     ...
;             PG8_WAIT_V(8); PG8_WAIT_L(0); PG8_BAR; PG8_MMA(0, 0, At, B0); PG8_MMA(0, 1, At, B1); PG8_BAR; PG8_SCHED;
;             PG8_LDA(At, 0, 1); PG8_STAGE(PG8_SB(0, 0), b2, voffB); PG8_STAGE(PG8_SB(0, 1), b2 + hstepB, voffB); PG8_STAGE(PG8_SA(0, 0), a2, voffA);
;             PG8_WAIT_V(8); PG8_WAIT_L(0); PG8_BAR; PG8_MMA(1, 0, At, B0); PG8_MMA(1, 1, At, B1); PG8_BAR; PG8_SCHED;
;             PG8_LDB(B0, 1, 0); PG8_LDB(B1, 1, 1); PG8_SCHED; PG8_LDA(At, 1, 0); PG8_STAGE(PG8_SA(0, 1), a2 + hstepA, voffA);
;             PG8_WAIT_V(8); PG8_WAIT_L(0); PG8_BAR; PG8_MMA(0, 0, At, B0); PG8_MMA(0, 1, At, B1); PG8_BAR; PG8_SCHED;
	s_setprio 1
	s_waitcnt lgkmcnt(0)
	v_mfma_f32_16x16x32_bf16 v[92:95], v[100:103], v[164:167], v[92:95]
	v_mfma_f32_16x16x32_bf16 v[88:91], v[108:111], v[164:167], v[88:91]
	v_mfma_f32_16x16x32_bf16 v[84:87], v[100:103], v[192:195], v[84:87]
	v_mfma_f32_16x16x32_bf16 v[80:83], v[108:111], v[192:195], v[80:83]
	v_mfma_f32_16x16x32_bf16 v[76:79], v[100:103], v[200:203], v[76:79]
	v_mfma_f32_16x16x32_bf16 v[72:75], v[108:111], v[200:203], v[72:75]
	v_mfma_f32_16x16x32_bf16 v[68:71], v[100:103], v[228:231], v[68:71]
	v_mfma_f32_16x16x32_bf16 v[64:67], v[108:111], v[228:231], v[64:67]
	v_mfma_f32_16x16x32_bf16 v[92:95], v[104:107], v[168:171], v[92:95]
	v_mfma_f32_16x16x32_bf16 v[88:91], v[120:123], v[168:171], v[88:91]
	v_mfma_f32_16x16x32_bf16 v[84:87], v[104:107], v[196:199], v[84:87]
	v_mfma_f32_16x16x32_bf16 v[80:83], v[120:123], v[196:199], v[80:83]
	v_mfma_f32_16x16x32_bf16 v[76:79], v[104:107], v[204:207], v[76:79]
	v_mfma_f32_16x16x32_bf16 v[72:75], v[120:123], v[204:207], v[72:75]
	v_mfma_f32_16x16x32_bf16 v[68:71], v[104:107], v[232:235], v[68:71]
	v_mfma_f32_16x16x32_bf16 v[64:67], v[120:123], v[232:235], v[64:67]
	s_setprio 0
	s_setprio 1
	v_mfma_f32_16x16x32_bf16 v[28:31], v[124:127], v[164:167], v[28:31]
	v_mfma_f32_16x16x32_bf16 v[24:27], v[132:135], v[164:167], v[24:27]
	v_mfma_f32_16x16x32_bf16 v[20:23], v[124:127], v[192:195], v[20:23]
	v_mfma_f32_16x16x32_bf16 v[16:19], v[132:135], v[192:195], v[16:19]
	v_mfma_f32_16x16x32_bf16 v[12:15], v[124:127], v[200:203], v[12:15]
	v_mfma_f32_16x16x32_bf16 v[8:11], v[132:135], v[200:203], v[8:11]
	v_mfma_f32_16x16x32_bf16 v[4:7], v[124:127], v[228:231], v[4:7]
	v_mfma_f32_16x16x32_bf16 v[0:3], v[132:135], v[228:231], v[0:3]
	v_mfma_f32_16x16x32_bf16 v[28:31], v[128:131], v[168:171], v[28:31]
	v_mfma_f32_16x16x32_bf16 v[24:27], v[160:163], v[168:171], v[24:27]
	v_mfma_f32_16x16x32_bf16 v[20:23], v[128:131], v[196:199], v[20:23]
	v_mfma_f32_16x16x32_bf16 v[16:19], v[160:163], v[196:199], v[16:19]
	v_mfma_f32_16x16x32_bf16 v[12:15], v[128:131], v[204:207], v[12:15]
	v_mfma_f32_16x16x32_bf16 v[8:11], v[160:163], v[204:207], v[8:11]
	v_mfma_f32_16x16x32_bf16 v[4:7], v[128:131], v[232:235], v[4:7]
	v_mfma_f32_16x16x32_bf16 v[0:3], v[160:163], v[232:235], v[0:3]
	s_setprio 0
	s_barrier
	s_add_i32 s70, 0, 0x18000
	s_add_i32 s71, 0, 0x1c000
	v_add_u32_e32 v120, s70, v189
	v_add_u32_e32 v160, s71, v189
	ds_read_b128 v[100:103], v120
	ds_read_b128 v[104:107], v120 offset:1024
	ds_read_b128 v[108:111], v120 offset:2048
	ds_read_b128 v[120:123], v120 offset:3072
	ds_read_b128 v[124:127], v160
	ds_read_b128 v[128:131], v160 offset:1024
	ds_read_b128 v[132:135], v160 offset:2048
	ds_read_b128 v[160:163], v160 offset:3072
	s_add_u32 s48, s48, 0x40000
	s_addc_u32 s49, s49, 0
	s_mov_b32 m0, s59
	ds_read_b128 v[164:167], v209 offset:32768
	ds_read_b128 v[168:171], v209 offset:33792
	ds_read_b128 v[192:195], v209 offset:34816
	ds_read_b128 v[196:199], v209 offset:35840
	ds_read_b128 v[200:203], v209 offset:36864
	ds_read_b128 v[204:207], v209 offset:37888
	ds_read_b128 v[228:231], v209 offset:38912
	ds_read_b128 v[232:235], v209 offset:39936
	global_load_lds_dwordx4 v172, s[48:49]
	v_lshl_add_u64 v[240:241], s[48:49], 0, v[176:177]
	s_mov_b32 m0, s60
	s_nop 0
	global_load_lds_dwordx4 v176, s[48:49]
	s_waitcnt vmcnt(8)
	s_waitcnt lgkmcnt(0)
	s_barrier
	s_setprio 1
	s_waitcnt lgkmcnt(0)
	v_mfma_f32_16x16x32_bf16 v[156:159], v[100:103], v[164:167], v[156:159]
	v_mfma_f32_16x16x32_bf16 v[152:155], v[108:111], v[164:167], v[152:155]
	v_mfma_f32_16x16x32_bf16 v[148:151], v[100:103], v[192:195], v[148:151]
	v_mfma_f32_16x16x32_bf16 v[144:147], v[108:111], v[192:195], v[144:147]
	v_mfma_f32_16x16x32_bf16 v[140:143], v[100:103], v[200:203], v[140:143]
	v_mfma_f32_16x16x32_bf16 v[136:139], v[108:111], v[200:203], v[136:139]
	v_mfma_f32_16x16x32_bf16 v[116:119], v[100:103], v[228:231], v[116:119]
	v_mfma_f32_16x16x32_bf16 v[112:115], v[108:111], v[228:231], v[112:115]
	v_mfma_f32_16x16x32_bf16 v[156:159], v[104:107], v[168:171], v[156:159]
	v_mfma_f32_16x16x32_bf16 v[152:155], v[120:123], v[168:171], v[152:155]
	v_mfma_f32_16x16x32_bf16 v[148:151], v[104:107], v[196:199], v[148:151]
	v_mfma_f32_16x16x32_bf16 v[144:147], v[120:123], v[196:199], v[144:147]
	v_mfma_f32_16x16x32_bf16 v[140:143], v[104:107], v[204:207], v[140:143]
	v_mfma_f32_16x16x32_bf16 v[136:139], v[120:123], v[204:207], v[136:139]
	v_mfma_f32_16x16x32_bf16 v[116:119], v[104:107], v[232:235], v[116:119]
	v_mfma_f32_16x16x32_bf16 v[112:115], v[120:123], v[232:235], v[112:115]
	s_setprio 0
	s_setprio 1
	v_mfma_f32_16x16x32_bf16 v[60:63], v[124:127], v[164:167], v[60:63]
	v_mfma_f32_16x16x32_bf16 v[56:59], v[132:135], v[164:167], v[56:59]
	v_mfma_f32_16x16x32_bf16 v[52:55], v[124:127], v[192:195], v[52:55]
	v_mfma_f32_16x16x32_bf16 v[48:51], v[132:135], v[192:195], v[48:51]
	v_mfma_f32_16x16x32_bf16 v[44:47], v[124:127], v[200:203], v[44:47]
	v_mfma_f32_16x16x32_bf16 v[40:43], v[132:135], v[200:203], v[40:43]
	v_mfma_f32_16x16x32_bf16 v[36:39], v[124:127], v[228:231], v[36:39]
	v_mfma_f32_16x16x32_bf16 v[32:35], v[132:135], v[228:231], v[32:35]
	v_mfma_f32_16x16x32_bf16 v[60:63], v[128:131], v[168:171], v[60:63]
	v_mfma_f32_16x16x32_bf16 v[56:59], v[160:163], v[168:171], v[56:59]
	v_mfma_f32_16x16x32_bf16 v[52:55], v[128:131], v[196:199], v[52:55]
	v_mfma_f32_16x16x32_bf16 v[48:51], v[160:163], v[196:199], v[48:51]
	v_mfma_f32_16x16x32_bf16 v[44:47], v[128:131], v[204:207], v[44:47]
	v_mfma_f32_16x16x32_bf16 v[40:43], v[160:163], v[204:207], v[40:43]
	v_mfma_f32_16x16x32_bf16 v[36:39], v[128:131], v[232:235], v[36:39]
	v_mfma_f32_16x16x32_bf16 v[32:35], v[160:163], v[232:235], v[32:35]
	s_setprio 0
	s_barrier
; #define PG8_STAGE(bufoff, gbase, voff) do { _Pragma("unroll") for (int _i = 0; _i < 2; ++_i) \
;         __builtin_amdgcn_global_load_lds((const unsigned*)((const char*)(gbase) + (voff)[_i]), (PG8_LAS unsigned*)(lds + (bufoff) + ldsw + _i * 8192), 16, 0, 0); } while (0)
; #define PG8_LDA(dst, b, h) do { _Pragma("unroll") for (int m = 0; m < 4; ++m) _Pragma("unroll") for (int k = 0; k < 2; ++k) dst[m][k] = *(const PG8_LAS bf16x8*)(lds + PG8_SA(b, h) + aoff + m * 2048 + k * 1024); } while (0)
; #define PG8_MMA(ai, bj, At, Bt) do { __builtin_amdgcn_s_setprio(1); _Pragma("unroll") for (int m = 0; m < 4; ++m) _Pragma("unroll") for (int n = 0; n < 2; ++n) _Pragma("unroll") for (int k = 0; k < 2; ++k) \
;         acc[ai][bj][m][n] = __builtin_amdgcn_mfma_f32_16x16x32_bf16(Bt[n][k], At[m][k], acc[ai][bj][m][n], 0, 0, 0); __builtin_amdgcn_s_setprio(0); } while (0)
; #define PG8_WAIT_V(n) asm volatile("s_waitcnt vmcnt(" #n ")" ::: "memory")
; #define PG8_WAIT_L(n) asm volatile("s_waitcnt lgkmcnt(" #n ")" ::: "memory")
; #define PG8_BAR __builtin_amdgcn_s_barrier()
; #define PG8_SCHED __builtin_amdgcn_sched_barrier(0)
; template <class Epi, class Sched, bool ALIGN_EPI = false, bool SP2 = false>
; __device__ __forceinline__ void gemm_phase(PG8_LAS unsigned char* lds, const Gemm g, const Sched& S, const Epi& E) {
;     ...
;         for (int t = 0; t < nt; t += 2) {
;     ...
;             PG8_LDA(At, 1, 1); PG8_STAGE(PG8_SB(1, 0), b3, voffB); PG8_STAGE(PG8_SB(1, 1), b3 + hstepB, voffB); PG8_STAGE(PG8_SA(1, 0), a3, voffA);
;             PG8_WAIT_V(8); PG8_WAIT_L(0); PG8_BAR; PG8_MMA(1, 0, At, B0); PG8_MMA(1, 1, At, B1); PG8_BAR; PG8_SCHED;
	s_add_i32 s48, s70, s56
	v_lshl_add_u64 v[236:237], v[236:237], 0, s[10:11]
	s_mov_b32 m0, s48
	ds_read_b128 v[164:167], v209 offset:49152
	ds_read_b128 v[168:171], v209 offset:50176
	ds_read_b128 v[192:195], v209 offset:51200
	ds_read_b128 v[196:199], v209 offset:52224
	ds_read_b128 v[200:203], v209 offset:53248
	ds_read_b128 v[204:207], v209 offset:54272
	ds_read_b128 v[228:231], v209 offset:55296
	ds_read_b128 v[232:235], v209 offset:56320
	global_load_lds_dwordx4 v[236:237], off
	s_add_i32 m0, s48, 0x2000
	s_add_u32 s46, s46, 0x40080
	v_lshl_add_u64 v[236:237], v[238:239], 0, s[10:11]
	s_addc_u32 s47, s47, 0
	s_add_i32 s48, s71, s56
	global_load_lds_dwordx4 v[236:237], off
	s_mov_b32 m0, s48
	s_nop 0
	global_load_lds_dwordx4 v174, s[46:47]
	s_add_i32 m0, s48, 0x2000
	s_nop 0
	global_load_lds_dwordx4 v178, s[46:47]
	s_mov_b32 m0, s66
	s_nop 0
	global_load_lds_dwordx4 v172, s[44:45]
	v_lshl_add_u64 v[236:237], s[44:45], 0, v[176:177]
	s_mov_b32 m0, s67
	s_nop 0
	global_load_lds_dwordx4 v176, s[44:45]
	s_waitcnt vmcnt(8)
	s_waitcnt lgkmcnt(0)
	s_barrier
	s_setprio 1
	s_waitcnt lgkmcnt(0)
	v_mfma_f32_16x16x32_bf16 v[92:95], v[100:103], v[164:167], v[92:95]
	v_mfma_f32_16x16x32_bf16 v[88:91], v[108:111], v[164:167], v[88:91]
	v_mfma_f32_16x16x32_bf16 v[84:87], v[100:103], v[192:195], v[84:87]
	v_mfma_f32_16x16x32_bf16 v[80:83], v[108:111], v[192:195], v[80:83]
	v_mfma_f32_16x16x32_bf16 v[76:79], v[100:103], v[200:203], v[76:79]
	v_mfma_f32_16x16x32_bf16 v[72:75], v[108:111], v[200:203], v[72:75]
	v_mfma_f32_16x16x32_bf16 v[68:71], v[100:103], v[228:231], v[68:71]
	v_mfma_f32_16x16x32_bf16 v[64:67], v[108:111], v[228:231], v[64:67]
	v_mfma_f32_16x16x32_bf16 v[92:95], v[104:107], v[168:171], v[92:95]
	v_mfma_f32_16x16x32_bf16 v[88:91], v[120:123], v[168:171], v[88:91]
	v_mfma_f32_16x16x32_bf16 v[84:87], v[104:107], v[196:199], v[84:87]
	v_mfma_f32_16x16x32_bf16 v[80:83], v[120:123], v[196:199], v[80:83]
	v_mfma_f32_16x16x32_bf16 v[76:79], v[104:107], v[204:207], v[76:79]
	v_mfma_f32_16x16x32_bf16 v[72:75], v[120:123], v[204:207], v[72:75]
	v_mfma_f32_16x16x32_bf16 v[68:71], v[104:107], v[232:235], v[68:71]
	v_mfma_f32_16x16x32_bf16 v[64:67], v[120:123], v[232:235], v[64:67]
	s_setprio 0
	s_setprio 1
	v_mfma_f32_16x16x32_bf16 v[28:31], v[124:127], v[164:167], v[28:31]
	v_mfma_f32_16x16x32_bf16 v[24:27], v[132:135], v[164:167], v[24:27]
	v_mfma_f32_16x16x32_bf16 v[20:23], v[124:127], v[192:195], v[20:23]
	v_mfma_f32_16x16x32_bf16 v[16:19], v[132:135], v[192:195], v[16:19]
	v_mfma_f32_16x16x32_bf16 v[12:15], v[124:127], v[200:203], v[12:15]
	v_mfma_f32_16x16x32_bf16 v[8:11], v[132:135], v[200:203], v[8:11]
	v_mfma_f32_16x16x32_bf16 v[4:7], v[124:127], v[228:231], v[4:7]
	v_mfma_f32_16x16x32_bf16 v[0:3], v[132:135], v[228:231], v[0:3]
	v_mfma_f32_16x16x32_bf16 v[28:31], v[128:131], v[168:171], v[28:31]
	v_mfma_f32_16x16x32_bf16 v[24:27], v[160:163], v[168:171], v[24:27]
	v_mfma_f32_16x16x32_bf16 v[20:23], v[128:131], v[196:199], v[20:23]
	v_mfma_f32_16x16x32_bf16 v[16:19], v[160:163], v[196:199], v[16:19]
	v_mfma_f32_16x16x32_bf16 v[12:15], v[128:131], v[204:207], v[12:15]
	v_mfma_f32_16x16x32_bf16 v[8:11], v[160:163], v[204:207], v[8:11]
	v_mfma_f32_16x16x32_bf16 v[4:7], v[128:131], v[232:235], v[4:7]
	v_mfma_f32_16x16x32_bf16 v[0:3], v[160:163], v[232:235], v[0:3]
	s_setprio 0
	s_barrier
	s_add_i32 s85, s85, 2
	s_add_u32 s42, s42, 0x100
	s_addc_u32 s43, s43, 0
	s_cmp_gt_u32 s85, 13
	s_cbranch_scc0 .LBB0_612
	s_and_b64 vcc, exec, s[24:25]
	s_cbranch_vccz .LBB0_615
	s_barrier

; #define PG8_STAGE(bufoff, gbase, voff) do { _Pragma("unroll") for (int _i = 0; _i < 2; ++_i) \
;         __builtin_amdgcn_global_load_lds((const unsigned*)((const char*)(gbase) + (voff)[_i]), (PG8_LAS unsigned*)(lds + (bufoff) + ldsw + _i * 8192), 16, 0, 0); } while (0)
; #define PG8_LDA(dst, b, h) do { _Pragma("unroll") for (int m = 0; m < 4; ++m) _Pragma("unroll") for (int k = 0; k < 2; ++k) dst[m][k] = *(const PG8_LAS bf16x8*)(lds + PG8_SA(b, h) + aoff + m * 2048 + k * 1024); } while (0)
; #define PG8_LDB(dst, b, h) do { _Pragma("unroll") for (int n = 0; n < 2; ++n) _Pragma("unroll") for (int k = 0; k < 2; ++k) dst[n][k] = *(const PG8_LAS bf16x8*)(lds + PG8_SB(b, h) + boff + n * 2048 + k * 1024); } while (0)
; #define PG8_MMA(ai, bj, At, Bt) do { __builtin_amdgcn_s_setprio(1); _Pragma("unroll") for (int m = 0; m < 4; ++m) _Pragma("unroll") for (int n = 0; n < 2; ++n) _Pragma("unroll") for (int k = 0; k < 2; ++k) \
;         acc[ai][bj][m][n] = __builtin_amdgcn_mfma_f32_16x16x32_bf16(Bt[n][k], At[m][k], acc[ai][bj][m][n], 0, 0, 0); __builtin_amdgcn_s_setprio(0); } while (0)
; #define PG8_WAIT_V(n) asm volatile("s_waitcnt vmcnt(" #n ")" ::: "memory")
; #define PG8_WAIT_L(n) asm volatile("s_waitcnt lgkmcnt(" #n ")" ::: "memory")
; #define PG8_BAR __builtin_amdgcn_s_barrier()
; #define PG8_SCHED __builtin_amdgcn_sched_barrier(0)
; template <class Epi, class Sched, bool ALIGN_EPI = false, bool SP2 = false>
; __device__ __forceinline__ void gemm_phase(PG8_LAS unsigned char* lds, const Gemm g, const Sched& S, const Epi& E) {
;     ...
;             const bool last = (t == nt - 2);
;             const char* a1 = cA + PG8_AK(t + 1);
;             const char* a2 = last ? nA : cA + PG8_AK(t + 2); const char* b2 = last ? nB : cB + (size_t)(t + 2) * kstep;
;             const char* a3 = last ? nA + PG8_AK(1) : cA + PG8_AK(t + 3); const char* b3 = b2 + kstep;
;             if (last && has_next) S.a_ready(nxt);
;             if constexpr (SP2) {
;             PG8_LDB(B0, 0, 0); PG8_LDB(B1, 0, 1); PG8_SCHED; PG8_LDA(At, 0, 0); PG8_STAGE(PG8_SA(1, 1), a1 + hstepA, voffA);
;             PG8_WAIT_V(8); PG8_WAIT_L(0); PG8_BAR; PG8_MMA(0, 0, At, B0); PG8_MMA(0, 1, At, B1); PG8_BAR; PG8_SCHED;
;             PG8_LDA(At, 0, 1); PG8_STAGE(PG8_SB(0, 0), b2, voffB); PG8_STAGE(PG8_SB(0, 1), b2 + hstepB, voffB); PG8_STAGE(PG8_SA(0, 0), a2, voffA);
.LBB0_782:
	ds_read_b128 v[100:103], v167
	ds_read_b128 v[154:157], v167 offset:1024
	ds_read_b128 v[158:161], v167 offset:2048
	ds_read_b128 v[170:173], v167 offset:3072
	ds_read_b128 v[174:177], v168
	ds_read_b128 v[178:181], v168 offset:1024
	ds_read_b128 v[182:185], v168 offset:2048
	ds_read_b128 v[186:189], v168 offset:3072
	s_add_u32 s36, s6, s34
	s_addc_u32 s37, s7, s35
	s_add_u32 s40, s36, 0x100
	s_addc_u32 s41, s37, 0
	s_add_u32 s38, s62, s34
	s_addc_u32 s39, s63, s35
	s_add_u32 s36, s36, 0x180
	s_addc_u32 s37, s37, 0
	s_cmpk_eq_i32 s34, 0x700
	s_cselect_b32 s37, s61, s37
	s_cselect_b32 s36, s31, s36
	s_cselect_b32 s39, s23, s39
	s_cselect_b32 s38, s25, s38
	s_cselect_b32 s41, s3, s41
	s_cselect_b32 s40, s9, s40
	v_lshl_add_u64 v[162:163], v[98:99], 0, s[34:35]
	s_add_i32 m0, s47, 0xc000
	ds_read_b128 v[190:193], v169
	ds_read_b128 v[194:197], v169 offset:1024
	ds_read_b128 v[198:201], v169 offset:2048
	ds_read_b128 v[202:205], v169 offset:3072
	ds_read_b128 v[206:209], v169 offset:4096
	ds_read_b128 v[210:213], v169 offset:5120
	ds_read_b128 v[214:217], v169 offset:6144
	ds_read_b128 v[218:221], v169 offset:7168
	global_load_lds_dwordx4 v[162:163], off
	v_lshl_add_u64 v[162:163], v[96:97], 0, s[34:35]
	s_add_i32 m0, s47, 0xe000
	s_nop 0
	global_load_lds_dwordx4 v[162:163], off
	s_waitcnt vmcnt(8)
	s_waitcnt lgkmcnt(0)
	s_barrier
	s_setprio 1
	s_waitcnt lgkmcnt(0)
	v_mfma_f32_16x16x32_bf16 v[132:135], v[100:103], v[190:193], v[132:135]
	v_mfma_f32_16x16x32_bf16 v[128:131], v[158:161], v[190:193], v[128:131]
	v_mfma_f32_16x16x32_bf16 v[124:127], v[100:103], v[198:201], v[124:127]
	v_mfma_f32_16x16x32_bf16 v[120:123], v[158:161], v[198:201], v[120:123]
	v_mfma_f32_16x16x32_bf16 v[116:119], v[100:103], v[206:209], v[116:119]
	v_mfma_f32_16x16x32_bf16 v[112:115], v[158:161], v[206:209], v[112:115]
	v_mfma_f32_16x16x32_bf16 v[108:111], v[100:103], v[214:217], v[108:111]
	v_mfma_f32_16x16x32_bf16 v[104:107], v[158:161], v[214:217], v[104:107]
	v_mfma_f32_16x16x32_bf16 v[132:135], v[154:157], v[194:197], v[132:135]
	v_mfma_f32_16x16x32_bf16 v[128:131], v[170:173], v[194:197], v[128:131]
	v_mfma_f32_16x16x32_bf16 v[124:127], v[154:157], v[202:205], v[124:127]
	v_mfma_f32_16x16x32_bf16 v[120:123], v[170:173], v[202:205], v[120:123]
	v_mfma_f32_16x16x32_bf16 v[116:119], v[154:157], v[210:213], v[116:119]
	v_mfma_f32_16x16x32_bf16 v[112:115], v[170:173], v[210:213], v[112:115]
	v_mfma_f32_16x16x32_bf16 v[108:111], v[154:157], v[218:221], v[108:111]
	v_mfma_f32_16x16x32_bf16 v[104:107], v[170:173], v[218:221], v[104:107]
	s_setprio 0
	s_setprio 1
	v_mfma_f32_16x16x32_bf16 v[60:63], v[174:177], v[190:193], v[60:63]
	v_mfma_f32_16x16x32_bf16 v[56:59], v[182:185], v[190:193], v[56:59]
	v_mfma_f32_16x16x32_bf16 v[52:55], v[174:177], v[198:201], v[52:55]
	v_mfma_f32_16x16x32_bf16 v[48:51], v[182:185], v[198:201], v[48:51]
	v_mfma_f32_16x16x32_bf16 v[44:47], v[174:177], v[206:209], v[44:47]
	v_mfma_f32_16x16x32_bf16 v[40:43], v[182:185], v[206:209], v[40:43]
	v_mfma_f32_16x16x32_bf16 v[36:39], v[174:177], v[214:217], v[36:39]
	v_mfma_f32_16x16x32_bf16 v[32:35], v[182:185], v[214:217], v[32:35]
	v_mfma_f32_16x16x32_bf16 v[60:63], v[178:181], v[194:197], v[60:63]
	v_mfma_f32_16x16x32_bf16 v[56:59], v[186:189], v[194:197], v[56:59]
	v_mfma_f32_16x16x32_bf16 v[52:55], v[178:181], v[202:205], v[52:55]
	v_mfma_f32_16x16x32_bf16 v[48:51], v[186:189], v[202:205], v[48:51]
	v_mfma_f32_16x16x32_bf16 v[44:47], v[178:181], v[210:213], v[44:47]
	v_mfma_f32_16x16x32_bf16 v[40:43], v[186:189], v[210:213], v[40:43]
	v_mfma_f32_16x16x32_bf16 v[36:39], v[178:181], v[218:221], v[36:39]
	v_mfma_f32_16x16x32_bf16 v[32:35], v[186:189], v[218:221], v[32:35]
	s_setprio 0
	s_barrier
	s_add_i32 s65, s58, s46
	v_lshl_add_u64 v[162:163], s[38:39], 0, v[138:139]
	s_mov_b32 m0, s65
	ds_read_b128 v[190:193], v169 offset:16384
	ds_read_b128 v[194:197], v169 offset:17408
	ds_read_b128 v[198:201], v169 offset:18432
	ds_read_b128 v[202:205], v169 offset:19456
	ds_read_b128 v[206:209], v169 offset:20480
	ds_read_b128 v[210:213], v169 offset:21504
	ds_read_b128 v[214:217], v169 offset:22528
	ds_read_b128 v[218:221], v169 offset:23552
	global_load_lds_dwordx4 v138, s[38:39]
	s_add_i32 m0, s65, 0x2000
	s_add_u32 s66, s38, 0x40000
	v_lshl_add_u64 v[222:223], s[38:39], 0, v[142:143]
	s_addc_u32 s67, s39, 0
	s_add_i32 s65, s59, s46
	global_load_lds_dwordx4 v142, s[38:39]
	s_mov_b32 m0, s65
	s_nop 0
	global_load_lds_dwordx4 v138, s[66:67]
	s_add_i32 m0, s65, 0x2000
	s_nop 0
	global_load_lds_dwordx4 v142, s[66:67]
	s_mov_b32 m0, s47
	s_nop 0
	global_load_lds_dwordx4 v136, s[40:41]
	v_lshl_add_u64 v[224:225], s[40:41], 0, v[140:141]
	s_mov_b32 m0, s48
	s_nop 0
	global_load_lds_dwordx4 v140, s[40:41]
	s_waitcnt vmcnt(8)
	s_waitcnt lgkmcnt(0)
	s_barrier
; #define PG8_STAGE(bufoff, gbase, voff) do { _Pragma("unroll") for (int _i = 0; _i < 2; ++_i) \
;         __builtin_amdgcn_global_load_lds((const unsigned*)((const char*)(gbase) + (voff)[_i]), (PG8_LAS unsigned*)(lds + (bufoff) + ldsw + _i * 8192), 16, 0, 0); } while (0)
; #define PG8_LDA(dst, b, h) do { _Pragma("unroll") for (int m = 0; m < 4; ++m) _Pragma("unroll") for (int k = 0; k < 2; ++k) dst[m][k] = *(const PG8_LAS bf16x8*)(lds + PG8_SA(b, h) + aoff + m * 2048 + k * 1024); } while (0)
; #define PG8_LDB(dst, b, h) do { _Pragma("unroll") for (int n = 0; n < 2; ++n) _Pragma("unroll") for (int k = 0; k < 2; ++k) dst[n][k] = *(const PG8_LAS bf16x8*)(lds + PG8_SB(b, h) + boff + n * 2048 + k * 1024); } while (0)
; #define PG8_MMA(ai, bj, At, Bt) do { __builtin_amdgcn_s_setprio(1); _Pragma("unroll") for (int m = 0; m < 4; ++m) _Pragma("unroll") for (int n = 0; n < 2; ++n) _Pragma("unroll") for (int k = 0; k < 2; ++k) \
;         acc[ai][bj][m][n] = __builtin_amdgcn_mfma_f32_16x16x32_bf16(Bt[n][k], At[m][k], acc[ai][bj][m][n], 0, 0, 0); __builtin_amdgcn_s_setprio(0); } while (0)
; #define PG8_WAIT_V(n) asm volatile("s_waitcnt vmcnt(" #n ")" ::: "memory")
; #define PG8_WAIT_L(n) asm volatile("s_waitcnt lgkmcnt(" #n ")" ::: "memory")
; #define PG8_BAR __builtin_amdgcn_s_barrier()
; #define PG8_SCHED __builtin_amdgcn_sched_barrier(0)
; template <class Epi, class Sched, bool ALIGN_EPI = false, bool SP2 = false>
; __device__ __forceinline__ void gemm_phase(PG8_LAS unsigned char* lds, const Gemm g, const Sched& S, const Epi& E) {
;     ...
;             PG8_WAIT_V(8); PG8_WAIT_L(0); PG8_BAR; PG8_MMA(0, 0, At, B0); PG8_MMA(0, 1, At, B1); PG8_BAR; PG8_SCHED;
;             PG8_LDA(At, 0, 1); PG8_STAGE(PG8_SB(0, 0), b2, voffB); PG8_STAGE(PG8_SB(0, 1), b2 + hstepB, voffB); PG8_STAGE(PG8_SA(0, 0), a2, voffA);
;             PG8_WAIT_V(8); PG8_WAIT_L(0); PG8_BAR; PG8_MMA(1, 0, At, B0); PG8_MMA(1, 1, At, B1); PG8_BAR; PG8_SCHED;
;             PG8_LDB(B0, 1, 0); PG8_LDB(B1, 1, 1); PG8_SCHED; PG8_LDA(At, 1, 0); PG8_STAGE(PG8_SA(0, 1), a2 + hstepA, voffA);
;             PG8_WAIT_V(8); PG8_WAIT_L(0); PG8_BAR; PG8_MMA(0, 0, At, B0); PG8_MMA(0, 1, At, B1); PG8_BAR; PG8_SCHED;
	s_setprio 1
	s_waitcnt lgkmcnt(0)
	v_mfma_f32_16x16x32_bf16 v[92:95], v[100:103], v[190:193], v[92:95]
	v_mfma_f32_16x16x32_bf16 v[88:91], v[158:161], v[190:193], v[88:91]
	v_mfma_f32_16x16x32_bf16 v[84:87], v[100:103], v[198:201], v[84:87]
	v_mfma_f32_16x16x32_bf16 v[80:83], v[158:161], v[198:201], v[80:83]
	v_mfma_f32_16x16x32_bf16 v[76:79], v[100:103], v[206:209], v[76:79]
	v_mfma_f32_16x16x32_bf16 v[72:75], v[158:161], v[206:209], v[72:75]
	v_mfma_f32_16x16x32_bf16 v[68:71], v[100:103], v[214:217], v[68:71]
	v_mfma_f32_16x16x32_bf16 v[64:67], v[158:161], v[214:217], v[64:67]
	v_mfma_f32_16x16x32_bf16 v[92:95], v[154:157], v[194:197], v[92:95]
	v_mfma_f32_16x16x32_bf16 v[88:91], v[170:173], v[194:197], v[88:91]
	v_mfma_f32_16x16x32_bf16 v[84:87], v[154:157], v[202:205], v[84:87]
	v_mfma_f32_16x16x32_bf16 v[80:83], v[170:173], v[202:205], v[80:83]
	v_mfma_f32_16x16x32_bf16 v[76:79], v[154:157], v[210:213], v[76:79]
	v_mfma_f32_16x16x32_bf16 v[72:75], v[170:173], v[210:213], v[72:75]
	v_mfma_f32_16x16x32_bf16 v[68:71], v[154:157], v[218:221], v[68:71]
	v_mfma_f32_16x16x32_bf16 v[64:67], v[170:173], v[218:221], v[64:67]
	s_setprio 0
	s_setprio 1
	v_mfma_f32_16x16x32_bf16 v[28:31], v[174:177], v[190:193], v[28:31]
	v_mfma_f32_16x16x32_bf16 v[24:27], v[182:185], v[190:193], v[24:27]
	v_mfma_f32_16x16x32_bf16 v[20:23], v[174:177], v[198:201], v[20:23]
	v_mfma_f32_16x16x32_bf16 v[16:19], v[182:185], v[198:201], v[16:19]
	v_mfma_f32_16x16x32_bf16 v[12:15], v[174:177], v[206:209], v[12:15]
	v_mfma_f32_16x16x32_bf16 v[8:11], v[182:185], v[206:209], v[8:11]
	v_mfma_f32_16x16x32_bf16 v[4:7], v[174:177], v[214:217], v[4:7]
	v_mfma_f32_16x16x32_bf16 v[0:3], v[182:185], v[214:217], v[0:3]
	v_mfma_f32_16x16x32_bf16 v[28:31], v[178:181], v[194:197], v[28:31]
	v_mfma_f32_16x16x32_bf16 v[24:27], v[186:189], v[194:197], v[24:27]
	v_mfma_f32_16x16x32_bf16 v[20:23], v[178:181], v[202:205], v[20:23]
	v_mfma_f32_16x16x32_bf16 v[16:19], v[186:189], v[202:205], v[16:19]
	v_mfma_f32_16x16x32_bf16 v[12:15], v[178:181], v[210:213], v[12:15]
	v_mfma_f32_16x16x32_bf16 v[8:11], v[186:189], v[210:213], v[8:11]
	v_mfma_f32_16x16x32_bf16 v[4:7], v[178:181], v[218:221], v[4:7]
	v_mfma_f32_16x16x32_bf16 v[0:3], v[186:189], v[218:221], v[0:3]
	s_setprio 0
	s_barrier
	s_add_i32 s65, 0, 0x18000
	s_add_i32 s66, 0, 0x1c000
	v_add_u32_e32 v170, s65, v165
	v_add_u32_e32 v186, s66, v165
	ds_read_b128 v[100:103], v170
	ds_read_b128 v[154:157], v170 offset:1024
	ds_read_b128 v[158:161], v170 offset:2048
	ds_read_b128 v[170:173], v170 offset:3072
	ds_read_b128 v[174:177], v186
	ds_read_b128 v[178:181], v186 offset:1024
	ds_read_b128 v[182:185], v186 offset:2048
	ds_read_b128 v[186:189], v186 offset:3072
	s_add_u32 s40, s40, 0x40000
	s_addc_u32 s41, s41, 0
	s_mov_b32 m0, s49
	ds_read_b128 v[190:193], v169 offset:32768
	ds_read_b128 v[194:197], v169 offset:33792
	ds_read_b128 v[198:201], v169 offset:34816
	ds_read_b128 v[202:205], v169 offset:35840
	ds_read_b128 v[206:209], v169 offset:36864
	ds_read_b128 v[210:213], v169 offset:37888
	ds_read_b128 v[214:217], v169 offset:38912
	ds_read_b128 v[218:221], v169 offset:39936
	global_load_lds_dwordx4 v136, s[40:41]
	v_lshl_add_u64 v[224:225], s[40:41], 0, v[140:141]
	s_mov_b32 m0, s50
	s_nop 0
	global_load_lds_dwordx4 v140, s[40:41]
	s_waitcnt vmcnt(8)
	s_waitcnt lgkmcnt(0)
	s_barrier
	s_setprio 1
	s_waitcnt lgkmcnt(0)
	v_mfma_f32_16x16x32_bf16 v[132:135], v[100:103], v[190:193], v[132:135]
	v_mfma_f32_16x16x32_bf16 v[128:131], v[158:161], v[190:193], v[128:131]
	v_mfma_f32_16x16x32_bf16 v[124:127], v[100:103], v[198:201], v[124:127]
	v_mfma_f32_16x16x32_bf16 v[120:123], v[158:161], v[198:201], v[120:123]
	v_mfma_f32_16x16x32_bf16 v[116:119], v[100:103], v[206:209], v[116:119]
	v_mfma_f32_16x16x32_bf16 v[112:115], v[158:161], v[206:209], v[112:115]
	v_mfma_f32_16x16x32_bf16 v[108:111], v[100:103], v[214:217], v[108:111]
	v_mfma_f32_16x16x32_bf16 v[104:107], v[158:161], v[214:217], v[104:107]
	v_mfma_f32_16x16x32_bf16 v[132:135], v[154:157], v[194:197], v[132:135]
	v_mfma_f32_16x16x32_bf16 v[128:131], v[170:173], v[194:197], v[128:131]
	v_mfma_f32_16x16x32_bf16 v[124:127], v[154:157], v[202:205], v[124:127]
	v_mfma_f32_16x16x32_bf16 v[120:123], v[170:173], v[202:205], v[120:123]
	v_mfma_f32_16x16x32_bf16 v[116:119], v[154:157], v[210:213], v[116:119]
	v_mfma_f32_16x16x32_bf16 v[112:115], v[170:173], v[210:213], v[112:115]
	v_mfma_f32_16x16x32_bf16 v[108:111], v[154:157], v[218:221], v[108:111]
	v_mfma_f32_16x16x32_bf16 v[104:107], v[170:173], v[218:221], v[104:107]
	s_setprio 0
	s_setprio 1
	v_mfma_f32_16x16x32_bf16 v[60:63], v[174:177], v[190:193], v[60:63]
	v_mfma_f32_16x16x32_bf16 v[56:59], v[182:185], v[190:193], v[56:59]
	v_mfma_f32_16x16x32_bf16 v[52:55], v[174:177], v[198:201], v[52:55]
	v_mfma_f32_16x16x32_bf16 v[48:51], v[182:185], v[198:201], v[48:51]
	v_mfma_f32_16x16x32_bf16 v[44:47], v[174:177], v[206:209], v[44:47]
	v_mfma_f32_16x16x32_bf16 v[40:43], v[182:185], v[206:209], v[40:43]
	v_mfma_f32_16x16x32_bf16 v[36:39], v[174:177], v[214:217], v[36:39]
	v_mfma_f32_16x16x32_bf16 v[32:35], v[182:185], v[214:217], v[32:35]
	v_mfma_f32_16x16x32_bf16 v[60:63], v[178:181], v[194:197], v[60:63]
	v_mfma_f32_16x16x32_bf16 v[56:59], v[186:189], v[194:197], v[56:59]
	v_mfma_f32_16x16x32_bf16 v[52:55], v[178:181], v[202:205], v[52:55]
	v_mfma_f32_16x16x32_bf16 v[48:51], v[186:189], v[202:205], v[48:51]
	v_mfma_f32_16x16x32_bf16 v[44:47], v[178:181], v[210:213], v[44:47]
	v_mfma_f32_16x16x32_bf16 v[40:43], v[186:189], v[210:213], v[40:43]
	v_mfma_f32_16x16x32_bf16 v[36:39], v[178:181], v[218:221], v[36:39]
	v_mfma_f32_16x16x32_bf16 v[32:35], v[186:189], v[218:221], v[32:35]
	s_setprio 0
	s_barrier
; #define PG8_STAGE(bufoff, gbase, voff) do { _Pragma("unroll") for (int _i = 0; _i < 2; ++_i) \
;         __builtin_amdgcn_global_load_lds((const unsigned*)((const char*)(gbase) + (voff)[_i]), (PG8_LAS unsigned*)(lds + (bufoff) + ldsw + _i * 8192), 16, 0, 0); } while (0)
; #define PG8_LDA(dst, b, h) do { _Pragma("unroll") for (int m = 0; m < 4; ++m) _Pragma("unroll") for (int k = 0; k < 2; ++k) dst[m][k] = *(const PG8_LAS bf16x8*)(lds + PG8_SA(b, h) + aoff + m * 2048 + k * 1024); } while (0)
; #define PG8_MMA(ai, bj, At, Bt) do { __builtin_amdgcn_s_setprio(1); _Pragma("unroll") for (int m = 0; m < 4; ++m) _Pragma("unroll") for (int n = 0; n < 2; ++n) _Pragma("unroll") for (int k = 0; k < 2; ++k) \
;         acc[ai][bj][m][n] = __builtin_amdgcn_mfma_f32_16x16x32_bf16(Bt[n][k], At[m][k], acc[ai][bj][m][n], 0, 0, 0); __builtin_amdgcn_s_setprio(0); } while (0)
; #define PG8_WAIT_V(n) asm volatile("s_waitcnt vmcnt(" #n ")" ::: "memory")
; #define PG8_WAIT_L(n) asm volatile("s_waitcnt lgkmcnt(" #n ")" ::: "memory")
; #define PG8_BAR __builtin_amdgcn_s_barrier()
; #define PG8_SCHED __builtin_amdgcn_sched_barrier(0)
; template <class Epi, class Sched, bool ALIGN_EPI = false, bool SP2 = false>
; __device__ __forceinline__ void gemm_phase(PG8_LAS unsigned char* lds, const Gemm g, const Sched& S, const Epi& E) {
;     ...
;         for (int t = 0; t < nt; t += 2) {
;     ...
;             PG8_LDA(At, 1, 1); PG8_STAGE(PG8_SB(1, 0), b3, voffB); PG8_STAGE(PG8_SB(1, 1), b3 + hstepB, voffB); PG8_STAGE(PG8_SA(1, 0), a3, voffA);
;             PG8_WAIT_V(8); PG8_WAIT_L(0); PG8_BAR; PG8_MMA(1, 0, At, B0); PG8_MMA(1, 1, At, B1); PG8_BAR; PG8_SCHED;
	s_add_i32 s40, s65, s46
	v_lshl_add_u64 v[162:163], v[162:163], 0, s[18:19]
	s_mov_b32 m0, s40
	ds_read_b128 v[190:193], v169 offset:49152
	ds_read_b128 v[194:197], v169 offset:50176
	ds_read_b128 v[198:201], v169 offset:51200
	ds_read_b128 v[202:205], v169 offset:52224
	ds_read_b128 v[206:209], v169 offset:53248
	ds_read_b128 v[210:213], v169 offset:54272
	ds_read_b128 v[214:217], v169 offset:55296
	ds_read_b128 v[218:221], v169 offset:56320
	global_load_lds_dwordx4 v[162:163], off
	s_add_i32 m0, s40, 0x2000
	s_add_u32 s38, s38, 0x40080
	v_lshl_add_u64 v[162:163], v[222:223], 0, s[18:19]
	s_addc_u32 s39, s39, 0
	s_add_i32 s40, s66, s46
	global_load_lds_dwordx4 v[162:163], off
	s_mov_b32 m0, s40
	s_nop 0
	global_load_lds_dwordx4 v138, s[38:39]
	s_add_i32 m0, s40, 0x2000
	s_nop 0
	global_load_lds_dwordx4 v142, s[38:39]
	s_mov_b32 m0, s53
	s_nop 0
	global_load_lds_dwordx4 v136, s[36:37]
	v_lshl_add_u64 v[162:163], s[36:37], 0, v[140:141]
	s_mov_b32 m0, s54
	s_nop 0
	global_load_lds_dwordx4 v140, s[36:37]
	s_waitcnt vmcnt(8)
	s_waitcnt lgkmcnt(0)
	s_barrier
	s_setprio 1
	s_waitcnt lgkmcnt(0)
	v_mfma_f32_16x16x32_bf16 v[92:95], v[100:103], v[190:193], v[92:95]
	v_mfma_f32_16x16x32_bf16 v[88:91], v[158:161], v[190:193], v[88:91]
	v_mfma_f32_16x16x32_bf16 v[84:87], v[100:103], v[198:201], v[84:87]
	v_mfma_f32_16x16x32_bf16 v[80:83], v[158:161], v[198:201], v[80:83]
	v_mfma_f32_16x16x32_bf16 v[76:79], v[100:103], v[206:209], v[76:79]
	v_mfma_f32_16x16x32_bf16 v[72:75], v[158:161], v[206:209], v[72:75]
	v_mfma_f32_16x16x32_bf16 v[68:71], v[100:103], v[214:217], v[68:71]
	v_mfma_f32_16x16x32_bf16 v[64:67], v[158:161], v[214:217], v[64:67]
	v_mfma_f32_16x16x32_bf16 v[92:95], v[154:157], v[194:197], v[92:95]
	v_mfma_f32_16x16x32_bf16 v[88:91], v[170:173], v[194:197], v[88:91]
	v_mfma_f32_16x16x32_bf16 v[84:87], v[154:157], v[202:205], v[84:87]
	v_mfma_f32_16x16x32_bf16 v[80:83], v[170:173], v[202:205], v[80:83]
	v_mfma_f32_16x16x32_bf16 v[76:79], v[154:157], v[210:213], v[76:79]
	v_mfma_f32_16x16x32_bf16 v[72:75], v[170:173], v[210:213], v[72:75]
	v_mfma_f32_16x16x32_bf16 v[68:71], v[154:157], v[218:221], v[68:71]
	v_mfma_f32_16x16x32_bf16 v[64:67], v[170:173], v[218:221], v[64:67]
	s_setprio 0
	s_setprio 1
	v_mfma_f32_16x16x32_bf16 v[28:31], v[174:177], v[190:193], v[28:31]
	v_mfma_f32_16x16x32_bf16 v[24:27], v[182:185], v[190:193], v[24:27]
	v_mfma_f32_16x16x32_bf16 v[20:23], v[174:177], v[198:201], v[20:23]
	v_mfma_f32_16x16x32_bf16 v[16:19], v[182:185], v[198:201], v[16:19]
	v_mfma_f32_16x16x32_bf16 v[12:15], v[174:177], v[206:209], v[12:15]
	v_mfma_f32_16x16x32_bf16 v[8:11], v[182:185], v[206:209], v[8:11]
	v_mfma_f32_16x16x32_bf16 v[4:7], v[174:177], v[214:217], v[4:7]
	v_mfma_f32_16x16x32_bf16 v[0:3], v[182:185], v[214:217], v[0:3]
	v_mfma_f32_16x16x32_bf16 v[28:31], v[178:181], v[194:197], v[28:31]
	v_mfma_f32_16x16x32_bf16 v[24:27], v[186:189], v[194:197], v[24:27]
	v_mfma_f32_16x16x32_bf16 v[20:23], v[178:181], v[202:205], v[20:23]
	v_mfma_f32_16x16x32_bf16 v[16:19], v[186:189], v[202:205], v[16:19]
	v_mfma_f32_16x16x32_bf16 v[12:15], v[178:181], v[210:213], v[12:15]
	v_mfma_f32_16x16x32_bf16 v[8:11], v[186:189], v[210:213], v[8:11]
	v_mfma_f32_16x16x32_bf16 v[4:7], v[178:181], v[218:221], v[4:7]
	v_mfma_f32_16x16x32_bf16 v[0:3], v[186:189], v[218:221], v[0:3]
	s_setprio 0
	s_barrier
	s_add_i32 s64, s64, 2
	s_add_u32 s34, s34, 0x100
	s_addc_u32 s35, s35, 0
	s_cmp_gt_u32 s64, 13
	s_cbranch_scc0 .LBB0_782
	s_and_b64 vcc, exec, s[20:21]
	s_cbranch_vccz .LBB0_785
	s_barrier

; #define PG8_STAGE(bufoff, gbase, voff) do { _Pragma("unroll") for (int _i = 0; _i < 2; ++_i) \
;         __builtin_amdgcn_global_load_lds((const unsigned*)((const char*)(gbase) + (voff)[_i]), (PG8_LAS unsigned*)(lds + (bufoff) + ldsw + _i * 8192), 16, 0, 0); } while (0)
; #define PG8_LDA(dst, b, h) do { _Pragma("unroll") for (int m = 0; m < 4; ++m) _Pragma("unroll") for (int k = 0; k < 2; ++k) dst[m][k] = *(const PG8_LAS bf16x8*)(lds + PG8_SA(b, h) + aoff + m * 2048 + k * 1024); } while (0)
; #define PG8_LDB(dst, b, h) do { _Pragma("unroll") for (int n = 0; n < 2; ++n) _Pragma("unroll") for (int k = 0; k < 2; ++k) dst[n][k] = *(const PG8_LAS bf16x8*)(lds + PG8_SB(b, h) + boff + n * 2048 + k * 1024); } while (0)
; #define PG8_MMA(ai, bj, At, Bt) do { __builtin_amdgcn_s_setprio(1); _Pragma("unroll") for (int m = 0; m < 4; ++m) _Pragma("unroll") for (int n = 0; n < 2; ++n) _Pragma("unroll") for (int k = 0; k < 2; ++k) \
;         acc[ai][bj][m][n] = __builtin_amdgcn_mfma_f32_16x16x32_bf16(Bt[n][k], At[m][k], acc[ai][bj][m][n], 0, 0, 0); __builtin_amdgcn_s_setprio(0); } while (0)
; #define PG8_WAIT_V(n) asm volatile("s_waitcnt vmcnt(" #n ")" ::: "memory")
; #define PG8_WAIT_L(n) asm volatile("s_waitcnt lgkmcnt(" #n ")" ::: "memory")
; #define PG8_BAR __builtin_amdgcn_s_barrier()
; #define PG8_SCHED __builtin_amdgcn_sched_barrier(0)
; template <class Epi, class Sched, bool ALIGN_EPI = false, bool SP2 = false>
; __device__ __forceinline__ void gemm_phase(PG8_LAS unsigned char* lds, const Gemm g, const Sched& S, const Epi& E) {
;     ...
;             const bool last = (t == nt - 2);
;             const char* a1 = cA + PG8_AK(t + 1);
;             const char* a2 = last ? nA : cA + PG8_AK(t + 2); const char* b2 = last ? nB : cB + (size_t)(t + 2) * kstep;
;             const char* a3 = last ? nA + PG8_AK(1) : cA + PG8_AK(t + 3); const char* b3 = b2 + kstep;
;             if (last && has_next) S.a_ready(nxt);
;             if constexpr (SP2) {
;             PG8_LDB(B0, 0, 0); PG8_LDB(B1, 0, 1); PG8_SCHED; PG8_LDA(At, 0, 0); PG8_STAGE(PG8_SA(1, 1), a1 + hstepA, voffA);
;             PG8_WAIT_V(8); PG8_WAIT_L(0); PG8_BAR; PG8_MMA(0, 0, At, B0); PG8_MMA(0, 1, At, B1); PG8_BAR; PG8_SCHED;
;             PG8_LDA(At, 0, 1); PG8_STAGE(PG8_SB(0, 0), b2, voffB); PG8_STAGE(PG8_SB(0, 1), b2 + hstepB, voffB); PG8_STAGE(PG8_SA(0, 0), a2, voffA);
.LBB0_1191:
	ds_read_b128 v[128:131], v191
	ds_read_b128 v[132:135], v191 offset:1024
	ds_read_b128 v[136:139], v191 offset:2048
	ds_read_b128 v[140:143], v191 offset:3072
	ds_read_b128 v[162:165], v192
	ds_read_b128 v[166:169], v192 offset:1024
	ds_read_b128 v[194:197], v192 offset:2048
	ds_read_b128 v[198:201], v192 offset:3072
	s_add_u32 s38, s36, 0x800000
	s_addc_u32 s39, s37, 0
	s_cmp_eq_u32 s67, 12
	s_cselect_b32 s43, s3, s39
	s_cselect_b32 s42, s27, s38
	s_cselect_b32 s41, s25, s66
	s_cselect_b32 s40, s35, s65
	s_add_i32 m0, s50, 0xc000
	ds_read_b128 v[202:205], v174
	ds_read_b128 v[206:209], v174 offset:1024
	ds_read_b128 v[210:213], v174 offset:2048
	ds_read_b128 v[214:217], v174 offset:3072
	ds_read_b128 v[218:221], v174 offset:4096
	ds_read_b128 v[222:225], v174 offset:5120
	ds_read_b128 v[226:229], v174 offset:6144
	ds_read_b128 v[230:233], v174 offset:7168
	global_load_lds_dwordx4 v156, s[36:37]
	v_lshl_add_u64 v[170:171], s[36:37], 0, v[154:155]
	s_add_i32 m0, s50, 0xe000
	s_nop 0
	global_load_lds_dwordx4 v154, s[36:37]
	s_waitcnt vmcnt(8)
	s_waitcnt lgkmcnt(0)
	s_barrier
	s_setprio 1
	s_waitcnt lgkmcnt(0)
	v_mfma_f32_16x16x32_bf16 v[124:127], v[128:131], v[202:205], v[124:127]
	v_mfma_f32_16x16x32_bf16 v[120:123], v[136:139], v[202:205], v[120:123]
	v_mfma_f32_16x16x32_bf16 v[116:119], v[128:131], v[210:213], v[116:119]
	v_mfma_f32_16x16x32_bf16 v[112:115], v[136:139], v[210:213], v[112:115]
	v_mfma_f32_16x16x32_bf16 v[108:111], v[128:131], v[218:221], v[108:111]
	v_mfma_f32_16x16x32_bf16 v[104:107], v[136:139], v[218:221], v[104:107]
	v_mfma_f32_16x16x32_bf16 v[100:103], v[128:131], v[226:229], v[100:103]
	v_mfma_f32_16x16x32_bf16 v[96:99], v[136:139], v[226:229], v[96:99]
	v_mfma_f32_16x16x32_bf16 v[124:127], v[132:135], v[206:209], v[124:127]
	v_mfma_f32_16x16x32_bf16 v[120:123], v[140:143], v[206:209], v[120:123]
	v_mfma_f32_16x16x32_bf16 v[116:119], v[132:135], v[214:217], v[116:119]
	v_mfma_f32_16x16x32_bf16 v[112:115], v[140:143], v[214:217], v[112:115]
	v_mfma_f32_16x16x32_bf16 v[108:111], v[132:135], v[222:225], v[108:111]
	v_mfma_f32_16x16x32_bf16 v[104:107], v[140:143], v[222:225], v[104:107]
	v_mfma_f32_16x16x32_bf16 v[100:103], v[132:135], v[230:233], v[100:103]
	v_mfma_f32_16x16x32_bf16 v[96:99], v[140:143], v[230:233], v[96:99]
	s_setprio 0
	s_setprio 1
	v_mfma_f32_16x16x32_bf16 v[60:63], v[162:165], v[202:205], v[60:63]
	v_mfma_f32_16x16x32_bf16 v[56:59], v[194:197], v[202:205], v[56:59]
	v_mfma_f32_16x16x32_bf16 v[52:55], v[162:165], v[210:213], v[52:55]
	v_mfma_f32_16x16x32_bf16 v[48:51], v[194:197], v[210:213], v[48:51]
	v_mfma_f32_16x16x32_bf16 v[44:47], v[162:165], v[218:221], v[44:47]
	v_mfma_f32_16x16x32_bf16 v[40:43], v[194:197], v[218:221], v[40:43]
	v_mfma_f32_16x16x32_bf16 v[36:39], v[162:165], v[226:229], v[36:39]
	v_mfma_f32_16x16x32_bf16 v[32:35], v[194:197], v[226:229], v[32:35]
	v_mfma_f32_16x16x32_bf16 v[60:63], v[166:169], v[206:209], v[60:63]
	v_mfma_f32_16x16x32_bf16 v[56:59], v[198:201], v[206:209], v[56:59]
	v_mfma_f32_16x16x32_bf16 v[52:55], v[166:169], v[214:217], v[52:55]
	v_mfma_f32_16x16x32_bf16 v[48:51], v[198:201], v[214:217], v[48:51]
	v_mfma_f32_16x16x32_bf16 v[44:47], v[166:169], v[222:225], v[44:47]
	v_mfma_f32_16x16x32_bf16 v[40:43], v[198:201], v[222:225], v[40:43]
	v_mfma_f32_16x16x32_bf16 v[36:39], v[166:169], v[230:233], v[36:39]
	v_mfma_f32_16x16x32_bf16 v[32:35], v[198:201], v[230:233], v[32:35]
	s_setprio 0
	s_barrier
	s_add_i32 s36, s62, s49
	v_lshl_add_u64 v[170:171], s[40:41], 0, v[146:147]
	s_mov_b32 m0, s36
	ds_read_b128 v[202:205], v174 offset:16384
	ds_read_b128 v[206:209], v174 offset:17408
	ds_read_b128 v[210:213], v174 offset:18432
	ds_read_b128 v[214:217], v174 offset:19456
	ds_read_b128 v[218:221], v174 offset:20480
	ds_read_b128 v[222:225], v174 offset:21504
	ds_read_b128 v[226:229], v174 offset:22528
	ds_read_b128 v[230:233], v174 offset:23552
	global_load_lds_dwordx4 v146, s[40:41]
	s_add_i32 m0, s36, 0x2000
	s_add_u32 s36, s40, 0x40000
	v_lshl_add_u64 v[234:235], s[40:41], 0, v[150:151]
	s_addc_u32 s37, s41, 0
	s_add_i32 s68, s63, s49
	global_load_lds_dwordx4 v150, s[40:41]
	s_mov_b32 m0, s68
	v_lshl_add_u64 v[238:239], s[42:43], 0, v[148:149]
	global_load_lds_dwordx4 v146, s[36:37]
	s_add_i32 m0, s68, 0x2000
	s_nop 0
	global_load_lds_dwordx4 v150, s[36:37]
	v_lshl_add_u64 v[236:237], s[42:43], 0, v[144:145]
	s_mov_b32 m0, s50
	s_nop 0
	global_load_lds_dwordx4 v144, s[42:43]
	s_mov_b32 m0, s51
	s_nop 0
	global_load_lds_dwordx4 v148, s[42:43]
	s_waitcnt vmcnt(8)
	s_waitcnt lgkmcnt(0)
	s_barrier
; #define PG8_STAGE(bufoff, gbase, voff) do { _Pragma("unroll") for (int _i = 0; _i < 2; ++_i) \
;         __builtin_amdgcn_global_load_lds((const unsigned*)((const char*)(gbase) + (voff)[_i]), (PG8_LAS unsigned*)(lds + (bufoff) + ldsw + _i * 8192), 16, 0, 0); } while (0)
; #define PG8_LDA(dst, b, h) do { _Pragma("unroll") for (int m = 0; m < 4; ++m) _Pragma("unroll") for (int k = 0; k < 2; ++k) dst[m][k] = *(const PG8_LAS bf16x8*)(lds + PG8_SA(b, h) + aoff + m * 2048 + k * 1024); } while (0)
; #define PG8_LDB(dst, b, h) do { _Pragma("unroll") for (int n = 0; n < 2; ++n) _Pragma("unroll") for (int k = 0; k < 2; ++k) dst[n][k] = *(const PG8_LAS bf16x8*)(lds + PG8_SB(b, h) + boff + n * 2048 + k * 1024); } while (0)
; #define PG8_MMA(ai, bj, At, Bt) do { __builtin_amdgcn_s_setprio(1); _Pragma("unroll") for (int m = 0; m < 4; ++m) _Pragma("unroll") for (int n = 0; n < 2; ++n) _Pragma("unroll") for (int k = 0; k < 2; ++k) \
;         acc[ai][bj][m][n] = __builtin_amdgcn_mfma_f32_16x16x32_bf16(Bt[n][k], At[m][k], acc[ai][bj][m][n], 0, 0, 0); __builtin_amdgcn_s_setprio(0); } while (0)
; #define PG8_WAIT_V(n) asm volatile("s_waitcnt vmcnt(" #n ")" ::: "memory")
; #define PG8_WAIT_L(n) asm volatile("s_waitcnt lgkmcnt(" #n ")" ::: "memory")
; #define PG8_BAR __builtin_amdgcn_s_barrier()
; #define PG8_SCHED __builtin_amdgcn_sched_barrier(0)
; template <class Epi, class Sched, bool ALIGN_EPI = false, bool SP2 = false>
; __device__ __forceinline__ void gemm_phase(PG8_LAS unsigned char* lds, const Gemm g, const Sched& S, const Epi& E) {
;     ...
;             PG8_WAIT_V(8); PG8_WAIT_L(0); PG8_BAR; PG8_MMA(0, 0, At, B0); PG8_MMA(0, 1, At, B1); PG8_BAR; PG8_SCHED;
;             PG8_LDA(At, 0, 1); PG8_STAGE(PG8_SB(0, 0), b2, voffB); PG8_STAGE(PG8_SB(0, 1), b2 + hstepB, voffB); PG8_STAGE(PG8_SA(0, 0), a2, voffA);
;             PG8_WAIT_V(8); PG8_WAIT_L(0); PG8_BAR; PG8_MMA(1, 0, At, B0); PG8_MMA(1, 1, At, B1); PG8_BAR; PG8_SCHED;
;             PG8_LDB(B0, 1, 0); PG8_LDB(B1, 1, 1); PG8_SCHED; PG8_LDA(At, 1, 0); PG8_STAGE(PG8_SA(0, 1), a2 + hstepA, voffA);
;             PG8_WAIT_V(8); PG8_WAIT_L(0); PG8_BAR; PG8_MMA(0, 0, At, B0); PG8_MMA(0, 1, At, B1); PG8_BAR; PG8_SCHED;
	s_setprio 1
	s_waitcnt lgkmcnt(0)
	v_mfma_f32_16x16x32_bf16 v[92:95], v[128:131], v[202:205], v[92:95]
	v_mfma_f32_16x16x32_bf16 v[88:91], v[136:139], v[202:205], v[88:91]
	v_mfma_f32_16x16x32_bf16 v[84:87], v[128:131], v[210:213], v[84:87]
	v_mfma_f32_16x16x32_bf16 v[80:83], v[136:139], v[210:213], v[80:83]
	v_mfma_f32_16x16x32_bf16 v[76:79], v[128:131], v[218:221], v[76:79]
	v_mfma_f32_16x16x32_bf16 v[72:75], v[136:139], v[218:221], v[72:75]
	v_mfma_f32_16x16x32_bf16 v[68:71], v[128:131], v[226:229], v[68:71]
	v_mfma_f32_16x16x32_bf16 v[64:67], v[136:139], v[226:229], v[64:67]
	v_mfma_f32_16x16x32_bf16 v[92:95], v[132:135], v[206:209], v[92:95]
	v_mfma_f32_16x16x32_bf16 v[88:91], v[140:143], v[206:209], v[88:91]
	v_mfma_f32_16x16x32_bf16 v[84:87], v[132:135], v[214:217], v[84:87]
	v_mfma_f32_16x16x32_bf16 v[80:83], v[140:143], v[214:217], v[80:83]
	v_mfma_f32_16x16x32_bf16 v[76:79], v[132:135], v[222:225], v[76:79]
	v_mfma_f32_16x16x32_bf16 v[72:75], v[140:143], v[222:225], v[72:75]
	v_mfma_f32_16x16x32_bf16 v[68:71], v[132:135], v[230:233], v[68:71]
	v_mfma_f32_16x16x32_bf16 v[64:67], v[140:143], v[230:233], v[64:67]
	s_setprio 0
	s_setprio 1
	v_mfma_f32_16x16x32_bf16 v[28:31], v[162:165], v[202:205], v[28:31]
	v_mfma_f32_16x16x32_bf16 v[24:27], v[194:197], v[202:205], v[24:27]
	v_mfma_f32_16x16x32_bf16 v[20:23], v[162:165], v[210:213], v[20:23]
	v_mfma_f32_16x16x32_bf16 v[16:19], v[194:197], v[210:213], v[16:19]
	v_mfma_f32_16x16x32_bf16 v[12:15], v[162:165], v[218:221], v[12:15]
	v_mfma_f32_16x16x32_bf16 v[8:11], v[194:197], v[218:221], v[8:11]
	v_mfma_f32_16x16x32_bf16 v[4:7], v[162:165], v[226:229], v[4:7]
	v_mfma_f32_16x16x32_bf16 v[0:3], v[194:197], v[226:229], v[0:3]
	v_mfma_f32_16x16x32_bf16 v[28:31], v[166:169], v[206:209], v[28:31]
	v_mfma_f32_16x16x32_bf16 v[24:27], v[198:201], v[206:209], v[24:27]
	v_mfma_f32_16x16x32_bf16 v[20:23], v[166:169], v[214:217], v[20:23]
	v_mfma_f32_16x16x32_bf16 v[16:19], v[198:201], v[214:217], v[16:19]
	v_mfma_f32_16x16x32_bf16 v[12:15], v[166:169], v[222:225], v[12:15]
	v_mfma_f32_16x16x32_bf16 v[8:11], v[198:201], v[222:225], v[8:11]
	v_mfma_f32_16x16x32_bf16 v[4:7], v[166:169], v[230:233], v[4:7]
	v_mfma_f32_16x16x32_bf16 v[0:3], v[198:201], v[230:233], v[0:3]
	s_setprio 0
	s_barrier
	s_add_i32 s68, 0, 0x18000
	s_add_i32 s69, 0, 0x1c000
	v_add_u32_e32 v140, s68, v173
	v_add_u32_e32 v153, s69, v173
	ds_read_b128 v[128:131], v140
	ds_read_b128 v[132:135], v140 offset:1024
	ds_read_b128 v[136:139], v140 offset:2048
	ds_read_b128 v[140:143], v140 offset:3072
	ds_read_b128 v[162:165], v153
	ds_read_b128 v[166:169], v153 offset:1024
	ds_read_b128 v[194:197], v153 offset:2048
	ds_read_b128 v[198:201], v153 offset:3072
	s_add_u32 s36, s42, 0x8000
	s_addc_u32 s37, s43, 0
	s_mov_b32 m0, s52
	ds_read_b128 v[202:205], v174 offset:32768
	ds_read_b128 v[206:209], v174 offset:33792
	ds_read_b128 v[210:213], v174 offset:34816
	ds_read_b128 v[214:217], v174 offset:35840
	ds_read_b128 v[218:221], v174 offset:36864
	ds_read_b128 v[222:225], v174 offset:37888
	ds_read_b128 v[226:229], v174 offset:38912
	ds_read_b128 v[230:233], v174 offset:39936
	global_load_lds_dwordx4 v144, s[36:37]
	v_lshl_add_u64 v[240:241], s[36:37], 0, v[148:149]
	s_mov_b32 m0, s53
	s_nop 0
	global_load_lds_dwordx4 v148, s[36:37]
	s_waitcnt vmcnt(8)
	s_waitcnt lgkmcnt(0)
	s_barrier
	s_setprio 1
	s_waitcnt lgkmcnt(0)
	v_mfma_f32_16x16x32_bf16 v[124:127], v[128:131], v[202:205], v[124:127]
	v_mfma_f32_16x16x32_bf16 v[120:123], v[136:139], v[202:205], v[120:123]
	v_mfma_f32_16x16x32_bf16 v[116:119], v[128:131], v[210:213], v[116:119]
	v_mfma_f32_16x16x32_bf16 v[112:115], v[136:139], v[210:213], v[112:115]
	v_mfma_f32_16x16x32_bf16 v[108:111], v[128:131], v[218:221], v[108:111]
	v_mfma_f32_16x16x32_bf16 v[104:107], v[136:139], v[218:221], v[104:107]
	v_mfma_f32_16x16x32_bf16 v[100:103], v[128:131], v[226:229], v[100:103]
	v_mfma_f32_16x16x32_bf16 v[96:99], v[136:139], v[226:229], v[96:99]
	v_mfma_f32_16x16x32_bf16 v[124:127], v[132:135], v[206:209], v[124:127]
	v_mfma_f32_16x16x32_bf16 v[120:123], v[140:143], v[206:209], v[120:123]
	v_mfma_f32_16x16x32_bf16 v[116:119], v[132:135], v[214:217], v[116:119]
	v_mfma_f32_16x16x32_bf16 v[112:115], v[140:143], v[214:217], v[112:115]
	v_mfma_f32_16x16x32_bf16 v[108:111], v[132:135], v[222:225], v[108:111]
	v_mfma_f32_16x16x32_bf16 v[104:107], v[140:143], v[222:225], v[104:107]
	v_mfma_f32_16x16x32_bf16 v[100:103], v[132:135], v[230:233], v[100:103]
	v_mfma_f32_16x16x32_bf16 v[96:99], v[140:143], v[230:233], v[96:99]
	s_setprio 0
	s_setprio 1
	v_mfma_f32_16x16x32_bf16 v[60:63], v[162:165], v[202:205], v[60:63]
	v_mfma_f32_16x16x32_bf16 v[56:59], v[194:197], v[202:205], v[56:59]
	v_mfma_f32_16x16x32_bf16 v[52:55], v[162:165], v[210:213], v[52:55]
	v_mfma_f32_16x16x32_bf16 v[48:51], v[194:197], v[210:213], v[48:51]
	v_mfma_f32_16x16x32_bf16 v[44:47], v[162:165], v[218:221], v[44:47]
	v_mfma_f32_16x16x32_bf16 v[40:43], v[194:197], v[218:221], v[40:43]
	v_mfma_f32_16x16x32_bf16 v[36:39], v[162:165], v[226:229], v[36:39]
	v_mfma_f32_16x16x32_bf16 v[32:35], v[194:197], v[226:229], v[32:35]
	v_mfma_f32_16x16x32_bf16 v[60:63], v[166:169], v[206:209], v[60:63]
	v_mfma_f32_16x16x32_bf16 v[56:59], v[198:201], v[206:209], v[56:59]
	v_mfma_f32_16x16x32_bf16 v[52:55], v[166:169], v[214:217], v[52:55]
	v_mfma_f32_16x16x32_bf16 v[48:51], v[198:201], v[214:217], v[48:51]
	v_mfma_f32_16x16x32_bf16 v[44:47], v[166:169], v[222:225], v[44:47]
	v_mfma_f32_16x16x32_bf16 v[40:43], v[198:201], v[222:225], v[40:43]
	v_mfma_f32_16x16x32_bf16 v[36:39], v[166:169], v[230:233], v[36:39]
	v_mfma_f32_16x16x32_bf16 v[32:35], v[198:201], v[230:233], v[32:35]
	s_setprio 0
	s_barrier
; #define PG8_STAGE(bufoff, gbase, voff) do { _Pragma("unroll") for (int _i = 0; _i < 2; ++_i) \
;         __builtin_amdgcn_global_load_lds((const unsigned*)((const char*)(gbase) + (voff)[_i]), (PG8_LAS unsigned*)(lds + (bufoff) + ldsw + _i * 8192), 16, 0, 0); } while (0)
; #define PG8_LDA(dst, b, h) do { _Pragma("unroll") for (int m = 0; m < 4; ++m) _Pragma("unroll") for (int k = 0; k < 2; ++k) dst[m][k] = *(const PG8_LAS bf16x8*)(lds + PG8_SA(b, h) + aoff + m * 2048 + k * 1024); } while (0)
; #define PG8_MMA(ai, bj, At, Bt) do { __builtin_amdgcn_s_setprio(1); _Pragma("unroll") for (int m = 0; m < 4; ++m) _Pragma("unroll") for (int n = 0; n < 2; ++n) _Pragma("unroll") for (int k = 0; k < 2; ++k) \
;         acc[ai][bj][m][n] = __builtin_amdgcn_mfma_f32_16x16x32_bf16(Bt[n][k], At[m][k], acc[ai][bj][m][n], 0, 0, 0); __builtin_amdgcn_s_setprio(0); } while (0)
; #define PG8_WAIT_V(n) asm volatile("s_waitcnt vmcnt(" #n ")" ::: "memory")
; #define PG8_WAIT_L(n) asm volatile("s_waitcnt lgkmcnt(" #n ")" ::: "memory")
; #define PG8_BAR __builtin_amdgcn_s_barrier()
; #define PG8_SCHED __builtin_amdgcn_sched_barrier(0)
; template <class Epi, class Sched, bool ALIGN_EPI = false, bool SP2 = false>
; __device__ __forceinline__ void gemm_phase(PG8_LAS unsigned char* lds, const Gemm g, const Sched& S, const Epi& E) {
;     ...
;         for (int t = 0; t < nt; t += 2) {
;     ...
;             PG8_LDA(At, 1, 1); PG8_STAGE(PG8_SB(1, 0), b3, voffB); PG8_STAGE(PG8_SB(1, 1), b3 + hstepB, voffB); PG8_STAGE(PG8_SA(1, 0), a3, voffA);
;             PG8_WAIT_V(8); PG8_WAIT_L(0); PG8_BAR; PG8_MMA(1, 0, At, B0); PG8_MMA(1, 1, At, B1); PG8_BAR; PG8_SCHED;
	s_add_i32 s36, s68, s49
	v_lshl_add_u64 v[170:171], v[170:171], 0, s[18:19]
	s_mov_b32 m0, s36
	ds_read_b128 v[202:205], v174 offset:49152
	ds_read_b128 v[206:209], v174 offset:50176
	ds_read_b128 v[210:213], v174 offset:51200
	ds_read_b128 v[214:217], v174 offset:52224
	ds_read_b128 v[218:221], v174 offset:53248
	ds_read_b128 v[222:225], v174 offset:54272
	ds_read_b128 v[226:229], v174 offset:55296
	ds_read_b128 v[230:233], v174 offset:56320
	global_load_lds_dwordx4 v[170:171], off
	s_add_i32 m0, s36, 0x2000
	s_add_u32 s36, s40, 0x40080
	v_lshl_add_u64 v[170:171], v[234:235], 0, s[18:19]
	s_addc_u32 s37, s41, 0
	s_add_i32 s40, s69, s49
	global_load_lds_dwordx4 v[170:171], off
	s_mov_b32 m0, s40
	s_nop 0
	global_load_lds_dwordx4 v146, s[36:37]
	s_add_i32 m0, s40, 0x2000
	s_nop 0
	global_load_lds_dwordx4 v150, s[36:37]
	v_lshl_add_u64 v[170:171], v[236:237], 0, s[18:19]
	s_mov_b32 m0, s58
	s_nop 0
	global_load_lds_dwordx4 v[170:171], off
	v_lshl_add_u64 v[170:171], v[238:239], 0, s[18:19]
	s_mov_b32 m0, s59
	s_nop 0
	global_load_lds_dwordx4 v[170:171], off
	s_waitcnt vmcnt(8)
	s_waitcnt lgkmcnt(0)
	s_barrier
	s_setprio 1
	s_waitcnt lgkmcnt(0)
	v_mfma_f32_16x16x32_bf16 v[92:95], v[128:131], v[202:205], v[92:95]
	v_mfma_f32_16x16x32_bf16 v[88:91], v[136:139], v[202:205], v[88:91]
	v_mfma_f32_16x16x32_bf16 v[84:87], v[128:131], v[210:213], v[84:87]
	v_mfma_f32_16x16x32_bf16 v[80:83], v[136:139], v[210:213], v[80:83]
	v_mfma_f32_16x16x32_bf16 v[76:79], v[128:131], v[218:221], v[76:79]
	v_mfma_f32_16x16x32_bf16 v[72:75], v[136:139], v[218:221], v[72:75]
	v_mfma_f32_16x16x32_bf16 v[68:71], v[128:131], v[226:229], v[68:71]
	v_mfma_f32_16x16x32_bf16 v[64:67], v[136:139], v[226:229], v[64:67]
	v_mfma_f32_16x16x32_bf16 v[92:95], v[132:135], v[206:209], v[92:95]
	v_mfma_f32_16x16x32_bf16 v[88:91], v[140:143], v[206:209], v[88:91]
	v_mfma_f32_16x16x32_bf16 v[84:87], v[132:135], v[214:217], v[84:87]
	v_mfma_f32_16x16x32_bf16 v[80:83], v[140:143], v[214:217], v[80:83]
	v_mfma_f32_16x16x32_bf16 v[76:79], v[132:135], v[222:225], v[76:79]
	v_mfma_f32_16x16x32_bf16 v[72:75], v[140:143], v[222:225], v[72:75]
	v_mfma_f32_16x16x32_bf16 v[68:71], v[132:135], v[230:233], v[68:71]
	v_mfma_f32_16x16x32_bf16 v[64:67], v[140:143], v[230:233], v[64:67]
	s_setprio 0
	s_setprio 1
	v_mfma_f32_16x16x32_bf16 v[28:31], v[162:165], v[202:205], v[28:31]
	v_mfma_f32_16x16x32_bf16 v[24:27], v[194:197], v[202:205], v[24:27]
	v_mfma_f32_16x16x32_bf16 v[20:23], v[162:165], v[210:213], v[20:23]
	v_mfma_f32_16x16x32_bf16 v[16:19], v[194:197], v[210:213], v[16:19]
	v_mfma_f32_16x16x32_bf16 v[12:15], v[162:165], v[218:221], v[12:15]
	v_mfma_f32_16x16x32_bf16 v[8:11], v[194:197], v[218:221], v[8:11]
	v_mfma_f32_16x16x32_bf16 v[4:7], v[162:165], v[226:229], v[4:7]
	v_mfma_f32_16x16x32_bf16 v[0:3], v[194:197], v[226:229], v[0:3]
	v_mfma_f32_16x16x32_bf16 v[28:31], v[166:169], v[206:209], v[28:31]
	v_mfma_f32_16x16x32_bf16 v[24:27], v[198:201], v[206:209], v[24:27]
	v_mfma_f32_16x16x32_bf16 v[20:23], v[166:169], v[214:217], v[20:23]
	v_mfma_f32_16x16x32_bf16 v[16:19], v[198:201], v[214:217], v[16:19]
	v_mfma_f32_16x16x32_bf16 v[12:15], v[166:169], v[222:225], v[12:15]
	v_mfma_f32_16x16x32_bf16 v[8:11], v[198:201], v[222:225], v[8:11]
	v_mfma_f32_16x16x32_bf16 v[4:7], v[166:169], v[230:233], v[4:7]
	v_mfma_f32_16x16x32_bf16 v[0:3], v[198:201], v[230:233], v[0:3]
	s_setprio 0
	s_barrier
	s_add_i32 s67, s67, 2
	s_add_u32 s65, s65, 0x100
	s_addc_u32 s66, s66, 0
	s_cmp_gt_u32 s67, 13
	s_mov_b64 s[36:37], s[38:39]
	s_cbranch_scc0 .LBB0_1191
	s_and_b64 vcc, exec, s[20:21]
	s_cbranch_vccz .LBB0_1194
	s_barrier

; #define PG8_STAGE(bufoff, gbase, voff) do { _Pragma("unroll") for (int _i = 0; _i < 2; ++_i) \
;         __builtin_amdgcn_global_load_lds((const unsigned*)((const char*)(gbase) + (voff)[_i]), (PG8_LAS unsigned*)(lds + (bufoff) + ldsw + _i * 8192), 16, 0, 0); } while (0)
; #define PG8_LDA(dst, b, h) do { _Pragma("unroll") for (int m = 0; m < 4; ++m) _Pragma("unroll") for (int k = 0; k < 2; ++k) dst[m][k] = *(const PG8_LAS bf16x8*)(lds + PG8_SA(b, h) + aoff + m * 2048 + k * 1024); } while (0)
; #define PG8_LDB(dst, b, h) do { _Pragma("unroll") for (int n = 0; n < 2; ++n) _Pragma("unroll") for (int k = 0; k < 2; ++k) dst[n][k] = *(const PG8_LAS bf16x8*)(lds + PG8_SB(b, h) + boff + n * 2048 + k * 1024); } while (0)
; #define PG8_MMA(ai, bj, At, Bt) do { __builtin_amdgcn_s_setprio(1); _Pragma("unroll") for (int m = 0; m < 4; ++m) _Pragma("unroll") for (int n = 0; n < 2; ++n) _Pragma("unroll") for (int k = 0; k < 2; ++k) \
;         acc[ai][bj][m][n] = __builtin_amdgcn_mfma_f32_16x16x32_bf16(Bt[n][k], At[m][k], acc[ai][bj][m][n], 0, 0, 0); __builtin_amdgcn_s_setprio(0); } while (0)
; #define PG8_WAIT_V(n) asm volatile("s_waitcnt vmcnt(" #n ")" ::: "memory")
; #define PG8_WAIT_L(n) asm volatile("s_waitcnt lgkmcnt(" #n ")" ::: "memory")
; #define PG8_BAR __builtin_amdgcn_s_barrier()
; #define PG8_SCHED __builtin_amdgcn_sched_barrier(0)
; template <class Epi, class Sched, bool ALIGN_EPI = false, bool SP2 = false>
; __device__ __forceinline__ void gemm_phase(PG8_LAS unsigned char* lds, const Gemm g, const Sched& S, const Epi& E) {
;     ...
;             const bool last = (t == nt - 2);
;             const char* a1 = cA + PG8_AK(t + 1);
;             const char* a2 = last ? nA : cA + PG8_AK(t + 2); const char* b2 = last ? nB : cB + (size_t)(t + 2) * kstep;
;             const char* a3 = last ? nA + PG8_AK(1) : cA + PG8_AK(t + 3); const char* b3 = b2 + kstep;
;             if (last && has_next) S.a_ready(nxt);
;             if constexpr (SP2) {
;             PG8_LDB(B0, 0, 0); PG8_LDB(B1, 0, 1); PG8_SCHED; PG8_LDA(At, 0, 0); PG8_STAGE(PG8_SA(1, 1), a1 + hstepA, voffA);
;             PG8_WAIT_V(8); PG8_WAIT_L(0); PG8_BAR; PG8_MMA(0, 0, At, B0); PG8_MMA(0, 1, At, B1); PG8_BAR; PG8_SCHED;
;             PG8_LDA(At, 0, 1); PG8_STAGE(PG8_SB(0, 0), b2, voffB); PG8_STAGE(PG8_SB(0, 1), b2 + hstepB, voffB); PG8_STAGE(PG8_SA(0, 0), a2, voffA);
.LBB0_1275:
	ds_read_b128 v[132:135], v171
	ds_read_b128 v[136:139], v171 offset:1024
	ds_read_b128 v[140:143], v171 offset:2048
	ds_read_b128 v[178:181], v171 offset:3072
	ds_read_b128 v[182:185], v173
	ds_read_b128 v[186:189], v173 offset:1024
	ds_read_b128 v[190:193], v173 offset:2048
	ds_read_b128 v[194:197], v173 offset:3072
	s_add_u32 s38, s34, s36
	s_addc_u32 s39, s35, s37
	s_add_u32 s42, s38, 0x100
	s_addc_u32 s43, s39, 0
	s_add_u32 s40, s66, s36
	s_addc_u32 s41, s67, s37
	s_add_u32 s38, s38, 0x180
	s_addc_u32 s39, s39, 0
	s_cmpk_eq_i32 s36, 0x700
	s_cselect_b32 s39, s65, s39
	s_cselect_b32 s38, s64, s38
	s_cselect_b32 s41, s23, s41
	s_cselect_b32 s40, s63, s40
	s_cselect_b32 s43, s3, s43
	s_cselect_b32 s42, s25, s42
	v_lshl_add_u64 v[230:231], v[130:131], 0, s[36:37]
	s_add_i32 m0, s31, 0xc000
	ds_read_b128 v[198:201], v175
	ds_read_b128 v[202:205], v175 offset:1024
	ds_read_b128 v[206:209], v175 offset:2048
	ds_read_b128 v[210:213], v175 offset:3072
	ds_read_b128 v[214:217], v175 offset:4096
	ds_read_b128 v[218:221], v175 offset:5120
	ds_read_b128 v[222:225], v175 offset:6144
	ds_read_b128 v[226:229], v175 offset:7168
	global_load_lds_dwordx4 v[230:231], off
	v_lshl_add_u64 v[230:231], v[128:129], 0, s[36:37]
	s_add_i32 m0, s31, 0xe000
	s_nop 0
	global_load_lds_dwordx4 v[230:231], off
	s_waitcnt vmcnt(8)
	s_waitcnt lgkmcnt(0)
	s_barrier
	s_setprio 1
	s_waitcnt lgkmcnt(0)
	v_mfma_f32_16x16x32_bf16 v[124:127], v[132:135], v[198:201], v[124:127]
	v_mfma_f32_16x16x32_bf16 v[120:123], v[140:143], v[198:201], v[120:123]
	v_mfma_f32_16x16x32_bf16 v[116:119], v[132:135], v[206:209], v[116:119]
	v_mfma_f32_16x16x32_bf16 v[112:115], v[140:143], v[206:209], v[112:115]
	v_mfma_f32_16x16x32_bf16 v[108:111], v[132:135], v[214:217], v[108:111]
	v_mfma_f32_16x16x32_bf16 v[104:107], v[140:143], v[214:217], v[104:107]
	v_mfma_f32_16x16x32_bf16 v[100:103], v[132:135], v[222:225], v[100:103]
	v_mfma_f32_16x16x32_bf16 v[96:99], v[140:143], v[222:225], v[96:99]
	v_mfma_f32_16x16x32_bf16 v[124:127], v[136:139], v[202:205], v[124:127]
	v_mfma_f32_16x16x32_bf16 v[120:123], v[178:181], v[202:205], v[120:123]
	v_mfma_f32_16x16x32_bf16 v[116:119], v[136:139], v[210:213], v[116:119]
	v_mfma_f32_16x16x32_bf16 v[112:115], v[178:181], v[210:213], v[112:115]
	v_mfma_f32_16x16x32_bf16 v[108:111], v[136:139], v[218:221], v[108:111]
	v_mfma_f32_16x16x32_bf16 v[104:107], v[178:181], v[218:221], v[104:107]
	v_mfma_f32_16x16x32_bf16 v[100:103], v[136:139], v[226:229], v[100:103]
	v_mfma_f32_16x16x32_bf16 v[96:99], v[178:181], v[226:229], v[96:99]
	s_setprio 0
	s_setprio 1
	v_mfma_f32_16x16x32_bf16 v[64:67], v[182:185], v[198:201], v[64:67]
	v_mfma_f32_16x16x32_bf16 v[56:59], v[190:193], v[198:201], v[56:59]
	v_mfma_f32_16x16x32_bf16 v[52:55], v[182:185], v[206:209], v[52:55]
	v_mfma_f32_16x16x32_bf16 v[48:51], v[190:193], v[206:209], v[48:51]
	v_mfma_f32_16x16x32_bf16 v[44:47], v[182:185], v[214:217], v[44:47]
	v_mfma_f32_16x16x32_bf16 v[40:43], v[190:193], v[214:217], v[40:43]
	v_mfma_f32_16x16x32_bf16 v[36:39], v[182:185], v[222:225], v[36:39]
	v_mfma_f32_16x16x32_bf16 v[32:35], v[190:193], v[222:225], v[32:35]
	v_mfma_f32_16x16x32_bf16 v[64:67], v[186:189], v[202:205], v[64:67]
	v_mfma_f32_16x16x32_bf16 v[56:59], v[194:197], v[202:205], v[56:59]
	v_mfma_f32_16x16x32_bf16 v[52:55], v[186:189], v[210:213], v[52:55]
	v_mfma_f32_16x16x32_bf16 v[48:51], v[194:197], v[210:213], v[48:51]
	v_mfma_f32_16x16x32_bf16 v[44:47], v[186:189], v[218:221], v[44:47]
	v_mfma_f32_16x16x32_bf16 v[40:43], v[194:197], v[218:221], v[40:43]
	v_mfma_f32_16x16x32_bf16 v[36:39], v[186:189], v[226:229], v[36:39]
	v_mfma_f32_16x16x32_bf16 v[32:35], v[194:197], v[226:229], v[32:35]
	s_setprio 0
	s_barrier
	s_add_i32 s69, s59, s49
	v_lshl_add_u64 v[230:231], s[40:41], 0, v[148:149]
	s_mov_b32 m0, s69
	ds_read_b128 v[198:201], v175 offset:16384
	ds_read_b128 v[202:205], v175 offset:17408
	ds_read_b128 v[206:209], v175 offset:18432
	ds_read_b128 v[210:213], v175 offset:19456
	ds_read_b128 v[214:217], v175 offset:20480
	ds_read_b128 v[218:221], v175 offset:21504
	ds_read_b128 v[222:225], v175 offset:22528
	ds_read_b128 v[226:229], v175 offset:23552
	global_load_lds_dwordx4 v148, s[40:41]
	s_add_i32 m0, s69, 0x2000
	s_add_u32 s70, s40, 0x40000
	v_lshl_add_u64 v[232:233], s[40:41], 0, v[144:145]
	s_addc_u32 s71, s41, 0
	s_add_i32 s69, s60, s49
	global_load_lds_dwordx4 v144, s[40:41]
	s_mov_b32 m0, s69
	s_nop 0
	global_load_lds_dwordx4 v148, s[70:71]
	s_add_i32 m0, s69, 0x2000
	s_nop 0
	global_load_lds_dwordx4 v144, s[70:71]
	s_mov_b32 m0, s31
	s_nop 0
	global_load_lds_dwordx4 v150, s[42:43]
	v_lshl_add_u64 v[234:235], s[42:43], 0, v[146:147]
	s_mov_b32 m0, s52
	s_nop 0
	global_load_lds_dwordx4 v146, s[42:43]
	s_waitcnt vmcnt(8)
	s_waitcnt lgkmcnt(0)
	s_barrier
; #define PG8_STAGE(bufoff, gbase, voff) do { _Pragma("unroll") for (int _i = 0; _i < 2; ++_i) \
;         __builtin_amdgcn_global_load_lds((const unsigned*)((const char*)(gbase) + (voff)[_i]), (PG8_LAS unsigned*)(lds + (bufoff) + ldsw + _i * 8192), 16, 0, 0); } while (0)
; #define PG8_LDA(dst, b, h) do { _Pragma("unroll") for (int m = 0; m < 4; ++m) _Pragma("unroll") for (int k = 0; k < 2; ++k) dst[m][k] = *(const PG8_LAS bf16x8*)(lds + PG8_SA(b, h) + aoff + m * 2048 + k * 1024); } while (0)
; #define PG8_LDB(dst, b, h) do { _Pragma("unroll") for (int n = 0; n < 2; ++n) _Pragma("unroll") for (int k = 0; k < 2; ++k) dst[n][k] = *(const PG8_LAS bf16x8*)(lds + PG8_SB(b, h) + boff + n * 2048 + k * 1024); } while (0)
; #define PG8_MMA(ai, bj, At, Bt) do { __builtin_amdgcn_s_setprio(1); _Pragma("unroll") for (int m = 0; m < 4; ++m) _Pragma("unroll") for (int n = 0; n < 2; ++n) _Pragma("unroll") for (int k = 0; k < 2; ++k) \
;         acc[ai][bj][m][n] = __builtin_amdgcn_mfma_f32_16x16x32_bf16(Bt[n][k], At[m][k], acc[ai][bj][m][n], 0, 0, 0); __builtin_amdgcn_s_setprio(0); } while (0)
; #define PG8_WAIT_V(n) asm volatile("s_waitcnt vmcnt(" #n ")" ::: "memory")
; #define PG8_WAIT_L(n) asm volatile("s_waitcnt lgkmcnt(" #n ")" ::: "memory")
; #define PG8_BAR __builtin_amdgcn_s_barrier()
; #define PG8_SCHED __builtin_amdgcn_sched_barrier(0)
; template <class Epi, class Sched, bool ALIGN_EPI = false, bool SP2 = false>
; __device__ __forceinline__ void gemm_phase(PG8_LAS unsigned char* lds, const Gemm g, const Sched& S, const Epi& E) {
;     ...
;             PG8_WAIT_V(8); PG8_WAIT_L(0); PG8_BAR; PG8_MMA(0, 0, At, B0); PG8_MMA(0, 1, At, B1); PG8_BAR; PG8_SCHED;
;             PG8_LDA(At, 0, 1); PG8_STAGE(PG8_SB(0, 0), b2, voffB); PG8_STAGE(PG8_SB(0, 1), b2 + hstepB, voffB); PG8_STAGE(PG8_SA(0, 0), a2, voffA);
;             PG8_WAIT_V(8); PG8_WAIT_L(0); PG8_BAR; PG8_MMA(1, 0, At, B0); PG8_MMA(1, 1, At, B1); PG8_BAR; PG8_SCHED;
;             PG8_LDB(B0, 1, 0); PG8_LDB(B1, 1, 1); PG8_SCHED; PG8_LDA(At, 1, 0); PG8_STAGE(PG8_SA(0, 1), a2 + hstepA, voffA);
;             PG8_WAIT_V(8); PG8_WAIT_L(0); PG8_BAR; PG8_MMA(0, 0, At, B0); PG8_MMA(0, 1, At, B1); PG8_BAR; PG8_SCHED;
	s_setprio 1
	s_waitcnt lgkmcnt(0)
	v_mfma_f32_16x16x32_bf16 v[92:95], v[132:135], v[198:201], v[92:95]
	v_mfma_f32_16x16x32_bf16 v[88:91], v[140:143], v[198:201], v[88:91]
	v_mfma_f32_16x16x32_bf16 v[84:87], v[132:135], v[206:209], v[84:87]
	v_mfma_f32_16x16x32_bf16 v[80:83], v[140:143], v[206:209], v[80:83]
	v_mfma_f32_16x16x32_bf16 v[76:79], v[132:135], v[214:217], v[76:79]
	v_mfma_f32_16x16x32_bf16 v[72:75], v[140:143], v[214:217], v[72:75]
	v_mfma_f32_16x16x32_bf16 v[68:71], v[132:135], v[222:225], v[68:71]
	v_mfma_f32_16x16x32_bf16 v[60:63], v[140:143], v[222:225], v[60:63]
	v_mfma_f32_16x16x32_bf16 v[92:95], v[136:139], v[202:205], v[92:95]
	v_mfma_f32_16x16x32_bf16 v[88:91], v[178:181], v[202:205], v[88:91]
	v_mfma_f32_16x16x32_bf16 v[84:87], v[136:139], v[210:213], v[84:87]
	v_mfma_f32_16x16x32_bf16 v[80:83], v[178:181], v[210:213], v[80:83]
	v_mfma_f32_16x16x32_bf16 v[76:79], v[136:139], v[218:221], v[76:79]
	v_mfma_f32_16x16x32_bf16 v[72:75], v[178:181], v[218:221], v[72:75]
	v_mfma_f32_16x16x32_bf16 v[68:71], v[136:139], v[226:229], v[68:71]
	v_mfma_f32_16x16x32_bf16 v[60:63], v[178:181], v[226:229], v[60:63]
	s_setprio 0
	s_setprio 1
	v_mfma_f32_16x16x32_bf16 v[28:31], v[182:185], v[198:201], v[28:31]
	v_mfma_f32_16x16x32_bf16 v[24:27], v[190:193], v[198:201], v[24:27]
	v_mfma_f32_16x16x32_bf16 v[20:23], v[182:185], v[206:209], v[20:23]
	v_mfma_f32_16x16x32_bf16 v[16:19], v[190:193], v[206:209], v[16:19]
	v_mfma_f32_16x16x32_bf16 v[12:15], v[182:185], v[214:217], v[12:15]
	v_mfma_f32_16x16x32_bf16 v[8:11], v[190:193], v[214:217], v[8:11]
	v_mfma_f32_16x16x32_bf16 v[4:7], v[182:185], v[222:225], v[4:7]
	v_mfma_f32_16x16x32_bf16 v[0:3], v[190:193], v[222:225], v[0:3]
	v_mfma_f32_16x16x32_bf16 v[28:31], v[186:189], v[202:205], v[28:31]
	v_mfma_f32_16x16x32_bf16 v[24:27], v[194:197], v[202:205], v[24:27]
	v_mfma_f32_16x16x32_bf16 v[20:23], v[186:189], v[210:213], v[20:23]
	v_mfma_f32_16x16x32_bf16 v[16:19], v[194:197], v[210:213], v[16:19]
	v_mfma_f32_16x16x32_bf16 v[12:15], v[186:189], v[218:221], v[12:15]
	v_mfma_f32_16x16x32_bf16 v[8:11], v[194:197], v[218:221], v[8:11]
	v_mfma_f32_16x16x32_bf16 v[4:7], v[186:189], v[226:229], v[4:7]
	v_mfma_f32_16x16x32_bf16 v[0:3], v[194:197], v[226:229], v[0:3]
	s_setprio 0
	s_barrier
	s_add_i32 s69, 0, 0x18000
	v_add_u32_e32 v160, s69, v163
	s_add_i32 s70, 0, 0x1c000
	ds_read_b128 v[132:135], v160
	ds_read_b128 v[136:139], v160 offset:1024
	ds_read_b128 v[140:143], v160 offset:2048
	ds_read_b128 v[178:181], v160 offset:3072
	v_add_u32_e32 v160, s70, v163
	ds_read_b128 v[182:185], v160
	ds_read_b128 v[186:189], v160 offset:1024
	ds_read_b128 v[190:193], v160 offset:2048
	ds_read_b128 v[194:197], v160 offset:3072
	s_add_u32 s42, s42, 0x40000
	s_addc_u32 s43, s43, 0
	s_mov_b32 m0, s53
	ds_read_b128 v[198:201], v175 offset:32768
	ds_read_b128 v[202:205], v175 offset:33792
	ds_read_b128 v[206:209], v175 offset:34816
	ds_read_b128 v[210:213], v175 offset:35840
	ds_read_b128 v[214:217], v175 offset:36864
	ds_read_b128 v[218:221], v175 offset:37888
	ds_read_b128 v[222:225], v175 offset:38912
	ds_read_b128 v[226:229], v175 offset:39936
	global_load_lds_dwordx4 v150, s[42:43]
	v_lshl_add_u64 v[234:235], s[42:43], 0, v[146:147]
	s_mov_b32 m0, s54
	s_nop 0
	global_load_lds_dwordx4 v146, s[42:43]
	s_waitcnt vmcnt(8)
	s_waitcnt lgkmcnt(0)
	s_barrier
	s_setprio 1
	s_waitcnt lgkmcnt(0)
	v_mfma_f32_16x16x32_bf16 v[124:127], v[132:135], v[198:201], v[124:127]
	v_mfma_f32_16x16x32_bf16 v[120:123], v[140:143], v[198:201], v[120:123]
	v_mfma_f32_16x16x32_bf16 v[116:119], v[132:135], v[206:209], v[116:119]
	v_mfma_f32_16x16x32_bf16 v[112:115], v[140:143], v[206:209], v[112:115]
	v_mfma_f32_16x16x32_bf16 v[108:111], v[132:135], v[214:217], v[108:111]
	v_mfma_f32_16x16x32_bf16 v[104:107], v[140:143], v[214:217], v[104:107]
	v_mfma_f32_16x16x32_bf16 v[100:103], v[132:135], v[222:225], v[100:103]
	v_mfma_f32_16x16x32_bf16 v[96:99], v[140:143], v[222:225], v[96:99]
	v_mfma_f32_16x16x32_bf16 v[124:127], v[136:139], v[202:205], v[124:127]
	v_mfma_f32_16x16x32_bf16 v[120:123], v[178:181], v[202:205], v[120:123]
	v_mfma_f32_16x16x32_bf16 v[116:119], v[136:139], v[210:213], v[116:119]
	v_mfma_f32_16x16x32_bf16 v[112:115], v[178:181], v[210:213], v[112:115]
	v_mfma_f32_16x16x32_bf16 v[108:111], v[136:139], v[218:221], v[108:111]
	v_mfma_f32_16x16x32_bf16 v[104:107], v[178:181], v[218:221], v[104:107]
	v_mfma_f32_16x16x32_bf16 v[100:103], v[136:139], v[226:229], v[100:103]
	v_mfma_f32_16x16x32_bf16 v[96:99], v[178:181], v[226:229], v[96:99]
	s_setprio 0
	s_setprio 1
	v_mfma_f32_16x16x32_bf16 v[64:67], v[182:185], v[198:201], v[64:67]
	v_mfma_f32_16x16x32_bf16 v[56:59], v[190:193], v[198:201], v[56:59]
	v_mfma_f32_16x16x32_bf16 v[52:55], v[182:185], v[206:209], v[52:55]
	v_mfma_f32_16x16x32_bf16 v[48:51], v[190:193], v[206:209], v[48:51]
	v_mfma_f32_16x16x32_bf16 v[44:47], v[182:185], v[214:217], v[44:47]
	v_mfma_f32_16x16x32_bf16 v[40:43], v[190:193], v[214:217], v[40:43]
	v_mfma_f32_16x16x32_bf16 v[36:39], v[182:185], v[222:225], v[36:39]
	v_mfma_f32_16x16x32_bf16 v[32:35], v[190:193], v[222:225], v[32:35]
	v_mfma_f32_16x16x32_bf16 v[64:67], v[186:189], v[202:205], v[64:67]
	v_mfma_f32_16x16x32_bf16 v[56:59], v[194:197], v[202:205], v[56:59]
	v_mfma_f32_16x16x32_bf16 v[52:55], v[186:189], v[210:213], v[52:55]
	v_mfma_f32_16x16x32_bf16 v[48:51], v[194:197], v[210:213], v[48:51]
	v_mfma_f32_16x16x32_bf16 v[44:47], v[186:189], v[218:221], v[44:47]
	v_mfma_f32_16x16x32_bf16 v[40:43], v[194:197], v[218:221], v[40:43]
	v_mfma_f32_16x16x32_bf16 v[36:39], v[186:189], v[226:229], v[36:39]
	v_mfma_f32_16x16x32_bf16 v[32:35], v[194:197], v[226:229], v[32:35]
	s_setprio 0
	s_barrier
; #define PG8_STAGE(bufoff, gbase, voff) do { _Pragma("unroll") for (int _i = 0; _i < 2; ++_i) \
;         __builtin_amdgcn_global_load_lds((const unsigned*)((const char*)(gbase) + (voff)[_i]), (PG8_LAS unsigned*)(lds + (bufoff) + ldsw + _i * 8192), 16, 0, 0); } while (0)
; #define PG8_LDA(dst, b, h) do { _Pragma("unroll") for (int m = 0; m < 4; ++m) _Pragma("unroll") for (int k = 0; k < 2; ++k) dst[m][k] = *(const PG8_LAS bf16x8*)(lds + PG8_SA(b, h) + aoff + m * 2048 + k * 1024); } while (0)
; #define PG8_MMA(ai, bj, At, Bt) do { __builtin_amdgcn_s_setprio(1); _Pragma("unroll") for (int m = 0; m < 4; ++m) _Pragma("unroll") for (int n = 0; n < 2; ++n) _Pragma("unroll") for (int k = 0; k < 2; ++k) \
;         acc[ai][bj][m][n] = __builtin_amdgcn_mfma_f32_16x16x32_bf16(Bt[n][k], At[m][k], acc[ai][bj][m][n], 0, 0, 0); __builtin_amdgcn_s_setprio(0); } while (0)
; #define PG8_WAIT_V(n) asm volatile("s_waitcnt vmcnt(" #n ")" ::: "memory")
; #define PG8_WAIT_L(n) asm volatile("s_waitcnt lgkmcnt(" #n ")" ::: "memory")
; #define PG8_BAR __builtin_amdgcn_s_barrier()
; #define PG8_SCHED __builtin_amdgcn_sched_barrier(0)
; template <class Epi, class Sched, bool ALIGN_EPI = false, bool SP2 = false>
; __device__ __forceinline__ void gemm_phase(PG8_LAS unsigned char* lds, const Gemm g, const Sched& S, const Epi& E) {
;     ...
;         for (int t = 0; t < nt; t += 2) {
;     ...
;             PG8_LDA(At, 1, 1); PG8_STAGE(PG8_SB(1, 0), b3, voffB); PG8_STAGE(PG8_SB(1, 1), b3 + hstepB, voffB); PG8_STAGE(PG8_SA(1, 0), a3, voffA);
;             PG8_WAIT_V(8); PG8_WAIT_L(0); PG8_BAR; PG8_MMA(1, 0, At, B0); PG8_MMA(1, 1, At, B1); PG8_BAR; PG8_SCHED;
	s_add_i32 s42, s69, s49
	v_lshl_add_u64 v[230:231], v[230:231], 0, s[16:17]
	s_mov_b32 m0, s42
	ds_read_b128 v[198:201], v175 offset:49152
	ds_read_b128 v[202:205], v175 offset:50176
	ds_read_b128 v[206:209], v175 offset:51200
	ds_read_b128 v[210:213], v175 offset:52224
	ds_read_b128 v[214:217], v175 offset:53248
	ds_read_b128 v[218:221], v175 offset:54272
	ds_read_b128 v[222:225], v175 offset:55296
	ds_read_b128 v[226:229], v175 offset:56320
	global_load_lds_dwordx4 v[230:231], off
	s_add_i32 m0, s42, 0x2000
	s_add_u32 s40, s40, 0x40080
	v_lshl_add_u64 v[230:231], v[232:233], 0, s[16:17]
	s_addc_u32 s41, s41, 0
	s_add_i32 s42, s70, s49
	global_load_lds_dwordx4 v[230:231], off
	s_mov_b32 m0, s42
	s_nop 0
	global_load_lds_dwordx4 v148, s[40:41]
	s_add_i32 m0, s42, 0x2000
	s_nop 0
	global_load_lds_dwordx4 v144, s[40:41]
	s_mov_b32 m0, s56
	s_nop 0
	global_load_lds_dwordx4 v150, s[38:39]
	v_lshl_add_u64 v[230:231], s[38:39], 0, v[146:147]
	s_mov_b32 m0, s57
	s_nop 0
	global_load_lds_dwordx4 v146, s[38:39]
	s_waitcnt vmcnt(8)
	s_waitcnt lgkmcnt(0)
	s_barrier
	s_setprio 1
	s_waitcnt lgkmcnt(0)
	v_mfma_f32_16x16x32_bf16 v[92:95], v[132:135], v[198:201], v[92:95]
	v_mfma_f32_16x16x32_bf16 v[88:91], v[140:143], v[198:201], v[88:91]
	v_mfma_f32_16x16x32_bf16 v[84:87], v[132:135], v[206:209], v[84:87]
	v_mfma_f32_16x16x32_bf16 v[80:83], v[140:143], v[206:209], v[80:83]
	v_mfma_f32_16x16x32_bf16 v[76:79], v[132:135], v[214:217], v[76:79]
	v_mfma_f32_16x16x32_bf16 v[72:75], v[140:143], v[214:217], v[72:75]
	v_mfma_f32_16x16x32_bf16 v[68:71], v[132:135], v[222:225], v[68:71]
	v_mfma_f32_16x16x32_bf16 v[60:63], v[140:143], v[222:225], v[60:63]
	v_mfma_f32_16x16x32_bf16 v[92:95], v[136:139], v[202:205], v[92:95]
	v_mfma_f32_16x16x32_bf16 v[88:91], v[178:181], v[202:205], v[88:91]
	v_mfma_f32_16x16x32_bf16 v[84:87], v[136:139], v[210:213], v[84:87]
	v_mfma_f32_16x16x32_bf16 v[80:83], v[178:181], v[210:213], v[80:83]
	v_mfma_f32_16x16x32_bf16 v[76:79], v[136:139], v[218:221], v[76:79]
	v_mfma_f32_16x16x32_bf16 v[72:75], v[178:181], v[218:221], v[72:75]
	v_mfma_f32_16x16x32_bf16 v[68:71], v[136:139], v[226:229], v[68:71]
	v_mfma_f32_16x16x32_bf16 v[60:63], v[178:181], v[226:229], v[60:63]
	s_setprio 0
	s_setprio 1
	v_mfma_f32_16x16x32_bf16 v[28:31], v[182:185], v[198:201], v[28:31]
	v_mfma_f32_16x16x32_bf16 v[24:27], v[190:193], v[198:201], v[24:27]
	v_mfma_f32_16x16x32_bf16 v[20:23], v[182:185], v[206:209], v[20:23]
	v_mfma_f32_16x16x32_bf16 v[16:19], v[190:193], v[206:209], v[16:19]
	v_mfma_f32_16x16x32_bf16 v[12:15], v[182:185], v[214:217], v[12:15]
	v_mfma_f32_16x16x32_bf16 v[8:11], v[190:193], v[214:217], v[8:11]
	v_mfma_f32_16x16x32_bf16 v[4:7], v[182:185], v[222:225], v[4:7]
	v_mfma_f32_16x16x32_bf16 v[0:3], v[190:193], v[222:225], v[0:3]
	v_mfma_f32_16x16x32_bf16 v[28:31], v[186:189], v[202:205], v[28:31]
	v_mfma_f32_16x16x32_bf16 v[24:27], v[194:197], v[202:205], v[24:27]
	v_mfma_f32_16x16x32_bf16 v[20:23], v[186:189], v[210:213], v[20:23]
	v_mfma_f32_16x16x32_bf16 v[16:19], v[194:197], v[210:213], v[16:19]
	v_mfma_f32_16x16x32_bf16 v[12:15], v[186:189], v[218:221], v[12:15]
	v_mfma_f32_16x16x32_bf16 v[8:11], v[194:197], v[218:221], v[8:11]
	v_mfma_f32_16x16x32_bf16 v[4:7], v[186:189], v[226:229], v[4:7]
	v_mfma_f32_16x16x32_bf16 v[0:3], v[194:197], v[226:229], v[0:3]
	s_setprio 0
	s_barrier
	s_add_i32 s68, s68, 2
	s_add_u32 s36, s36, 0x100
	s_addc_u32 s37, s37, 0
	s_cmp_gt_u32 s68, 13
	s_cbranch_scc0 .LBB0_1275
	s_and_b64 vcc, exec, s[18:19]
	s_cbranch_vccz .LBB0_1278
	s_barrier

; #define PG8_STAGE(bufoff, gbase, voff) do { _Pragma("unroll") for (int _i = 0; _i < 2; ++_i) \
;         __builtin_amdgcn_global_load_lds((const unsigned*)((const char*)(gbase) + (voff)[_i]), (PG8_LAS unsigned*)(lds + (bufoff) + ldsw + _i * 8192), 16, 0, 0); } while (0)
; #define PG8_LDA(dst, b, h) do { _Pragma("unroll") for (int m = 0; m < 4; ++m) _Pragma("unroll") for (int k = 0; k < 2; ++k) dst[m][k] = *(const PG8_LAS bf16x8*)(lds + PG8_SA(b, h) + aoff + m * 2048 + k * 1024); } while (0)
; #define PG8_LDB(dst, b, h) do { _Pragma("unroll") for (int n = 0; n < 2; ++n) _Pragma("unroll") for (int k = 0; k < 2; ++k) dst[n][k] = *(const PG8_LAS bf16x8*)(lds + PG8_SB(b, h) + boff + n * 2048 + k * 1024); } while (0)
; #define PG8_MMA(ai, bj, At, Bt) do { __builtin_amdgcn_s_setprio(1); _Pragma("unroll") for (int m = 0; m < 4; ++m) _Pragma("unroll") for (int n = 0; n < 2; ++n) _Pragma("unroll") for (int k = 0; k < 2; ++k) \
;         acc[ai][bj][m][n] = __builtin_amdgcn_mfma_f32_16x16x32_bf16(Bt[n][k], At[m][k], acc[ai][bj][m][n], 0, 0, 0); __builtin_amdgcn_s_setprio(0); } while (0)
; template <class Epi, class Sched, bool ALIGN_EPI = false, bool SP2 = false>
; __device__ __forceinline__ void gemm_phase(PG8_LAS unsigned char* lds, const Gemm g, const Sched& S, const Epi& E) {
;     ...
;         const bool has_next = S.next(ui + 1, nxt);
;         const char* nA = has_next ? (const char*)g.A + (size_t)nxt.pm * tstepA : cA; const char* nB = has_next ? (const char*)g.Bt + (size_t)nxt.pn * tstepB : cB;
;         for (int t = 0; t < nt; t += 2) {
;             const bool last = (t == nt - 2);
;             const char* a1 = cA + PG8_AK(t + 1);
;             const char* a2 = last ? nA : cA + PG8_AK(t + 2); const char* b2 = last ? nB : cB + (size_t)(t + 2) * kstep;
;             const char* a3 = last ? nA + PG8_AK(1) : cA + PG8_AK(t + 3); const char* b3 = b2 + kstep;
;             if (last && has_next) S.a_ready(nxt);
;             if constexpr (SP2) {
;             PG8_LDB(B0, 0, 0); PG8_LDB(B1, 0, 1); PG8_SCHED; PG8_LDA(At, 0, 0); PG8_STAGE(PG8_SA(1, 1), a1 + hstepA, voffA);
;             PG8_WAIT_V(8); PG8_WAIT_L(0); PG8_BAR; PG8_MMA(0, 0, At, B0); PG8_MMA(0, 1, At, B1); PG8_BAR; PG8_SCHED;
;             PG8_LDA(At, 0, 1); PG8_STAGE(PG8_SB(0, 0), b2, voffB); PG8_STAGE(PG8_SB(0, 1), b2 + hstepB, voffB); PG8_STAGE(PG8_SA(0, 0), a2, voffA);
.LBB0_1298:
	ds_read_b128 v[0:3], v145
	ds_read_b128 v[4:7], v145 offset:1024
	ds_read_b128 v[8:11], v145 offset:2048
	ds_read_b128 v[12:15], v145 offset:3072
	ds_read_b128 v[16:19], v146
	ds_read_b128 v[20:23], v146 offset:1024
	ds_read_b128 v[24:27], v146 offset:2048
	ds_read_b128 v[28:31], v146 offset:3072
	s_ashr_i32 s31, s30, 31
	s_lshl_b64 s[34:35], s[30:31], 17
	s_add_u32 s34, s49, s34
	s_addc_u32 s35, s50, s35
	s_and_b64 s[36:37], s[4:5], exec
	s_cselect_b32 s47, s35, s41
	s_cselect_b32 s46, s34, s40
	s_ashr_i32 s29, s28, 31
	s_lshl_b64 s[36:37], s[28:29], 17
	s_add_u32 s36, s51, s36
	s_addc_u32 s37, s52, s37
	s_and_b64 s[44:45], s[4:5], exec
	s_cselect_b32 s45, s37, s43
	s_cselect_b32 s44, s36, s42
	s_add_u32 s66, s40, 0x10080
	s_addc_u32 s67, s41, 0
	s_add_i32 s78, s3, 0xc000
	s_mov_b32 m0, s78
	s_add_i32 s29, s3, 0xe000
	ds_read_b128 v[32:35], v147
	ds_read_b128 v[36:39], v147 offset:1024
	ds_read_b128 v[40:43], v147 offset:2048
	ds_read_b128 v[44:47], v147 offset:3072
	ds_read_b128 v[48:51], v147 offset:4096
	ds_read_b128 v[52:55], v147 offset:5120
	ds_read_b128 v[56:59], v147 offset:6144
	ds_read_b128 v[60:63], v147 offset:7168
	global_load_lds_dwordx4 v128, s[66:67]
	v_lshl_add_u64 v[64:65], s[66:67], 0, v[132:133]
	s_mov_b32 m0, s29
	s_nop 0
	global_load_lds_dwordx4 v132, s[66:67]
	s_waitcnt vmcnt(8)
	s_waitcnt lgkmcnt(0)
	s_barrier
	s_setprio 1
	s_waitcnt lgkmcnt(0)
	v_mfma_f32_16x16x32_bf16 v[64:67], v[0:3], v[32:35], 0
	v_mfma_f32_16x16x32_bf16 v[68:71], v[8:11], v[32:35], 0
	v_mfma_f32_16x16x32_bf16 v[72:75], v[0:3], v[40:43], 0
	v_mfma_f32_16x16x32_bf16 v[76:79], v[8:11], v[40:43], 0
	v_mfma_f32_16x16x32_bf16 v[80:83], v[0:3], v[48:51], 0
	v_mfma_f32_16x16x32_bf16 v[84:87], v[8:11], v[48:51], 0
	v_mfma_f32_16x16x32_bf16 v[88:91], v[0:3], v[56:59], 0
	v_mfma_f32_16x16x32_bf16 v[92:95], v[8:11], v[56:59], 0
	v_mfma_f32_16x16x32_bf16 v[64:67], v[4:7], v[36:39], v[64:67]
	v_mfma_f32_16x16x32_bf16 v[68:71], v[12:15], v[36:39], v[68:71]
	v_mfma_f32_16x16x32_bf16 v[72:75], v[4:7], v[44:47], v[72:75]
	v_mfma_f32_16x16x32_bf16 v[76:79], v[12:15], v[44:47], v[76:79]
	v_mfma_f32_16x16x32_bf16 v[80:83], v[4:7], v[52:55], v[80:83]
	v_mfma_f32_16x16x32_bf16 v[84:87], v[12:15], v[52:55], v[84:87]
	v_mfma_f32_16x16x32_bf16 v[88:91], v[4:7], v[60:63], v[88:91]
	v_mfma_f32_16x16x32_bf16 v[92:95], v[12:15], v[60:63], v[92:95]
	s_setprio 0
	s_setprio 1
	v_mfma_f32_16x16x32_bf16 v[96:99], v[16:19], v[32:35], 0
	v_mfma_f32_16x16x32_bf16 v[32:35], v[24:27], v[32:35], 0
	v_mfma_f32_16x16x32_bf16 v[96:99], v[20:23], v[36:39], v[96:99]
	v_mfma_f32_16x16x32_bf16 v[32:35], v[28:31], v[36:39], v[32:35]
	v_mfma_f32_16x16x32_bf16 v[36:39], v[16:19], v[40:43], 0
	v_mfma_f32_16x16x32_bf16 v[40:43], v[24:27], v[40:43], 0
	v_mfma_f32_16x16x32_bf16 v[36:39], v[20:23], v[44:47], v[36:39]
	v_mfma_f32_16x16x32_bf16 v[40:43], v[28:31], v[44:47], v[40:43]
	v_mfma_f32_16x16x32_bf16 v[44:47], v[16:19], v[48:51], 0
	v_mfma_f32_16x16x32_bf16 v[48:51], v[24:27], v[48:51], 0
	v_mfma_f32_16x16x32_bf16 v[44:47], v[20:23], v[52:55], v[44:47]
	v_mfma_f32_16x16x32_bf16 v[48:51], v[28:31], v[52:55], v[48:51]
	v_mfma_f32_16x16x32_bf16 v[52:55], v[16:19], v[56:59], 0
	v_mfma_f32_16x16x32_bf16 v[56:59], v[24:27], v[56:59], 0
	v_mfma_f32_16x16x32_bf16 v[52:55], v[20:23], v[60:63], v[52:55]
	v_mfma_f32_16x16x32_bf16 v[56:59], v[28:31], v[60:63], v[56:59]
	s_setprio 0
	s_barrier
	s_add_i32 s68, s59, s53
	v_lshl_add_u64 v[140:141], s[42:43], 0, v[130:131]
	s_add_i32 s31, s68, 0x2000
	v_lshl_add_u64 v[148:149], v[140:141], 0, s[16:17]
	s_mov_b32 m0, s68
	v_lshl_add_u64 v[212:213], s[42:43], 0, v[134:135]
	s_add_u32 s70, s42, 0x10100
	ds_read_b128 v[60:63], v147 offset:16384
	ds_read_b128 v[100:103], v147 offset:17408
	ds_read_b128 v[104:107], v147 offset:18432
	ds_read_b128 v[108:111], v147 offset:19456
	ds_read_b128 v[112:115], v147 offset:20480
	ds_read_b128 v[116:119], v147 offset:21504
	ds_read_b128 v[120:123], v147 offset:22528
	ds_read_b128 v[124:127], v147 offset:23552
	global_load_lds_dwordx4 v[148:149], off
	v_lshl_add_u64 v[148:149], v[212:213], 0, s[16:17]
	s_mov_b32 m0, s31
	s_addc_u32 s71, s43, 0
	s_add_i32 s66, s60, s53
	global_load_lds_dwordx4 v[148:149], off
	s_mov_b32 m0, s66
	s_add_i32 s67, s66, 0x2000
	global_load_lds_dwordx4 v130, s[70:71]
	s_mov_b32 m0, s67
	v_lshl_add_u64 v[214:215], s[40:41], 0, v[128:129]
	global_load_lds_dwordx4 v134, s[70:71]
	v_lshl_add_u64 v[148:149], v[214:215], 0, s[16:17]
	s_mov_b32 m0, s3
	v_lshl_add_u64 v[216:217], s[40:41], 0, v[132:133]
	global_load_lds_dwordx4 v[148:149], off
	v_lshl_add_u64 v[148:149], v[216:217], 0, s[16:17]
	s_mov_b32 m0, s39
	s_nop 0
	global_load_lds_dwordx4 v[148:149], off
	s_waitcnt vmcnt(8)
	s_waitcnt lgkmcnt(0)
	s_barrier
; #define PG8_STAGE(bufoff, gbase, voff) do { _Pragma("unroll") for (int _i = 0; _i < 2; ++_i) \
;         __builtin_amdgcn_global_load_lds((const unsigned*)((const char*)(gbase) + (voff)[_i]), (PG8_LAS unsigned*)(lds + (bufoff) + ldsw + _i * 8192), 16, 0, 0); } while (0)
; #define PG8_LDA(dst, b, h) do { _Pragma("unroll") for (int m = 0; m < 4; ++m) _Pragma("unroll") for (int k = 0; k < 2; ++k) dst[m][k] = *(const PG8_LAS bf16x8*)(lds + PG8_SA(b, h) + aoff + m * 2048 + k * 1024); } while (0)
; #define PG8_LDB(dst, b, h) do { _Pragma("unroll") for (int n = 0; n < 2; ++n) _Pragma("unroll") for (int k = 0; k < 2; ++k) dst[n][k] = *(const PG8_LAS bf16x8*)(lds + PG8_SB(b, h) + boff + n * 2048 + k * 1024); } while (0)
; #define PG8_MMA(ai, bj, At, Bt) do { __builtin_amdgcn_s_setprio(1); _Pragma("unroll") for (int m = 0; m < 4; ++m) _Pragma("unroll") for (int n = 0; n < 2; ++n) _Pragma("unroll") for (int k = 0; k < 2; ++k) \
;         acc[ai][bj][m][n] = __builtin_amdgcn_mfma_f32_16x16x32_bf16(Bt[n][k], At[m][k], acc[ai][bj][m][n], 0, 0, 0); __builtin_amdgcn_s_setprio(0); } while (0)
; #define PG8_WAIT_V(n) asm volatile("s_waitcnt vmcnt(" #n ")" ::: "memory")
; #define PG8_WAIT_L(n) asm volatile("s_waitcnt lgkmcnt(" #n ")" ::: "memory")
; #define PG8_BAR __builtin_amdgcn_s_barrier()
; #define PG8_SCHED __builtin_amdgcn_sched_barrier(0)
; template <class Epi, class Sched, bool ALIGN_EPI = false, bool SP2 = false>
; __device__ __forceinline__ void gemm_phase(PG8_LAS unsigned char* lds, const Gemm g, const Sched& S, const Epi& E) {
;     ...
;             PG8_LDA(At, 0, 1); PG8_STAGE(PG8_SB(0, 0), b2, voffB); PG8_STAGE(PG8_SB(0, 1), b2 + hstepB, voffB); PG8_STAGE(PG8_SA(0, 0), a2, voffA);
;             PG8_WAIT_V(8); PG8_WAIT_L(0); PG8_BAR; PG8_MMA(1, 0, At, B0); PG8_MMA(1, 1, At, B1); PG8_BAR; PG8_SCHED;
;             PG8_LDB(B0, 1, 0); PG8_LDB(B1, 1, 1); PG8_SCHED; PG8_LDA(At, 1, 0); PG8_STAGE(PG8_SA(0, 1), a2 + hstepA, voffA);
;             PG8_WAIT_V(8); PG8_WAIT_L(0); PG8_BAR; PG8_MMA(0, 0, At, B0); PG8_MMA(0, 1, At, B1); PG8_BAR; PG8_SCHED;
	s_setprio 1
	s_waitcnt lgkmcnt(0)
	v_mfma_f32_16x16x32_bf16 v[148:151], v[0:3], v[60:63], 0
	v_mfma_f32_16x16x32_bf16 v[156:159], v[0:3], v[104:107], 0
	v_mfma_f32_16x16x32_bf16 v[164:167], v[0:3], v[112:115], 0
	v_mfma_f32_16x16x32_bf16 v[0:3], v[0:3], v[120:123], 0
	v_mfma_f32_16x16x32_bf16 v[148:151], v[4:7], v[100:103], v[148:151]
	v_mfma_f32_16x16x32_bf16 v[156:159], v[4:7], v[108:111], v[156:159]
	v_mfma_f32_16x16x32_bf16 v[164:167], v[4:7], v[116:119], v[164:167]
	v_mfma_f32_16x16x32_bf16 v[0:3], v[4:7], v[124:127], v[0:3]
	v_mfma_f32_16x16x32_bf16 v[4:7], v[8:11], v[120:123], 0
	v_mfma_f32_16x16x32_bf16 v[152:155], v[8:11], v[60:63], 0
	v_mfma_f32_16x16x32_bf16 v[160:163], v[8:11], v[104:107], 0
	v_mfma_f32_16x16x32_bf16 v[168:171], v[8:11], v[112:115], 0
	v_mfma_f32_16x16x32_bf16 v[4:7], v[12:15], v[124:127], v[4:7]
	v_mfma_f32_16x16x32_bf16 v[152:155], v[12:15], v[100:103], v[152:155]
	v_mfma_f32_16x16x32_bf16 v[160:163], v[12:15], v[108:111], v[160:163]
	v_mfma_f32_16x16x32_bf16 v[168:171], v[12:15], v[116:119], v[168:171]
	s_setprio 0
	s_setprio 1
	v_mfma_f32_16x16x32_bf16 v[8:11], v[16:19], v[60:63], 0
	v_mfma_f32_16x16x32_bf16 v[12:15], v[24:27], v[60:63], 0
	v_mfma_f32_16x16x32_bf16 v[8:11], v[20:23], v[100:103], v[8:11]
	v_mfma_f32_16x16x32_bf16 v[12:15], v[28:31], v[100:103], v[12:15]
	v_mfma_f32_16x16x32_bf16 v[60:63], v[16:19], v[104:107], 0
	v_mfma_f32_16x16x32_bf16 v[100:103], v[24:27], v[104:107], 0
	v_mfma_f32_16x16x32_bf16 v[104:107], v[16:19], v[112:115], 0
	v_mfma_f32_16x16x32_bf16 v[16:19], v[16:19], v[120:123], 0
	v_mfma_f32_16x16x32_bf16 v[60:63], v[20:23], v[108:111], v[60:63]
	v_mfma_f32_16x16x32_bf16 v[100:103], v[28:31], v[108:111], v[100:103]
	v_mfma_f32_16x16x32_bf16 v[104:107], v[20:23], v[116:119], v[104:107]
	v_mfma_f32_16x16x32_bf16 v[108:111], v[24:27], v[112:115], 0
	v_mfma_f32_16x16x32_bf16 v[16:19], v[20:23], v[124:127], v[16:19]
	v_mfma_f32_16x16x32_bf16 v[20:23], v[24:27], v[120:123], 0
	v_mfma_f32_16x16x32_bf16 v[108:111], v[28:31], v[116:119], v[108:111]
	v_mfma_f32_16x16x32_bf16 v[20:23], v[28:31], v[124:127], v[20:23]
	s_setprio 0
	s_barrier
	s_add_i32 s79, 0, 0x18000
	s_add_i32 s80, 0, 0x1c000
	v_add_u32_e32 v224, s79, v143
	v_add_u32_e32 v232, s80, v143
	ds_read_b128 v[24:27], v224
	ds_read_b128 v[28:31], v224 offset:1024
	ds_read_b128 v[112:115], v224 offset:2048
	ds_read_b128 v[116:119], v224 offset:3072
	ds_read_b128 v[120:123], v232
	ds_read_b128 v[124:127], v232 offset:1024
	ds_read_b128 v[172:175], v232 offset:2048
	ds_read_b128 v[176:179], v232 offset:3072
	s_add_u32 s70, s40, 0x10100
	s_addc_u32 s71, s41, 0
	s_mov_b32 m0, s54
	ds_read_b128 v[180:183], v147 offset:32768
	ds_read_b128 v[184:187], v147 offset:33792
	ds_read_b128 v[188:191], v147 offset:34816
	ds_read_b128 v[192:195], v147 offset:35840
	ds_read_b128 v[196:199], v147 offset:36864
	ds_read_b128 v[200:203], v147 offset:37888
	ds_read_b128 v[204:207], v147 offset:38912
	ds_read_b128 v[208:211], v147 offset:39936
	global_load_lds_dwordx4 v128, s[70:71]
	v_lshl_add_u64 v[218:219], s[70:71], 0, v[132:133]
	s_mov_b32 m0, s55
	s_nop 0
	global_load_lds_dwordx4 v132, s[70:71]
	s_waitcnt vmcnt(8)
	s_waitcnt lgkmcnt(0)
	s_barrier
	s_setprio 1
	s_waitcnt lgkmcnt(0)
	v_mfma_f32_16x16x32_bf16 v[64:67], v[24:27], v[180:183], v[64:67]
	v_mfma_f32_16x16x32_bf16 v[68:71], v[112:115], v[180:183], v[68:71]
	v_mfma_f32_16x16x32_bf16 v[72:75], v[24:27], v[188:191], v[72:75]
	v_mfma_f32_16x16x32_bf16 v[76:79], v[112:115], v[188:191], v[76:79]
	v_mfma_f32_16x16x32_bf16 v[80:83], v[24:27], v[196:199], v[80:83]
	v_mfma_f32_16x16x32_bf16 v[84:87], v[112:115], v[196:199], v[84:87]
	v_mfma_f32_16x16x32_bf16 v[88:91], v[24:27], v[204:207], v[88:91]
	v_mfma_f32_16x16x32_bf16 v[92:95], v[112:115], v[204:207], v[92:95]
	v_mfma_f32_16x16x32_bf16 v[64:67], v[28:31], v[184:187], v[64:67]
	v_mfma_f32_16x16x32_bf16 v[68:71], v[116:119], v[184:187], v[68:71]
	v_mfma_f32_16x16x32_bf16 v[72:75], v[28:31], v[192:195], v[72:75]
	v_mfma_f32_16x16x32_bf16 v[76:79], v[116:119], v[192:195], v[76:79]
	v_mfma_f32_16x16x32_bf16 v[80:83], v[28:31], v[200:203], v[80:83]
	v_mfma_f32_16x16x32_bf16 v[84:87], v[116:119], v[200:203], v[84:87]
	v_mfma_f32_16x16x32_bf16 v[88:91], v[28:31], v[208:211], v[88:91]
	v_mfma_f32_16x16x32_bf16 v[92:95], v[116:119], v[208:211], v[92:95]
	s_setprio 0
	s_setprio 1
	v_mfma_f32_16x16x32_bf16 v[96:99], v[120:123], v[180:183], v[96:99]
	v_mfma_f32_16x16x32_bf16 v[32:35], v[172:175], v[180:183], v[32:35]
	v_mfma_f32_16x16x32_bf16 v[36:39], v[120:123], v[188:191], v[36:39]
	v_mfma_f32_16x16x32_bf16 v[40:43], v[172:175], v[188:191], v[40:43]
	v_mfma_f32_16x16x32_bf16 v[44:47], v[120:123], v[196:199], v[44:47]
	v_mfma_f32_16x16x32_bf16 v[48:51], v[172:175], v[196:199], v[48:51]
	v_mfma_f32_16x16x32_bf16 v[52:55], v[120:123], v[204:207], v[52:55]
	v_mfma_f32_16x16x32_bf16 v[56:59], v[172:175], v[204:207], v[56:59]
	v_mfma_f32_16x16x32_bf16 v[96:99], v[124:127], v[184:187], v[96:99]
	v_mfma_f32_16x16x32_bf16 v[32:35], v[176:179], v[184:187], v[32:35]
	v_mfma_f32_16x16x32_bf16 v[36:39], v[124:127], v[192:195], v[36:39]
	v_mfma_f32_16x16x32_bf16 v[40:43], v[176:179], v[192:195], v[40:43]
	v_mfma_f32_16x16x32_bf16 v[44:47], v[124:127], v[200:203], v[44:47]
	v_mfma_f32_16x16x32_bf16 v[48:51], v[176:179], v[200:203], v[48:51]
	v_mfma_f32_16x16x32_bf16 v[52:55], v[124:127], v[208:211], v[52:55]
	v_mfma_f32_16x16x32_bf16 v[56:59], v[176:179], v[208:211], v[56:59]
	s_setprio 0
	s_barrier
; #define PG8_STAGE(bufoff, gbase, voff) do { _Pragma("unroll") for (int _i = 0; _i < 2; ++_i) \
;         __builtin_amdgcn_global_load_lds((const unsigned*)((const char*)(gbase) + (voff)[_i]), (PG8_LAS unsigned*)(lds + (bufoff) + ldsw + _i * 8192), 16, 0, 0); } while (0)
; #define PG8_LDA(dst, b, h) do { _Pragma("unroll") for (int m = 0; m < 4; ++m) _Pragma("unroll") for (int k = 0; k < 2; ++k) dst[m][k] = *(const PG8_LAS bf16x8*)(lds + PG8_SA(b, h) + aoff + m * 2048 + k * 1024); } while (0)
; #define PG8_LDB(dst, b, h) do { _Pragma("unroll") for (int n = 0; n < 2; ++n) _Pragma("unroll") for (int k = 0; k < 2; ++k) dst[n][k] = *(const PG8_LAS bf16x8*)(lds + PG8_SB(b, h) + boff + n * 2048 + k * 1024); } while (0)
; #define PG8_MMA(ai, bj, At, Bt) do { __builtin_amdgcn_s_setprio(1); _Pragma("unroll") for (int m = 0; m < 4; ++m) _Pragma("unroll") for (int n = 0; n < 2; ++n) _Pragma("unroll") for (int k = 0; k < 2; ++k) \
;         acc[ai][bj][m][n] = __builtin_amdgcn_mfma_f32_16x16x32_bf16(Bt[n][k], At[m][k], acc[ai][bj][m][n], 0, 0, 0); __builtin_amdgcn_s_setprio(0); } while (0)
; #define PG8_WAIT_V(n) asm volatile("s_waitcnt vmcnt(" #n ")" ::: "memory")
; #define PG8_WAIT_L(n) asm volatile("s_waitcnt lgkmcnt(" #n ")" ::: "memory")
; #define PG8_BAR __builtin_amdgcn_s_barrier()
; #define PG8_SCHED __builtin_amdgcn_sched_barrier(0)
; template <class Epi, class Sched, bool ALIGN_EPI = false, bool SP2 = false>
; __device__ __forceinline__ void gemm_phase(PG8_LAS unsigned char* lds, const Gemm g, const Sched& S, const Epi& E) {
;     ...
;             PG8_LDB(B0, 0, 0); PG8_LDB(B1, 0, 1); PG8_SCHED; PG8_LDA(At, 0, 0); PG8_STAGE(PG8_SA(1, 1), a1 + hstepA, voffA);
;             PG8_WAIT_V(8); PG8_WAIT_L(0); PG8_BAR; PG8_MMA(0, 0, At, B0); PG8_MMA(0, 1, At, B1); PG8_BAR; PG8_SCHED;
;     ...
;             PG8_LDA(At, 1, 1); PG8_STAGE(PG8_SB(1, 0), b3, voffB); PG8_STAGE(PG8_SB(1, 1), b3 + hstepB, voffB); PG8_STAGE(PG8_SA(1, 0), a3, voffA);
;             PG8_WAIT_V(8); PG8_WAIT_L(0); PG8_BAR; PG8_MMA(1, 0, At, B0); PG8_MMA(1, 1, At, B1); PG8_BAR; PG8_SCHED;
	s_add_i32 s79, s79, s53
	s_add_i32 s69, s79, 0x2000
	v_lshl_add_u64 v[140:141], v[140:141], 0, s[18:19]
	s_mov_b32 m0, s79
	s_add_u32 s70, s42, 0x10180
	ds_read_b128 v[180:183], v147 offset:49152
	ds_read_b128 v[184:187], v147 offset:50176
	ds_read_b128 v[188:191], v147 offset:51200
	ds_read_b128 v[192:195], v147 offset:52224
	ds_read_b128 v[196:199], v147 offset:53248
	ds_read_b128 v[200:203], v147 offset:54272
	ds_read_b128 v[204:207], v147 offset:55296
	ds_read_b128 v[208:211], v147 offset:56320
	global_load_lds_dwordx4 v[140:141], off
	v_lshl_add_u64 v[140:141], v[212:213], 0, s[18:19]
	s_mov_b32 m0, s69
	s_addc_u32 s71, s43, 0
	s_add_i32 s42, s80, s53
	global_load_lds_dwordx4 v[140:141], off
	s_mov_b32 m0, s42
	s_add_i32 s43, s42, 0x2000
	global_load_lds_dwordx4 v130, s[70:71]
	s_mov_b32 m0, s43
	s_nop 0
	global_load_lds_dwordx4 v134, s[70:71]
	v_lshl_add_u64 v[140:141], v[214:215], 0, s[18:19]
	s_mov_b32 m0, s56
	s_nop 0
	global_load_lds_dwordx4 v[140:141], off
	v_lshl_add_u64 v[140:141], v[216:217], 0, s[18:19]
	s_mov_b32 m0, s57
	s_nop 0
	global_load_lds_dwordx4 v[140:141], off
	s_waitcnt vmcnt(8)
	s_waitcnt lgkmcnt(0)
	s_barrier
	s_setprio 1
	s_waitcnt lgkmcnt(0)
	v_mfma_f32_16x16x32_bf16 v[0:3], v[24:27], v[204:207], v[0:3]
	v_mfma_f32_16x16x32_bf16 v[4:7], v[112:115], v[204:207], v[4:7]
	v_mfma_f32_16x16x32_bf16 v[148:151], v[24:27], v[180:183], v[148:151]
	v_mfma_f32_16x16x32_bf16 v[152:155], v[112:115], v[180:183], v[152:155]
	v_mfma_f32_16x16x32_bf16 v[156:159], v[24:27], v[188:191], v[156:159]
	v_mfma_f32_16x16x32_bf16 v[160:163], v[112:115], v[188:191], v[160:163]
	v_mfma_f32_16x16x32_bf16 v[164:167], v[24:27], v[196:199], v[164:167]
	v_mfma_f32_16x16x32_bf16 v[168:171], v[112:115], v[196:199], v[168:171]
	v_mfma_f32_16x16x32_bf16 v[0:3], v[28:31], v[208:211], v[0:3]
	v_mfma_f32_16x16x32_bf16 v[4:7], v[116:119], v[208:211], v[4:7]
	v_mfma_f32_16x16x32_bf16 v[148:151], v[28:31], v[184:187], v[148:151]
	v_mfma_f32_16x16x32_bf16 v[152:155], v[116:119], v[184:187], v[152:155]
	v_mfma_f32_16x16x32_bf16 v[156:159], v[28:31], v[192:195], v[156:159]
	v_mfma_f32_16x16x32_bf16 v[160:163], v[116:119], v[192:195], v[160:163]
	v_mfma_f32_16x16x32_bf16 v[164:167], v[28:31], v[200:203], v[164:167]
	v_mfma_f32_16x16x32_bf16 v[168:171], v[116:119], v[200:203], v[168:171]
	s_setprio 0
	s_setprio 1
	v_mfma_f32_16x16x32_bf16 v[8:11], v[120:123], v[180:183], v[8:11]
	v_mfma_f32_16x16x32_bf16 v[12:15], v[172:175], v[180:183], v[12:15]
	v_mfma_f32_16x16x32_bf16 v[24:27], v[120:123], v[188:191], v[60:63]
	v_mfma_f32_16x16x32_bf16 v[28:31], v[172:175], v[188:191], v[100:103]
	v_mfma_f32_16x16x32_bf16 v[60:63], v[120:123], v[196:199], v[104:107]
	v_mfma_f32_16x16x32_bf16 v[100:103], v[172:175], v[196:199], v[108:111]
	v_mfma_f32_16x16x32_bf16 v[16:19], v[120:123], v[204:207], v[16:19]
	v_mfma_f32_16x16x32_bf16 v[20:23], v[172:175], v[204:207], v[20:23]
	v_mfma_f32_16x16x32_bf16 v[8:11], v[124:127], v[184:187], v[8:11]
	v_mfma_f32_16x16x32_bf16 v[12:15], v[176:179], v[184:187], v[12:15]
	v_mfma_f32_16x16x32_bf16 v[24:27], v[124:127], v[192:195], v[24:27]
	v_mfma_f32_16x16x32_bf16 v[28:31], v[176:179], v[192:195], v[28:31]
	v_mfma_f32_16x16x32_bf16 v[60:63], v[124:127], v[200:203], v[60:63]
	v_mfma_f32_16x16x32_bf16 v[100:103], v[176:179], v[200:203], v[100:103]
	v_mfma_f32_16x16x32_bf16 v[16:19], v[124:127], v[208:211], v[16:19]
	v_mfma_f32_16x16x32_bf16 v[20:23], v[176:179], v[208:211], v[20:23]
	s_setprio 0
	s_barrier
	ds_read_b128 v[104:107], v145
	ds_read_b128 v[108:111], v145 offset:1024
	ds_read_b128 v[112:115], v145 offset:2048
	ds_read_b128 v[116:119], v145 offset:3072
	ds_read_b128 v[120:123], v146
	ds_read_b128 v[124:127], v146 offset:1024
	ds_read_b128 v[172:175], v146 offset:2048
	ds_read_b128 v[176:179], v146 offset:3072
	s_add_u32 s40, s40, 0x10180
	s_addc_u32 s41, s41, 0
	s_mov_b32 m0, s78
	ds_read_b128 v[180:183], v147
	ds_read_b128 v[184:187], v147 offset:1024
	ds_read_b128 v[188:191], v147 offset:2048
	ds_read_b128 v[192:195], v147 offset:3072
	ds_read_b128 v[196:199], v147 offset:4096
	ds_read_b128 v[200:203], v147 offset:5120
	ds_read_b128 v[204:207], v147 offset:6144
	ds_read_b128 v[208:211], v147 offset:7168
	global_load_lds_dwordx4 v128, s[40:41]
	v_lshl_add_u64 v[140:141], s[40:41], 0, v[132:133]
	s_mov_b32 m0, s29
	s_nop 0
	global_load_lds_dwordx4 v132, s[40:41]
	s_waitcnt vmcnt(8)
	s_waitcnt lgkmcnt(0)
	s_barrier
	s_setprio 1
	s_waitcnt lgkmcnt(0)
	v_mfma_f32_16x16x32_bf16 v[88:91], v[104:107], v[204:207], v[88:91]
	v_mfma_f32_16x16x32_bf16 v[64:67], v[104:107], v[180:183], v[64:67]
	v_mfma_f32_16x16x32_bf16 v[68:71], v[112:115], v[180:183], v[68:71]
	v_mfma_f32_16x16x32_bf16 v[72:75], v[104:107], v[188:191], v[72:75]
	v_mfma_f32_16x16x32_bf16 v[76:79], v[112:115], v[188:191], v[76:79]
	v_mfma_f32_16x16x32_bf16 v[80:83], v[104:107], v[196:199], v[80:83]
	v_mfma_f32_16x16x32_bf16 v[84:87], v[112:115], v[196:199], v[84:87]
	v_mfma_f32_16x16x32_bf16 v[212:215], v[108:111], v[208:211], v[88:91]
	v_mfma_f32_16x16x32_bf16 v[88:91], v[112:115], v[204:207], v[92:95]
	v_mfma_f32_16x16x32_bf16 v[64:67], v[108:111], v[184:187], v[64:67]
	v_mfma_f32_16x16x32_bf16 v[68:71], v[116:119], v[184:187], v[68:71]
	v_mfma_f32_16x16x32_bf16 v[72:75], v[108:111], v[192:195], v[72:75]
	v_mfma_f32_16x16x32_bf16 v[76:79], v[116:119], v[192:195], v[76:79]
	v_mfma_f32_16x16x32_bf16 v[80:83], v[108:111], v[200:203], v[80:83]
	v_mfma_f32_16x16x32_bf16 v[84:87], v[116:119], v[200:203], v[84:87]
	v_mfma_f32_16x16x32_bf16 v[92:95], v[116:119], v[208:211], v[88:91]
	s_setprio 0
	s_setprio 1
	v_mfma_f32_16x16x32_bf16 v[48:51], v[172:175], v[196:199], v[48:51]
	v_mfma_f32_16x16x32_bf16 v[88:91], v[120:123], v[180:183], v[96:99]
	v_mfma_f32_16x16x32_bf16 v[32:35], v[172:175], v[180:183], v[32:35]
	v_mfma_f32_16x16x32_bf16 v[36:39], v[120:123], v[188:191], v[36:39]
	v_mfma_f32_16x16x32_bf16 v[40:43], v[172:175], v[188:191], v[40:43]
	v_mfma_f32_16x16x32_bf16 v[44:47], v[120:123], v[196:199], v[44:47]
	v_mfma_f32_16x16x32_bf16 v[180:183], v[176:179], v[200:203], v[48:51]
	v_mfma_f32_16x16x32_bf16 v[48:51], v[120:123], v[204:207], v[52:55]
	v_mfma_f32_16x16x32_bf16 v[32:35], v[176:179], v[184:187], v[32:35]
	v_mfma_f32_16x16x32_bf16 v[36:39], v[124:127], v[192:195], v[36:39]
	v_mfma_f32_16x16x32_bf16 v[40:43], v[176:179], v[192:195], v[40:43]
	v_mfma_f32_16x16x32_bf16 v[44:47], v[124:127], v[200:203], v[44:47]
	v_mfma_f32_16x16x32_bf16 v[52:55], v[124:127], v[208:211], v[48:51]
	v_mfma_f32_16x16x32_bf16 v[48:51], v[172:175], v[204:207], v[56:59]
	v_mfma_f32_16x16x32_bf16 v[216:219], v[124:127], v[184:187], v[88:91]
	v_mfma_f32_16x16x32_bf16 v[184:187], v[176:179], v[208:211], v[48:51]
	s_setprio 0
	s_barrier
; #define PG8_STAGE(bufoff, gbase, voff) do { _Pragma("unroll") for (int _i = 0; _i < 2; ++_i) \
;         __builtin_amdgcn_global_load_lds((const unsigned*)((const char*)(gbase) + (voff)[_i]), (PG8_LAS unsigned*)(lds + (bufoff) + ldsw + _i * 8192), 16, 0, 0); } while (0)
; #define PG8_LDA(dst, b, h) do { _Pragma("unroll") for (int m = 0; m < 4; ++m) _Pragma("unroll") for (int k = 0; k < 2; ++k) dst[m][k] = *(const PG8_LAS bf16x8*)(lds + PG8_SA(b, h) + aoff + m * 2048 + k * 1024); } while (0)
; #define PG8_LDB(dst, b, h) do { _Pragma("unroll") for (int n = 0; n < 2; ++n) _Pragma("unroll") for (int k = 0; k < 2; ++k) dst[n][k] = *(const PG8_LAS bf16x8*)(lds + PG8_SB(b, h) + boff + n * 2048 + k * 1024); } while (0)
; #define PG8_MMA(ai, bj, At, Bt) do { __builtin_amdgcn_s_setprio(1); _Pragma("unroll") for (int m = 0; m < 4; ++m) _Pragma("unroll") for (int n = 0; n < 2; ++n) _Pragma("unroll") for (int k = 0; k < 2; ++k) \
;         acc[ai][bj][m][n] = __builtin_amdgcn_mfma_f32_16x16x32_bf16(Bt[n][k], At[m][k], acc[ai][bj][m][n], 0, 0, 0); __builtin_amdgcn_s_setprio(0); } while (0)
; #define PG8_WAIT_V(n) asm volatile("s_waitcnt vmcnt(" #n ")" ::: "memory")
; #define PG8_WAIT_L(n) asm volatile("s_waitcnt lgkmcnt(" #n ")" ::: "memory")
; #define PG8_BAR __builtin_amdgcn_s_barrier()
; #define PG8_SCHED __builtin_amdgcn_sched_barrier(0)
; template <class Epi, class Sched, bool ALIGN_EPI = false, bool SP2 = false>
; __device__ __forceinline__ void gemm_phase(PG8_LAS unsigned char* lds, const Gemm g, const Sched& S, const Epi& E) {
;     ...
;             PG8_LDA(At, 0, 1); PG8_STAGE(PG8_SB(0, 0), b2, voffB); PG8_STAGE(PG8_SB(0, 1), b2 + hstepB, voffB); PG8_STAGE(PG8_SA(0, 0), a2, voffA);
;             PG8_WAIT_V(8); PG8_WAIT_L(0); PG8_BAR; PG8_MMA(1, 0, At, B0); PG8_MMA(1, 1, At, B1); PG8_BAR; PG8_SCHED;
;             PG8_LDB(B0, 1, 0); PG8_LDB(B1, 1, 1); PG8_SCHED; PG8_LDA(At, 1, 0); PG8_STAGE(PG8_SA(0, 1), a2 + hstepA, voffA);
;             PG8_WAIT_V(8); PG8_WAIT_L(0); PG8_BAR; PG8_MMA(0, 0, At, B0); PG8_MMA(0, 1, At, B1); PG8_BAR; PG8_SCHED;
	s_mov_b32 m0, s68
	v_lshl_add_u64 v[140:141], s[44:45], 0, v[130:131]
	s_add_u32 s40, s44, 0x10000
	s_nop 0
	ds_read_b128 v[48:51], v147 offset:16384
	ds_read_b128 v[56:59], v147 offset:17408
	ds_read_b128 v[88:91], v147 offset:18432
	ds_read_b128 v[96:99], v147 offset:19456
	ds_read_b128 v[188:191], v147 offset:20480
	ds_read_b128 v[192:195], v147 offset:21504
	ds_read_b128 v[196:199], v147 offset:22528
	ds_read_b128 v[200:203], v147 offset:23552
	global_load_lds_dwordx4 v130, s[44:45]
	v_lshl_add_u64 v[252:253], s[44:45], 0, v[134:135]
	s_mov_b32 m0, s31
	s_addc_u32 s41, s45, 0
	global_load_lds_dwordx4 v134, s[44:45]
	s_mov_b32 m0, s66
	v_lshl_add_u64 v[136:137], s[46:47], 0, v[128:129]
	global_load_lds_dwordx4 v130, s[40:41]
	v_lshl_add_u64 v[204:205], s[40:41], 0, v[134:135]
	s_mov_b32 m0, s67
	v_lshl_add_u64 v[138:139], s[46:47], 0, v[132:133]
	global_load_lds_dwordx4 v134, s[40:41]
	s_mov_b32 m0, s3
	s_nop 0
	global_load_lds_dwordx4 v128, s[46:47]
	s_mov_b32 m0, s39
	s_nop 0
	global_load_lds_dwordx4 v132, s[46:47]
	s_waitcnt vmcnt(8)
	s_waitcnt lgkmcnt(0)
	s_barrier
	s_setprio 1
	s_waitcnt lgkmcnt(0)
	v_mfma_f32_16x16x32_bf16 v[0:3], v[104:107], v[196:199], v[0:3]
	v_mfma_f32_16x16x32_bf16 v[4:7], v[112:115], v[196:199], v[4:7]
	v_mfma_f32_16x16x32_bf16 v[148:151], v[104:107], v[48:51], v[148:151]
	v_mfma_f32_16x16x32_bf16 v[152:155], v[112:115], v[48:51], v[152:155]
	v_mfma_f32_16x16x32_bf16 v[156:159], v[104:107], v[88:91], v[156:159]
	v_mfma_f32_16x16x32_bf16 v[160:163], v[112:115], v[88:91], v[160:163]
	v_mfma_f32_16x16x32_bf16 v[164:167], v[104:107], v[188:191], v[164:167]
	v_mfma_f32_16x16x32_bf16 v[168:171], v[112:115], v[188:191], v[168:171]
	v_mfma_f32_16x16x32_bf16 v[0:3], v[108:111], v[200:203], v[0:3]
	v_mfma_f32_16x16x32_bf16 v[4:7], v[116:119], v[200:203], v[4:7]
	v_mfma_f32_16x16x32_bf16 v[148:151], v[108:111], v[56:59], v[148:151]
	v_mfma_f32_16x16x32_bf16 v[152:155], v[116:119], v[56:59], v[152:155]
	v_mfma_f32_16x16x32_bf16 v[156:159], v[108:111], v[96:99], v[156:159]
	v_mfma_f32_16x16x32_bf16 v[160:163], v[116:119], v[96:99], v[160:163]
	v_mfma_f32_16x16x32_bf16 v[164:167], v[108:111], v[192:195], v[164:167]
	v_mfma_f32_16x16x32_bf16 v[168:171], v[116:119], v[192:195], v[168:171]
	s_setprio 0
	s_setprio 1
	v_mfma_f32_16x16x32_bf16 v[12:15], v[172:175], v[48:51], v[12:15]
	v_mfma_f32_16x16x32_bf16 v[204:207], v[176:179], v[56:59], v[12:15]
	v_mfma_f32_16x16x32_bf16 v[12:15], v[120:123], v[88:91], v[24:27]
	v_mfma_f32_16x16x32_bf16 v[24:27], v[124:127], v[96:99], v[12:15]
	v_mfma_f32_16x16x32_bf16 v[12:15], v[172:175], v[88:91], v[28:31]
	v_mfma_f32_16x16x32_bf16 v[208:211], v[176:179], v[96:99], v[12:15]
	v_mfma_f32_16x16x32_bf16 v[12:15], v[120:123], v[188:191], v[60:63]
	v_mfma_f32_16x16x32_bf16 v[220:223], v[124:127], v[192:195], v[12:15]
	v_mfma_f32_16x16x32_bf16 v[12:15], v[172:175], v[188:191], v[100:103]
	v_mfma_f32_16x16x32_bf16 v[8:11], v[120:123], v[48:51], v[8:11]
	v_mfma_f32_16x16x32_bf16 v[188:191], v[176:179], v[192:195], v[12:15]
	v_mfma_f32_16x16x32_bf16 v[12:15], v[120:123], v[196:199], v[16:19]
	v_mfma_f32_16x16x32_bf16 v[8:11], v[124:127], v[56:59], v[8:11]
	v_mfma_f32_16x16x32_bf16 v[192:195], v[124:127], v[200:203], v[12:15]
	v_mfma_f32_16x16x32_bf16 v[12:15], v[172:175], v[196:199], v[20:23]
	v_mfma_f32_16x16x32_bf16 v[172:175], v[176:179], v[200:203], v[12:15]
	s_setprio 0
	s_barrier
	s_nop 4
	ds_read_b128 v[12:15], v224
	ds_read_b128 v[16:19], v224 offset:1024
	ds_read_b128 v[176:179], v224 offset:2048
	ds_read_b128 v[196:199], v224 offset:3072
	ds_read_b128 v[200:203], v232
	ds_read_b128 v[224:227], v232 offset:1024
	ds_read_b128 v[228:231], v232 offset:2048
	ds_read_b128 v[232:235], v232 offset:3072
	s_add_u32 s40, s46, 0x10000
	s_addc_u32 s41, s47, 0
	s_mov_b32 m0, s54
	ds_read_b128 v[20:23], v147 offset:32768
	ds_read_b128 v[28:31], v147 offset:33792
	ds_read_b128 v[60:63], v147 offset:34816
	ds_read_b128 v[100:103], v147 offset:35840
	ds_read_b128 v[236:239], v147 offset:36864
	ds_read_b128 v[240:243], v147 offset:37888
	ds_read_b128 v[244:247], v147 offset:38912
	ds_read_b128 v[248:251], v147 offset:39936
	global_load_lds_dwordx4 v128, s[40:41]
	v_lshl_add_u64 v[48:49], s[40:41], 0, v[132:133]
	s_mov_b32 m0, s55
	s_nop 0
	global_load_lds_dwordx4 v132, s[40:41]
	s_waitcnt vmcnt(8)
	s_waitcnt lgkmcnt(0)
	s_barrier
; #define PG8_STAGE(bufoff, gbase, voff) do { _Pragma("unroll") for (int _i = 0; _i < 2; ++_i) \
;         __builtin_amdgcn_global_load_lds((const unsigned*)((const char*)(gbase) + (voff)[_i]), (PG8_LAS unsigned*)(lds + (bufoff) + ldsw + _i * 8192), 16, 0, 0); } while (0)
; #define PG8_LDA(dst, b, h) do { _Pragma("unroll") for (int m = 0; m < 4; ++m) _Pragma("unroll") for (int k = 0; k < 2; ++k) dst[m][k] = *(const PG8_LAS bf16x8*)(lds + PG8_SA(b, h) + aoff + m * 2048 + k * 1024); } while (0)
; #define PG8_MMA(ai, bj, At, Bt) do { __builtin_amdgcn_s_setprio(1); _Pragma("unroll") for (int m = 0; m < 4; ++m) _Pragma("unroll") for (int n = 0; n < 2; ++n) _Pragma("unroll") for (int k = 0; k < 2; ++k) \
;         acc[ai][bj][m][n] = __builtin_amdgcn_mfma_f32_16x16x32_bf16(Bt[n][k], At[m][k], acc[ai][bj][m][n], 0, 0, 0); __builtin_amdgcn_s_setprio(0); } while (0)
; #define PG8_WAIT_V(n) asm volatile("s_waitcnt vmcnt(" #n ")" ::: "memory")
; #define PG8_WAIT_L(n) asm volatile("s_waitcnt lgkmcnt(" #n ")" ::: "memory")
; #define PG8_BAR __builtin_amdgcn_s_barrier()
; #define PG8_SCHED __builtin_amdgcn_sched_barrier(0)
; template <class Epi, class Sched, bool ALIGN_EPI = false, bool SP2 = false>
; __device__ __forceinline__ void gemm_phase(PG8_LAS unsigned char* lds, const Gemm g, const Sched& S, const Epi& E) {
;     ...
;             PG8_WAIT_V(8); PG8_WAIT_L(0); PG8_BAR; PG8_MMA(0, 0, At, B0); PG8_MMA(0, 1, At, B1); PG8_BAR; PG8_SCHED;
;             PG8_LDA(At, 1, 1); PG8_STAGE(PG8_SB(1, 0), b3, voffB); PG8_STAGE(PG8_SB(1, 1), b3 + hstepB, voffB); PG8_STAGE(PG8_SA(1, 0), a3, voffA);
;             PG8_WAIT_V(8); PG8_WAIT_L(0); PG8_BAR; PG8_MMA(1, 0, At, B0); PG8_MMA(1, 1, At, B1); PG8_BAR; PG8_SCHED;
	s_setprio 1
	s_waitcnt lgkmcnt(0)
	v_mfma_f32_16x16x32_bf16 v[48:51], v[12:15], v[20:23], v[64:67]
	v_mfma_f32_16x16x32_bf16 v[120:123], v[16:19], v[28:31], v[48:51]
	v_mfma_f32_16x16x32_bf16 v[48:51], v[176:179], v[20:23], v[68:71]
	v_mfma_f32_16x16x32_bf16 v[112:115], v[196:199], v[28:31], v[48:51]
	v_mfma_f32_16x16x32_bf16 v[48:51], v[12:15], v[60:63], v[72:75]
	v_mfma_f32_16x16x32_bf16 v[104:107], v[16:19], v[100:103], v[48:51]
	v_mfma_f32_16x16x32_bf16 v[48:51], v[176:179], v[60:63], v[76:79]
	v_mfma_f32_16x16x32_bf16 v[96:99], v[196:199], v[100:103], v[48:51]
	v_mfma_f32_16x16x32_bf16 v[48:51], v[12:15], v[236:239], v[80:83]
	v_mfma_f32_16x16x32_bf16 v[88:91], v[16:19], v[240:243], v[48:51]
	v_mfma_f32_16x16x32_bf16 v[48:51], v[176:179], v[236:239], v[84:87]
	v_mfma_f32_16x16x32_bf16 v[80:83], v[196:199], v[240:243], v[48:51]
	v_mfma_f32_16x16x32_bf16 v[48:51], v[12:15], v[244:247], v[212:215]
	v_mfma_f32_16x16x32_bf16 v[56:59], v[16:19], v[248:251], v[48:51]
	v_mfma_f32_16x16x32_bf16 v[48:51], v[176:179], v[244:247], v[92:95]
	v_mfma_f32_16x16x32_bf16 v[48:51], v[196:199], v[248:251], v[48:51]
	s_setprio 0
	s_setprio 1
	v_mfma_f32_16x16x32_bf16 v[64:67], v[200:203], v[20:23], v[216:219]
	v_mfma_f32_16x16x32_bf16 v[20:23], v[228:231], v[20:23], v[32:35]
	v_mfma_f32_16x16x32_bf16 v[116:119], v[232:235], v[28:31], v[20:23]
	v_mfma_f32_16x16x32_bf16 v[20:23], v[200:203], v[60:63], v[36:39]
	v_mfma_f32_16x16x32_bf16 v[108:111], v[224:227], v[100:103], v[20:23]
	v_mfma_f32_16x16x32_bf16 v[20:23], v[228:231], v[60:63], v[40:43]
	v_mfma_f32_16x16x32_bf16 v[100:103], v[232:235], v[100:103], v[20:23]
	v_mfma_f32_16x16x32_bf16 v[20:23], v[200:203], v[236:239], v[44:47]
	v_mfma_f32_16x16x32_bf16 v[92:95], v[224:227], v[240:243], v[20:23]
	v_mfma_f32_16x16x32_bf16 v[20:23], v[228:231], v[236:239], v[180:183]
	v_mfma_f32_16x16x32_bf16 v[84:87], v[232:235], v[240:243], v[20:23]
	v_mfma_f32_16x16x32_bf16 v[20:23], v[200:203], v[244:247], v[52:55]
	v_mfma_f32_16x16x32_bf16 v[60:63], v[224:227], v[248:251], v[20:23]
	v_mfma_f32_16x16x32_bf16 v[20:23], v[228:231], v[244:247], v[184:187]
	v_mfma_f32_16x16x32_bf16 v[124:127], v[224:227], v[28:31], v[64:67]
	v_mfma_f32_16x16x32_bf16 v[52:55], v[232:235], v[248:251], v[20:23]
	s_setprio 0
	s_barrier
	s_mov_b32 m0, s79
	s_nop 2
	v_lshl_add_u64 v[20:21], v[140:141], 0, s[10:11]
	s_add_u32 s40, s44, 0x10080
	ds_read_b128 v[32:35], v147 offset:49152
	ds_read_b128 v[40:43], v147 offset:50176
	ds_read_b128 v[180:183], v147 offset:51200
	ds_read_b128 v[184:187], v147 offset:52224
	ds_read_b128 v[212:215], v147 offset:53248
	ds_read_b128 v[216:219], v147 offset:54272
	ds_read_b128 v[236:239], v147 offset:55296
	ds_read_b128 v[240:243], v147 offset:56320
	global_load_lds_dwordx4 v[20:21], off
	v_lshl_add_u64 v[20:21], v[252:253], 0, s[10:11]
	s_mov_b32 m0, s69
	s_addc_u32 s41, s45, 0
	global_load_lds_dwordx4 v[20:21], off
	s_mov_b32 m0, s42
	s_nop 0
	global_load_lds_dwordx4 v130, s[40:41]
	s_mov_b32 m0, s43
	s_nop 0
	global_load_lds_dwordx4 v134, s[40:41]
	v_lshl_add_u64 v[20:21], v[136:137], 0, s[10:11]
	s_mov_b32 m0, s56
	s_nop 0
	global_load_lds_dwordx4 v[20:21], off
	v_lshl_add_u64 v[20:21], v[138:139], 0, s[10:11]
	s_mov_b32 m0, s57
	s_nop 0
	global_load_lds_dwordx4 v[20:21], off
	s_waitcnt vmcnt(8)
	s_waitcnt lgkmcnt(0)
	s_barrier
	s_setprio 1
	s_waitcnt lgkmcnt(0)
	v_mfma_f32_16x16x32_bf16 v[20:23], v[12:15], v[32:35], v[148:151]
	v_mfma_f32_16x16x32_bf16 v[76:79], v[16:19], v[40:43], v[20:23]
	v_mfma_f32_16x16x32_bf16 v[20:23], v[176:179], v[32:35], v[152:155]
	v_mfma_f32_16x16x32_bf16 v[68:71], v[196:199], v[40:43], v[20:23]
	v_mfma_f32_16x16x32_bf16 v[20:23], v[12:15], v[180:183], v[156:159]
	v_mfma_f32_16x16x32_bf16 v[44:47], v[16:19], v[184:187], v[20:23]
	v_mfma_f32_16x16x32_bf16 v[20:23], v[176:179], v[180:183], v[160:163]
	v_mfma_f32_16x16x32_bf16 v[36:39], v[196:199], v[184:187], v[20:23]
	v_mfma_f32_16x16x32_bf16 v[20:23], v[12:15], v[212:215], v[164:167]
	v_mfma_f32_16x16x32_bf16 v[0:3], v[12:15], v[236:239], v[0:3]
	v_mfma_f32_16x16x32_bf16 v[28:31], v[16:19], v[216:219], v[20:23]
	v_mfma_f32_16x16x32_bf16 v[20:23], v[176:179], v[212:215], v[168:171]
	v_mfma_f32_16x16x32_bf16 v[12:15], v[16:19], v[240:243], v[0:3]
	v_mfma_f32_16x16x32_bf16 v[0:3], v[176:179], v[236:239], v[4:7]
	v_mfma_f32_16x16x32_bf16 v[20:23], v[196:199], v[216:219], v[20:23]
	v_mfma_f32_16x16x32_bf16 v[4:7], v[196:199], v[240:243], v[0:3]
	s_setprio 0
	s_setprio 1
	v_mfma_f32_16x16x32_bf16 v[0:3], v[200:203], v[32:35], v[8:11]
	v_mfma_f32_16x16x32_bf16 v[72:75], v[224:227], v[40:43], v[0:3]
	v_mfma_f32_16x16x32_bf16 v[0:3], v[228:231], v[32:35], v[204:207]
	v_mfma_f32_16x16x32_bf16 v[64:67], v[232:235], v[40:43], v[0:3]
	v_mfma_f32_16x16x32_bf16 v[0:3], v[200:203], v[180:183], v[24:27]
	v_mfma_f32_16x16x32_bf16 v[40:43], v[224:227], v[184:187], v[0:3]
	v_mfma_f32_16x16x32_bf16 v[0:3], v[228:231], v[180:183], v[208:211]
	v_mfma_f32_16x16x32_bf16 v[32:35], v[232:235], v[184:187], v[0:3]
	v_mfma_f32_16x16x32_bf16 v[0:3], v[200:203], v[212:215], v[220:223]
	v_mfma_f32_16x16x32_bf16 v[24:27], v[224:227], v[216:219], v[0:3]
	v_mfma_f32_16x16x32_bf16 v[0:3], v[228:231], v[212:215], v[188:191]
	v_mfma_f32_16x16x32_bf16 v[16:19], v[232:235], v[216:219], v[0:3]
	v_mfma_f32_16x16x32_bf16 v[0:3], v[200:203], v[236:239], v[192:195]
	v_mfma_f32_16x16x32_bf16 v[8:11], v[224:227], v[240:243], v[0:3]
	v_mfma_f32_16x16x32_bf16 v[0:3], v[228:231], v[236:239], v[172:175]
	v_mfma_f32_16x16x32_bf16 v[0:3], v[232:235], v[240:243], v[0:3]
	s_setprio 0
	s_barrier
	s_andn2_b64 vcc, exec, s[12:13]
	s_cbranch_vccnz .LBB0_1300
	s_barrier

; #define PG8_STAGE(bufoff, gbase, voff) do { _Pragma("unroll") for (int _i = 0; _i < 2; ++_i) \
;         __builtin_amdgcn_global_load_lds((const unsigned*)((const char*)(gbase) + (voff)[_i]), (PG8_LAS unsigned*)(lds + (bufoff) + ldsw + _i * 8192), 16, 0, 0); } while (0)
; #define PG8_LDA(dst, b, h) do { _Pragma("unroll") for (int m = 0; m < 4; ++m) _Pragma("unroll") for (int k = 0; k < 2; ++k) dst[m][k] = *(const PG8_LAS bf16x8*)(lds + PG8_SA(b, h) + aoff + m * 2048 + k * 1024); } while (0)
; #define PG8_LDB(dst, b, h) do { _Pragma("unroll") for (int n = 0; n < 2; ++n) _Pragma("unroll") for (int k = 0; k < 2; ++k) dst[n][k] = *(const PG8_LAS bf16x8*)(lds + PG8_SB(b, h) + boff + n * 2048 + k * 1024); } while (0)
; #define PG8_MMA(ai, bj, At, Bt) do { __builtin_amdgcn_s_setprio(1); _Pragma("unroll") for (int m = 0; m < 4; ++m) _Pragma("unroll") for (int n = 0; n < 2; ++n) _Pragma("unroll") for (int k = 0; k < 2; ++k) \
;         acc[ai][bj][m][n] = __builtin_amdgcn_mfma_f32_16x16x32_bf16(Bt[n][k], At[m][k], acc[ai][bj][m][n], 0, 0, 0); __builtin_amdgcn_s_setprio(0); } while (0)
; #define PG8_WAIT_V(n) asm volatile("s_waitcnt vmcnt(" #n ")" ::: "memory")
; #define PG8_WAIT_L(n) asm volatile("s_waitcnt lgkmcnt(" #n ")" ::: "memory")
; #define PG8_BAR __builtin_amdgcn_s_barrier()
; #define PG8_SCHED __builtin_amdgcn_sched_barrier(0)
; template <class Epi, class Sched, bool ALIGN_EPI = false, bool SP2 = false>
; __device__ __forceinline__ void gemm_phase(PG8_LAS unsigned char* lds, const Gemm g, const Sched& S, const Epi& E) {
;     ...
;         for (int t = 0; t < nt; t += 2) {
;             const bool last = (t == nt - 2);
;             const char* a1 = cA + PG8_AK(t + 1);
;             const char* a2 = last ? nA : cA + PG8_AK(t + 2); const char* b2 = last ? nB : cB + (size_t)(t + 2) * kstep;
;             const char* a3 = last ? nA + PG8_AK(1) : cA + PG8_AK(t + 3); const char* b3 = b2 + kstep;
;             if (last && has_next) S.a_ready(nxt);
;             if constexpr (SP2) {
;             PG8_LDB(B0, 0, 0); PG8_LDB(B1, 0, 1); PG8_SCHED; PG8_LDA(At, 0, 0); PG8_STAGE(PG8_SA(1, 1), a1 + hstepA, voffA);
;             PG8_WAIT_V(8); PG8_WAIT_L(0); PG8_BAR; PG8_MMA(0, 0, At, B0); PG8_MMA(0, 1, At, B1); PG8_BAR; PG8_SCHED;
;             PG8_LDA(At, 0, 1); PG8_STAGE(PG8_SB(0, 0), b2, voffB); PG8_STAGE(PG8_SB(0, 1), b2 + hstepB, voffB); PG8_STAGE(PG8_SA(0, 0), a2, voffA);
.LBB0_1379:
	ds_read_b128 v[124:127], v210
	ds_read_b128 v[128:131], v210 offset:1024
	ds_read_b128 v[132:135], v210 offset:2048
	ds_read_b128 v[144:147], v210 offset:3072
	ds_read_b128 v[148:151], v211
	ds_read_b128 v[170:173], v211 offset:1024
	ds_read_b128 v[174:177], v211 offset:2048
	ds_read_b128 v[178:181], v211 offset:3072
	s_add_u32 s42, s38, s40
	s_addc_u32 s43, s39, s41
	s_add_u32 s46, s42, 0x100
	s_addc_u32 s47, s43, 0
	s_add_u32 s44, s78, s40
	s_addc_u32 s45, s79, s41
	s_add_u32 s42, s42, 0x180
	s_addc_u32 s43, s43, 0
	s_cmpk_eq_i32 s40, 0x1500
	s_cselect_b32 s43, s10, s43
	s_cselect_b32 s42, s3, s42
	s_cselect_b32 s45, s37, s45
	s_cselect_b32 s44, s36, s44
	s_cselect_b32 s47, s9, s47
	s_cselect_b32 s46, s8, s46
	v_lshl_add_u64 v[206:207], v[122:123], 0, s[40:41]
	s_add_i32 m0, s53, 0xc000
	ds_read_b128 v[212:215], v191
	ds_read_b128 v[216:219], v191 offset:1024
	ds_read_b128 v[220:223], v191 offset:2048
	ds_read_b128 v[224:227], v191 offset:3072
	ds_read_b128 v[228:231], v191 offset:4096
	ds_read_b128 v[232:235], v191 offset:5120
	ds_read_b128 v[236:239], v191 offset:6144
	ds_read_b128 v[240:243], v191 offset:7168
	global_load_lds_dwordx4 v[206:207], off
	v_lshl_add_u64 v[206:207], v[120:121], 0, s[40:41]
	s_add_i32 m0, s53, 0xe000
	s_nop 0
	global_load_lds_dwordx4 v[206:207], off
	s_waitcnt vmcnt(8)
	s_waitcnt lgkmcnt(0)
	s_barrier
	s_setprio 1
	s_waitcnt lgkmcnt(0)
	v_mfma_f32_16x16x32_bf16 v[140:143], v[124:127], v[212:215], v[140:143]
	v_mfma_f32_16x16x32_bf16 v[136:139], v[132:135], v[212:215], v[136:139]
	v_mfma_f32_16x16x32_bf16 v[116:119], v[124:127], v[220:223], v[116:119]
	v_mfma_f32_16x16x32_bf16 v[112:115], v[132:135], v[220:223], v[112:115]
	v_mfma_f32_16x16x32_bf16 v[108:111], v[124:127], v[228:231], v[108:111]
	v_mfma_f32_16x16x32_bf16 v[104:107], v[132:135], v[228:231], v[104:107]
	v_mfma_f32_16x16x32_bf16 v[100:103], v[124:127], v[236:239], v[100:103]
	v_mfma_f32_16x16x32_bf16 v[96:99], v[132:135], v[236:239], v[96:99]
	v_mfma_f32_16x16x32_bf16 v[140:143], v[128:131], v[216:219], v[140:143]
	v_mfma_f32_16x16x32_bf16 v[136:139], v[144:147], v[216:219], v[136:139]
	v_mfma_f32_16x16x32_bf16 v[116:119], v[128:131], v[224:227], v[116:119]
	v_mfma_f32_16x16x32_bf16 v[112:115], v[144:147], v[224:227], v[112:115]
	v_mfma_f32_16x16x32_bf16 v[108:111], v[128:131], v[232:235], v[108:111]
	v_mfma_f32_16x16x32_bf16 v[104:107], v[144:147], v[232:235], v[104:107]
	v_mfma_f32_16x16x32_bf16 v[100:103], v[128:131], v[240:243], v[100:103]
	v_mfma_f32_16x16x32_bf16 v[96:99], v[144:147], v[240:243], v[96:99]
	s_setprio 0
	s_setprio 1
	v_mfma_f32_16x16x32_bf16 v[60:63], v[148:151], v[212:215], v[60:63]
	v_mfma_f32_16x16x32_bf16 v[56:59], v[174:177], v[212:215], v[56:59]
	v_mfma_f32_16x16x32_bf16 v[52:55], v[148:151], v[220:223], v[52:55]
	v_mfma_f32_16x16x32_bf16 v[48:51], v[174:177], v[220:223], v[48:51]
	v_mfma_f32_16x16x32_bf16 v[44:47], v[148:151], v[228:231], v[44:47]
	v_mfma_f32_16x16x32_bf16 v[40:43], v[174:177], v[228:231], v[40:43]
	v_mfma_f32_16x16x32_bf16 v[36:39], v[148:151], v[236:239], v[36:39]
	v_mfma_f32_16x16x32_bf16 v[32:35], v[174:177], v[236:239], v[32:35]
	v_mfma_f32_16x16x32_bf16 v[60:63], v[170:173], v[216:219], v[60:63]
	v_mfma_f32_16x16x32_bf16 v[56:59], v[178:181], v[216:219], v[56:59]
	v_mfma_f32_16x16x32_bf16 v[52:55], v[170:173], v[224:227], v[52:55]
	v_mfma_f32_16x16x32_bf16 v[48:51], v[178:181], v[224:227], v[48:51]
	v_mfma_f32_16x16x32_bf16 v[44:47], v[170:173], v[232:235], v[44:47]
	v_mfma_f32_16x16x32_bf16 v[40:43], v[178:181], v[232:235], v[40:43]
	v_mfma_f32_16x16x32_bf16 v[36:39], v[170:173], v[240:243], v[36:39]
	v_mfma_f32_16x16x32_bf16 v[32:35], v[178:181], v[240:243], v[32:35]
	s_setprio 0
	s_barrier
	s_add_i32 s70, s67, s52
	v_lshl_add_u64 v[206:207], s[44:45], 0, v[154:155]
	s_mov_b32 m0, s70
	ds_read_b128 v[212:215], v191 offset:16384
	ds_read_b128 v[216:219], v191 offset:17408
	ds_read_b128 v[220:223], v191 offset:18432
	ds_read_b128 v[224:227], v191 offset:19456
	ds_read_b128 v[228:231], v191 offset:20480
	ds_read_b128 v[232:235], v191 offset:21504
	ds_read_b128 v[236:239], v191 offset:22528
	ds_read_b128 v[240:243], v191 offset:23552
	global_load_lds_dwordx4 v154, s[44:45]
	s_add_i32 m0, s70, 0x2000
	s_add_u32 s70, s44, 0xb0000
	v_lshl_add_u64 v[244:245], s[44:45], 0, v[158:159]
	s_addc_u32 s71, s45, 0
	s_add_i32 s85, s68, s52
	global_load_lds_dwordx4 v158, s[44:45]
	s_mov_b32 m0, s85
	s_nop 0
	global_load_lds_dwordx4 v154, s[70:71]
	s_add_i32 m0, s85, 0x2000
	s_nop 0
	global_load_lds_dwordx4 v158, s[70:71]
	s_mov_b32 m0, s53
	s_nop 0
	global_load_lds_dwordx4 v152, s[46:47]
	v_lshl_add_u64 v[246:247], s[46:47], 0, v[156:157]
	s_mov_b32 m0, s54
	s_nop 0
	global_load_lds_dwordx4 v156, s[46:47]
	s_waitcnt vmcnt(8)
	s_waitcnt lgkmcnt(0)
	s_barrier
; #define PG8_STAGE(bufoff, gbase, voff) do { _Pragma("unroll") for (int _i = 0; _i < 2; ++_i) \
;         __builtin_amdgcn_global_load_lds((const unsigned*)((const char*)(gbase) + (voff)[_i]), (PG8_LAS unsigned*)(lds + (bufoff) + ldsw + _i * 8192), 16, 0, 0); } while (0)
; #define PG8_LDA(dst, b, h) do { _Pragma("unroll") for (int m = 0; m < 4; ++m) _Pragma("unroll") for (int k = 0; k < 2; ++k) dst[m][k] = *(const PG8_LAS bf16x8*)(lds + PG8_SA(b, h) + aoff + m * 2048 + k * 1024); } while (0)
; #define PG8_LDB(dst, b, h) do { _Pragma("unroll") for (int n = 0; n < 2; ++n) _Pragma("unroll") for (int k = 0; k < 2; ++k) dst[n][k] = *(const PG8_LAS bf16x8*)(lds + PG8_SB(b, h) + boff + n * 2048 + k * 1024); } while (0)
; #define PG8_MMA(ai, bj, At, Bt) do { __builtin_amdgcn_s_setprio(1); _Pragma("unroll") for (int m = 0; m < 4; ++m) _Pragma("unroll") for (int n = 0; n < 2; ++n) _Pragma("unroll") for (int k = 0; k < 2; ++k) \
;         acc[ai][bj][m][n] = __builtin_amdgcn_mfma_f32_16x16x32_bf16(Bt[n][k], At[m][k], acc[ai][bj][m][n], 0, 0, 0); __builtin_amdgcn_s_setprio(0); } while (0)
; #define PG8_WAIT_V(n) asm volatile("s_waitcnt vmcnt(" #n ")" ::: "memory")
; #define PG8_WAIT_L(n) asm volatile("s_waitcnt lgkmcnt(" #n ")" ::: "memory")
; #define PG8_BAR __builtin_amdgcn_s_barrier()
; #define PG8_SCHED __builtin_amdgcn_sched_barrier(0)
; template <class Epi, class Sched, bool ALIGN_EPI = false, bool SP2 = false>
; __device__ __forceinline__ void gemm_phase(PG8_LAS unsigned char* lds, const Gemm g, const Sched& S, const Epi& E) {
;     ...
;             PG8_WAIT_V(8); PG8_WAIT_L(0); PG8_BAR; PG8_MMA(1, 0, At, B0); PG8_MMA(1, 1, At, B1); PG8_BAR; PG8_SCHED;
;             PG8_LDB(B0, 1, 0); PG8_LDB(B1, 1, 1); PG8_SCHED; PG8_LDA(At, 1, 0); PG8_STAGE(PG8_SA(0, 1), a2 + hstepA, voffA);
;             PG8_WAIT_V(8); PG8_WAIT_L(0); PG8_BAR; PG8_MMA(0, 0, At, B0); PG8_MMA(0, 1, At, B1); PG8_BAR; PG8_SCHED;
	s_setprio 1
	s_waitcnt lgkmcnt(0)
	v_mfma_f32_16x16x32_bf16 v[92:95], v[124:127], v[212:215], v[92:95]
	v_mfma_f32_16x16x32_bf16 v[88:91], v[132:135], v[212:215], v[88:91]
	v_mfma_f32_16x16x32_bf16 v[84:87], v[124:127], v[220:223], v[84:87]
	v_mfma_f32_16x16x32_bf16 v[80:83], v[132:135], v[220:223], v[80:83]
	v_mfma_f32_16x16x32_bf16 v[76:79], v[124:127], v[228:231], v[76:79]
	v_mfma_f32_16x16x32_bf16 v[72:75], v[132:135], v[228:231], v[72:75]
	v_mfma_f32_16x16x32_bf16 v[68:71], v[124:127], v[236:239], v[68:71]
	v_mfma_f32_16x16x32_bf16 v[64:67], v[132:135], v[236:239], v[64:67]
	v_mfma_f32_16x16x32_bf16 v[92:95], v[128:131], v[216:219], v[92:95]
	v_mfma_f32_16x16x32_bf16 v[88:91], v[144:147], v[216:219], v[88:91]
	v_mfma_f32_16x16x32_bf16 v[84:87], v[128:131], v[224:227], v[84:87]
	v_mfma_f32_16x16x32_bf16 v[80:83], v[144:147], v[224:227], v[80:83]
	v_mfma_f32_16x16x32_bf16 v[76:79], v[128:131], v[232:235], v[76:79]
	v_mfma_f32_16x16x32_bf16 v[72:75], v[144:147], v[232:235], v[72:75]
	v_mfma_f32_16x16x32_bf16 v[68:71], v[128:131], v[240:243], v[68:71]
	v_mfma_f32_16x16x32_bf16 v[64:67], v[144:147], v[240:243], v[64:67]
	s_setprio 0
	s_setprio 1
	v_mfma_f32_16x16x32_bf16 v[28:31], v[148:151], v[212:215], v[28:31]
	v_mfma_f32_16x16x32_bf16 v[24:27], v[174:177], v[212:215], v[24:27]
	v_mfma_f32_16x16x32_bf16 v[20:23], v[148:151], v[220:223], v[20:23]
	v_mfma_f32_16x16x32_bf16 v[16:19], v[174:177], v[220:223], v[16:19]
	v_mfma_f32_16x16x32_bf16 v[12:15], v[148:151], v[228:231], v[12:15]
	v_mfma_f32_16x16x32_bf16 v[8:11], v[174:177], v[228:231], v[8:11]
	v_mfma_f32_16x16x32_bf16 v[4:7], v[148:151], v[236:239], v[4:7]
	v_mfma_f32_16x16x32_bf16 v[0:3], v[174:177], v[236:239], v[0:3]
	v_mfma_f32_16x16x32_bf16 v[28:31], v[170:173], v[216:219], v[28:31]
	v_mfma_f32_16x16x32_bf16 v[24:27], v[178:181], v[216:219], v[24:27]
	v_mfma_f32_16x16x32_bf16 v[20:23], v[170:173], v[224:227], v[20:23]
	v_mfma_f32_16x16x32_bf16 v[16:19], v[178:181], v[224:227], v[16:19]
	v_mfma_f32_16x16x32_bf16 v[12:15], v[170:173], v[232:235], v[12:15]
	v_mfma_f32_16x16x32_bf16 v[8:11], v[178:181], v[232:235], v[8:11]
	v_mfma_f32_16x16x32_bf16 v[4:7], v[170:173], v[240:243], v[4:7]
	v_mfma_f32_16x16x32_bf16 v[0:3], v[178:181], v[240:243], v[0:3]
	s_setprio 0
	s_barrier
	s_add_i32 s70, 0, 0x18000
	s_add_i32 s71, 0, 0x1c000
	v_add_u32_e32 v144, s70, v185
	v_add_u32_e32 v161, s71, v185
	ds_read_b128 v[124:127], v144
	ds_read_b128 v[128:131], v144 offset:1024
	ds_read_b128 v[132:135], v144 offset:2048
	ds_read_b128 v[144:147], v144 offset:3072
	ds_read_b128 v[148:151], v161
	ds_read_b128 v[170:173], v161 offset:1024
	ds_read_b128 v[174:177], v161 offset:2048
	ds_read_b128 v[178:181], v161 offset:3072
	s_add_u32 s46, s46, 0xb0000
	s_addc_u32 s47, s47, 0
	s_mov_b32 m0, s55
	ds_read_b128 v[212:215], v191 offset:32768
	ds_read_b128 v[216:219], v191 offset:33792
	ds_read_b128 v[220:223], v191 offset:34816
	ds_read_b128 v[224:227], v191 offset:35840
	ds_read_b128 v[228:231], v191 offset:36864
	ds_read_b128 v[232:235], v191 offset:37888
	ds_read_b128 v[236:239], v191 offset:38912
	ds_read_b128 v[240:243], v191 offset:39936
	global_load_lds_dwordx4 v152, s[46:47]
	v_lshl_add_u64 v[246:247], s[46:47], 0, v[156:157]
	s_mov_b32 m0, s56
	s_nop 0
	global_load_lds_dwordx4 v156, s[46:47]
	s_waitcnt vmcnt(8)
	s_waitcnt lgkmcnt(0)
	s_barrier
	s_setprio 1
	s_waitcnt lgkmcnt(0)
	v_mfma_f32_16x16x32_bf16 v[140:143], v[124:127], v[212:215], v[140:143]
	v_mfma_f32_16x16x32_bf16 v[136:139], v[132:135], v[212:215], v[136:139]
	v_mfma_f32_16x16x32_bf16 v[116:119], v[124:127], v[220:223], v[116:119]
	v_mfma_f32_16x16x32_bf16 v[112:115], v[132:135], v[220:223], v[112:115]
	v_mfma_f32_16x16x32_bf16 v[108:111], v[124:127], v[228:231], v[108:111]
	v_mfma_f32_16x16x32_bf16 v[104:107], v[132:135], v[228:231], v[104:107]
	v_mfma_f32_16x16x32_bf16 v[100:103], v[124:127], v[236:239], v[100:103]
	v_mfma_f32_16x16x32_bf16 v[96:99], v[132:135], v[236:239], v[96:99]
	v_mfma_f32_16x16x32_bf16 v[140:143], v[128:131], v[216:219], v[140:143]
	v_mfma_f32_16x16x32_bf16 v[136:139], v[144:147], v[216:219], v[136:139]
	v_mfma_f32_16x16x32_bf16 v[116:119], v[128:131], v[224:227], v[116:119]
	v_mfma_f32_16x16x32_bf16 v[112:115], v[144:147], v[224:227], v[112:115]
	v_mfma_f32_16x16x32_bf16 v[108:111], v[128:131], v[232:235], v[108:111]
	v_mfma_f32_16x16x32_bf16 v[104:107], v[144:147], v[232:235], v[104:107]
	v_mfma_f32_16x16x32_bf16 v[100:103], v[128:131], v[240:243], v[100:103]
	v_mfma_f32_16x16x32_bf16 v[96:99], v[144:147], v[240:243], v[96:99]
	s_setprio 0
	s_setprio 1
	v_mfma_f32_16x16x32_bf16 v[60:63], v[148:151], v[212:215], v[60:63]
	v_mfma_f32_16x16x32_bf16 v[56:59], v[174:177], v[212:215], v[56:59]
	v_mfma_f32_16x16x32_bf16 v[52:55], v[148:151], v[220:223], v[52:55]
	v_mfma_f32_16x16x32_bf16 v[48:51], v[174:177], v[220:223], v[48:51]
	v_mfma_f32_16x16x32_bf16 v[44:47], v[148:151], v[228:231], v[44:47]
	v_mfma_f32_16x16x32_bf16 v[40:43], v[174:177], v[228:231], v[40:43]
	v_mfma_f32_16x16x32_bf16 v[36:39], v[148:151], v[236:239], v[36:39]
	v_mfma_f32_16x16x32_bf16 v[32:35], v[174:177], v[236:239], v[32:35]
	v_mfma_f32_16x16x32_bf16 v[60:63], v[170:173], v[216:219], v[60:63]
	v_mfma_f32_16x16x32_bf16 v[56:59], v[178:181], v[216:219], v[56:59]
	v_mfma_f32_16x16x32_bf16 v[52:55], v[170:173], v[224:227], v[52:55]
	v_mfma_f32_16x16x32_bf16 v[48:51], v[178:181], v[224:227], v[48:51]
	v_mfma_f32_16x16x32_bf16 v[44:47], v[170:173], v[232:235], v[44:47]
	v_mfma_f32_16x16x32_bf16 v[40:43], v[178:181], v[232:235], v[40:43]
	v_mfma_f32_16x16x32_bf16 v[36:39], v[170:173], v[240:243], v[36:39]
	v_mfma_f32_16x16x32_bf16 v[32:35], v[178:181], v[240:243], v[32:35]
	s_setprio 0
	s_barrier
; #define PG8_STAGE(bufoff, gbase, voff) do { _Pragma("unroll") for (int _i = 0; _i < 2; ++_i) \
;         __builtin_amdgcn_global_load_lds((const unsigned*)((const char*)(gbase) + (voff)[_i]), (PG8_LAS unsigned*)(lds + (bufoff) + ldsw + _i * 8192), 16, 0, 0); } while (0)
; #define PG8_LDA(dst, b, h) do { _Pragma("unroll") for (int m = 0; m < 4; ++m) _Pragma("unroll") for (int k = 0; k < 2; ++k) dst[m][k] = *(const PG8_LAS bf16x8*)(lds + PG8_SA(b, h) + aoff + m * 2048 + k * 1024); } while (0)
; #define PG8_MMA(ai, bj, At, Bt) do { __builtin_amdgcn_s_setprio(1); _Pragma("unroll") for (int m = 0; m < 4; ++m) _Pragma("unroll") for (int n = 0; n < 2; ++n) _Pragma("unroll") for (int k = 0; k < 2; ++k) \
;         acc[ai][bj][m][n] = __builtin_amdgcn_mfma_f32_16x16x32_bf16(Bt[n][k], At[m][k], acc[ai][bj][m][n], 0, 0, 0); __builtin_amdgcn_s_setprio(0); } while (0)
; #define PG8_WAIT_V(n) asm volatile("s_waitcnt vmcnt(" #n ")" ::: "memory")
; #define PG8_WAIT_L(n) asm volatile("s_waitcnt lgkmcnt(" #n ")" ::: "memory")
; #define PG8_BAR __builtin_amdgcn_s_barrier()
; #define PG8_SCHED __builtin_amdgcn_sched_barrier(0)
; template <class Epi, class Sched, bool ALIGN_EPI = false, bool SP2 = false>
; __device__ __forceinline__ void gemm_phase(PG8_LAS unsigned char* lds, const Gemm g, const Sched& S, const Epi& E) {
;     ...
;             PG8_LDA(At, 1, 1); PG8_STAGE(PG8_SB(1, 0), b3, voffB); PG8_STAGE(PG8_SB(1, 1), b3 + hstepB, voffB); PG8_STAGE(PG8_SA(1, 0), a3, voffA);
;             PG8_WAIT_V(8); PG8_WAIT_L(0); PG8_BAR; PG8_MMA(1, 0, At, B0); PG8_MMA(1, 1, At, B1); PG8_BAR; PG8_SCHED;
	s_add_i32 s46, s70, s52
	v_lshl_add_u64 v[206:207], v[206:207], 0, s[26:27]
	s_mov_b32 m0, s46
	ds_read_b128 v[212:215], v191 offset:49152
	ds_read_b128 v[216:219], v191 offset:50176
	ds_read_b128 v[220:223], v191 offset:51200
	ds_read_b128 v[224:227], v191 offset:52224
	ds_read_b128 v[228:231], v191 offset:53248
	ds_read_b128 v[232:235], v191 offset:54272
	ds_read_b128 v[236:239], v191 offset:55296
	ds_read_b128 v[240:243], v191 offset:56320
	global_load_lds_dwordx4 v[206:207], off
	s_add_i32 m0, s46, 0x2000
	s_add_u32 s44, s44, 0xb0080
	v_lshl_add_u64 v[206:207], v[244:245], 0, s[26:27]
	s_addc_u32 s45, s45, 0
	s_add_i32 s46, s71, s52
	global_load_lds_dwordx4 v[206:207], off
	s_mov_b32 m0, s46
	s_nop 0
	global_load_lds_dwordx4 v154, s[44:45]
	s_add_i32 m0, s46, 0x2000
	s_nop 0
	global_load_lds_dwordx4 v158, s[44:45]
	s_mov_b32 m0, s63
	s_nop 0
	global_load_lds_dwordx4 v152, s[42:43]
	v_lshl_add_u64 v[206:207], s[42:43], 0, v[156:157]
	s_mov_b32 m0, s64
	s_nop 0
	global_load_lds_dwordx4 v156, s[42:43]
	s_waitcnt vmcnt(8)
	s_waitcnt lgkmcnt(0)
	s_barrier
	s_setprio 1
	s_waitcnt lgkmcnt(0)
	v_mfma_f32_16x16x32_bf16 v[92:95], v[124:127], v[212:215], v[92:95]
	v_mfma_f32_16x16x32_bf16 v[88:91], v[132:135], v[212:215], v[88:91]
	v_mfma_f32_16x16x32_bf16 v[84:87], v[124:127], v[220:223], v[84:87]
	v_mfma_f32_16x16x32_bf16 v[80:83], v[132:135], v[220:223], v[80:83]
	v_mfma_f32_16x16x32_bf16 v[76:79], v[124:127], v[228:231], v[76:79]
	v_mfma_f32_16x16x32_bf16 v[72:75], v[132:135], v[228:231], v[72:75]
	v_mfma_f32_16x16x32_bf16 v[68:71], v[124:127], v[236:239], v[68:71]
	v_mfma_f32_16x16x32_bf16 v[64:67], v[132:135], v[236:239], v[64:67]
	v_mfma_f32_16x16x32_bf16 v[92:95], v[128:131], v[216:219], v[92:95]
	v_mfma_f32_16x16x32_bf16 v[88:91], v[144:147], v[216:219], v[88:91]
	v_mfma_f32_16x16x32_bf16 v[84:87], v[128:131], v[224:227], v[84:87]
	v_mfma_f32_16x16x32_bf16 v[80:83], v[144:147], v[224:227], v[80:83]
	v_mfma_f32_16x16x32_bf16 v[76:79], v[128:131], v[232:235], v[76:79]
	v_mfma_f32_16x16x32_bf16 v[72:75], v[144:147], v[232:235], v[72:75]
	v_mfma_f32_16x16x32_bf16 v[68:71], v[128:131], v[240:243], v[68:71]
	v_mfma_f32_16x16x32_bf16 v[64:67], v[144:147], v[240:243], v[64:67]
	s_setprio 0
	s_setprio 1
	v_mfma_f32_16x16x32_bf16 v[28:31], v[148:151], v[212:215], v[28:31]
	v_mfma_f32_16x16x32_bf16 v[24:27], v[174:177], v[212:215], v[24:27]
	v_mfma_f32_16x16x32_bf16 v[20:23], v[148:151], v[220:223], v[20:23]
	v_mfma_f32_16x16x32_bf16 v[16:19], v[174:177], v[220:223], v[16:19]
	v_mfma_f32_16x16x32_bf16 v[12:15], v[148:151], v[228:231], v[12:15]
	v_mfma_f32_16x16x32_bf16 v[8:11], v[174:177], v[228:231], v[8:11]
	v_mfma_f32_16x16x32_bf16 v[4:7], v[148:151], v[236:239], v[4:7]
	v_mfma_f32_16x16x32_bf16 v[0:3], v[174:177], v[236:239], v[0:3]
	v_mfma_f32_16x16x32_bf16 v[28:31], v[170:173], v[216:219], v[28:31]
	v_mfma_f32_16x16x32_bf16 v[24:27], v[178:181], v[216:219], v[24:27]
	v_mfma_f32_16x16x32_bf16 v[20:23], v[170:173], v[224:227], v[20:23]
	v_mfma_f32_16x16x32_bf16 v[16:19], v[178:181], v[224:227], v[16:19]
	v_mfma_f32_16x16x32_bf16 v[12:15], v[170:173], v[232:235], v[12:15]
	v_mfma_f32_16x16x32_bf16 v[8:11], v[178:181], v[232:235], v[8:11]
	v_mfma_f32_16x16x32_bf16 v[4:7], v[170:173], v[240:243], v[4:7]
	v_mfma_f32_16x16x32_bf16 v[0:3], v[178:181], v[240:243], v[0:3]
	s_setprio 0
	s_barrier
	s_add_i32 s84, s84, 2
	s_add_u32 s40, s40, 0x100
	s_addc_u32 s41, s41, 0
	s_cmp_gt_u32 s84, 41
	s_cbranch_scc0 .LBB0_1379
	s_and_b64 vcc, exec, s[28:29]
	s_cbranch_vccz .LBB0_1382
	s_barrier

; #define PG8_STAGE(bufoff, gbase, voff) do { _Pragma("unroll") for (int _i = 0; _i < 2; ++_i) \
;         __builtin_amdgcn_global_load_lds((const unsigned*)((const char*)(gbase) + (voff)[_i]), (PG8_LAS unsigned*)(lds + (bufoff) + ldsw + _i * 8192), 16, 0, 0); } while (0)
; #define PG8_LDA(dst, b, h) do { _Pragma("unroll") for (int m = 0; m < 4; ++m) _Pragma("unroll") for (int k = 0; k < 2; ++k) dst[m][k] = *(const PG8_LAS bf16x8*)(lds + PG8_SA(b, h) + aoff + m * 2048 + k * 1024); } while (0)
; #define PG8_LDB(dst, b, h) do { _Pragma("unroll") for (int n = 0; n < 2; ++n) _Pragma("unroll") for (int k = 0; k < 2; ++k) dst[n][k] = *(const PG8_LAS bf16x8*)(lds + PG8_SB(b, h) + boff + n * 2048 + k * 1024); } while (0)
; #define PG8_MMA(ai, bj, At, Bt) do { __builtin_amdgcn_s_setprio(1); _Pragma("unroll") for (int m = 0; m < 4; ++m) _Pragma("unroll") for (int n = 0; n < 2; ++n) _Pragma("unroll") for (int k = 0; k < 2; ++k) \
;         acc[ai][bj][m][n] = __builtin_amdgcn_mfma_f32_16x16x32_bf16(Bt[n][k], At[m][k], acc[ai][bj][m][n], 0, 0, 0); __builtin_amdgcn_s_setprio(0); } while (0)
; #define PG8_WAIT_V(n) asm volatile("s_waitcnt vmcnt(" #n ")" ::: "memory")
; #define PG8_WAIT_L(n) asm volatile("s_waitcnt lgkmcnt(" #n ")" ::: "memory")
; #define PG8_BAR __builtin_amdgcn_s_barrier()
; #define PG8_SCHED __builtin_amdgcn_sched_barrier(0)
; template <class Epi, class Sched, bool ALIGN_EPI = false, bool SP2 = false>
; __device__ __forceinline__ void gemm_phase(PG8_LAS unsigned char* lds, const Gemm g, const Sched& S, const Epi& E) {
;     ...
;         for (int t = 0; t < nt; t += 2) {
;             const bool last = (t == nt - 2);
;             const char* a1 = cA + PG8_AK(t + 1);
;             const char* a2 = last ? nA : cA + PG8_AK(t + 2); const char* b2 = last ? nB : cB + (size_t)(t + 2) * kstep;
;             const char* a3 = last ? nA + PG8_AK(1) : cA + PG8_AK(t + 3); const char* b3 = b2 + kstep;
;             if (last && has_next) S.a_ready(nxt);
;             if constexpr (SP2) {
;             PG8_LDB(B0, 0, 0); PG8_LDB(B1, 0, 1); PG8_SCHED; PG8_LDA(At, 0, 0); PG8_STAGE(PG8_SA(1, 1), a1 + hstepA, voffA);
;             PG8_WAIT_V(8); PG8_WAIT_L(0); PG8_BAR; PG8_MMA(0, 0, At, B0); PG8_MMA(0, 1, At, B1); PG8_BAR; PG8_SCHED;
;             PG8_LDA(At, 0, 1); PG8_STAGE(PG8_SB(0, 0), b2, voffB); PG8_STAGE(PG8_SB(0, 1), b2 + hstepB, voffB); PG8_STAGE(PG8_SA(0, 0), a2, voffA);
.LBB0_1471:
	ds_read_b128 v[100:103], v222
	ds_read_b128 v[104:107], v222 offset:1024
	ds_read_b128 v[108:111], v222 offset:2048
	ds_read_b128 v[120:123], v222 offset:3072
	ds_read_b128 v[124:127], v223
	ds_read_b128 v[128:131], v223 offset:1024
	ds_read_b128 v[132:135], v223 offset:2048
	ds_read_b128 v[160:163], v223 offset:3072
	s_add_u32 s44, s40, s42
	s_addc_u32 s45, s41, s43
	s_add_u32 s48, s44, 0x100
	s_addc_u32 s49, s45, 0
	s_add_u32 s46, s83, s42
	s_addc_u32 s47, s84, s43
	s_add_u32 s44, s44, 0x180
	s_addc_u32 s45, s45, 0
	s_cmpk_eq_i32 s42, 0x700
	s_cselect_b32 s45, s82, s45
	s_cselect_b32 s44, s79, s44
	s_cselect_b32 s47, s29, s47
	s_cselect_b32 s46, s78, s46
	s_cselect_b32 s49, s3, s49
	s_cselect_b32 s48, s31, s48
	v_lshl_add_u64 v[200:201], v[98:99], 0, s[42:43]
	s_add_i32 m0, s57, 0xc000
	ds_read_b128 v[164:167], v203
	ds_read_b128 v[168:171], v203 offset:1024
	ds_read_b128 v[192:195], v203 offset:2048
	ds_read_b128 v[196:199], v203 offset:3072
	ds_read_b128 v[224:227], v203 offset:4096
	ds_read_b128 v[228:231], v203 offset:5120
	ds_read_b128 v[232:235], v203 offset:6144
	ds_read_b128 v[236:239], v203 offset:7168
	global_load_lds_dwordx4 v[200:201], off
	v_lshl_add_u64 v[200:201], v[96:97], 0, s[42:43]
	s_add_i32 m0, s57, 0xe000
	s_nop 0
	global_load_lds_dwordx4 v[200:201], off
	s_waitcnt vmcnt(8)
	s_waitcnt lgkmcnt(0)
	s_barrier
	s_setprio 1
	s_waitcnt lgkmcnt(0)
	v_mfma_f32_16x16x32_bf16 v[156:159], v[100:103], v[164:167], v[156:159]
	v_mfma_f32_16x16x32_bf16 v[152:155], v[108:111], v[164:167], v[152:155]
	v_mfma_f32_16x16x32_bf16 v[148:151], v[100:103], v[192:195], v[148:151]
	v_mfma_f32_16x16x32_bf16 v[144:147], v[108:111], v[192:195], v[144:147]
	v_mfma_f32_16x16x32_bf16 v[140:143], v[100:103], v[224:227], v[140:143]
	v_mfma_f32_16x16x32_bf16 v[136:139], v[108:111], v[224:227], v[136:139]
	v_mfma_f32_16x16x32_bf16 v[116:119], v[100:103], v[232:235], v[116:119]
	v_mfma_f32_16x16x32_bf16 v[112:115], v[108:111], v[232:235], v[112:115]
	v_mfma_f32_16x16x32_bf16 v[156:159], v[104:107], v[168:171], v[156:159]
	v_mfma_f32_16x16x32_bf16 v[152:155], v[120:123], v[168:171], v[152:155]
	v_mfma_f32_16x16x32_bf16 v[148:151], v[104:107], v[196:199], v[148:151]
	v_mfma_f32_16x16x32_bf16 v[144:147], v[120:123], v[196:199], v[144:147]
	v_mfma_f32_16x16x32_bf16 v[140:143], v[104:107], v[228:231], v[140:143]
	v_mfma_f32_16x16x32_bf16 v[136:139], v[120:123], v[228:231], v[136:139]
	v_mfma_f32_16x16x32_bf16 v[116:119], v[104:107], v[236:239], v[116:119]
	v_mfma_f32_16x16x32_bf16 v[112:115], v[120:123], v[236:239], v[112:115]
	s_setprio 0
	s_setprio 1
	v_mfma_f32_16x16x32_bf16 v[60:63], v[124:127], v[164:167], v[60:63]
	v_mfma_f32_16x16x32_bf16 v[56:59], v[132:135], v[164:167], v[56:59]
	v_mfma_f32_16x16x32_bf16 v[52:55], v[124:127], v[192:195], v[52:55]
	v_mfma_f32_16x16x32_bf16 v[48:51], v[132:135], v[192:195], v[48:51]
	v_mfma_f32_16x16x32_bf16 v[44:47], v[124:127], v[224:227], v[44:47]
	v_mfma_f32_16x16x32_bf16 v[40:43], v[132:135], v[224:227], v[40:43]
	v_mfma_f32_16x16x32_bf16 v[36:39], v[124:127], v[232:235], v[36:39]
	v_mfma_f32_16x16x32_bf16 v[32:35], v[132:135], v[232:235], v[32:35]
	v_mfma_f32_16x16x32_bf16 v[60:63], v[128:131], v[168:171], v[60:63]
	v_mfma_f32_16x16x32_bf16 v[56:59], v[160:163], v[168:171], v[56:59]
	v_mfma_f32_16x16x32_bf16 v[52:55], v[128:131], v[196:199], v[52:55]
	v_mfma_f32_16x16x32_bf16 v[48:51], v[160:163], v[196:199], v[48:51]
	v_mfma_f32_16x16x32_bf16 v[44:47], v[128:131], v[228:231], v[44:47]
	v_mfma_f32_16x16x32_bf16 v[40:43], v[160:163], v[228:231], v[40:43]
	v_mfma_f32_16x16x32_bf16 v[36:39], v[128:131], v[236:239], v[36:39]
	v_mfma_f32_16x16x32_bf16 v[32:35], v[160:163], v[236:239], v[32:35]
	s_setprio 0
	s_barrier
	s_add_i32 s70, s69, s56
	v_lshl_add_u64 v[200:201], s[46:47], 0, v[174:175]
	s_mov_b32 m0, s70
	ds_read_b128 v[164:167], v203 offset:16384
	ds_read_b128 v[168:171], v203 offset:17408
	ds_read_b128 v[192:195], v203 offset:18432
	ds_read_b128 v[196:199], v203 offset:19456
	ds_read_b128 v[224:227], v203 offset:20480
	ds_read_b128 v[228:231], v203 offset:21504
	ds_read_b128 v[232:235], v203 offset:22528
	ds_read_b128 v[236:239], v203 offset:23552
	global_load_lds_dwordx4 v174, s[46:47]
	s_add_i32 m0, s70, 0x2000
	s_add_u32 s70, s46, 0x40000
	v_lshl_add_u64 v[206:207], s[46:47], 0, v[178:179]
	s_addc_u32 s71, s47, 0
	s_add_i32 s86, s80, s56
	global_load_lds_dwordx4 v178, s[46:47]
	s_mov_b32 m0, s86
	s_nop 0
	global_load_lds_dwordx4 v174, s[70:71]
	s_add_i32 m0, s86, 0x2000
	s_nop 0
	global_load_lds_dwordx4 v178, s[70:71]
	s_mov_b32 m0, s57
	s_nop 0
	global_load_lds_dwordx4 v172, s[48:49]
	v_lshl_add_u64 v[240:241], s[48:49], 0, v[176:177]
	s_mov_b32 m0, s58
	s_nop 0
	global_load_lds_dwordx4 v176, s[48:49]
	s_waitcnt vmcnt(8)
	s_waitcnt lgkmcnt(0)
	s_barrier
; #define PG8_STAGE(bufoff, gbase, voff) do { _Pragma("unroll") for (int _i = 0; _i < 2; ++_i) \
;         __builtin_amdgcn_global_load_lds((const unsigned*)((const char*)(gbase) + (voff)[_i]), (PG8_LAS unsigned*)(lds + (bufoff) + ldsw + _i * 8192), 16, 0, 0); } while (0)
; #define PG8_LDA(dst, b, h) do { _Pragma("unroll") for (int m = 0; m < 4; ++m) _Pragma("unroll") for (int k = 0; k < 2; ++k) dst[m][k] = *(const PG8_LAS bf16x8*)(lds + PG8_SA(b, h) + aoff + m * 2048 + k * 1024); } while (0)
; #define PG8_LDB(dst, b, h) do { _Pragma("unroll") for (int n = 0; n < 2; ++n) _Pragma("unroll") for (int k = 0; k < 2; ++k) dst[n][k] = *(const PG8_LAS bf16x8*)(lds + PG8_SB(b, h) + boff + n * 2048 + k * 1024); } while (0)
; #define PG8_MMA(ai, bj, At, Bt) do { __builtin_amdgcn_s_setprio(1); _Pragma("unroll") for (int m = 0; m < 4; ++m) _Pragma("unroll") for (int n = 0; n < 2; ++n) _Pragma("unroll") for (int k = 0; k < 2; ++k) \
;         acc[ai][bj][m][n] = __builtin_amdgcn_mfma_f32_16x16x32_bf16(Bt[n][k], At[m][k], acc[ai][bj][m][n], 0, 0, 0); __builtin_amdgcn_s_setprio(0); } while (0)
; #define PG8_WAIT_V(n) asm volatile("s_waitcnt vmcnt(" #n ")" ::: "memory")
; #define PG8_WAIT_L(n) asm volatile("s_waitcnt lgkmcnt(" #n ")" ::: "memory")
; #define PG8_BAR __builtin_amdgcn_s_barrier()
; #define PG8_SCHED __builtin_amdgcn_sched_barrier(0)
; template <class Epi, class Sched, bool ALIGN_EPI = false, bool SP2 = false>
; __device__ __forceinline__ void gemm_phase(PG8_LAS unsigned char* lds, const Gemm g, const Sched& S, const Epi& E) {
;     ...
;             PG8_WAIT_V(8); PG8_WAIT_L(0); PG8_BAR; PG8_MMA(1, 0, At, B0); PG8_MMA(1, 1, At, B1); PG8_BAR; PG8_SCHED;
;             PG8_LDB(B0, 1, 0); PG8_LDB(B1, 1, 1); PG8_SCHED; PG8_LDA(At, 1, 0); PG8_STAGE(PG8_SA(0, 1), a2 + hstepA, voffA);
;             PG8_WAIT_V(8); PG8_WAIT_L(0); PG8_BAR; PG8_MMA(0, 0, At, B0); PG8_MMA(0, 1, At, B1); PG8_BAR; PG8_SCHED;
	s_setprio 1
	s_waitcnt lgkmcnt(0)
	v_mfma_f32_16x16x32_bf16 v[92:95], v[100:103], v[164:167], v[92:95]
	v_mfma_f32_16x16x32_bf16 v[88:91], v[108:111], v[164:167], v[88:91]
	v_mfma_f32_16x16x32_bf16 v[84:87], v[100:103], v[192:195], v[84:87]
	v_mfma_f32_16x16x32_bf16 v[80:83], v[108:111], v[192:195], v[80:83]
	v_mfma_f32_16x16x32_bf16 v[76:79], v[100:103], v[224:227], v[76:79]
	v_mfma_f32_16x16x32_bf16 v[72:75], v[108:111], v[224:227], v[72:75]
	v_mfma_f32_16x16x32_bf16 v[68:71], v[100:103], v[232:235], v[68:71]
	v_mfma_f32_16x16x32_bf16 v[64:67], v[108:111], v[232:235], v[64:67]
	v_mfma_f32_16x16x32_bf16 v[92:95], v[104:107], v[168:171], v[92:95]
	v_mfma_f32_16x16x32_bf16 v[88:91], v[120:123], v[168:171], v[88:91]
	v_mfma_f32_16x16x32_bf16 v[84:87], v[104:107], v[196:199], v[84:87]
	v_mfma_f32_16x16x32_bf16 v[80:83], v[120:123], v[196:199], v[80:83]
	v_mfma_f32_16x16x32_bf16 v[76:79], v[104:107], v[228:231], v[76:79]
	v_mfma_f32_16x16x32_bf16 v[72:75], v[120:123], v[228:231], v[72:75]
	v_mfma_f32_16x16x32_bf16 v[68:71], v[104:107], v[236:239], v[68:71]
	v_mfma_f32_16x16x32_bf16 v[64:67], v[120:123], v[236:239], v[64:67]
	s_setprio 0
	s_setprio 1
	v_mfma_f32_16x16x32_bf16 v[28:31], v[124:127], v[164:167], v[28:31]
	v_mfma_f32_16x16x32_bf16 v[24:27], v[132:135], v[164:167], v[24:27]
	v_mfma_f32_16x16x32_bf16 v[20:23], v[124:127], v[192:195], v[20:23]
	v_mfma_f32_16x16x32_bf16 v[16:19], v[132:135], v[192:195], v[16:19]
	v_mfma_f32_16x16x32_bf16 v[12:15], v[124:127], v[224:227], v[12:15]
	v_mfma_f32_16x16x32_bf16 v[8:11], v[132:135], v[224:227], v[8:11]
	v_mfma_f32_16x16x32_bf16 v[4:7], v[124:127], v[232:235], v[4:7]
	v_mfma_f32_16x16x32_bf16 v[0:3], v[132:135], v[232:235], v[0:3]
	v_mfma_f32_16x16x32_bf16 v[28:31], v[128:131], v[168:171], v[28:31]
	v_mfma_f32_16x16x32_bf16 v[24:27], v[160:163], v[168:171], v[24:27]
	v_mfma_f32_16x16x32_bf16 v[20:23], v[128:131], v[196:199], v[20:23]
	v_mfma_f32_16x16x32_bf16 v[16:19], v[160:163], v[196:199], v[16:19]
	v_mfma_f32_16x16x32_bf16 v[12:15], v[128:131], v[228:231], v[12:15]
	v_mfma_f32_16x16x32_bf16 v[8:11], v[160:163], v[228:231], v[8:11]
	v_mfma_f32_16x16x32_bf16 v[4:7], v[128:131], v[236:239], v[4:7]
	v_mfma_f32_16x16x32_bf16 v[0:3], v[160:163], v[236:239], v[0:3]
	s_setprio 0
	s_barrier
	s_add_i32 s70, 0, 0x18000
	s_add_i32 s71, 0, 0x1c000
	v_add_u32_e32 v120, s70, v189
	v_add_u32_e32 v160, s71, v189
	ds_read_b128 v[100:103], v120
	ds_read_b128 v[104:107], v120 offset:1024
	ds_read_b128 v[108:111], v120 offset:2048
	ds_read_b128 v[120:123], v120 offset:3072
	ds_read_b128 v[124:127], v160
	ds_read_b128 v[128:131], v160 offset:1024
	ds_read_b128 v[132:135], v160 offset:2048
	ds_read_b128 v[160:163], v160 offset:3072
	s_add_u32 s48, s48, 0x40000
	s_addc_u32 s49, s49, 0
	s_mov_b32 m0, s59
	ds_read_b128 v[164:167], v203 offset:32768
	ds_read_b128 v[168:171], v203 offset:33792
	ds_read_b128 v[192:195], v203 offset:34816
	ds_read_b128 v[196:199], v203 offset:35840
	ds_read_b128 v[224:227], v203 offset:36864
	ds_read_b128 v[228:231], v203 offset:37888
	ds_read_b128 v[232:235], v203 offset:38912
	ds_read_b128 v[236:239], v203 offset:39936
	global_load_lds_dwordx4 v172, s[48:49]
	v_lshl_add_u64 v[240:241], s[48:49], 0, v[176:177]
	s_mov_b32 m0, s60
	s_nop 0
	global_load_lds_dwordx4 v176, s[48:49]
	s_waitcnt vmcnt(8)
	s_waitcnt lgkmcnt(0)
	s_barrier
	s_setprio 1
	s_waitcnt lgkmcnt(0)
	v_mfma_f32_16x16x32_bf16 v[156:159], v[100:103], v[164:167], v[156:159]
	v_mfma_f32_16x16x32_bf16 v[152:155], v[108:111], v[164:167], v[152:155]
	v_mfma_f32_16x16x32_bf16 v[148:151], v[100:103], v[192:195], v[148:151]
	v_mfma_f32_16x16x32_bf16 v[144:147], v[108:111], v[192:195], v[144:147]
	v_mfma_f32_16x16x32_bf16 v[140:143], v[100:103], v[224:227], v[140:143]
	v_mfma_f32_16x16x32_bf16 v[136:139], v[108:111], v[224:227], v[136:139]
	v_mfma_f32_16x16x32_bf16 v[116:119], v[100:103], v[232:235], v[116:119]
	v_mfma_f32_16x16x32_bf16 v[112:115], v[108:111], v[232:235], v[112:115]
	v_mfma_f32_16x16x32_bf16 v[156:159], v[104:107], v[168:171], v[156:159]
	v_mfma_f32_16x16x32_bf16 v[152:155], v[120:123], v[168:171], v[152:155]
	v_mfma_f32_16x16x32_bf16 v[148:151], v[104:107], v[196:199], v[148:151]
	v_mfma_f32_16x16x32_bf16 v[144:147], v[120:123], v[196:199], v[144:147]
	v_mfma_f32_16x16x32_bf16 v[140:143], v[104:107], v[228:231], v[140:143]
	v_mfma_f32_16x16x32_bf16 v[136:139], v[120:123], v[228:231], v[136:139]
	v_mfma_f32_16x16x32_bf16 v[116:119], v[104:107], v[236:239], v[116:119]
	v_mfma_f32_16x16x32_bf16 v[112:115], v[120:123], v[236:239], v[112:115]
	s_setprio 0
	s_setprio 1
	v_mfma_f32_16x16x32_bf16 v[60:63], v[124:127], v[164:167], v[60:63]
	v_mfma_f32_16x16x32_bf16 v[56:59], v[132:135], v[164:167], v[56:59]
	v_mfma_f32_16x16x32_bf16 v[52:55], v[124:127], v[192:195], v[52:55]
	v_mfma_f32_16x16x32_bf16 v[48:51], v[132:135], v[192:195], v[48:51]
	v_mfma_f32_16x16x32_bf16 v[44:47], v[124:127], v[224:227], v[44:47]
	v_mfma_f32_16x16x32_bf16 v[40:43], v[132:135], v[224:227], v[40:43]
	v_mfma_f32_16x16x32_bf16 v[36:39], v[124:127], v[232:235], v[36:39]
	v_mfma_f32_16x16x32_bf16 v[32:35], v[132:135], v[232:235], v[32:35]
	v_mfma_f32_16x16x32_bf16 v[60:63], v[128:131], v[168:171], v[60:63]
	v_mfma_f32_16x16x32_bf16 v[56:59], v[160:163], v[168:171], v[56:59]
	v_mfma_f32_16x16x32_bf16 v[52:55], v[128:131], v[196:199], v[52:55]
	v_mfma_f32_16x16x32_bf16 v[48:51], v[160:163], v[196:199], v[48:51]
	v_mfma_f32_16x16x32_bf16 v[44:47], v[128:131], v[228:231], v[44:47]
	v_mfma_f32_16x16x32_bf16 v[40:43], v[160:163], v[228:231], v[40:43]
	v_mfma_f32_16x16x32_bf16 v[36:39], v[128:131], v[236:239], v[36:39]
	v_mfma_f32_16x16x32_bf16 v[32:35], v[160:163], v[236:239], v[32:35]
	s_setprio 0
	s_barrier
; #define PG8_STAGE(bufoff, gbase, voff) do { _Pragma("unroll") for (int _i = 0; _i < 2; ++_i) \
;         __builtin_amdgcn_global_load_lds((const unsigned*)((const char*)(gbase) + (voff)[_i]), (PG8_LAS unsigned*)(lds + (bufoff) + ldsw + _i * 8192), 16, 0, 0); } while (0)
; #define PG8_LDA(dst, b, h) do { _Pragma("unroll") for (int m = 0; m < 4; ++m) _Pragma("unroll") for (int k = 0; k < 2; ++k) dst[m][k] = *(const PG8_LAS bf16x8*)(lds + PG8_SA(b, h) + aoff + m * 2048 + k * 1024); } while (0)
; #define PG8_MMA(ai, bj, At, Bt) do { __builtin_amdgcn_s_setprio(1); _Pragma("unroll") for (int m = 0; m < 4; ++m) _Pragma("unroll") for (int n = 0; n < 2; ++n) _Pragma("unroll") for (int k = 0; k < 2; ++k) \
;         acc[ai][bj][m][n] = __builtin_amdgcn_mfma_f32_16x16x32_bf16(Bt[n][k], At[m][k], acc[ai][bj][m][n], 0, 0, 0); __builtin_amdgcn_s_setprio(0); } while (0)
; #define PG8_WAIT_V(n) asm volatile("s_waitcnt vmcnt(" #n ")" ::: "memory")
; #define PG8_WAIT_L(n) asm volatile("s_waitcnt lgkmcnt(" #n ")" ::: "memory")
; #define PG8_BAR __builtin_amdgcn_s_barrier()
; #define PG8_SCHED __builtin_amdgcn_sched_barrier(0)
; template <class Epi, class Sched, bool ALIGN_EPI = false, bool SP2 = false>
; __device__ __forceinline__ void gemm_phase(PG8_LAS unsigned char* lds, const Gemm g, const Sched& S, const Epi& E) {
;     ...
;             PG8_LDA(At, 1, 1); PG8_STAGE(PG8_SB(1, 0), b3, voffB); PG8_STAGE(PG8_SB(1, 1), b3 + hstepB, voffB); PG8_STAGE(PG8_SA(1, 0), a3, voffA);
;             PG8_WAIT_V(8); PG8_WAIT_L(0); PG8_BAR; PG8_MMA(1, 0, At, B0); PG8_MMA(1, 1, At, B1); PG8_BAR; PG8_SCHED;
	s_add_i32 s48, s70, s56
	v_lshl_add_u64 v[200:201], v[200:201], 0, s[10:11]
	s_mov_b32 m0, s48
	ds_read_b128 v[164:167], v203 offset:49152
	ds_read_b128 v[168:171], v203 offset:50176
	ds_read_b128 v[192:195], v203 offset:51200
	ds_read_b128 v[196:199], v203 offset:52224
	ds_read_b128 v[224:227], v203 offset:53248
	ds_read_b128 v[228:231], v203 offset:54272
	ds_read_b128 v[232:235], v203 offset:55296
	ds_read_b128 v[236:239], v203 offset:56320
	global_load_lds_dwordx4 v[200:201], off
	s_add_i32 m0, s48, 0x2000
	s_add_u32 s46, s46, 0x40080
	v_lshl_add_u64 v[200:201], v[206:207], 0, s[10:11]
	s_addc_u32 s47, s47, 0
	s_add_i32 s48, s71, s56
	global_load_lds_dwordx4 v[200:201], off
	s_mov_b32 m0, s48
	s_nop 0
	global_load_lds_dwordx4 v174, s[46:47]
	s_add_i32 m0, s48, 0x2000
	s_nop 0
	global_load_lds_dwordx4 v178, s[46:47]
	s_mov_b32 m0, s66
	s_nop 0
	global_load_lds_dwordx4 v172, s[44:45]
	v_lshl_add_u64 v[200:201], s[44:45], 0, v[176:177]
	s_mov_b32 m0, s67
	s_nop 0
	global_load_lds_dwordx4 v176, s[44:45]
	s_waitcnt vmcnt(8)
	s_waitcnt lgkmcnt(0)
	s_barrier
	s_setprio 1
	s_waitcnt lgkmcnt(0)
	v_mfma_f32_16x16x32_bf16 v[92:95], v[100:103], v[164:167], v[92:95]
	v_mfma_f32_16x16x32_bf16 v[88:91], v[108:111], v[164:167], v[88:91]
	v_mfma_f32_16x16x32_bf16 v[84:87], v[100:103], v[192:195], v[84:87]
	v_mfma_f32_16x16x32_bf16 v[80:83], v[108:111], v[192:195], v[80:83]
	v_mfma_f32_16x16x32_bf16 v[76:79], v[100:103], v[224:227], v[76:79]
	v_mfma_f32_16x16x32_bf16 v[72:75], v[108:111], v[224:227], v[72:75]
	v_mfma_f32_16x16x32_bf16 v[68:71], v[100:103], v[232:235], v[68:71]
	v_mfma_f32_16x16x32_bf16 v[64:67], v[108:111], v[232:235], v[64:67]
	v_mfma_f32_16x16x32_bf16 v[92:95], v[104:107], v[168:171], v[92:95]
	v_mfma_f32_16x16x32_bf16 v[88:91], v[120:123], v[168:171], v[88:91]
	v_mfma_f32_16x16x32_bf16 v[84:87], v[104:107], v[196:199], v[84:87]
	v_mfma_f32_16x16x32_bf16 v[80:83], v[120:123], v[196:199], v[80:83]
	v_mfma_f32_16x16x32_bf16 v[76:79], v[104:107], v[228:231], v[76:79]
	v_mfma_f32_16x16x32_bf16 v[72:75], v[120:123], v[228:231], v[72:75]
	v_mfma_f32_16x16x32_bf16 v[68:71], v[104:107], v[236:239], v[68:71]
	v_mfma_f32_16x16x32_bf16 v[64:67], v[120:123], v[236:239], v[64:67]
	s_setprio 0
	s_setprio 1
	v_mfma_f32_16x16x32_bf16 v[28:31], v[124:127], v[164:167], v[28:31]
	v_mfma_f32_16x16x32_bf16 v[24:27], v[132:135], v[164:167], v[24:27]
	v_mfma_f32_16x16x32_bf16 v[20:23], v[124:127], v[192:195], v[20:23]
	v_mfma_f32_16x16x32_bf16 v[16:19], v[132:135], v[192:195], v[16:19]
	v_mfma_f32_16x16x32_bf16 v[12:15], v[124:127], v[224:227], v[12:15]
	v_mfma_f32_16x16x32_bf16 v[8:11], v[132:135], v[224:227], v[8:11]
	v_mfma_f32_16x16x32_bf16 v[4:7], v[124:127], v[232:235], v[4:7]
	v_mfma_f32_16x16x32_bf16 v[0:3], v[132:135], v[232:235], v[0:3]
	v_mfma_f32_16x16x32_bf16 v[28:31], v[128:131], v[168:171], v[28:31]
	v_mfma_f32_16x16x32_bf16 v[24:27], v[160:163], v[168:171], v[24:27]
	v_mfma_f32_16x16x32_bf16 v[20:23], v[128:131], v[196:199], v[20:23]
	v_mfma_f32_16x16x32_bf16 v[16:19], v[160:163], v[196:199], v[16:19]
	v_mfma_f32_16x16x32_bf16 v[12:15], v[128:131], v[228:231], v[12:15]
	v_mfma_f32_16x16x32_bf16 v[8:11], v[160:163], v[228:231], v[8:11]
	v_mfma_f32_16x16x32_bf16 v[4:7], v[128:131], v[236:239], v[4:7]
	v_mfma_f32_16x16x32_bf16 v[0:3], v[160:163], v[236:239], v[0:3]
	s_setprio 0
	s_barrier
	s_add_i32 s85, s85, 2
	s_add_u32 s42, s42, 0x100
	s_addc_u32 s43, s43, 0
	s_cmp_gt_u32 s85, 13
	s_cbranch_scc0 .LBB0_1471
	s_and_b64 vcc, exec, s[24:25]
	s_cbranch_vccz .LBB0_1474
	s_barrier

; #define PG8_STAGE(bufoff, gbase, voff) do { _Pragma("unroll") for (int _i = 0; _i < 2; ++_i) \
;         __builtin_amdgcn_global_load_lds((const unsigned*)((const char*)(gbase) + (voff)[_i]), (PG8_LAS unsigned*)(lds + (bufoff) + ldsw + _i * 8192), 16, 0, 0); } while (0)
; #define PG8_LDA(dst, b, h) do { _Pragma("unroll") for (int m = 0; m < 4; ++m) _Pragma("unroll") for (int k = 0; k < 2; ++k) dst[m][k] = *(const PG8_LAS bf16x8*)(lds + PG8_SA(b, h) + aoff + m * 2048 + k * 1024); } while (0)
; #define PG8_LDB(dst, b, h) do { _Pragma("unroll") for (int n = 0; n < 2; ++n) _Pragma("unroll") for (int k = 0; k < 2; ++k) dst[n][k] = *(const PG8_LAS bf16x8*)(lds + PG8_SB(b, h) + boff + n * 2048 + k * 1024); } while (0)
; #define PG8_MMA(ai, bj, At, Bt) do { __builtin_amdgcn_s_setprio(1); _Pragma("unroll") for (int m = 0; m < 4; ++m) _Pragma("unroll") for (int n = 0; n < 2; ++n) _Pragma("unroll") for (int k = 0; k < 2; ++k) \
;         acc[ai][bj][m][n] = __builtin_amdgcn_mfma_f32_16x16x32_bf16(Bt[n][k], At[m][k], acc[ai][bj][m][n], 0, 0, 0); __builtin_amdgcn_s_setprio(0); } while (0)
; #define PG8_WAIT_V(n) asm volatile("s_waitcnt vmcnt(" #n ")" ::: "memory")
; #define PG8_WAIT_L(n) asm volatile("s_waitcnt lgkmcnt(" #n ")" ::: "memory")
; #define PG8_BAR __builtin_amdgcn_s_barrier()
; #define PG8_SCHED __builtin_amdgcn_sched_barrier(0)
; template <class Epi, class Sched, bool ALIGN_EPI = false, bool SP2 = false>
; __device__ __forceinline__ void gemm_phase(PG8_LAS unsigned char* lds, const Gemm g, const Sched& S, const Epi& E) {
;     ...
;         for (int t = 0; t < nt; t += 2) {
;             const bool last = (t == nt - 2);
;             const char* a1 = cA + PG8_AK(t + 1);
;             const char* a2 = last ? nA : cA + PG8_AK(t + 2); const char* b2 = last ? nB : cB + (size_t)(t + 2) * kstep;
;             const char* a3 = last ? nA + PG8_AK(1) : cA + PG8_AK(t + 3); const char* b3 = b2 + kstep;
;             if (last && has_next) S.a_ready(nxt);
;             if constexpr (SP2) {
;             PG8_LDB(B0, 0, 0); PG8_LDB(B1, 0, 1); PG8_SCHED; PG8_LDA(At, 0, 0); PG8_STAGE(PG8_SA(1, 1), a1 + hstepA, voffA);
;             PG8_WAIT_V(8); PG8_WAIT_L(0); PG8_BAR; PG8_MMA(0, 0, At, B0); PG8_MMA(0, 1, At, B1); PG8_BAR; PG8_SCHED;
;             PG8_LDA(At, 0, 1); PG8_STAGE(PG8_SB(0, 0), b2, voffB); PG8_STAGE(PG8_SB(0, 1), b2 + hstepB, voffB); PG8_STAGE(PG8_SA(0, 0), a2, voffA);
.LBB0_1638:
	ds_read_b128 v[132:135], v172
	ds_read_b128 v[158:161], v172 offset:1024
	ds_read_b128 v[176:179], v172 offset:2048
	ds_read_b128 v[180:183], v172 offset:3072
	ds_read_b128 v[184:187], v173
	ds_read_b128 v[188:191], v173 offset:1024
	ds_read_b128 v[192:195], v173 offset:2048
	ds_read_b128 v[196:199], v173 offset:3072
	s_add_u32 s38, s28, s34
	s_addc_u32 s39, s29, s35
	s_add_u32 s42, s38, 0x100
	s_addc_u32 s43, s39, 0
	s_add_u32 s40, s62, s34
	s_addc_u32 s41, s63, s35
	s_add_u32 s38, s38, 0x180
	s_addc_u32 s39, s39, 0
	s_cmpk_eq_i32 s34, 0x700
	s_cselect_b32 s39, s37, s39
	s_cselect_b32 s38, s31, s38
	s_cselect_b32 s41, s21, s41
	s_cselect_b32 s40, s23, s40
	s_cselect_b32 s43, s3, s43
	s_cselect_b32 s42, s10, s42
	v_lshl_add_u64 v[232:233], v[130:131], 0, s[34:35]
	s_add_i32 m0, s49, 0xc000
	ds_read_b128 v[200:203], v174
	ds_read_b128 v[204:207], v174 offset:1024
	ds_read_b128 v[208:211], v174 offset:2048
	ds_read_b128 v[212:215], v174 offset:3072
	ds_read_b128 v[216:219], v174 offset:4096
	ds_read_b128 v[220:223], v174 offset:5120
	ds_read_b128 v[224:227], v174 offset:6144
	ds_read_b128 v[228:231], v174 offset:7168
	global_load_lds_dwordx4 v[232:233], off
	v_lshl_add_u64 v[232:233], v[128:129], 0, s[34:35]
	s_add_i32 m0, s49, 0xe000
	s_nop 0
	global_load_lds_dwordx4 v[232:233], off
	s_waitcnt vmcnt(8)
	s_waitcnt lgkmcnt(0)
	s_barrier
	s_setprio 1
	s_waitcnt lgkmcnt(0)
	v_mfma_f32_16x16x32_bf16 v[124:127], v[132:135], v[200:203], v[124:127]
	v_mfma_f32_16x16x32_bf16 v[120:123], v[176:179], v[200:203], v[120:123]
	v_mfma_f32_16x16x32_bf16 v[108:111], v[132:135], v[208:211], v[108:111]
	v_mfma_f32_16x16x32_bf16 v[104:107], v[176:179], v[208:211], v[104:107]
	v_mfma_f32_16x16x32_bf16 v[92:95], v[132:135], v[216:219], v[92:95]
	v_mfma_f32_16x16x32_bf16 v[88:91], v[176:179], v[216:219], v[88:91]
	v_mfma_f32_16x16x32_bf16 v[76:79], v[132:135], v[224:227], v[76:79]
	v_mfma_f32_16x16x32_bf16 v[72:75], v[176:179], v[224:227], v[72:75]
	v_mfma_f32_16x16x32_bf16 v[124:127], v[158:161], v[204:207], v[124:127]
	v_mfma_f32_16x16x32_bf16 v[120:123], v[180:183], v[204:207], v[120:123]
	v_mfma_f32_16x16x32_bf16 v[108:111], v[158:161], v[212:215], v[108:111]
	v_mfma_f32_16x16x32_bf16 v[104:107], v[180:183], v[212:215], v[104:107]
	v_mfma_f32_16x16x32_bf16 v[92:95], v[158:161], v[220:223], v[92:95]
	v_mfma_f32_16x16x32_bf16 v[88:91], v[180:183], v[220:223], v[88:91]
	v_mfma_f32_16x16x32_bf16 v[76:79], v[158:161], v[228:231], v[76:79]
	v_mfma_f32_16x16x32_bf16 v[72:75], v[180:183], v[228:231], v[72:75]
	s_setprio 0
	s_setprio 1
	v_mfma_f32_16x16x32_bf16 v[116:119], v[184:187], v[200:203], v[116:119]
	v_mfma_f32_16x16x32_bf16 v[112:115], v[192:195], v[200:203], v[112:115]
	v_mfma_f32_16x16x32_bf16 v[100:103], v[184:187], v[208:211], v[100:103]
	v_mfma_f32_16x16x32_bf16 v[96:99], v[192:195], v[208:211], v[96:99]
	v_mfma_f32_16x16x32_bf16 v[84:87], v[184:187], v[216:219], v[84:87]
	v_mfma_f32_16x16x32_bf16 v[80:83], v[192:195], v[216:219], v[80:83]
	v_mfma_f32_16x16x32_bf16 v[68:71], v[184:187], v[224:227], v[68:71]
	v_mfma_f32_16x16x32_bf16 v[64:67], v[192:195], v[224:227], v[64:67]
	v_mfma_f32_16x16x32_bf16 v[116:119], v[188:191], v[204:207], v[116:119]
	v_mfma_f32_16x16x32_bf16 v[112:115], v[196:199], v[204:207], v[112:115]
	v_mfma_f32_16x16x32_bf16 v[100:103], v[188:191], v[212:215], v[100:103]
	v_mfma_f32_16x16x32_bf16 v[96:99], v[196:199], v[212:215], v[96:99]
	v_mfma_f32_16x16x32_bf16 v[84:87], v[188:191], v[220:223], v[84:87]
	v_mfma_f32_16x16x32_bf16 v[80:83], v[196:199], v[220:223], v[80:83]
	v_mfma_f32_16x16x32_bf16 v[68:71], v[188:191], v[228:231], v[68:71]
	v_mfma_f32_16x16x32_bf16 v[64:67], v[196:199], v[228:231], v[64:67]
	s_setprio 0
	s_barrier
	s_add_i32 s65, s58, s48
	v_lshl_add_u64 v[232:233], s[40:41], 0, v[138:139]
	s_mov_b32 m0, s65
	ds_read_b128 v[200:203], v174 offset:16384
	ds_read_b128 v[204:207], v174 offset:17408
	ds_read_b128 v[208:211], v174 offset:18432
	ds_read_b128 v[212:215], v174 offset:19456
	ds_read_b128 v[216:219], v174 offset:20480
	ds_read_b128 v[220:223], v174 offset:21504
	ds_read_b128 v[224:227], v174 offset:22528
	ds_read_b128 v[228:231], v174 offset:23552
	global_load_lds_dwordx4 v138, s[40:41]
	s_add_i32 m0, s65, 0x2000
	s_add_u32 s66, s40, 0x40000
	v_lshl_add_u64 v[234:235], s[40:41], 0, v[142:143]
	s_addc_u32 s67, s41, 0
	s_add_i32 s65, s59, s48
	global_load_lds_dwordx4 v142, s[40:41]
	s_mov_b32 m0, s65
	s_nop 0
	global_load_lds_dwordx4 v138, s[66:67]
	s_add_i32 m0, s65, 0x2000
	s_nop 0
	global_load_lds_dwordx4 v142, s[66:67]
	s_mov_b32 m0, s49
	s_nop 0
	global_load_lds_dwordx4 v136, s[42:43]
	v_lshl_add_u64 v[236:237], s[42:43], 0, v[140:141]
	s_mov_b32 m0, s50
	s_nop 0
	global_load_lds_dwordx4 v140, s[42:43]
	s_waitcnt vmcnt(8)
	s_waitcnt lgkmcnt(0)
	s_barrier
; #define PG8_STAGE(bufoff, gbase, voff) do { _Pragma("unroll") for (int _i = 0; _i < 2; ++_i) \
;         __builtin_amdgcn_global_load_lds((const unsigned*)((const char*)(gbase) + (voff)[_i]), (PG8_LAS unsigned*)(lds + (bufoff) + ldsw + _i * 8192), 16, 0, 0); } while (0)
; #define PG8_LDA(dst, b, h) do { _Pragma("unroll") for (int m = 0; m < 4; ++m) _Pragma("unroll") for (int k = 0; k < 2; ++k) dst[m][k] = *(const PG8_LAS bf16x8*)(lds + PG8_SA(b, h) + aoff + m * 2048 + k * 1024); } while (0)
; #define PG8_LDB(dst, b, h) do { _Pragma("unroll") for (int n = 0; n < 2; ++n) _Pragma("unroll") for (int k = 0; k < 2; ++k) dst[n][k] = *(const PG8_LAS bf16x8*)(lds + PG8_SB(b, h) + boff + n * 2048 + k * 1024); } while (0)
; #define PG8_MMA(ai, bj, At, Bt) do { __builtin_amdgcn_s_setprio(1); _Pragma("unroll") for (int m = 0; m < 4; ++m) _Pragma("unroll") for (int n = 0; n < 2; ++n) _Pragma("unroll") for (int k = 0; k < 2; ++k) \
;         acc[ai][bj][m][n] = __builtin_amdgcn_mfma_f32_16x16x32_bf16(Bt[n][k], At[m][k], acc[ai][bj][m][n], 0, 0, 0); __builtin_amdgcn_s_setprio(0); } while (0)
; #define PG8_WAIT_V(n) asm volatile("s_waitcnt vmcnt(" #n ")" ::: "memory")
; #define PG8_WAIT_L(n) asm volatile("s_waitcnt lgkmcnt(" #n ")" ::: "memory")
; #define PG8_BAR __builtin_amdgcn_s_barrier()
; #define PG8_SCHED __builtin_amdgcn_sched_barrier(0)
; template <class Epi, class Sched, bool ALIGN_EPI = false, bool SP2 = false>
; __device__ __forceinline__ void gemm_phase(PG8_LAS unsigned char* lds, const Gemm g, const Sched& S, const Epi& E) {
;     ...
;             PG8_WAIT_V(8); PG8_WAIT_L(0); PG8_BAR; PG8_MMA(1, 0, At, B0); PG8_MMA(1, 1, At, B1); PG8_BAR; PG8_SCHED;
;             PG8_LDB(B0, 1, 0); PG8_LDB(B1, 1, 1); PG8_SCHED; PG8_LDA(At, 1, 0); PG8_STAGE(PG8_SA(0, 1), a2 + hstepA, voffA);
;             PG8_WAIT_V(8); PG8_WAIT_L(0); PG8_BAR; PG8_MMA(0, 0, At, B0); PG8_MMA(0, 1, At, B1); PG8_BAR; PG8_SCHED;
	s_setprio 1
	s_waitcnt lgkmcnt(0)
	v_mfma_f32_16x16x32_bf16 v[60:63], v[132:135], v[200:203], v[60:63]
	v_mfma_f32_16x16x32_bf16 v[56:59], v[176:179], v[200:203], v[56:59]
	v_mfma_f32_16x16x32_bf16 v[44:47], v[132:135], v[208:211], v[44:47]
	v_mfma_f32_16x16x32_bf16 v[40:43], v[176:179], v[208:211], v[40:43]
	v_mfma_f32_16x16x32_bf16 v[28:31], v[132:135], v[216:219], v[28:31]
	v_mfma_f32_16x16x32_bf16 v[24:27], v[176:179], v[216:219], v[24:27]
	v_mfma_f32_16x16x32_bf16 v[12:15], v[132:135], v[224:227], v[12:15]
	v_mfma_f32_16x16x32_bf16 v[8:11], v[176:179], v[224:227], v[8:11]
	v_mfma_f32_16x16x32_bf16 v[60:63], v[158:161], v[204:207], v[60:63]
	v_mfma_f32_16x16x32_bf16 v[56:59], v[180:183], v[204:207], v[56:59]
	v_mfma_f32_16x16x32_bf16 v[44:47], v[158:161], v[212:215], v[44:47]
	v_mfma_f32_16x16x32_bf16 v[40:43], v[180:183], v[212:215], v[40:43]
	v_mfma_f32_16x16x32_bf16 v[28:31], v[158:161], v[220:223], v[28:31]
	v_mfma_f32_16x16x32_bf16 v[24:27], v[180:183], v[220:223], v[24:27]
	v_mfma_f32_16x16x32_bf16 v[12:15], v[158:161], v[228:231], v[12:15]
	v_mfma_f32_16x16x32_bf16 v[8:11], v[180:183], v[228:231], v[8:11]
	s_setprio 0
	s_setprio 1
	v_mfma_f32_16x16x32_bf16 v[52:55], v[184:187], v[200:203], v[52:55]
	v_mfma_f32_16x16x32_bf16 v[48:51], v[192:195], v[200:203], v[48:51]
	v_mfma_f32_16x16x32_bf16 v[36:39], v[184:187], v[208:211], v[36:39]
	v_mfma_f32_16x16x32_bf16 v[32:35], v[192:195], v[208:211], v[32:35]
	v_mfma_f32_16x16x32_bf16 v[20:23], v[184:187], v[216:219], v[20:23]
	v_mfma_f32_16x16x32_bf16 v[16:19], v[192:195], v[216:219], v[16:19]
	v_mfma_f32_16x16x32_bf16 v[4:7], v[184:187], v[224:227], v[4:7]
	v_mfma_f32_16x16x32_bf16 v[0:3], v[192:195], v[224:227], v[0:3]
	v_mfma_f32_16x16x32_bf16 v[52:55], v[188:191], v[204:207], v[52:55]
	v_mfma_f32_16x16x32_bf16 v[48:51], v[196:199], v[204:207], v[48:51]
	v_mfma_f32_16x16x32_bf16 v[36:39], v[188:191], v[212:215], v[36:39]
	v_mfma_f32_16x16x32_bf16 v[32:35], v[196:199], v[212:215], v[32:35]
	v_mfma_f32_16x16x32_bf16 v[20:23], v[188:191], v[220:223], v[20:23]
	v_mfma_f32_16x16x32_bf16 v[16:19], v[196:199], v[220:223], v[16:19]
	v_mfma_f32_16x16x32_bf16 v[4:7], v[188:191], v[228:231], v[4:7]
	v_mfma_f32_16x16x32_bf16 v[0:3], v[196:199], v[228:231], v[0:3]
	s_setprio 0
	s_barrier
	s_add_i32 s65, 0, 0x18000
	v_add_u32_e32 v144, s65, v163
	s_add_i32 s66, 0, 0x1c000
	ds_read_b128 v[132:135], v144
	ds_read_b128 v[158:161], v144 offset:1024
	ds_read_b128 v[176:179], v144 offset:2048
	ds_read_b128 v[180:183], v144 offset:3072
	v_add_u32_e32 v144, s66, v163
	ds_read_b128 v[184:187], v144
	ds_read_b128 v[188:191], v144 offset:1024
	ds_read_b128 v[192:195], v144 offset:2048
	ds_read_b128 v[196:199], v144 offset:3072
	s_add_u32 s42, s42, 0x40000
	s_addc_u32 s43, s43, 0
	s_mov_b32 m0, s51
	ds_read_b128 v[200:203], v174 offset:32768
	ds_read_b128 v[204:207], v174 offset:33792
	ds_read_b128 v[208:211], v174 offset:34816
	ds_read_b128 v[212:215], v174 offset:35840
	ds_read_b128 v[216:219], v174 offset:36864
	ds_read_b128 v[220:223], v174 offset:37888
	ds_read_b128 v[224:227], v174 offset:38912
	ds_read_b128 v[228:231], v174 offset:39936
	global_load_lds_dwordx4 v136, s[42:43]
	v_lshl_add_u64 v[236:237], s[42:43], 0, v[140:141]
	s_mov_b32 m0, s52
	s_nop 0
	global_load_lds_dwordx4 v140, s[42:43]
	s_waitcnt vmcnt(8)
	s_waitcnt lgkmcnt(0)
	s_barrier
	s_setprio 1
	s_waitcnt lgkmcnt(0)
	v_mfma_f32_16x16x32_bf16 v[124:127], v[132:135], v[200:203], v[124:127]
	v_mfma_f32_16x16x32_bf16 v[120:123], v[176:179], v[200:203], v[120:123]
	v_mfma_f32_16x16x32_bf16 v[108:111], v[132:135], v[208:211], v[108:111]
	v_mfma_f32_16x16x32_bf16 v[104:107], v[176:179], v[208:211], v[104:107]
	v_mfma_f32_16x16x32_bf16 v[92:95], v[132:135], v[216:219], v[92:95]
	v_mfma_f32_16x16x32_bf16 v[88:91], v[176:179], v[216:219], v[88:91]
	v_mfma_f32_16x16x32_bf16 v[76:79], v[132:135], v[224:227], v[76:79]
	v_mfma_f32_16x16x32_bf16 v[72:75], v[176:179], v[224:227], v[72:75]
	v_mfma_f32_16x16x32_bf16 v[124:127], v[158:161], v[204:207], v[124:127]
	v_mfma_f32_16x16x32_bf16 v[120:123], v[180:183], v[204:207], v[120:123]
	v_mfma_f32_16x16x32_bf16 v[108:111], v[158:161], v[212:215], v[108:111]
	v_mfma_f32_16x16x32_bf16 v[104:107], v[180:183], v[212:215], v[104:107]
	v_mfma_f32_16x16x32_bf16 v[92:95], v[158:161], v[220:223], v[92:95]
	v_mfma_f32_16x16x32_bf16 v[88:91], v[180:183], v[220:223], v[88:91]
	v_mfma_f32_16x16x32_bf16 v[76:79], v[158:161], v[228:231], v[76:79]
	v_mfma_f32_16x16x32_bf16 v[72:75], v[180:183], v[228:231], v[72:75]
	s_setprio 0
	s_setprio 1
	v_mfma_f32_16x16x32_bf16 v[116:119], v[184:187], v[200:203], v[116:119]
	v_mfma_f32_16x16x32_bf16 v[112:115], v[192:195], v[200:203], v[112:115]
	v_mfma_f32_16x16x32_bf16 v[100:103], v[184:187], v[208:211], v[100:103]
	v_mfma_f32_16x16x32_bf16 v[96:99], v[192:195], v[208:211], v[96:99]
	v_mfma_f32_16x16x32_bf16 v[84:87], v[184:187], v[216:219], v[84:87]
	v_mfma_f32_16x16x32_bf16 v[80:83], v[192:195], v[216:219], v[80:83]
	v_mfma_f32_16x16x32_bf16 v[68:71], v[184:187], v[224:227], v[68:71]
	v_mfma_f32_16x16x32_bf16 v[64:67], v[192:195], v[224:227], v[64:67]
	v_mfma_f32_16x16x32_bf16 v[116:119], v[188:191], v[204:207], v[116:119]
	v_mfma_f32_16x16x32_bf16 v[112:115], v[196:199], v[204:207], v[112:115]
	v_mfma_f32_16x16x32_bf16 v[100:103], v[188:191], v[212:215], v[100:103]
	v_mfma_f32_16x16x32_bf16 v[96:99], v[196:199], v[212:215], v[96:99]
	v_mfma_f32_16x16x32_bf16 v[84:87], v[188:191], v[220:223], v[84:87]
	v_mfma_f32_16x16x32_bf16 v[80:83], v[196:199], v[220:223], v[80:83]
	v_mfma_f32_16x16x32_bf16 v[68:71], v[188:191], v[228:231], v[68:71]
	v_mfma_f32_16x16x32_bf16 v[64:67], v[196:199], v[228:231], v[64:67]
	s_setprio 0
	s_barrier
; #define PG8_STAGE(bufoff, gbase, voff) do { _Pragma("unroll") for (int _i = 0; _i < 2; ++_i) \
;         __builtin_amdgcn_global_load_lds((const unsigned*)((const char*)(gbase) + (voff)[_i]), (PG8_LAS unsigned*)(lds + (bufoff) + ldsw + _i * 8192), 16, 0, 0); } while (0)
; #define PG8_LDA(dst, b, h) do { _Pragma("unroll") for (int m = 0; m < 4; ++m) _Pragma("unroll") for (int k = 0; k < 2; ++k) dst[m][k] = *(const PG8_LAS bf16x8*)(lds + PG8_SA(b, h) + aoff + m * 2048 + k * 1024); } while (0)
; #define PG8_MMA(ai, bj, At, Bt) do { __builtin_amdgcn_s_setprio(1); _Pragma("unroll") for (int m = 0; m < 4; ++m) _Pragma("unroll") for (int n = 0; n < 2; ++n) _Pragma("unroll") for (int k = 0; k < 2; ++k) \
;         acc[ai][bj][m][n] = __builtin_amdgcn_mfma_f32_16x16x32_bf16(Bt[n][k], At[m][k], acc[ai][bj][m][n], 0, 0, 0); __builtin_amdgcn_s_setprio(0); } while (0)
; #define PG8_WAIT_V(n) asm volatile("s_waitcnt vmcnt(" #n ")" ::: "memory")
; #define PG8_WAIT_L(n) asm volatile("s_waitcnt lgkmcnt(" #n ")" ::: "memory")
; #define PG8_BAR __builtin_amdgcn_s_barrier()
; #define PG8_SCHED __builtin_amdgcn_sched_barrier(0)
; template <class Epi, class Sched, bool ALIGN_EPI = false, bool SP2 = false>
; __device__ __forceinline__ void gemm_phase(PG8_LAS unsigned char* lds, const Gemm g, const Sched& S, const Epi& E) {
;     ...
;             PG8_LDA(At, 1, 1); PG8_STAGE(PG8_SB(1, 0), b3, voffB); PG8_STAGE(PG8_SB(1, 1), b3 + hstepB, voffB); PG8_STAGE(PG8_SA(1, 0), a3, voffA);
;             PG8_WAIT_V(8); PG8_WAIT_L(0); PG8_BAR; PG8_MMA(1, 0, At, B0); PG8_MMA(1, 1, At, B1); PG8_BAR; PG8_SCHED;
	s_add_i32 s42, s65, s48
	v_lshl_add_u64 v[232:233], v[232:233], 0, s[14:15]
	s_mov_b32 m0, s42
	ds_read_b128 v[200:203], v174 offset:49152
	ds_read_b128 v[204:207], v174 offset:50176
	ds_read_b128 v[208:211], v174 offset:51200
	ds_read_b128 v[212:215], v174 offset:52224
	ds_read_b128 v[216:219], v174 offset:53248
	ds_read_b128 v[220:223], v174 offset:54272
	ds_read_b128 v[224:227], v174 offset:55296
	ds_read_b128 v[228:231], v174 offset:56320
	global_load_lds_dwordx4 v[232:233], off
	s_add_i32 m0, s42, 0x2000
	s_add_u32 s40, s40, 0x40080
	v_lshl_add_u64 v[232:233], v[234:235], 0, s[14:15]
	s_addc_u32 s41, s41, 0
	s_add_i32 s42, s66, s48
	global_load_lds_dwordx4 v[232:233], off
	s_mov_b32 m0, s42
	s_nop 0
	global_load_lds_dwordx4 v138, s[40:41]
	s_add_i32 m0, s42, 0x2000
	s_nop 0
	global_load_lds_dwordx4 v142, s[40:41]
	s_mov_b32 m0, s53
	s_nop 0
	global_load_lds_dwordx4 v136, s[38:39]
	v_lshl_add_u64 v[232:233], s[38:39], 0, v[140:141]
	s_mov_b32 m0, s54
	s_nop 0
	global_load_lds_dwordx4 v140, s[38:39]
	s_waitcnt vmcnt(8)
	s_waitcnt lgkmcnt(0)
	s_barrier
	s_setprio 1
	s_waitcnt lgkmcnt(0)
	v_mfma_f32_16x16x32_bf16 v[60:63], v[132:135], v[200:203], v[60:63]
	v_mfma_f32_16x16x32_bf16 v[56:59], v[176:179], v[200:203], v[56:59]
	v_mfma_f32_16x16x32_bf16 v[44:47], v[132:135], v[208:211], v[44:47]
	v_mfma_f32_16x16x32_bf16 v[40:43], v[176:179], v[208:211], v[40:43]
	v_mfma_f32_16x16x32_bf16 v[28:31], v[132:135], v[216:219], v[28:31]
	v_mfma_f32_16x16x32_bf16 v[24:27], v[176:179], v[216:219], v[24:27]
	v_mfma_f32_16x16x32_bf16 v[12:15], v[132:135], v[224:227], v[12:15]
	v_mfma_f32_16x16x32_bf16 v[8:11], v[176:179], v[224:227], v[8:11]
	v_mfma_f32_16x16x32_bf16 v[60:63], v[158:161], v[204:207], v[60:63]
	v_mfma_f32_16x16x32_bf16 v[56:59], v[180:183], v[204:207], v[56:59]
	v_mfma_f32_16x16x32_bf16 v[44:47], v[158:161], v[212:215], v[44:47]
	v_mfma_f32_16x16x32_bf16 v[40:43], v[180:183], v[212:215], v[40:43]
	v_mfma_f32_16x16x32_bf16 v[28:31], v[158:161], v[220:223], v[28:31]
	v_mfma_f32_16x16x32_bf16 v[24:27], v[180:183], v[220:223], v[24:27]
	v_mfma_f32_16x16x32_bf16 v[12:15], v[158:161], v[228:231], v[12:15]
	v_mfma_f32_16x16x32_bf16 v[8:11], v[180:183], v[228:231], v[8:11]
	s_setprio 0
	s_setprio 1
	v_mfma_f32_16x16x32_bf16 v[52:55], v[184:187], v[200:203], v[52:55]
	v_mfma_f32_16x16x32_bf16 v[48:51], v[192:195], v[200:203], v[48:51]
	v_mfma_f32_16x16x32_bf16 v[36:39], v[184:187], v[208:211], v[36:39]
	v_mfma_f32_16x16x32_bf16 v[32:35], v[192:195], v[208:211], v[32:35]
	v_mfma_f32_16x16x32_bf16 v[20:23], v[184:187], v[216:219], v[20:23]
	v_mfma_f32_16x16x32_bf16 v[16:19], v[192:195], v[216:219], v[16:19]
	v_mfma_f32_16x16x32_bf16 v[4:7], v[184:187], v[224:227], v[4:7]
	v_mfma_f32_16x16x32_bf16 v[0:3], v[192:195], v[224:227], v[0:3]
	v_mfma_f32_16x16x32_bf16 v[52:55], v[188:191], v[204:207], v[52:55]
	v_mfma_f32_16x16x32_bf16 v[48:51], v[196:199], v[204:207], v[48:51]
	v_mfma_f32_16x16x32_bf16 v[36:39], v[188:191], v[212:215], v[36:39]
	v_mfma_f32_16x16x32_bf16 v[32:35], v[196:199], v[212:215], v[32:35]
	v_mfma_f32_16x16x32_bf16 v[20:23], v[188:191], v[220:223], v[20:23]
	v_mfma_f32_16x16x32_bf16 v[16:19], v[196:199], v[220:223], v[16:19]
	v_mfma_f32_16x16x32_bf16 v[4:7], v[188:191], v[228:231], v[4:7]
	v_mfma_f32_16x16x32_bf16 v[0:3], v[196:199], v[228:231], v[0:3]
	s_setprio 0
	s_barrier
	s_add_i32 s64, s64, 2
	s_add_u32 s34, s34, 0x100
	s_addc_u32 s35, s35, 0
	s_cmp_gt_u32 s64, 13
	s_cbranch_scc0 .LBB0_1638
	s_and_b64 vcc, exec, s[16:17]
	s_cbranch_vccz .LBB0_1643
	s_barrier
	s_cmp_gt_i32 s30, 3
	s_mov_b64 s[28:29], -1
	s_cbranch_scc1 .LBB0_1644

; #define PG8_STAGE(bufoff, gbase, voff) do { _Pragma("unroll") for (int _i = 0; _i < 2; ++_i) \
;         __builtin_amdgcn_global_load_lds((const unsigned*)((const char*)(gbase) + (voff)[_i]), (PG8_LAS unsigned*)(lds + (bufoff) + ldsw + _i * 8192), 16, 0, 0); } while (0)
; #define PG8_LDA(dst, b, h) do { _Pragma("unroll") for (int m = 0; m < 4; ++m) _Pragma("unroll") for (int k = 0; k < 2; ++k) dst[m][k] = *(const PG8_LAS bf16x8*)(lds + PG8_SA(b, h) + aoff + m * 2048 + k * 1024); } while (0)
; #define PG8_LDB(dst, b, h) do { _Pragma("unroll") for (int n = 0; n < 2; ++n) _Pragma("unroll") for (int k = 0; k < 2; ++k) dst[n][k] = *(const PG8_LAS bf16x8*)(lds + PG8_SB(b, h) + boff + n * 2048 + k * 1024); } while (0)
; #define PG8_MMA(ai, bj, At, Bt) do { __builtin_amdgcn_s_setprio(1); _Pragma("unroll") for (int m = 0; m < 4; ++m) _Pragma("unroll") for (int n = 0; n < 2; ++n) _Pragma("unroll") for (int k = 0; k < 2; ++k) \
;         acc[ai][bj][m][n] = __builtin_amdgcn_mfma_f32_16x16x32_bf16(Bt[n][k], At[m][k], acc[ai][bj][m][n], 0, 0, 0); __builtin_amdgcn_s_setprio(0); } while (0)
; #define PG8_WAIT_V(n) asm volatile("s_waitcnt vmcnt(" #n ")" ::: "memory")
; #define PG8_WAIT_L(n) asm volatile("s_waitcnt lgkmcnt(" #n ")" ::: "memory")
; #define PG8_BAR __builtin_amdgcn_s_barrier()
; #define PG8_SCHED __builtin_amdgcn_sched_barrier(0)
; template <class Epi, class Sched, bool ALIGN_EPI = false, bool SP2 = false>
; __device__ __forceinline__ void gemm_phase(PG8_LAS unsigned char* lds, const Gemm g, const Sched& S, const Epi& E) {
;     ...
;         for (int t = 0; t < nt; t += 2) {
;             const bool last = (t == nt - 2);
;             const char* a1 = cA + PG8_AK(t + 1);
;             const char* a2 = last ? nA : cA + PG8_AK(t + 2); const char* b2 = last ? nB : cB + (size_t)(t + 2) * kstep;
;             const char* a3 = last ? nA + PG8_AK(1) : cA + PG8_AK(t + 3); const char* b3 = b2 + kstep;
;             if (last && has_next) S.a_ready(nxt);
;             if constexpr (SP2) {
;             PG8_LDB(B0, 0, 0); PG8_LDB(B1, 0, 1); PG8_SCHED; PG8_LDA(At, 0, 0); PG8_STAGE(PG8_SA(1, 1), a1 + hstepA, voffA);
;             PG8_WAIT_V(8); PG8_WAIT_L(0); PG8_BAR; PG8_MMA(0, 0, At, B0); PG8_MMA(0, 1, At, B1); PG8_BAR; PG8_SCHED;
;             PG8_LDA(At, 0, 1); PG8_STAGE(PG8_SB(0, 0), b2, voffB); PG8_STAGE(PG8_SB(0, 1), b2 + hstepB, voffB); PG8_STAGE(PG8_SA(0, 0), a2, voffA);
.LBB0_1841:
	ds_read_b128 v[132:135], v191
	ds_read_b128 v[136:139], v191 offset:1024
	ds_read_b128 v[140:143], v191 offset:2048
	ds_read_b128 v[162:165], v191 offset:3072
	ds_read_b128 v[166:169], v192
	ds_read_b128 v[194:197], v192 offset:1024
	ds_read_b128 v[198:201], v192 offset:2048
	ds_read_b128 v[202:205], v192 offset:3072
	s_add_u32 s40, s36, s38
	s_addc_u32 s41, s37, s39
	s_add_u32 s42, s40, 0x100
	s_addc_u32 s43, s41, 0
	s_add_u32 s70, s69, s38
	s_addc_u32 s71, s78, s39
	s_add_u32 s40, s40, 0x180
	s_addc_u32 s41, s41, 0
	s_cmpk_eq_i32 s38, 0x700
	s_cselect_b32 s45, s3, s43
	s_cselect_b32 s44, s27, s42
	s_cselect_b32 s43, s25, s71
	s_cselect_b32 s42, s35, s70
	s_cselect_b32 s41, s68, s41
	s_cselect_b32 s40, s67, s40
	v_lshl_add_u64 v[170:171], v[130:131], 0, s[38:39]
	s_add_i32 m0, s52, 0xc000
	ds_read_b128 v[206:209], v174
	ds_read_b128 v[210:213], v174 offset:1024
	ds_read_b128 v[214:217], v174 offset:2048
	ds_read_b128 v[218:221], v174 offset:3072
	ds_read_b128 v[222:225], v174 offset:4096
	ds_read_b128 v[226:229], v174 offset:5120
	ds_read_b128 v[230:233], v174 offset:6144
	ds_read_b128 v[234:237], v174 offset:7168
	global_load_lds_dwordx4 v[170:171], off
	v_lshl_add_u64 v[170:171], v[128:129], 0, s[38:39]
	s_add_i32 m0, s52, 0xe000
	s_nop 0
	global_load_lds_dwordx4 v[170:171], off
	s_waitcnt vmcnt(8)
	s_waitcnt lgkmcnt(0)
	s_barrier
	s_setprio 1
	s_waitcnt lgkmcnt(0)
	v_mfma_f32_16x16x32_bf16 v[124:127], v[132:135], v[206:209], v[124:127]
	v_mfma_f32_16x16x32_bf16 v[120:123], v[140:143], v[206:209], v[120:123]
	v_mfma_f32_16x16x32_bf16 v[116:119], v[132:135], v[214:217], v[116:119]
	v_mfma_f32_16x16x32_bf16 v[112:115], v[140:143], v[214:217], v[112:115]
	v_mfma_f32_16x16x32_bf16 v[108:111], v[132:135], v[222:225], v[108:111]
	v_mfma_f32_16x16x32_bf16 v[104:107], v[140:143], v[222:225], v[104:107]
	v_mfma_f32_16x16x32_bf16 v[100:103], v[132:135], v[230:233], v[100:103]
	v_mfma_f32_16x16x32_bf16 v[96:99], v[140:143], v[230:233], v[96:99]
	v_mfma_f32_16x16x32_bf16 v[124:127], v[136:139], v[210:213], v[124:127]
	v_mfma_f32_16x16x32_bf16 v[120:123], v[162:165], v[210:213], v[120:123]
	v_mfma_f32_16x16x32_bf16 v[116:119], v[136:139], v[218:221], v[116:119]
	v_mfma_f32_16x16x32_bf16 v[112:115], v[162:165], v[218:221], v[112:115]
	v_mfma_f32_16x16x32_bf16 v[108:111], v[136:139], v[226:229], v[108:111]
	v_mfma_f32_16x16x32_bf16 v[104:107], v[162:165], v[226:229], v[104:107]
	v_mfma_f32_16x16x32_bf16 v[100:103], v[136:139], v[234:237], v[100:103]
	v_mfma_f32_16x16x32_bf16 v[96:99], v[162:165], v[234:237], v[96:99]
	s_setprio 0
	s_setprio 1
	v_mfma_f32_16x16x32_bf16 v[60:63], v[166:169], v[206:209], v[60:63]
	v_mfma_f32_16x16x32_bf16 v[56:59], v[198:201], v[206:209], v[56:59]
	v_mfma_f32_16x16x32_bf16 v[52:55], v[166:169], v[214:217], v[52:55]
	v_mfma_f32_16x16x32_bf16 v[48:51], v[198:201], v[214:217], v[48:51]
	v_mfma_f32_16x16x32_bf16 v[44:47], v[166:169], v[222:225], v[44:47]
	v_mfma_f32_16x16x32_bf16 v[40:43], v[198:201], v[222:225], v[40:43]
	v_mfma_f32_16x16x32_bf16 v[36:39], v[166:169], v[230:233], v[36:39]
	v_mfma_f32_16x16x32_bf16 v[32:35], v[198:201], v[230:233], v[32:35]
	v_mfma_f32_16x16x32_bf16 v[60:63], v[194:197], v[210:213], v[60:63]
	v_mfma_f32_16x16x32_bf16 v[56:59], v[202:205], v[210:213], v[56:59]
	v_mfma_f32_16x16x32_bf16 v[52:55], v[194:197], v[218:221], v[52:55]
	v_mfma_f32_16x16x32_bf16 v[48:51], v[202:205], v[218:221], v[48:51]
	v_mfma_f32_16x16x32_bf16 v[44:47], v[194:197], v[226:229], v[44:47]
	v_mfma_f32_16x16x32_bf16 v[40:43], v[202:205], v[226:229], v[40:43]
	v_mfma_f32_16x16x32_bf16 v[36:39], v[194:197], v[234:237], v[36:39]
	v_mfma_f32_16x16x32_bf16 v[32:35], v[202:205], v[234:237], v[32:35]
	s_setprio 0
	s_barrier
	s_add_i32 s70, s64, s51
	v_lshl_add_u64 v[170:171], s[42:43], 0, v[146:147]
	s_mov_b32 m0, s70
	ds_read_b128 v[206:209], v174 offset:16384
	ds_read_b128 v[210:213], v174 offset:17408
	ds_read_b128 v[214:217], v174 offset:18432
	ds_read_b128 v[218:221], v174 offset:19456
	ds_read_b128 v[222:225], v174 offset:20480
	ds_read_b128 v[226:229], v174 offset:21504
	ds_read_b128 v[230:233], v174 offset:22528
	ds_read_b128 v[234:237], v174 offset:23552
	global_load_lds_dwordx4 v146, s[42:43]
	s_add_i32 m0, s70, 0x2000
	s_add_u32 s70, s42, 0x40000
	v_lshl_add_u64 v[238:239], s[42:43], 0, v[150:151]
	s_addc_u32 s71, s43, 0
	s_add_i32 s80, s65, s51
	global_load_lds_dwordx4 v150, s[42:43]
	s_mov_b32 m0, s80
	s_nop 0
	global_load_lds_dwordx4 v146, s[70:71]
	s_add_i32 m0, s80, 0x2000
	s_nop 0
	global_load_lds_dwordx4 v150, s[70:71]
	s_mov_b32 m0, s52
	s_nop 0
	global_load_lds_dwordx4 v144, s[44:45]
	v_lshl_add_u64 v[240:241], s[44:45], 0, v[148:149]
	s_mov_b32 m0, s53
	s_nop 0
	global_load_lds_dwordx4 v148, s[44:45]
	s_waitcnt vmcnt(8)
	s_waitcnt lgkmcnt(0)
	s_barrier
; #define PG8_STAGE(bufoff, gbase, voff) do { _Pragma("unroll") for (int _i = 0; _i < 2; ++_i) \
;         __builtin_amdgcn_global_load_lds((const unsigned*)((const char*)(gbase) + (voff)[_i]), (PG8_LAS unsigned*)(lds + (bufoff) + ldsw + _i * 8192), 16, 0, 0); } while (0)
; #define PG8_LDA(dst, b, h) do { _Pragma("unroll") for (int m = 0; m < 4; ++m) _Pragma("unroll") for (int k = 0; k < 2; ++k) dst[m][k] = *(const PG8_LAS bf16x8*)(lds + PG8_SA(b, h) + aoff + m * 2048 + k * 1024); } while (0)
; #define PG8_LDB(dst, b, h) do { _Pragma("unroll") for (int n = 0; n < 2; ++n) _Pragma("unroll") for (int k = 0; k < 2; ++k) dst[n][k] = *(const PG8_LAS bf16x8*)(lds + PG8_SB(b, h) + boff + n * 2048 + k * 1024); } while (0)
; #define PG8_MMA(ai, bj, At, Bt) do { __builtin_amdgcn_s_setprio(1); _Pragma("unroll") for (int m = 0; m < 4; ++m) _Pragma("unroll") for (int n = 0; n < 2; ++n) _Pragma("unroll") for (int k = 0; k < 2; ++k) \
;         acc[ai][bj][m][n] = __builtin_amdgcn_mfma_f32_16x16x32_bf16(Bt[n][k], At[m][k], acc[ai][bj][m][n], 0, 0, 0); __builtin_amdgcn_s_setprio(0); } while (0)
; #define PG8_WAIT_V(n) asm volatile("s_waitcnt vmcnt(" #n ")" ::: "memory")
; #define PG8_WAIT_L(n) asm volatile("s_waitcnt lgkmcnt(" #n ")" ::: "memory")
; #define PG8_BAR __builtin_amdgcn_s_barrier()
; #define PG8_SCHED __builtin_amdgcn_sched_barrier(0)
; template <class Epi, class Sched, bool ALIGN_EPI = false, bool SP2 = false>
; __device__ __forceinline__ void gemm_phase(PG8_LAS unsigned char* lds, const Gemm g, const Sched& S, const Epi& E) {
;     ...
;             PG8_WAIT_V(8); PG8_WAIT_L(0); PG8_BAR; PG8_MMA(1, 0, At, B0); PG8_MMA(1, 1, At, B1); PG8_BAR; PG8_SCHED;
;             PG8_LDB(B0, 1, 0); PG8_LDB(B1, 1, 1); PG8_SCHED; PG8_LDA(At, 1, 0); PG8_STAGE(PG8_SA(0, 1), a2 + hstepA, voffA);
;             PG8_WAIT_V(8); PG8_WAIT_L(0); PG8_BAR; PG8_MMA(0, 0, At, B0); PG8_MMA(0, 1, At, B1); PG8_BAR; PG8_SCHED;
	s_setprio 1
	s_waitcnt lgkmcnt(0)
	v_mfma_f32_16x16x32_bf16 v[92:95], v[132:135], v[206:209], v[92:95]
	v_mfma_f32_16x16x32_bf16 v[88:91], v[140:143], v[206:209], v[88:91]
	v_mfma_f32_16x16x32_bf16 v[84:87], v[132:135], v[214:217], v[84:87]
	v_mfma_f32_16x16x32_bf16 v[80:83], v[140:143], v[214:217], v[80:83]
	v_mfma_f32_16x16x32_bf16 v[76:79], v[132:135], v[222:225], v[76:79]
	v_mfma_f32_16x16x32_bf16 v[72:75], v[140:143], v[222:225], v[72:75]
	v_mfma_f32_16x16x32_bf16 v[68:71], v[132:135], v[230:233], v[68:71]
	v_mfma_f32_16x16x32_bf16 v[64:67], v[140:143], v[230:233], v[64:67]
	v_mfma_f32_16x16x32_bf16 v[92:95], v[136:139], v[210:213], v[92:95]
	v_mfma_f32_16x16x32_bf16 v[88:91], v[162:165], v[210:213], v[88:91]
	v_mfma_f32_16x16x32_bf16 v[84:87], v[136:139], v[218:221], v[84:87]
	v_mfma_f32_16x16x32_bf16 v[80:83], v[162:165], v[218:221], v[80:83]
	v_mfma_f32_16x16x32_bf16 v[76:79], v[136:139], v[226:229], v[76:79]
	v_mfma_f32_16x16x32_bf16 v[72:75], v[162:165], v[226:229], v[72:75]
	v_mfma_f32_16x16x32_bf16 v[68:71], v[136:139], v[234:237], v[68:71]
	v_mfma_f32_16x16x32_bf16 v[64:67], v[162:165], v[234:237], v[64:67]
	s_setprio 0
	s_setprio 1
	v_mfma_f32_16x16x32_bf16 v[28:31], v[166:169], v[206:209], v[28:31]
	v_mfma_f32_16x16x32_bf16 v[24:27], v[198:201], v[206:209], v[24:27]
	v_mfma_f32_16x16x32_bf16 v[20:23], v[166:169], v[214:217], v[20:23]
	v_mfma_f32_16x16x32_bf16 v[16:19], v[198:201], v[214:217], v[16:19]
	v_mfma_f32_16x16x32_bf16 v[12:15], v[166:169], v[222:225], v[12:15]
	v_mfma_f32_16x16x32_bf16 v[8:11], v[198:201], v[222:225], v[8:11]
	v_mfma_f32_16x16x32_bf16 v[4:7], v[166:169], v[230:233], v[4:7]
	v_mfma_f32_16x16x32_bf16 v[0:3], v[198:201], v[230:233], v[0:3]
	v_mfma_f32_16x16x32_bf16 v[28:31], v[194:197], v[210:213], v[28:31]
	v_mfma_f32_16x16x32_bf16 v[24:27], v[202:205], v[210:213], v[24:27]
	v_mfma_f32_16x16x32_bf16 v[20:23], v[194:197], v[218:221], v[20:23]
	v_mfma_f32_16x16x32_bf16 v[16:19], v[202:205], v[218:221], v[16:19]
	v_mfma_f32_16x16x32_bf16 v[12:15], v[194:197], v[226:229], v[12:15]
	v_mfma_f32_16x16x32_bf16 v[8:11], v[202:205], v[226:229], v[8:11]
	v_mfma_f32_16x16x32_bf16 v[4:7], v[194:197], v[234:237], v[4:7]
	v_mfma_f32_16x16x32_bf16 v[0:3], v[202:205], v[234:237], v[0:3]
	s_setprio 0
	s_barrier
	s_add_i32 s70, 0, 0x18000
	v_add_u32_e32 v153, s70, v173
	s_add_i32 s71, 0, 0x1c000
	ds_read_b128 v[132:135], v153
	ds_read_b128 v[136:139], v153 offset:1024
	ds_read_b128 v[140:143], v153 offset:2048
	ds_read_b128 v[162:165], v153 offset:3072
	v_add_u32_e32 v153, s71, v173
	ds_read_b128 v[166:169], v153
	ds_read_b128 v[194:197], v153 offset:1024
	ds_read_b128 v[198:201], v153 offset:2048
	ds_read_b128 v[202:205], v153 offset:3072
	s_add_u32 s44, s44, 0x40000
	s_addc_u32 s45, s45, 0
	s_mov_b32 m0, s54
	ds_read_b128 v[206:209], v174 offset:32768
	ds_read_b128 v[210:213], v174 offset:33792
	ds_read_b128 v[214:217], v174 offset:34816
	ds_read_b128 v[218:221], v174 offset:35840
	ds_read_b128 v[222:225], v174 offset:36864
	ds_read_b128 v[226:229], v174 offset:37888
	ds_read_b128 v[230:233], v174 offset:38912
	ds_read_b128 v[234:237], v174 offset:39936
	global_load_lds_dwordx4 v144, s[44:45]
	v_lshl_add_u64 v[240:241], s[44:45], 0, v[148:149]
	s_mov_b32 m0, s55
	s_nop 0
	global_load_lds_dwordx4 v148, s[44:45]
	s_waitcnt vmcnt(8)
	s_waitcnt lgkmcnt(0)
	s_barrier
	s_setprio 1
	s_waitcnt lgkmcnt(0)
	v_mfma_f32_16x16x32_bf16 v[124:127], v[132:135], v[206:209], v[124:127]
	v_mfma_f32_16x16x32_bf16 v[120:123], v[140:143], v[206:209], v[120:123]
	v_mfma_f32_16x16x32_bf16 v[116:119], v[132:135], v[214:217], v[116:119]
	v_mfma_f32_16x16x32_bf16 v[112:115], v[140:143], v[214:217], v[112:115]
	v_mfma_f32_16x16x32_bf16 v[108:111], v[132:135], v[222:225], v[108:111]
	v_mfma_f32_16x16x32_bf16 v[104:107], v[140:143], v[222:225], v[104:107]
	v_mfma_f32_16x16x32_bf16 v[100:103], v[132:135], v[230:233], v[100:103]
	v_mfma_f32_16x16x32_bf16 v[96:99], v[140:143], v[230:233], v[96:99]
	v_mfma_f32_16x16x32_bf16 v[124:127], v[136:139], v[210:213], v[124:127]
	v_mfma_f32_16x16x32_bf16 v[120:123], v[162:165], v[210:213], v[120:123]
	v_mfma_f32_16x16x32_bf16 v[116:119], v[136:139], v[218:221], v[116:119]
	v_mfma_f32_16x16x32_bf16 v[112:115], v[162:165], v[218:221], v[112:115]
	v_mfma_f32_16x16x32_bf16 v[108:111], v[136:139], v[226:229], v[108:111]
	v_mfma_f32_16x16x32_bf16 v[104:107], v[162:165], v[226:229], v[104:107]
	v_mfma_f32_16x16x32_bf16 v[100:103], v[136:139], v[234:237], v[100:103]
	v_mfma_f32_16x16x32_bf16 v[96:99], v[162:165], v[234:237], v[96:99]
	s_setprio 0
	s_setprio 1
	v_mfma_f32_16x16x32_bf16 v[60:63], v[166:169], v[206:209], v[60:63]
	v_mfma_f32_16x16x32_bf16 v[56:59], v[198:201], v[206:209], v[56:59]
	v_mfma_f32_16x16x32_bf16 v[52:55], v[166:169], v[214:217], v[52:55]
	v_mfma_f32_16x16x32_bf16 v[48:51], v[198:201], v[214:217], v[48:51]
	v_mfma_f32_16x16x32_bf16 v[44:47], v[166:169], v[222:225], v[44:47]
	v_mfma_f32_16x16x32_bf16 v[40:43], v[198:201], v[222:225], v[40:43]
	v_mfma_f32_16x16x32_bf16 v[36:39], v[166:169], v[230:233], v[36:39]
	v_mfma_f32_16x16x32_bf16 v[32:35], v[198:201], v[230:233], v[32:35]
	v_mfma_f32_16x16x32_bf16 v[60:63], v[194:197], v[210:213], v[60:63]
	v_mfma_f32_16x16x32_bf16 v[56:59], v[202:205], v[210:213], v[56:59]
	v_mfma_f32_16x16x32_bf16 v[52:55], v[194:197], v[218:221], v[52:55]
	v_mfma_f32_16x16x32_bf16 v[48:51], v[202:205], v[218:221], v[48:51]
	v_mfma_f32_16x16x32_bf16 v[44:47], v[194:197], v[226:229], v[44:47]
	v_mfma_f32_16x16x32_bf16 v[40:43], v[202:205], v[226:229], v[40:43]
	v_mfma_f32_16x16x32_bf16 v[36:39], v[194:197], v[234:237], v[36:39]
	v_mfma_f32_16x16x32_bf16 v[32:35], v[202:205], v[234:237], v[32:35]
	s_setprio 0
	s_barrier
; #define PG8_STAGE(bufoff, gbase, voff) do { _Pragma("unroll") for (int _i = 0; _i < 2; ++_i) \
;         __builtin_amdgcn_global_load_lds((const unsigned*)((const char*)(gbase) + (voff)[_i]), (PG8_LAS unsigned*)(lds + (bufoff) + ldsw + _i * 8192), 16, 0, 0); } while (0)
; #define PG8_LDA(dst, b, h) do { _Pragma("unroll") for (int m = 0; m < 4; ++m) _Pragma("unroll") for (int k = 0; k < 2; ++k) dst[m][k] = *(const PG8_LAS bf16x8*)(lds + PG8_SA(b, h) + aoff + m * 2048 + k * 1024); } while (0)
; #define PG8_MMA(ai, bj, At, Bt) do { __builtin_amdgcn_s_setprio(1); _Pragma("unroll") for (int m = 0; m < 4; ++m) _Pragma("unroll") for (int n = 0; n < 2; ++n) _Pragma("unroll") for (int k = 0; k < 2; ++k) \
;         acc[ai][bj][m][n] = __builtin_amdgcn_mfma_f32_16x16x32_bf16(Bt[n][k], At[m][k], acc[ai][bj][m][n], 0, 0, 0); __builtin_amdgcn_s_setprio(0); } while (0)
; #define PG8_WAIT_V(n) asm volatile("s_waitcnt vmcnt(" #n ")" ::: "memory")
; #define PG8_WAIT_L(n) asm volatile("s_waitcnt lgkmcnt(" #n ")" ::: "memory")
; #define PG8_BAR __builtin_amdgcn_s_barrier()
; #define PG8_SCHED __builtin_amdgcn_sched_barrier(0)
; template <class Epi, class Sched, bool ALIGN_EPI = false, bool SP2 = false>
; __device__ __forceinline__ void gemm_phase(PG8_LAS unsigned char* lds, const Gemm g, const Sched& S, const Epi& E) {
;     ...
;             PG8_LDA(At, 1, 1); PG8_STAGE(PG8_SB(1, 0), b3, voffB); PG8_STAGE(PG8_SB(1, 1), b3 + hstepB, voffB); PG8_STAGE(PG8_SA(1, 0), a3, voffA);
;             PG8_WAIT_V(8); PG8_WAIT_L(0); PG8_BAR; PG8_MMA(1, 0, At, B0); PG8_MMA(1, 1, At, B1); PG8_BAR; PG8_SCHED;
	s_add_i32 s44, s70, s51
	v_lshl_add_u64 v[170:171], v[170:171], 0, s[18:19]
	s_mov_b32 m0, s44
	ds_read_b128 v[206:209], v174 offset:49152
	ds_read_b128 v[210:213], v174 offset:50176
	ds_read_b128 v[214:217], v174 offset:51200
	ds_read_b128 v[218:221], v174 offset:52224
	ds_read_b128 v[222:225], v174 offset:53248
	ds_read_b128 v[226:229], v174 offset:54272
	ds_read_b128 v[230:233], v174 offset:55296
	ds_read_b128 v[234:237], v174 offset:56320
	global_load_lds_dwordx4 v[170:171], off
	s_add_i32 m0, s44, 0x2000
	s_add_u32 s42, s42, 0x40080
	v_lshl_add_u64 v[170:171], v[238:239], 0, s[18:19]
	s_addc_u32 s43, s43, 0
	s_add_i32 s44, s71, s51
	global_load_lds_dwordx4 v[170:171], off
	s_mov_b32 m0, s44
	s_nop 0
	global_load_lds_dwordx4 v146, s[42:43]
	s_add_i32 m0, s44, 0x2000
	s_nop 0
	global_load_lds_dwordx4 v150, s[42:43]
	s_mov_b32 m0, s60
	s_nop 0
	global_load_lds_dwordx4 v144, s[40:41]
	v_lshl_add_u64 v[170:171], s[40:41], 0, v[148:149]
	s_mov_b32 m0, s61
	s_nop 0
	global_load_lds_dwordx4 v148, s[40:41]
	s_waitcnt vmcnt(8)
	s_waitcnt lgkmcnt(0)
	s_barrier
	s_setprio 1
	s_waitcnt lgkmcnt(0)
	v_mfma_f32_16x16x32_bf16 v[92:95], v[132:135], v[206:209], v[92:95]
	v_mfma_f32_16x16x32_bf16 v[88:91], v[140:143], v[206:209], v[88:91]
	v_mfma_f32_16x16x32_bf16 v[84:87], v[132:135], v[214:217], v[84:87]
	v_mfma_f32_16x16x32_bf16 v[80:83], v[140:143], v[214:217], v[80:83]
	v_mfma_f32_16x16x32_bf16 v[76:79], v[132:135], v[222:225], v[76:79]
	v_mfma_f32_16x16x32_bf16 v[72:75], v[140:143], v[222:225], v[72:75]
	v_mfma_f32_16x16x32_bf16 v[68:71], v[132:135], v[230:233], v[68:71]
	v_mfma_f32_16x16x32_bf16 v[64:67], v[140:143], v[230:233], v[64:67]
	v_mfma_f32_16x16x32_bf16 v[92:95], v[136:139], v[210:213], v[92:95]
	v_mfma_f32_16x16x32_bf16 v[88:91], v[162:165], v[210:213], v[88:91]
	v_mfma_f32_16x16x32_bf16 v[84:87], v[136:139], v[218:221], v[84:87]
	v_mfma_f32_16x16x32_bf16 v[80:83], v[162:165], v[218:221], v[80:83]
	v_mfma_f32_16x16x32_bf16 v[76:79], v[136:139], v[226:229], v[76:79]
	v_mfma_f32_16x16x32_bf16 v[72:75], v[162:165], v[226:229], v[72:75]
	v_mfma_f32_16x16x32_bf16 v[68:71], v[136:139], v[234:237], v[68:71]
	v_mfma_f32_16x16x32_bf16 v[64:67], v[162:165], v[234:237], v[64:67]
	s_setprio 0
	s_setprio 1
	v_mfma_f32_16x16x32_bf16 v[28:31], v[166:169], v[206:209], v[28:31]
	v_mfma_f32_16x16x32_bf16 v[24:27], v[198:201], v[206:209], v[24:27]
	v_mfma_f32_16x16x32_bf16 v[20:23], v[166:169], v[214:217], v[20:23]
	v_mfma_f32_16x16x32_bf16 v[16:19], v[198:201], v[214:217], v[16:19]
	v_mfma_f32_16x16x32_bf16 v[12:15], v[166:169], v[222:225], v[12:15]
	v_mfma_f32_16x16x32_bf16 v[8:11], v[198:201], v[222:225], v[8:11]
	v_mfma_f32_16x16x32_bf16 v[4:7], v[166:169], v[230:233], v[4:7]
	v_mfma_f32_16x16x32_bf16 v[0:3], v[198:201], v[230:233], v[0:3]
	v_mfma_f32_16x16x32_bf16 v[28:31], v[194:197], v[210:213], v[28:31]
	v_mfma_f32_16x16x32_bf16 v[24:27], v[202:205], v[210:213], v[24:27]
	v_mfma_f32_16x16x32_bf16 v[20:23], v[194:197], v[218:221], v[20:23]
	v_mfma_f32_16x16x32_bf16 v[16:19], v[202:205], v[218:221], v[16:19]
	v_mfma_f32_16x16x32_bf16 v[12:15], v[194:197], v[226:229], v[12:15]
	v_mfma_f32_16x16x32_bf16 v[8:11], v[202:205], v[226:229], v[8:11]
	v_mfma_f32_16x16x32_bf16 v[4:7], v[194:197], v[234:237], v[4:7]
	v_mfma_f32_16x16x32_bf16 v[0:3], v[202:205], v[234:237], v[0:3]
	s_setprio 0
	s_barrier
	s_add_i32 s79, s79, 2
	s_add_u32 s38, s38, 0x100
	s_addc_u32 s39, s39, 0
	s_cmp_gt_u32 s79, 13
	s_cbranch_scc0 .LBB0_1841
	s_and_b64 vcc, exec, s[20:21]
	s_cbranch_vccz .LBB0_1844
	s_barrier

; #define PG8_STAGE(bufoff, gbase, voff) do { _Pragma("unroll") for (int _i = 0; _i < 2; ++_i) \
;         __builtin_amdgcn_global_load_lds((const unsigned*)((const char*)(gbase) + (voff)[_i]), (PG8_LAS unsigned*)(lds + (bufoff) + ldsw + _i * 8192), 16, 0, 0); } while (0)
; #define PG8_LDA(dst, b, h) do { _Pragma("unroll") for (int m = 0; m < 4; ++m) _Pragma("unroll") for (int k = 0; k < 2; ++k) dst[m][k] = *(const PG8_LAS bf16x8*)(lds + PG8_SA(b, h) + aoff + m * 2048 + k * 1024); } while (0)
; #define PG8_LDB(dst, b, h) do { _Pragma("unroll") for (int n = 0; n < 2; ++n) _Pragma("unroll") for (int k = 0; k < 2; ++k) dst[n][k] = *(const PG8_LAS bf16x8*)(lds + PG8_SB(b, h) + boff + n * 2048 + k * 1024); } while (0)
; #define PG8_MMA(ai, bj, At, Bt) do { __builtin_amdgcn_s_setprio(1); _Pragma("unroll") for (int m = 0; m < 4; ++m) _Pragma("unroll") for (int n = 0; n < 2; ++n) _Pragma("unroll") for (int k = 0; k < 2; ++k) \
;         acc[ai][bj][m][n] = __builtin_amdgcn_mfma_f32_16x16x32_bf16(Bt[n][k], At[m][k], acc[ai][bj][m][n], 0, 0, 0); __builtin_amdgcn_s_setprio(0); } while (0)
; #define PG8_WAIT_V(n) asm volatile("s_waitcnt vmcnt(" #n ")" ::: "memory")
; #define PG8_WAIT_L(n) asm volatile("s_waitcnt lgkmcnt(" #n ")" ::: "memory")
; #define PG8_BAR __builtin_amdgcn_s_barrier()
; #define PG8_SCHED __builtin_amdgcn_sched_barrier(0)
; template <class Epi, class Sched, bool ALIGN_EPI = false, bool SP2 = false>
; __device__ __forceinline__ void gemm_phase(PG8_LAS unsigned char* lds, const Gemm g, const Sched& S, const Epi& E) {
;     ...
;         for (int t = 0; t < nt; t += 2) {
;             const bool last = (t == nt - 2);
;             const char* a1 = cA + PG8_AK(t + 1);
;             const char* a2 = last ? nA : cA + PG8_AK(t + 2); const char* b2 = last ? nB : cB + (size_t)(t + 2) * kstep;
;             const char* a3 = last ? nA + PG8_AK(1) : cA + PG8_AK(t + 3); const char* b3 = b2 + kstep;
;             if (last && has_next) S.a_ready(nxt);
;             if constexpr (SP2) {
;             PG8_LDB(B0, 0, 0); PG8_LDB(B1, 0, 1); PG8_SCHED; PG8_LDA(At, 0, 0); PG8_STAGE(PG8_SA(1, 1), a1 + hstepA, voffA);
;             PG8_WAIT_V(8); PG8_WAIT_L(0); PG8_BAR; PG8_MMA(0, 0, At, B0); PG8_MMA(0, 1, At, B1); PG8_BAR; PG8_SCHED;
;             PG8_LDA(At, 0, 1); PG8_STAGE(PG8_SB(0, 0), b2, voffB); PG8_STAGE(PG8_SB(0, 1), b2 + hstepB, voffB); PG8_STAGE(PG8_SA(0, 0), a2, voffA);
.LBB0_2888:
	ds_read_b128 v[124:127], v210
	ds_read_b128 v[128:131], v210 offset:1024
	ds_read_b128 v[132:135], v210 offset:2048
	ds_read_b128 v[144:147], v210 offset:3072
	ds_read_b128 v[148:151], v211
	ds_read_b128 v[170:173], v211 offset:1024
	ds_read_b128 v[174:177], v211 offset:2048
	ds_read_b128 v[178:181], v211 offset:3072
	s_add_u32 s42, s38, s40
	s_addc_u32 s43, s39, s41
	s_add_u32 s46, s42, 0x100
	s_addc_u32 s47, s43, 0
	s_add_u32 s44, s78, s40
	s_addc_u32 s45, s79, s41
	s_add_u32 s42, s42, 0x180
	s_addc_u32 s43, s43, 0
	s_cmpk_eq_i32 s40, 0x1500
	s_cselect_b32 s43, s10, s43
	s_cselect_b32 s42, s3, s42
	s_cselect_b32 s45, s37, s45
	s_cselect_b32 s44, s36, s44
	s_cselect_b32 s47, s9, s47
	s_cselect_b32 s46, s8, s46
	v_lshl_add_u64 v[206:207], v[122:123], 0, s[40:41]
	s_add_i32 m0, s53, 0xc000
	ds_read_b128 v[212:215], v191
	ds_read_b128 v[216:219], v191 offset:1024
	ds_read_b128 v[220:223], v191 offset:2048
	ds_read_b128 v[224:227], v191 offset:3072
	ds_read_b128 v[228:231], v191 offset:4096
	ds_read_b128 v[232:235], v191 offset:5120
	ds_read_b128 v[236:239], v191 offset:6144
	ds_read_b128 v[240:243], v191 offset:7168
	global_load_lds_dwordx4 v[206:207], off
	v_lshl_add_u64 v[206:207], v[120:121], 0, s[40:41]
	s_add_i32 m0, s53, 0xe000
	s_nop 0
	global_load_lds_dwordx4 v[206:207], off
	s_waitcnt vmcnt(8)
	s_waitcnt lgkmcnt(0)
	s_barrier
	s_setprio 1
	s_waitcnt lgkmcnt(0)
	v_mfma_f32_16x16x32_bf16 v[140:143], v[124:127], v[212:215], v[140:143]
	v_mfma_f32_16x16x32_bf16 v[136:139], v[132:135], v[212:215], v[136:139]
	v_mfma_f32_16x16x32_bf16 v[116:119], v[124:127], v[220:223], v[116:119]
	v_mfma_f32_16x16x32_bf16 v[112:115], v[132:135], v[220:223], v[112:115]
	v_mfma_f32_16x16x32_bf16 v[108:111], v[124:127], v[228:231], v[108:111]
	v_mfma_f32_16x16x32_bf16 v[104:107], v[132:135], v[228:231], v[104:107]
	v_mfma_f32_16x16x32_bf16 v[100:103], v[124:127], v[236:239], v[100:103]
	v_mfma_f32_16x16x32_bf16 v[96:99], v[132:135], v[236:239], v[96:99]
	v_mfma_f32_16x16x32_bf16 v[140:143], v[128:131], v[216:219], v[140:143]
	v_mfma_f32_16x16x32_bf16 v[136:139], v[144:147], v[216:219], v[136:139]
	v_mfma_f32_16x16x32_bf16 v[116:119], v[128:131], v[224:227], v[116:119]
	v_mfma_f32_16x16x32_bf16 v[112:115], v[144:147], v[224:227], v[112:115]
	v_mfma_f32_16x16x32_bf16 v[108:111], v[128:131], v[232:235], v[108:111]
	v_mfma_f32_16x16x32_bf16 v[104:107], v[144:147], v[232:235], v[104:107]
	v_mfma_f32_16x16x32_bf16 v[100:103], v[128:131], v[240:243], v[100:103]
	v_mfma_f32_16x16x32_bf16 v[96:99], v[144:147], v[240:243], v[96:99]
	s_setprio 0
	s_setprio 1
	v_mfma_f32_16x16x32_bf16 v[60:63], v[148:151], v[212:215], v[60:63]
	v_mfma_f32_16x16x32_bf16 v[56:59], v[174:177], v[212:215], v[56:59]
	v_mfma_f32_16x16x32_bf16 v[52:55], v[148:151], v[220:223], v[52:55]
	v_mfma_f32_16x16x32_bf16 v[48:51], v[174:177], v[220:223], v[48:51]
	v_mfma_f32_16x16x32_bf16 v[44:47], v[148:151], v[228:231], v[44:47]
	v_mfma_f32_16x16x32_bf16 v[40:43], v[174:177], v[228:231], v[40:43]
	v_mfma_f32_16x16x32_bf16 v[36:39], v[148:151], v[236:239], v[36:39]
	v_mfma_f32_16x16x32_bf16 v[32:35], v[174:177], v[236:239], v[32:35]
	v_mfma_f32_16x16x32_bf16 v[60:63], v[170:173], v[216:219], v[60:63]
	v_mfma_f32_16x16x32_bf16 v[56:59], v[178:181], v[216:219], v[56:59]
	v_mfma_f32_16x16x32_bf16 v[52:55], v[170:173], v[224:227], v[52:55]
	v_mfma_f32_16x16x32_bf16 v[48:51], v[178:181], v[224:227], v[48:51]
	v_mfma_f32_16x16x32_bf16 v[44:47], v[170:173], v[232:235], v[44:47]
	v_mfma_f32_16x16x32_bf16 v[40:43], v[178:181], v[232:235], v[40:43]
	v_mfma_f32_16x16x32_bf16 v[36:39], v[170:173], v[240:243], v[36:39]
	v_mfma_f32_16x16x32_bf16 v[32:35], v[178:181], v[240:243], v[32:35]
	s_setprio 0
	s_barrier
	s_add_i32 s70, s69, s52
	v_lshl_add_u64 v[206:207], s[44:45], 0, v[154:155]
	s_mov_b32 m0, s70
	ds_read_b128 v[212:215], v191 offset:16384
	ds_read_b128 v[216:219], v191 offset:17408
	ds_read_b128 v[220:223], v191 offset:18432
	ds_read_b128 v[224:227], v191 offset:19456
	ds_read_b128 v[228:231], v191 offset:20480
	ds_read_b128 v[232:235], v191 offset:21504
	ds_read_b128 v[236:239], v191 offset:22528
	ds_read_b128 v[240:243], v191 offset:23552
	global_load_lds_dwordx4 v154, s[44:45]
	s_add_i32 m0, s70, 0x2000
	s_add_u32 s70, s44, 0xb0000
	v_lshl_add_u64 v[244:245], s[44:45], 0, v[158:159]
	s_addc_u32 s71, s45, 0
	s_add_i32 s87, s80, s52
	global_load_lds_dwordx4 v158, s[44:45]
	s_mov_b32 m0, s87
	s_nop 0
	global_load_lds_dwordx4 v154, s[70:71]
	s_add_i32 m0, s87, 0x2000
	s_nop 0
	global_load_lds_dwordx4 v158, s[70:71]
	s_mov_b32 m0, s53
	s_nop 0
	global_load_lds_dwordx4 v152, s[46:47]
	v_lshl_add_u64 v[246:247], s[46:47], 0, v[156:157]
	s_mov_b32 m0, s54
	s_nop 0
	global_load_lds_dwordx4 v156, s[46:47]
	s_waitcnt vmcnt(8)
	s_waitcnt lgkmcnt(0)
	s_barrier
; #define PG8_STAGE(bufoff, gbase, voff) do { _Pragma("unroll") for (int _i = 0; _i < 2; ++_i) \
;         __builtin_amdgcn_global_load_lds((const unsigned*)((const char*)(gbase) + (voff)[_i]), (PG8_LAS unsigned*)(lds + (bufoff) + ldsw + _i * 8192), 16, 0, 0); } while (0)
; #define PG8_LDA(dst, b, h) do { _Pragma("unroll") for (int m = 0; m < 4; ++m) _Pragma("unroll") for (int k = 0; k < 2; ++k) dst[m][k] = *(const PG8_LAS bf16x8*)(lds + PG8_SA(b, h) + aoff + m * 2048 + k * 1024); } while (0)
; #define PG8_LDB(dst, b, h) do { _Pragma("unroll") for (int n = 0; n < 2; ++n) _Pragma("unroll") for (int k = 0; k < 2; ++k) dst[n][k] = *(const PG8_LAS bf16x8*)(lds + PG8_SB(b, h) + boff + n * 2048 + k * 1024); } while (0)
; #define PG8_MMA(ai, bj, At, Bt) do { __builtin_amdgcn_s_setprio(1); _Pragma("unroll") for (int m = 0; m < 4; ++m) _Pragma("unroll") for (int n = 0; n < 2; ++n) _Pragma("unroll") for (int k = 0; k < 2; ++k) \
;         acc[ai][bj][m][n] = __builtin_amdgcn_mfma_f32_16x16x32_bf16(Bt[n][k], At[m][k], acc[ai][bj][m][n], 0, 0, 0); __builtin_amdgcn_s_setprio(0); } while (0)
; #define PG8_WAIT_V(n) asm volatile("s_waitcnt vmcnt(" #n ")" ::: "memory")
; #define PG8_WAIT_L(n) asm volatile("s_waitcnt lgkmcnt(" #n ")" ::: "memory")
; #define PG8_BAR __builtin_amdgcn_s_barrier()
; #define PG8_SCHED __builtin_amdgcn_sched_barrier(0)
; template <class Epi, class Sched, bool ALIGN_EPI = false, bool SP2 = false>
; __device__ __forceinline__ void gemm_phase(PG8_LAS unsigned char* lds, const Gemm g, const Sched& S, const Epi& E) {
;     ...
;             PG8_WAIT_V(8); PG8_WAIT_L(0); PG8_BAR; PG8_MMA(1, 0, At, B0); PG8_MMA(1, 1, At, B1); PG8_BAR; PG8_SCHED;
;             PG8_LDB(B0, 1, 0); PG8_LDB(B1, 1, 1); PG8_SCHED; PG8_LDA(At, 1, 0); PG8_STAGE(PG8_SA(0, 1), a2 + hstepA, voffA);
;             PG8_WAIT_V(8); PG8_WAIT_L(0); PG8_BAR; PG8_MMA(0, 0, At, B0); PG8_MMA(0, 1, At, B1); PG8_BAR; PG8_SCHED;
	s_setprio 1
	s_waitcnt lgkmcnt(0)
	v_mfma_f32_16x16x32_bf16 v[92:95], v[124:127], v[212:215], v[92:95]
	v_mfma_f32_16x16x32_bf16 v[88:91], v[132:135], v[212:215], v[88:91]
	v_mfma_f32_16x16x32_bf16 v[84:87], v[124:127], v[220:223], v[84:87]
	v_mfma_f32_16x16x32_bf16 v[80:83], v[132:135], v[220:223], v[80:83]
	v_mfma_f32_16x16x32_bf16 v[76:79], v[124:127], v[228:231], v[76:79]
	v_mfma_f32_16x16x32_bf16 v[72:75], v[132:135], v[228:231], v[72:75]
	v_mfma_f32_16x16x32_bf16 v[68:71], v[124:127], v[236:239], v[68:71]
	v_mfma_f32_16x16x32_bf16 v[64:67], v[132:135], v[236:239], v[64:67]
	v_mfma_f32_16x16x32_bf16 v[92:95], v[128:131], v[216:219], v[92:95]
	v_mfma_f32_16x16x32_bf16 v[88:91], v[144:147], v[216:219], v[88:91]
	v_mfma_f32_16x16x32_bf16 v[84:87], v[128:131], v[224:227], v[84:87]
	v_mfma_f32_16x16x32_bf16 v[80:83], v[144:147], v[224:227], v[80:83]
	v_mfma_f32_16x16x32_bf16 v[76:79], v[128:131], v[232:235], v[76:79]
	v_mfma_f32_16x16x32_bf16 v[72:75], v[144:147], v[232:235], v[72:75]
	v_mfma_f32_16x16x32_bf16 v[68:71], v[128:131], v[240:243], v[68:71]
	v_mfma_f32_16x16x32_bf16 v[64:67], v[144:147], v[240:243], v[64:67]
	s_setprio 0
	s_setprio 1
	v_mfma_f32_16x16x32_bf16 v[28:31], v[148:151], v[212:215], v[28:31]
	v_mfma_f32_16x16x32_bf16 v[24:27], v[174:177], v[212:215], v[24:27]
	v_mfma_f32_16x16x32_bf16 v[20:23], v[148:151], v[220:223], v[20:23]
	v_mfma_f32_16x16x32_bf16 v[16:19], v[174:177], v[220:223], v[16:19]
	v_mfma_f32_16x16x32_bf16 v[12:15], v[148:151], v[228:231], v[12:15]
	v_mfma_f32_16x16x32_bf16 v[8:11], v[174:177], v[228:231], v[8:11]
	v_mfma_f32_16x16x32_bf16 v[4:7], v[148:151], v[236:239], v[4:7]
	v_mfma_f32_16x16x32_bf16 v[0:3], v[174:177], v[236:239], v[0:3]
	v_mfma_f32_16x16x32_bf16 v[28:31], v[170:173], v[216:219], v[28:31]
	v_mfma_f32_16x16x32_bf16 v[24:27], v[178:181], v[216:219], v[24:27]
	v_mfma_f32_16x16x32_bf16 v[20:23], v[170:173], v[224:227], v[20:23]
	v_mfma_f32_16x16x32_bf16 v[16:19], v[178:181], v[224:227], v[16:19]
	v_mfma_f32_16x16x32_bf16 v[12:15], v[170:173], v[232:235], v[12:15]
	v_mfma_f32_16x16x32_bf16 v[8:11], v[178:181], v[232:235], v[8:11]
	v_mfma_f32_16x16x32_bf16 v[4:7], v[170:173], v[240:243], v[4:7]
	v_mfma_f32_16x16x32_bf16 v[0:3], v[178:181], v[240:243], v[0:3]
	s_setprio 0
	s_barrier
	s_add_i32 s70, 0, 0x18000
	s_add_i32 s71, 0, 0x1c000
	v_add_u32_e32 v144, s70, v185
	v_add_u32_e32 v161, s71, v185
	ds_read_b128 v[124:127], v144
	ds_read_b128 v[128:131], v144 offset:1024
	ds_read_b128 v[132:135], v144 offset:2048
	ds_read_b128 v[144:147], v144 offset:3072
	ds_read_b128 v[148:151], v161
	ds_read_b128 v[170:173], v161 offset:1024
	ds_read_b128 v[174:177], v161 offset:2048
	ds_read_b128 v[178:181], v161 offset:3072
	s_add_u32 s46, s46, 0xb0000
	s_addc_u32 s47, s47, 0
	s_mov_b32 m0, s55
	ds_read_b128 v[212:215], v191 offset:32768
	ds_read_b128 v[216:219], v191 offset:33792
	ds_read_b128 v[220:223], v191 offset:34816
	ds_read_b128 v[224:227], v191 offset:35840
	ds_read_b128 v[228:231], v191 offset:36864
	ds_read_b128 v[232:235], v191 offset:37888
	ds_read_b128 v[236:239], v191 offset:38912
	ds_read_b128 v[240:243], v191 offset:39936
	global_load_lds_dwordx4 v152, s[46:47]
	v_lshl_add_u64 v[246:247], s[46:47], 0, v[156:157]
	s_mov_b32 m0, s56
	s_nop 0
	global_load_lds_dwordx4 v156, s[46:47]
	s_waitcnt vmcnt(8)
	s_waitcnt lgkmcnt(0)
	s_barrier
	s_setprio 1
	s_waitcnt lgkmcnt(0)
	v_mfma_f32_16x16x32_bf16 v[140:143], v[124:127], v[212:215], v[140:143]
	v_mfma_f32_16x16x32_bf16 v[136:139], v[132:135], v[212:215], v[136:139]
	v_mfma_f32_16x16x32_bf16 v[116:119], v[124:127], v[220:223], v[116:119]
	v_mfma_f32_16x16x32_bf16 v[112:115], v[132:135], v[220:223], v[112:115]
	v_mfma_f32_16x16x32_bf16 v[108:111], v[124:127], v[228:231], v[108:111]
	v_mfma_f32_16x16x32_bf16 v[104:107], v[132:135], v[228:231], v[104:107]
	v_mfma_f32_16x16x32_bf16 v[100:103], v[124:127], v[236:239], v[100:103]
	v_mfma_f32_16x16x32_bf16 v[96:99], v[132:135], v[236:239], v[96:99]
	v_mfma_f32_16x16x32_bf16 v[140:143], v[128:131], v[216:219], v[140:143]
	v_mfma_f32_16x16x32_bf16 v[136:139], v[144:147], v[216:219], v[136:139]
	v_mfma_f32_16x16x32_bf16 v[116:119], v[128:131], v[224:227], v[116:119]
	v_mfma_f32_16x16x32_bf16 v[112:115], v[144:147], v[224:227], v[112:115]
	v_mfma_f32_16x16x32_bf16 v[108:111], v[128:131], v[232:235], v[108:111]
	v_mfma_f32_16x16x32_bf16 v[104:107], v[144:147], v[232:235], v[104:107]
	v_mfma_f32_16x16x32_bf16 v[100:103], v[128:131], v[240:243], v[100:103]
	v_mfma_f32_16x16x32_bf16 v[96:99], v[144:147], v[240:243], v[96:99]
	s_setprio 0
	s_setprio 1
	v_mfma_f32_16x16x32_bf16 v[60:63], v[148:151], v[212:215], v[60:63]
	v_mfma_f32_16x16x32_bf16 v[56:59], v[174:177], v[212:215], v[56:59]
	v_mfma_f32_16x16x32_bf16 v[52:55], v[148:151], v[220:223], v[52:55]
	v_mfma_f32_16x16x32_bf16 v[48:51], v[174:177], v[220:223], v[48:51]
	v_mfma_f32_16x16x32_bf16 v[44:47], v[148:151], v[228:231], v[44:47]
	v_mfma_f32_16x16x32_bf16 v[40:43], v[174:177], v[228:231], v[40:43]
	v_mfma_f32_16x16x32_bf16 v[36:39], v[148:151], v[236:239], v[36:39]
	v_mfma_f32_16x16x32_bf16 v[32:35], v[174:177], v[236:239], v[32:35]
	v_mfma_f32_16x16x32_bf16 v[60:63], v[170:173], v[216:219], v[60:63]
	v_mfma_f32_16x16x32_bf16 v[56:59], v[178:181], v[216:219], v[56:59]
	v_mfma_f32_16x16x32_bf16 v[52:55], v[170:173], v[224:227], v[52:55]
	v_mfma_f32_16x16x32_bf16 v[48:51], v[178:181], v[224:227], v[48:51]
	v_mfma_f32_16x16x32_bf16 v[44:47], v[170:173], v[232:235], v[44:47]
	v_mfma_f32_16x16x32_bf16 v[40:43], v[178:181], v[232:235], v[40:43]
	v_mfma_f32_16x16x32_bf16 v[36:39], v[170:173], v[240:243], v[36:39]
	v_mfma_f32_16x16x32_bf16 v[32:35], v[178:181], v[240:243], v[32:35]
	s_setprio 0
	s_barrier
; #define PG8_STAGE(bufoff, gbase, voff) do { _Pragma("unroll") for (int _i = 0; _i < 2; ++_i) \
;         __builtin_amdgcn_global_load_lds((const unsigned*)((const char*)(gbase) + (voff)[_i]), (PG8_LAS unsigned*)(lds + (bufoff) + ldsw + _i * 8192), 16, 0, 0); } while (0)
; #define PG8_LDA(dst, b, h) do { _Pragma("unroll") for (int m = 0; m < 4; ++m) _Pragma("unroll") for (int k = 0; k < 2; ++k) dst[m][k] = *(const PG8_LAS bf16x8*)(lds + PG8_SA(b, h) + aoff + m * 2048 + k * 1024); } while (0)
; #define PG8_MMA(ai, bj, At, Bt) do { __builtin_amdgcn_s_setprio(1); _Pragma("unroll") for (int m = 0; m < 4; ++m) _Pragma("unroll") for (int n = 0; n < 2; ++n) _Pragma("unroll") for (int k = 0; k < 2; ++k) \
;         acc[ai][bj][m][n] = __builtin_amdgcn_mfma_f32_16x16x32_bf16(Bt[n][k], At[m][k], acc[ai][bj][m][n], 0, 0, 0); __builtin_amdgcn_s_setprio(0); } while (0)
; #define PG8_WAIT_V(n) asm volatile("s_waitcnt vmcnt(" #n ")" ::: "memory")
; #define PG8_WAIT_L(n) asm volatile("s_waitcnt lgkmcnt(" #n ")" ::: "memory")
; #define PG8_BAR __builtin_amdgcn_s_barrier()
; #define PG8_SCHED __builtin_amdgcn_sched_barrier(0)
; template <class Epi, class Sched, bool ALIGN_EPI = false, bool SP2 = false>
; __device__ __forceinline__ void gemm_phase(PG8_LAS unsigned char* lds, const Gemm g, const Sched& S, const Epi& E) {
;     ...
;             PG8_LDA(At, 1, 1); PG8_STAGE(PG8_SB(1, 0), b3, voffB); PG8_STAGE(PG8_SB(1, 1), b3 + hstepB, voffB); PG8_STAGE(PG8_SA(1, 0), a3, voffA);
;             PG8_WAIT_V(8); PG8_WAIT_L(0); PG8_BAR; PG8_MMA(1, 0, At, B0); PG8_MMA(1, 1, At, B1); PG8_BAR; PG8_SCHED;
	s_add_i32 s46, s70, s52
	v_lshl_add_u64 v[206:207], v[206:207], 0, s[26:27]
	s_mov_b32 m0, s46
	ds_read_b128 v[212:215], v191 offset:49152
	ds_read_b128 v[216:219], v191 offset:50176
	ds_read_b128 v[220:223], v191 offset:51200
	ds_read_b128 v[224:227], v191 offset:52224
	ds_read_b128 v[228:231], v191 offset:53248
	ds_read_b128 v[232:235], v191 offset:54272
	ds_read_b128 v[236:239], v191 offset:55296
	ds_read_b128 v[240:243], v191 offset:56320
	global_load_lds_dwordx4 v[206:207], off
	s_add_i32 m0, s46, 0x2000
	s_add_u32 s44, s44, 0xb0080
	v_lshl_add_u64 v[206:207], v[244:245], 0, s[26:27]
	s_addc_u32 s45, s45, 0
	s_add_i32 s46, s71, s52
	global_load_lds_dwordx4 v[206:207], off
	s_mov_b32 m0, s46
	s_nop 0
	global_load_lds_dwordx4 v154, s[44:45]
	s_add_i32 m0, s46, 0x2000
	s_nop 0
	global_load_lds_dwordx4 v158, s[44:45]
	s_mov_b32 m0, s65
	s_nop 0
	global_load_lds_dwordx4 v152, s[42:43]
	v_lshl_add_u64 v[206:207], s[42:43], 0, v[156:157]
	s_mov_b32 m0, s66
	s_nop 0
	global_load_lds_dwordx4 v156, s[42:43]
	s_waitcnt vmcnt(8)
	s_waitcnt lgkmcnt(0)
	s_barrier
	s_setprio 1
	s_waitcnt lgkmcnt(0)
	v_mfma_f32_16x16x32_bf16 v[92:95], v[124:127], v[212:215], v[92:95]
	v_mfma_f32_16x16x32_bf16 v[88:91], v[132:135], v[212:215], v[88:91]
	v_mfma_f32_16x16x32_bf16 v[84:87], v[124:127], v[220:223], v[84:87]
	v_mfma_f32_16x16x32_bf16 v[80:83], v[132:135], v[220:223], v[80:83]
	v_mfma_f32_16x16x32_bf16 v[76:79], v[124:127], v[228:231], v[76:79]
	v_mfma_f32_16x16x32_bf16 v[72:75], v[132:135], v[228:231], v[72:75]
	v_mfma_f32_16x16x32_bf16 v[68:71], v[124:127], v[236:239], v[68:71]
	v_mfma_f32_16x16x32_bf16 v[64:67], v[132:135], v[236:239], v[64:67]
	v_mfma_f32_16x16x32_bf16 v[92:95], v[128:131], v[216:219], v[92:95]
	v_mfma_f32_16x16x32_bf16 v[88:91], v[144:147], v[216:219], v[88:91]
	v_mfma_f32_16x16x32_bf16 v[84:87], v[128:131], v[224:227], v[84:87]
	v_mfma_f32_16x16x32_bf16 v[80:83], v[144:147], v[224:227], v[80:83]
	v_mfma_f32_16x16x32_bf16 v[76:79], v[128:131], v[232:235], v[76:79]
	v_mfma_f32_16x16x32_bf16 v[72:75], v[144:147], v[232:235], v[72:75]
	v_mfma_f32_16x16x32_bf16 v[68:71], v[128:131], v[240:243], v[68:71]
	v_mfma_f32_16x16x32_bf16 v[64:67], v[144:147], v[240:243], v[64:67]
	s_setprio 0
	s_setprio 1
	v_mfma_f32_16x16x32_bf16 v[28:31], v[148:151], v[212:215], v[28:31]
	v_mfma_f32_16x16x32_bf16 v[24:27], v[174:177], v[212:215], v[24:27]
	v_mfma_f32_16x16x32_bf16 v[20:23], v[148:151], v[220:223], v[20:23]
	v_mfma_f32_16x16x32_bf16 v[16:19], v[174:177], v[220:223], v[16:19]
	v_mfma_f32_16x16x32_bf16 v[12:15], v[148:151], v[228:231], v[12:15]
	v_mfma_f32_16x16x32_bf16 v[8:11], v[174:177], v[228:231], v[8:11]
	v_mfma_f32_16x16x32_bf16 v[4:7], v[148:151], v[236:239], v[4:7]
	v_mfma_f32_16x16x32_bf16 v[0:3], v[174:177], v[236:239], v[0:3]
	v_mfma_f32_16x16x32_bf16 v[28:31], v[170:173], v[216:219], v[28:31]
	v_mfma_f32_16x16x32_bf16 v[24:27], v[178:181], v[216:219], v[24:27]
	v_mfma_f32_16x16x32_bf16 v[20:23], v[170:173], v[224:227], v[20:23]
	v_mfma_f32_16x16x32_bf16 v[16:19], v[178:181], v[224:227], v[16:19]
	v_mfma_f32_16x16x32_bf16 v[12:15], v[170:173], v[232:235], v[12:15]
	v_mfma_f32_16x16x32_bf16 v[8:11], v[178:181], v[232:235], v[8:11]
	v_mfma_f32_16x16x32_bf16 v[4:7], v[170:173], v[240:243], v[4:7]
	v_mfma_f32_16x16x32_bf16 v[0:3], v[178:181], v[240:243], v[0:3]
	s_setprio 0
	s_barrier
	s_add_i32 s86, s86, 2
	s_add_u32 s40, s40, 0x100
	s_addc_u32 s41, s41, 0
	s_cmp_gt_u32 s86, 41
	s_cbranch_scc0 .LBB0_2888
	s_and_b64 vcc, exec, s[28:29]
	s_cbranch_vccz .LBB0_2891
	s_barrier

; #define PG8_STAGE(bufoff, gbase, voff) do { _Pragma("unroll") for (int _i = 0; _i < 2; ++_i) \
;         __builtin_amdgcn_global_load_lds((const unsigned*)((const char*)(gbase) + (voff)[_i]), (PG8_LAS unsigned*)(lds + (bufoff) + ldsw + _i * 8192), 16, 0, 0); } while (0)
; #define PG8_LDA(dst, b, h) do { _Pragma("unroll") for (int m = 0; m < 4; ++m) _Pragma("unroll") for (int k = 0; k < 2; ++k) dst[m][k] = *(const PG8_LAS bf16x8*)(lds + PG8_SA(b, h) + aoff + m * 2048 + k * 1024); } while (0)
; #define PG8_LDB(dst, b, h) do { _Pragma("unroll") for (int n = 0; n < 2; ++n) _Pragma("unroll") for (int k = 0; k < 2; ++k) dst[n][k] = *(const PG8_LAS bf16x8*)(lds + PG8_SB(b, h) + boff + n * 2048 + k * 1024); } while (0)
; #define PG8_MMA(ai, bj, At, Bt) do { __builtin_amdgcn_s_setprio(1); _Pragma("unroll") for (int m = 0; m < 4; ++m) _Pragma("unroll") for (int n = 0; n < 2; ++n) _Pragma("unroll") for (int k = 0; k < 2; ++k) \
;         acc[ai][bj][m][n] = __builtin_amdgcn_mfma_f32_16x16x32_bf16(Bt[n][k], At[m][k], acc[ai][bj][m][n], 0, 0, 0); __builtin_amdgcn_s_setprio(0); } while (0)
; #define PG8_WAIT_V(n) asm volatile("s_waitcnt vmcnt(" #n ")" ::: "memory")
; #define PG8_WAIT_L(n) asm volatile("s_waitcnt lgkmcnt(" #n ")" ::: "memory")
; #define PG8_BAR __builtin_amdgcn_s_barrier()
; #define PG8_SCHED __builtin_amdgcn_sched_barrier(0)
; template <class Epi, class Sched, bool ALIGN_EPI = false, bool SP2 = false>
; __device__ __forceinline__ void gemm_phase(PG8_LAS unsigned char* lds, const Gemm g, const Sched& S, const Epi& E) {
;     ...
;         for (int t = 0; t < nt; t += 2) {
;             const bool last = (t == nt - 2);
;             const char* a1 = cA + PG8_AK(t + 1);
;             const char* a2 = last ? nA : cA + PG8_AK(t + 2); const char* b2 = last ? nB : cB + (size_t)(t + 2) * kstep;
;             const char* a3 = last ? nA + PG8_AK(1) : cA + PG8_AK(t + 3); const char* b3 = b2 + kstep;
;             if (last && has_next) S.a_ready(nxt);
;             if constexpr (SP2) {
;             PG8_LDB(B0, 0, 0); PG8_LDB(B1, 0, 1); PG8_SCHED; PG8_LDA(At, 0, 0); PG8_STAGE(PG8_SA(1, 1), a1 + hstepA, voffA);
;             PG8_WAIT_V(8); PG8_WAIT_L(0); PG8_BAR; PG8_MMA(0, 0, At, B0); PG8_MMA(0, 1, At, B1); PG8_BAR; PG8_SCHED;
;             PG8_LDA(At, 0, 1); PG8_STAGE(PG8_SB(0, 0), b2, voffB); PG8_STAGE(PG8_SB(0, 1), b2 + hstepB, voffB); PG8_STAGE(PG8_SA(0, 0), a2, voffA);
.LBB0_2980:
	ds_read_b128 v[108:111], v191
	ds_read_b128 v[112:115], v191 offset:1024
	ds_read_b128 v[116:119], v191 offset:2048
	ds_read_b128 v[120:123], v191 offset:3072
	ds_read_b128 v[124:127], v193
	ds_read_b128 v[128:131], v193 offset:1024
	ds_read_b128 v[132:135], v193 offset:2048
	ds_read_b128 v[160:163], v193 offset:3072
	s_add_u32 s42, s38, s40
	s_addc_u32 s43, s39, s41
	s_add_u32 s46, s42, 0x100
	s_addc_u32 s47, s43, 0
	s_add_u32 s44, s80, s40
	s_addc_u32 s45, s81, s41
	s_add_u32 s42, s42, 0x180
	s_addc_u32 s43, s43, 0
	s_cmpk_eq_i32 s40, 0x700
	s_cselect_b32 s43, s79, s43
	s_cselect_b32 s42, s78, s42
	s_cselect_b32 s45, s27, s45
	s_cselect_b32 s44, s69, s44
	s_cselect_b32 s47, s3, s47
	s_cselect_b32 s46, s29, s46
	v_lshl_add_u64 v[242:243], v[106:107], 0, s[40:41]
	s_add_i32 m0, s54, 0xc000
	ds_read_b128 v[164:167], v187
	ds_read_b128 v[168:171], v187 offset:1024
	ds_read_b128 v[218:221], v187 offset:2048
	ds_read_b128 v[222:225], v187 offset:3072
	ds_read_b128 v[226:229], v187 offset:4096
	ds_read_b128 v[230:233], v187 offset:5120
	ds_read_b128 v[234:237], v187 offset:6144
	ds_read_b128 v[238:241], v187 offset:7168
	global_load_lds_dwordx4 v[242:243], off
	v_lshl_add_u64 v[242:243], v[104:105], 0, s[40:41]
	s_add_i32 m0, s54, 0xe000
	s_nop 0
	global_load_lds_dwordx4 v[242:243], off
	s_waitcnt vmcnt(8)
	s_waitcnt lgkmcnt(0)
	s_barrier
	s_setprio 1
	s_waitcnt lgkmcnt(0)
	v_mfma_f32_16x16x32_bf16 v[156:159], v[108:111], v[164:167], v[156:159]
	v_mfma_f32_16x16x32_bf16 v[152:155], v[116:119], v[164:167], v[152:155]
	v_mfma_f32_16x16x32_bf16 v[148:151], v[108:111], v[218:221], v[148:151]
	v_mfma_f32_16x16x32_bf16 v[144:147], v[116:119], v[218:221], v[144:147]
	v_mfma_f32_16x16x32_bf16 v[140:143], v[108:111], v[226:229], v[140:143]
	v_mfma_f32_16x16x32_bf16 v[136:139], v[116:119], v[226:229], v[136:139]
	v_mfma_f32_16x16x32_bf16 v[100:103], v[108:111], v[234:237], v[100:103]
	v_mfma_f32_16x16x32_bf16 v[96:99], v[116:119], v[234:237], v[96:99]
	v_mfma_f32_16x16x32_bf16 v[156:159], v[112:115], v[168:171], v[156:159]
	v_mfma_f32_16x16x32_bf16 v[152:155], v[120:123], v[168:171], v[152:155]
	v_mfma_f32_16x16x32_bf16 v[148:151], v[112:115], v[222:225], v[148:151]
	v_mfma_f32_16x16x32_bf16 v[144:147], v[120:123], v[222:225], v[144:147]
	v_mfma_f32_16x16x32_bf16 v[140:143], v[112:115], v[230:233], v[140:143]
	v_mfma_f32_16x16x32_bf16 v[136:139], v[120:123], v[230:233], v[136:139]
	v_mfma_f32_16x16x32_bf16 v[100:103], v[112:115], v[238:241], v[100:103]
	v_mfma_f32_16x16x32_bf16 v[96:99], v[120:123], v[238:241], v[96:99]
	s_setprio 0
	s_setprio 1
	v_mfma_f32_16x16x32_bf16 v[60:63], v[124:127], v[164:167], v[60:63]
	v_mfma_f32_16x16x32_bf16 v[56:59], v[132:135], v[164:167], v[56:59]
	v_mfma_f32_16x16x32_bf16 v[52:55], v[124:127], v[218:221], v[52:55]
	v_mfma_f32_16x16x32_bf16 v[48:51], v[132:135], v[218:221], v[48:51]
	v_mfma_f32_16x16x32_bf16 v[44:47], v[124:127], v[226:229], v[44:47]
	v_mfma_f32_16x16x32_bf16 v[40:43], v[132:135], v[226:229], v[40:43]
	v_mfma_f32_16x16x32_bf16 v[36:39], v[124:127], v[234:237], v[36:39]
	v_mfma_f32_16x16x32_bf16 v[32:35], v[132:135], v[234:237], v[32:35]
	v_mfma_f32_16x16x32_bf16 v[60:63], v[128:131], v[168:171], v[60:63]
	v_mfma_f32_16x16x32_bf16 v[56:59], v[160:163], v[168:171], v[56:59]
	v_mfma_f32_16x16x32_bf16 v[52:55], v[128:131], v[222:225], v[52:55]
	v_mfma_f32_16x16x32_bf16 v[48:51], v[160:163], v[222:225], v[48:51]
	v_mfma_f32_16x16x32_bf16 v[44:47], v[128:131], v[230:233], v[44:47]
	v_mfma_f32_16x16x32_bf16 v[40:43], v[160:163], v[230:233], v[40:43]
	v_mfma_f32_16x16x32_bf16 v[36:39], v[128:131], v[238:241], v[36:39]
	v_mfma_f32_16x16x32_bf16 v[32:35], v[160:163], v[238:241], v[32:35]
	s_setprio 0
	s_barrier
	s_add_i32 s70, s66, s53
	v_lshl_add_u64 v[242:243], s[44:45], 0, v[174:175]
	s_mov_b32 m0, s70
	ds_read_b128 v[164:167], v187 offset:16384
	ds_read_b128 v[168:171], v187 offset:17408
	ds_read_b128 v[218:221], v187 offset:18432
	ds_read_b128 v[222:225], v187 offset:19456
	ds_read_b128 v[226:229], v187 offset:20480
	ds_read_b128 v[230:233], v187 offset:21504
	ds_read_b128 v[234:237], v187 offset:22528
	ds_read_b128 v[238:241], v187 offset:23552
	global_load_lds_dwordx4 v174, s[44:45]
	s_add_i32 m0, s70, 0x2000
	s_add_u32 s70, s44, 0x40000
	v_lshl_add_u64 v[244:245], s[44:45], 0, v[178:179]
	s_addc_u32 s71, s45, 0
	s_add_i32 s83, s67, s53
	global_load_lds_dwordx4 v178, s[44:45]
	s_mov_b32 m0, s83
	s_nop 0
	global_load_lds_dwordx4 v174, s[70:71]
	s_add_i32 m0, s83, 0x2000
	s_nop 0
	global_load_lds_dwordx4 v178, s[70:71]
	s_mov_b32 m0, s54
	s_nop 0
	global_load_lds_dwordx4 v172, s[46:47]
	v_lshl_add_u64 v[246:247], s[46:47], 0, v[176:177]
	s_mov_b32 m0, s55
	s_nop 0
	global_load_lds_dwordx4 v176, s[46:47]
	s_waitcnt vmcnt(8)
	s_waitcnt lgkmcnt(0)
	s_barrier
; #define PG8_STAGE(bufoff, gbase, voff) do { _Pragma("unroll") for (int _i = 0; _i < 2; ++_i) \
;         __builtin_amdgcn_global_load_lds((const unsigned*)((const char*)(gbase) + (voff)[_i]), (PG8_LAS unsigned*)(lds + (bufoff) + ldsw + _i * 8192), 16, 0, 0); } while (0)
; #define PG8_LDA(dst, b, h) do { _Pragma("unroll") for (int m = 0; m < 4; ++m) _Pragma("unroll") for (int k = 0; k < 2; ++k) dst[m][k] = *(const PG8_LAS bf16x8*)(lds + PG8_SA(b, h) + aoff + m * 2048 + k * 1024); } while (0)
; #define PG8_LDB(dst, b, h) do { _Pragma("unroll") for (int n = 0; n < 2; ++n) _Pragma("unroll") for (int k = 0; k < 2; ++k) dst[n][k] = *(const PG8_LAS bf16x8*)(lds + PG8_SB(b, h) + boff + n * 2048 + k * 1024); } while (0)
; #define PG8_MMA(ai, bj, At, Bt) do { __builtin_amdgcn_s_setprio(1); _Pragma("unroll") for (int m = 0; m < 4; ++m) _Pragma("unroll") for (int n = 0; n < 2; ++n) _Pragma("unroll") for (int k = 0; k < 2; ++k) \
;         acc[ai][bj][m][n] = __builtin_amdgcn_mfma_f32_16x16x32_bf16(Bt[n][k], At[m][k], acc[ai][bj][m][n], 0, 0, 0); __builtin_amdgcn_s_setprio(0); } while (0)
; #define PG8_WAIT_V(n) asm volatile("s_waitcnt vmcnt(" #n ")" ::: "memory")
; #define PG8_WAIT_L(n) asm volatile("s_waitcnt lgkmcnt(" #n ")" ::: "memory")
; #define PG8_BAR __builtin_amdgcn_s_barrier()
; #define PG8_SCHED __builtin_amdgcn_sched_barrier(0)
; template <class Epi, class Sched, bool ALIGN_EPI = false, bool SP2 = false>
; __device__ __forceinline__ void gemm_phase(PG8_LAS unsigned char* lds, const Gemm g, const Sched& S, const Epi& E) {
;     ...
;             PG8_WAIT_V(8); PG8_WAIT_L(0); PG8_BAR; PG8_MMA(1, 0, At, B0); PG8_MMA(1, 1, At, B1); PG8_BAR; PG8_SCHED;
;             PG8_LDB(B0, 1, 0); PG8_LDB(B1, 1, 1); PG8_SCHED; PG8_LDA(At, 1, 0); PG8_STAGE(PG8_SA(0, 1), a2 + hstepA, voffA);
;             PG8_WAIT_V(8); PG8_WAIT_L(0); PG8_BAR; PG8_MMA(0, 0, At, B0); PG8_MMA(0, 1, At, B1); PG8_BAR; PG8_SCHED;
	s_setprio 1
	s_waitcnt lgkmcnt(0)
	v_mfma_f32_16x16x32_bf16 v[92:95], v[108:111], v[164:167], v[92:95]
	v_mfma_f32_16x16x32_bf16 v[88:91], v[116:119], v[164:167], v[88:91]
	v_mfma_f32_16x16x32_bf16 v[84:87], v[108:111], v[218:221], v[84:87]
	v_mfma_f32_16x16x32_bf16 v[80:83], v[116:119], v[218:221], v[80:83]
	v_mfma_f32_16x16x32_bf16 v[76:79], v[108:111], v[226:229], v[76:79]
	v_mfma_f32_16x16x32_bf16 v[72:75], v[116:119], v[226:229], v[72:75]
	v_mfma_f32_16x16x32_bf16 v[68:71], v[108:111], v[234:237], v[68:71]
	v_mfma_f32_16x16x32_bf16 v[64:67], v[116:119], v[234:237], v[64:67]
	v_mfma_f32_16x16x32_bf16 v[92:95], v[112:115], v[168:171], v[92:95]
	v_mfma_f32_16x16x32_bf16 v[88:91], v[120:123], v[168:171], v[88:91]
	v_mfma_f32_16x16x32_bf16 v[84:87], v[112:115], v[222:225], v[84:87]
	v_mfma_f32_16x16x32_bf16 v[80:83], v[120:123], v[222:225], v[80:83]
	v_mfma_f32_16x16x32_bf16 v[76:79], v[112:115], v[230:233], v[76:79]
	v_mfma_f32_16x16x32_bf16 v[72:75], v[120:123], v[230:233], v[72:75]
	v_mfma_f32_16x16x32_bf16 v[68:71], v[112:115], v[238:241], v[68:71]
	v_mfma_f32_16x16x32_bf16 v[64:67], v[120:123], v[238:241], v[64:67]
	s_setprio 0
	s_setprio 1
	v_mfma_f32_16x16x32_bf16 v[28:31], v[124:127], v[164:167], v[28:31]
	v_mfma_f32_16x16x32_bf16 v[24:27], v[132:135], v[164:167], v[24:27]
	v_mfma_f32_16x16x32_bf16 v[20:23], v[124:127], v[218:221], v[20:23]
	v_mfma_f32_16x16x32_bf16 v[16:19], v[132:135], v[218:221], v[16:19]
	v_mfma_f32_16x16x32_bf16 v[12:15], v[124:127], v[226:229], v[12:15]
	v_mfma_f32_16x16x32_bf16 v[8:11], v[132:135], v[226:229], v[8:11]
	v_mfma_f32_16x16x32_bf16 v[4:7], v[124:127], v[234:237], v[4:7]
	v_mfma_f32_16x16x32_bf16 v[0:3], v[132:135], v[234:237], v[0:3]
	v_mfma_f32_16x16x32_bf16 v[28:31], v[128:131], v[168:171], v[28:31]
	v_mfma_f32_16x16x32_bf16 v[24:27], v[160:163], v[168:171], v[24:27]
	v_mfma_f32_16x16x32_bf16 v[20:23], v[128:131], v[222:225], v[20:23]
	v_mfma_f32_16x16x32_bf16 v[16:19], v[160:163], v[222:225], v[16:19]
	v_mfma_f32_16x16x32_bf16 v[12:15], v[128:131], v[230:233], v[12:15]
	v_mfma_f32_16x16x32_bf16 v[8:11], v[160:163], v[230:233], v[8:11]
	v_mfma_f32_16x16x32_bf16 v[4:7], v[128:131], v[238:241], v[4:7]
	v_mfma_f32_16x16x32_bf16 v[0:3], v[160:163], v[238:241], v[0:3]
	s_setprio 0
	s_barrier
	s_add_i32 s70, 0, 0x18000
	s_add_i32 s71, 0, 0x1c000
	v_add_u32_e32 v120, s70, v181
	v_add_u32_e32 v160, s71, v181
	ds_read_b128 v[108:111], v120
	ds_read_b128 v[112:115], v120 offset:1024
	ds_read_b128 v[116:119], v120 offset:2048
	ds_read_b128 v[120:123], v120 offset:3072
	ds_read_b128 v[124:127], v160
	ds_read_b128 v[128:131], v160 offset:1024
	ds_read_b128 v[132:135], v160 offset:2048
	ds_read_b128 v[160:163], v160 offset:3072
	s_add_u32 s46, s46, 0x40000
	s_addc_u32 s47, s47, 0
	s_mov_b32 m0, s56
	ds_read_b128 v[164:167], v187 offset:32768
	ds_read_b128 v[168:171], v187 offset:33792
	ds_read_b128 v[218:221], v187 offset:34816
	ds_read_b128 v[222:225], v187 offset:35840
	ds_read_b128 v[226:229], v187 offset:36864
	ds_read_b128 v[230:233], v187 offset:37888
	ds_read_b128 v[234:237], v187 offset:38912
	ds_read_b128 v[238:241], v187 offset:39936
	global_load_lds_dwordx4 v172, s[46:47]
	v_lshl_add_u64 v[246:247], s[46:47], 0, v[176:177]
	s_mov_b32 m0, s57
	s_nop 0
	global_load_lds_dwordx4 v176, s[46:47]
	s_waitcnt vmcnt(8)
	s_waitcnt lgkmcnt(0)
	s_barrier
	s_setprio 1
	s_waitcnt lgkmcnt(0)
	v_mfma_f32_16x16x32_bf16 v[156:159], v[108:111], v[164:167], v[156:159]
	v_mfma_f32_16x16x32_bf16 v[152:155], v[116:119], v[164:167], v[152:155]
	v_mfma_f32_16x16x32_bf16 v[148:151], v[108:111], v[218:221], v[148:151]
	v_mfma_f32_16x16x32_bf16 v[144:147], v[116:119], v[218:221], v[144:147]
	v_mfma_f32_16x16x32_bf16 v[140:143], v[108:111], v[226:229], v[140:143]
	v_mfma_f32_16x16x32_bf16 v[136:139], v[116:119], v[226:229], v[136:139]
	v_mfma_f32_16x16x32_bf16 v[100:103], v[108:111], v[234:237], v[100:103]
	v_mfma_f32_16x16x32_bf16 v[96:99], v[116:119], v[234:237], v[96:99]
	v_mfma_f32_16x16x32_bf16 v[156:159], v[112:115], v[168:171], v[156:159]
	v_mfma_f32_16x16x32_bf16 v[152:155], v[120:123], v[168:171], v[152:155]
	v_mfma_f32_16x16x32_bf16 v[148:151], v[112:115], v[222:225], v[148:151]
	v_mfma_f32_16x16x32_bf16 v[144:147], v[120:123], v[222:225], v[144:147]
	v_mfma_f32_16x16x32_bf16 v[140:143], v[112:115], v[230:233], v[140:143]
	v_mfma_f32_16x16x32_bf16 v[136:139], v[120:123], v[230:233], v[136:139]
	v_mfma_f32_16x16x32_bf16 v[100:103], v[112:115], v[238:241], v[100:103]
	v_mfma_f32_16x16x32_bf16 v[96:99], v[120:123], v[238:241], v[96:99]
	s_setprio 0
	s_setprio 1
	v_mfma_f32_16x16x32_bf16 v[60:63], v[124:127], v[164:167], v[60:63]
	v_mfma_f32_16x16x32_bf16 v[56:59], v[132:135], v[164:167], v[56:59]
	v_mfma_f32_16x16x32_bf16 v[52:55], v[124:127], v[218:221], v[52:55]
	v_mfma_f32_16x16x32_bf16 v[48:51], v[132:135], v[218:221], v[48:51]
	v_mfma_f32_16x16x32_bf16 v[44:47], v[124:127], v[226:229], v[44:47]
	v_mfma_f32_16x16x32_bf16 v[40:43], v[132:135], v[226:229], v[40:43]
	v_mfma_f32_16x16x32_bf16 v[36:39], v[124:127], v[234:237], v[36:39]
	v_mfma_f32_16x16x32_bf16 v[32:35], v[132:135], v[234:237], v[32:35]
	v_mfma_f32_16x16x32_bf16 v[60:63], v[128:131], v[168:171], v[60:63]
	v_mfma_f32_16x16x32_bf16 v[56:59], v[160:163], v[168:171], v[56:59]
	v_mfma_f32_16x16x32_bf16 v[52:55], v[128:131], v[222:225], v[52:55]
	v_mfma_f32_16x16x32_bf16 v[48:51], v[160:163], v[222:225], v[48:51]
	v_mfma_f32_16x16x32_bf16 v[44:47], v[128:131], v[230:233], v[44:47]
	v_mfma_f32_16x16x32_bf16 v[40:43], v[160:163], v[230:233], v[40:43]
	v_mfma_f32_16x16x32_bf16 v[36:39], v[128:131], v[238:241], v[36:39]
	v_mfma_f32_16x16x32_bf16 v[32:35], v[160:163], v[238:241], v[32:35]
	s_setprio 0
	s_barrier
; #define PG8_STAGE(bufoff, gbase, voff) do { _Pragma("unroll") for (int _i = 0; _i < 2; ++_i) \
;         __builtin_amdgcn_global_load_lds((const unsigned*)((const char*)(gbase) + (voff)[_i]), (PG8_LAS unsigned*)(lds + (bufoff) + ldsw + _i * 8192), 16, 0, 0); } while (0)
; #define PG8_LDA(dst, b, h) do { _Pragma("unroll") for (int m = 0; m < 4; ++m) _Pragma("unroll") for (int k = 0; k < 2; ++k) dst[m][k] = *(const PG8_LAS bf16x8*)(lds + PG8_SA(b, h) + aoff + m * 2048 + k * 1024); } while (0)
; #define PG8_MMA(ai, bj, At, Bt) do { __builtin_amdgcn_s_setprio(1); _Pragma("unroll") for (int m = 0; m < 4; ++m) _Pragma("unroll") for (int n = 0; n < 2; ++n) _Pragma("unroll") for (int k = 0; k < 2; ++k) \
;         acc[ai][bj][m][n] = __builtin_amdgcn_mfma_f32_16x16x32_bf16(Bt[n][k], At[m][k], acc[ai][bj][m][n], 0, 0, 0); __builtin_amdgcn_s_setprio(0); } while (0)
; #define PG8_WAIT_V(n) asm volatile("s_waitcnt vmcnt(" #n ")" ::: "memory")
; #define PG8_WAIT_L(n) asm volatile("s_waitcnt lgkmcnt(" #n ")" ::: "memory")
; #define PG8_BAR __builtin_amdgcn_s_barrier()
; #define PG8_SCHED __builtin_amdgcn_sched_barrier(0)
; template <class Epi, class Sched, bool ALIGN_EPI = false, bool SP2 = false>
; __device__ __forceinline__ void gemm_phase(PG8_LAS unsigned char* lds, const Gemm g, const Sched& S, const Epi& E) {
;     ...
;             PG8_LDA(At, 1, 1); PG8_STAGE(PG8_SB(1, 0), b3, voffB); PG8_STAGE(PG8_SB(1, 1), b3 + hstepB, voffB); PG8_STAGE(PG8_SA(1, 0), a3, voffA);
;             PG8_WAIT_V(8); PG8_WAIT_L(0); PG8_BAR; PG8_MMA(1, 0, At, B0); PG8_MMA(1, 1, At, B1); PG8_BAR; PG8_SCHED;
	s_add_i32 s46, s70, s53
	v_lshl_add_u64 v[242:243], v[242:243], 0, s[6:7]
	s_mov_b32 m0, s46
	ds_read_b128 v[164:167], v187 offset:49152
	ds_read_b128 v[168:171], v187 offset:50176
	ds_read_b128 v[218:221], v187 offset:51200
	ds_read_b128 v[222:225], v187 offset:52224
	ds_read_b128 v[226:229], v187 offset:53248
	ds_read_b128 v[230:233], v187 offset:54272
	ds_read_b128 v[234:237], v187 offset:55296
	ds_read_b128 v[238:241], v187 offset:56320
	global_load_lds_dwordx4 v[242:243], off
	s_add_i32 m0, s46, 0x2000
	s_add_u32 s44, s44, 0x40080
	v_lshl_add_u64 v[242:243], v[244:245], 0, s[6:7]
	s_addc_u32 s45, s45, 0
	s_add_i32 s46, s71, s53
	global_load_lds_dwordx4 v[242:243], off
	s_mov_b32 m0, s46
	s_nop 0
	global_load_lds_dwordx4 v174, s[44:45]
	s_add_i32 m0, s46, 0x2000
	s_nop 0
	global_load_lds_dwordx4 v178, s[44:45]
	s_mov_b32 m0, s63
	s_nop 0
	global_load_lds_dwordx4 v172, s[42:43]
	v_lshl_add_u64 v[242:243], s[42:43], 0, v[176:177]
	s_mov_b32 m0, s64
	s_nop 0
	global_load_lds_dwordx4 v176, s[42:43]
	s_waitcnt vmcnt(8)
	s_waitcnt lgkmcnt(0)
	s_barrier
	s_setprio 1
	s_waitcnt lgkmcnt(0)
	v_mfma_f32_16x16x32_bf16 v[92:95], v[108:111], v[164:167], v[92:95]
	v_mfma_f32_16x16x32_bf16 v[88:91], v[116:119], v[164:167], v[88:91]
	v_mfma_f32_16x16x32_bf16 v[84:87], v[108:111], v[218:221], v[84:87]
	v_mfma_f32_16x16x32_bf16 v[80:83], v[116:119], v[218:221], v[80:83]
	v_mfma_f32_16x16x32_bf16 v[76:79], v[108:111], v[226:229], v[76:79]
	v_mfma_f32_16x16x32_bf16 v[72:75], v[116:119], v[226:229], v[72:75]
	v_mfma_f32_16x16x32_bf16 v[68:71], v[108:111], v[234:237], v[68:71]
	v_mfma_f32_16x16x32_bf16 v[64:67], v[116:119], v[234:237], v[64:67]
	v_mfma_f32_16x16x32_bf16 v[92:95], v[112:115], v[168:171], v[92:95]
	v_mfma_f32_16x16x32_bf16 v[88:91], v[120:123], v[168:171], v[88:91]
	v_mfma_f32_16x16x32_bf16 v[84:87], v[112:115], v[222:225], v[84:87]
	v_mfma_f32_16x16x32_bf16 v[80:83], v[120:123], v[222:225], v[80:83]
	v_mfma_f32_16x16x32_bf16 v[76:79], v[112:115], v[230:233], v[76:79]
	v_mfma_f32_16x16x32_bf16 v[72:75], v[120:123], v[230:233], v[72:75]
	v_mfma_f32_16x16x32_bf16 v[68:71], v[112:115], v[238:241], v[68:71]
	v_mfma_f32_16x16x32_bf16 v[64:67], v[120:123], v[238:241], v[64:67]
	s_setprio 0
	s_setprio 1
	v_mfma_f32_16x16x32_bf16 v[28:31], v[124:127], v[164:167], v[28:31]
	v_mfma_f32_16x16x32_bf16 v[24:27], v[132:135], v[164:167], v[24:27]
	v_mfma_f32_16x16x32_bf16 v[20:23], v[124:127], v[218:221], v[20:23]
	v_mfma_f32_16x16x32_bf16 v[16:19], v[132:135], v[218:221], v[16:19]
	v_mfma_f32_16x16x32_bf16 v[12:15], v[124:127], v[226:229], v[12:15]
	v_mfma_f32_16x16x32_bf16 v[8:11], v[132:135], v[226:229], v[8:11]
	v_mfma_f32_16x16x32_bf16 v[4:7], v[124:127], v[234:237], v[4:7]
	v_mfma_f32_16x16x32_bf16 v[0:3], v[132:135], v[234:237], v[0:3]
	v_mfma_f32_16x16x32_bf16 v[28:31], v[128:131], v[168:171], v[28:31]
	v_mfma_f32_16x16x32_bf16 v[24:27], v[160:163], v[168:171], v[24:27]
	v_mfma_f32_16x16x32_bf16 v[20:23], v[128:131], v[222:225], v[20:23]
	v_mfma_f32_16x16x32_bf16 v[16:19], v[160:163], v[222:225], v[16:19]
	v_mfma_f32_16x16x32_bf16 v[12:15], v[128:131], v[230:233], v[12:15]
	v_mfma_f32_16x16x32_bf16 v[8:11], v[160:163], v[230:233], v[8:11]
	v_mfma_f32_16x16x32_bf16 v[4:7], v[128:131], v[238:241], v[4:7]
	v_mfma_f32_16x16x32_bf16 v[0:3], v[160:163], v[238:241], v[0:3]
	s_setprio 0
	s_barrier
	s_add_i32 s82, s82, 2
	s_add_u32 s40, s40, 0x100
	s_addc_u32 s41, s41, 0
	s_cmp_gt_u32 s82, 13
	s_cbranch_scc0 .LBB0_2980
	s_and_b64 vcc, exec, s[22:23]
	s_cbranch_vccz .LBB0_2983
	s_barrier
